# GEMM mainloops: LDS-DMA stage loads use scalar base + lane offset (as the GEMM prologue does); 164 vector address adds removed from the load sections
# speedup vs baseline: 1.0150x; 1.0011x over previous
.LBB0_606:
	ds_read_b128 v[148:151], v144
	ds_read_b128 v[152:155], v144 offset:1024
	ds_read_b128 v[156:159], v144 offset:2048
	ds_read_b128 v[160:163], v144 offset:3072
	s_add_u32 s22, s20, 0x100
	s_addc_u32 s23, s21, 0
	s_cmp_eq_u32 s47, 28
	s_cselect_b32 s27, s13, s23
	s_cselect_b32 s26, s41, s22
	s_cselect_b32 s25, s11, s46
	s_cselect_b32 s24, s42, s43
	s_add_i32 m0, s5, 0xc000
	ds_read_b128 v[164:167], v145
	ds_read_b128 v[168:171], v145 offset:1024
	ds_read_b128 v[172:175], v145 offset:2048
	ds_read_b128 v[176:179], v145 offset:3072
	ds_read_b128 v[180:183], v145 offset:4096
	ds_read_b128 v[184:187], v145 offset:5120
	ds_read_b128 v[188:191], v145 offset:6144
	ds_read_b128 v[192:195], v145 offset:7168
	global_load_lds_dwordx4 v134, s[20:21]
	s_add_i32 m0, s5, 0xe000
	s_nop 0
	global_load_lds_dwordx4 v136, s[20:21]
	s_waitcnt lgkmcnt(8)
	s_barrier
	s_waitcnt lgkmcnt(0)
	s_waitcnt lgkmcnt(0)
	v_mfma_f32_16x16x32_bf16 v[124:127], v[148:151], v[164:167], v[124:127]
	v_mfma_f32_16x16x32_bf16 v[120:123], v[156:159], v[164:167], v[120:123]
	v_mfma_f32_16x16x32_bf16 v[108:111], v[148:151], v[172:175], v[108:111]
	v_mfma_f32_16x16x32_bf16 v[104:107], v[156:159], v[172:175], v[104:107]
	v_mfma_f32_16x16x32_bf16 v[92:95], v[148:151], v[180:183], v[92:95]
	v_mfma_f32_16x16x32_bf16 v[88:91], v[156:159], v[180:183], v[88:91]
	v_mfma_f32_16x16x32_bf16 v[76:79], v[148:151], v[188:191], v[76:79]
	v_mfma_f32_16x16x32_bf16 v[72:75], v[156:159], v[188:191], v[72:75]
	v_mfma_f32_16x16x32_bf16 v[124:127], v[152:155], v[168:171], v[124:127]
	v_mfma_f32_16x16x32_bf16 v[120:123], v[160:163], v[168:171], v[120:123]
	v_mfma_f32_16x16x32_bf16 v[108:111], v[152:155], v[176:179], v[108:111]
	v_mfma_f32_16x16x32_bf16 v[104:107], v[160:163], v[176:179], v[104:107]
	v_mfma_f32_16x16x32_bf16 v[92:95], v[152:155], v[184:187], v[92:95]
	v_mfma_f32_16x16x32_bf16 v[88:91], v[160:163], v[184:187], v[88:91]
	v_mfma_f32_16x16x32_bf16 v[76:79], v[152:155], v[192:195], v[76:79]
	v_mfma_f32_16x16x32_bf16 v[72:75], v[160:163], v[192:195], v[72:75]
	s_barrier
	s_add_i32 s20, s38, s2
	s_mov_b32 m0, s20
	ds_read_b128 v[196:199], v146
	ds_read_b128 v[200:203], v146 offset:1024
	ds_read_b128 v[204:207], v146 offset:2048
	ds_read_b128 v[208:211], v146 offset:3072
	global_load_lds_dwordx4 v130, s[24:25]
	s_add_i32 m0, s20, 0x2000
	s_nop 0
	global_load_lds_dwordx4 v128, s[24:25]
	s_barrier
	s_waitcnt lgkmcnt(0)
	s_waitcnt lgkmcnt(0)
	v_mfma_f32_16x16x32_bf16 v[116:119], v[196:199], v[164:167], v[116:119]
	v_mfma_f32_16x16x32_bf16 v[112:115], v[204:207], v[164:167], v[112:115]
	v_mfma_f32_16x16x32_bf16 v[100:103], v[196:199], v[172:175], v[100:103]
	v_mfma_f32_16x16x32_bf16 v[96:99], v[204:207], v[172:175], v[96:99]
	v_mfma_f32_16x16x32_bf16 v[84:87], v[196:199], v[180:183], v[84:87]
	v_mfma_f32_16x16x32_bf16 v[80:83], v[204:207], v[180:183], v[80:83]
	v_mfma_f32_16x16x32_bf16 v[68:71], v[196:199], v[188:191], v[68:71]
	v_mfma_f32_16x16x32_bf16 v[64:67], v[204:207], v[188:191], v[64:67]
	v_mfma_f32_16x16x32_bf16 v[116:119], v[200:203], v[168:171], v[116:119]
	v_mfma_f32_16x16x32_bf16 v[112:115], v[208:211], v[168:171], v[112:115]
	v_mfma_f32_16x16x32_bf16 v[100:103], v[200:203], v[176:179], v[100:103]
	v_mfma_f32_16x16x32_bf16 v[96:99], v[208:211], v[176:179], v[96:99]
	v_mfma_f32_16x16x32_bf16 v[84:87], v[200:203], v[184:187], v[84:87]
	v_mfma_f32_16x16x32_bf16 v[80:83], v[208:211], v[184:187], v[80:83]
	v_mfma_f32_16x16x32_bf16 v[68:71], v[200:203], v[192:195], v[68:71]
	v_mfma_f32_16x16x32_bf16 v[64:67], v[208:211], v[192:195], v[64:67]
	s_mov_b32 m0, s5
	v_lshl_add_u64 v[216:217], s[26:27], 0, v[130:131]
	s_barrier
	ds_read_b128 v[164:167], v145 offset:16384
	ds_read_b128 v[168:171], v145 offset:17408
	ds_read_b128 v[172:175], v145 offset:18432
	ds_read_b128 v[176:179], v145 offset:19456
	ds_read_b128 v[180:183], v145 offset:20480
	ds_read_b128 v[184:187], v145 offset:21504
	ds_read_b128 v[188:191], v145 offset:22528
	ds_read_b128 v[192:195], v145 offset:23552
	global_load_lds_dwordx4 v130, s[26:27]
	v_lshl_add_u64 v[218:219], s[26:27], 0, v[128:129]
	s_mov_b32 m0, s28
	s_nop 0
	global_load_lds_dwordx4 v128, s[26:27]
	s_barrier
	s_waitcnt lgkmcnt(0)
	s_waitcnt lgkmcnt(0)
	v_mfma_f32_16x16x32_bf16 v[60:63], v[148:151], v[164:167], v[60:63]
	v_mfma_f32_16x16x32_bf16 v[56:59], v[156:159], v[164:167], v[56:59]
	v_mfma_f32_16x16x32_bf16 v[44:47], v[148:151], v[172:175], v[44:47]
	v_mfma_f32_16x16x32_bf16 v[40:43], v[156:159], v[172:175], v[40:43]
	v_mfma_f32_16x16x32_bf16 v[28:31], v[148:151], v[180:183], v[28:31]
	v_mfma_f32_16x16x32_bf16 v[24:27], v[156:159], v[180:183], v[24:27]
	v_mfma_f32_16x16x32_bf16 v[12:15], v[148:151], v[188:191], v[12:15]
	v_mfma_f32_16x16x32_bf16 v[8:11], v[156:159], v[188:191], v[8:11]
	v_mfma_f32_16x16x32_bf16 v[60:63], v[152:155], v[168:171], v[60:63]
	v_mfma_f32_16x16x32_bf16 v[56:59], v[160:163], v[168:171], v[56:59]
	v_mfma_f32_16x16x32_bf16 v[44:47], v[152:155], v[176:179], v[44:47]
	v_mfma_f32_16x16x32_bf16 v[40:43], v[160:163], v[176:179], v[40:43]
	v_mfma_f32_16x16x32_bf16 v[28:31], v[152:155], v[184:187], v[28:31]
	v_mfma_f32_16x16x32_bf16 v[24:27], v[160:163], v[184:187], v[24:27]
	v_mfma_f32_16x16x32_bf16 v[12:15], v[152:155], v[192:195], v[12:15]
	v_mfma_f32_16x16x32_bf16 v[8:11], v[160:163], v[192:195], v[8:11]
	s_barrier
	s_add_u32 s20, s24, 0x80000
	s_addc_u32 s21, s25, 0
	s_add_i32 s60, s39, s2
	s_mov_b32 m0, s60
	s_nop 0
	global_load_lds_dwordx4 v130, s[20:21]
	s_add_i32 m0, s60, 0x2000
	s_nop 0
	global_load_lds_dwordx4 v128, s[20:21]
	s_waitcnt vmcnt(6)
	s_barrier
	v_mfma_f32_16x16x32_bf16 v[52:55], v[196:199], v[164:167], v[52:55]
	v_mfma_f32_16x16x32_bf16 v[48:51], v[204:207], v[164:167], v[48:51]
	v_mfma_f32_16x16x32_bf16 v[36:39], v[196:199], v[172:175], v[36:39]
	v_mfma_f32_16x16x32_bf16 v[32:35], v[204:207], v[172:175], v[32:35]
	v_mfma_f32_16x16x32_bf16 v[20:23], v[196:199], v[180:183], v[20:23]
	v_mfma_f32_16x16x32_bf16 v[16:19], v[204:207], v[180:183], v[16:19]
	v_mfma_f32_16x16x32_bf16 v[4:7], v[196:199], v[188:191], v[4:7]
	v_mfma_f32_16x16x32_bf16 v[0:3], v[204:207], v[188:191], v[0:3]
	v_mfma_f32_16x16x32_bf16 v[52:55], v[200:203], v[168:171], v[52:55]
	v_mfma_f32_16x16x32_bf16 v[48:51], v[208:211], v[168:171], v[48:51]
	v_mfma_f32_16x16x32_bf16 v[36:39], v[200:203], v[176:179], v[36:39]
	v_mfma_f32_16x16x32_bf16 v[32:35], v[208:211], v[176:179], v[32:35]
	v_mfma_f32_16x16x32_bf16 v[20:23], v[200:203], v[184:187], v[20:23]
	v_mfma_f32_16x16x32_bf16 v[16:19], v[208:211], v[184:187], v[16:19]
	v_mfma_f32_16x16x32_bf16 v[4:7], v[200:203], v[192:195], v[4:7]
	v_mfma_f32_16x16x32_bf16 v[0:3], v[208:211], v[192:195], v[0:3]
	s_add_i32 s60, 0, 0x18000
	v_add_u32_e32 v147, s60, v143
	s_barrier
	ds_read_b128 v[148:151], v147
	ds_read_b128 v[152:155], v147 offset:1024
	ds_read_b128 v[156:159], v147 offset:2048
	ds_read_b128 v[160:163], v147 offset:3072
	s_add_u32 s20, s26, 0x80000
	s_addc_u32 s21, s27, 0
	s_mov_b32 m0, s29
	ds_read_b128 v[164:167], v145 offset:32768
	ds_read_b128 v[168:171], v145 offset:33792
	ds_read_b128 v[172:175], v145 offset:34816
	ds_read_b128 v[176:179], v145 offset:35840
	ds_read_b128 v[180:183], v145 offset:36864
	ds_read_b128 v[184:187], v145 offset:37888
	ds_read_b128 v[188:191], v145 offset:38912
	ds_read_b128 v[192:195], v145 offset:39936
	global_load_lds_dwordx4 v130, s[20:21]
	s_mov_b32 m0, s30
	s_nop 0
	global_load_lds_dwordx4 v128, s[20:21]
	s_waitcnt lgkmcnt(8)
	s_barrier
	s_waitcnt lgkmcnt(0)
	s_waitcnt lgkmcnt(0)
	v_mfma_f32_16x16x32_bf16 v[124:127], v[148:151], v[164:167], v[124:127]
	v_mfma_f32_16x16x32_bf16 v[120:123], v[156:159], v[164:167], v[120:123]
	v_mfma_f32_16x16x32_bf16 v[108:111], v[148:151], v[172:175], v[108:111]
	v_mfma_f32_16x16x32_bf16 v[104:107], v[156:159], v[172:175], v[104:107]
	v_mfma_f32_16x16x32_bf16 v[92:95], v[148:151], v[180:183], v[92:95]
	v_mfma_f32_16x16x32_bf16 v[88:91], v[156:159], v[180:183], v[88:91]
	v_mfma_f32_16x16x32_bf16 v[76:79], v[148:151], v[188:191], v[76:79]
	v_mfma_f32_16x16x32_bf16 v[72:75], v[156:159], v[188:191], v[72:75]
	v_mfma_f32_16x16x32_bf16 v[124:127], v[152:155], v[168:171], v[124:127]
	v_mfma_f32_16x16x32_bf16 v[120:123], v[160:163], v[168:171], v[120:123]
	v_mfma_f32_16x16x32_bf16 v[108:111], v[152:155], v[176:179], v[108:111]
	v_mfma_f32_16x16x32_bf16 v[104:107], v[160:163], v[176:179], v[104:107]
	v_mfma_f32_16x16x32_bf16 v[92:95], v[152:155], v[184:187], v[92:95]
	v_mfma_f32_16x16x32_bf16 v[88:91], v[160:163], v[184:187], v[88:91]
	v_mfma_f32_16x16x32_bf16 v[76:79], v[152:155], v[192:195], v[76:79]
	v_mfma_f32_16x16x32_bf16 v[72:75], v[160:163], v[192:195], v[72:75]
	s_barrier
	s_add_i32 s26, 0, 0x1c000
	s_add_i32 s20, s60, s2
	v_add_u32_e32 v147, s26, v143
	s_add_u32 s98, s24, s8
	s_addc_u32 s99, s25, s9
	s_mov_b32 m0, s20
	ds_read_b128 v[196:199], v147
	ds_read_b128 v[200:203], v147 offset:1024
	ds_read_b128 v[204:207], v147 offset:2048
	ds_read_b128 v[208:211], v147 offset:3072
	global_load_lds_dwordx4 v130, s[98:99]
	s_add_i32 m0, s20, 0x2000
	s_nop 0
	global_load_lds_dwordx4 v128, s[98:99]
	s_barrier
	s_waitcnt lgkmcnt(0)
	s_waitcnt lgkmcnt(0)
	v_mfma_f32_16x16x32_bf16 v[116:119], v[196:199], v[164:167], v[116:119]
	v_mfma_f32_16x16x32_bf16 v[112:115], v[204:207], v[164:167], v[112:115]
	v_mfma_f32_16x16x32_bf16 v[100:103], v[196:199], v[172:175], v[100:103]
	v_mfma_f32_16x16x32_bf16 v[96:99], v[204:207], v[172:175], v[96:99]
	v_mfma_f32_16x16x32_bf16 v[84:87], v[196:199], v[180:183], v[84:87]
	v_mfma_f32_16x16x32_bf16 v[80:83], v[204:207], v[180:183], v[80:83]
	v_mfma_f32_16x16x32_bf16 v[68:71], v[196:199], v[188:191], v[68:71]
	v_mfma_f32_16x16x32_bf16 v[64:67], v[204:207], v[188:191], v[64:67]
	v_mfma_f32_16x16x32_bf16 v[116:119], v[200:203], v[168:171], v[116:119]
	v_mfma_f32_16x16x32_bf16 v[112:115], v[208:211], v[168:171], v[112:115]
	v_mfma_f32_16x16x32_bf16 v[100:103], v[200:203], v[176:179], v[100:103]
	v_mfma_f32_16x16x32_bf16 v[96:99], v[208:211], v[176:179], v[96:99]
	v_mfma_f32_16x16x32_bf16 v[84:87], v[200:203], v[184:187], v[84:87]
	v_mfma_f32_16x16x32_bf16 v[80:83], v[208:211], v[184:187], v[80:83]
	v_mfma_f32_16x16x32_bf16 v[68:71], v[200:203], v[192:195], v[68:71]
	v_mfma_f32_16x16x32_bf16 v[64:67], v[208:211], v[192:195], v[64:67]
	s_mov_b32 m0, s34
	v_lshl_add_u64 v[212:213], v[216:217], 0, s[8:9]
	s_barrier
	ds_read_b128 v[164:167], v145 offset:49152
	ds_read_b128 v[168:171], v145 offset:50176
	ds_read_b128 v[172:175], v145 offset:51200
	ds_read_b128 v[176:179], v145 offset:52224
	ds_read_b128 v[180:183], v145 offset:53248
	ds_read_b128 v[184:187], v145 offset:54272
	ds_read_b128 v[188:191], v145 offset:55296
	ds_read_b128 v[192:195], v145 offset:56320
	global_load_lds_dwordx4 v[212:213], off
	v_lshl_add_u64 v[212:213], v[218:219], 0, s[8:9]
	s_mov_b32 m0, s35
	s_nop 0
	global_load_lds_dwordx4 v[212:213], off
	s_barrier
	s_waitcnt lgkmcnt(0)
	s_waitcnt lgkmcnt(0)
	v_mfma_f32_16x16x32_bf16 v[60:63], v[148:151], v[164:167], v[60:63]
	v_mfma_f32_16x16x32_bf16 v[56:59], v[156:159], v[164:167], v[56:59]
	v_mfma_f32_16x16x32_bf16 v[44:47], v[148:151], v[172:175], v[44:47]
	v_mfma_f32_16x16x32_bf16 v[40:43], v[156:159], v[172:175], v[40:43]
	v_mfma_f32_16x16x32_bf16 v[28:31], v[148:151], v[180:183], v[28:31]
	v_mfma_f32_16x16x32_bf16 v[24:27], v[156:159], v[180:183], v[24:27]
	v_mfma_f32_16x16x32_bf16 v[12:15], v[148:151], v[188:191], v[12:15]
	v_mfma_f32_16x16x32_bf16 v[8:11], v[156:159], v[188:191], v[8:11]
	v_mfma_f32_16x16x32_bf16 v[60:63], v[152:155], v[168:171], v[60:63]
	v_mfma_f32_16x16x32_bf16 v[56:59], v[160:163], v[168:171], v[56:59]
	v_mfma_f32_16x16x32_bf16 v[44:47], v[152:155], v[176:179], v[44:47]
	v_mfma_f32_16x16x32_bf16 v[40:43], v[160:163], v[176:179], v[40:43]
	v_mfma_f32_16x16x32_bf16 v[28:31], v[152:155], v[184:187], v[28:31]
	v_mfma_f32_16x16x32_bf16 v[24:27], v[160:163], v[184:187], v[24:27]
	v_mfma_f32_16x16x32_bf16 v[12:15], v[152:155], v[192:195], v[12:15]
	v_mfma_f32_16x16x32_bf16 v[8:11], v[160:163], v[192:195], v[8:11]
	s_barrier
	s_add_u32 s20, s24, 0x80080
	s_addc_u32 s21, s25, 0
	s_add_i32 s24, s26, s2
	s_mov_b32 m0, s24
	s_nop 0
	global_load_lds_dwordx4 v130, s[20:21]
	s_add_i32 m0, s24, 0x2000
	s_nop 0
	global_load_lds_dwordx4 v128, s[20:21]
	s_waitcnt vmcnt(6)
	s_barrier
	v_mfma_f32_16x16x32_bf16 v[52:55], v[196:199], v[164:167], v[52:55]
	v_mfma_f32_16x16x32_bf16 v[48:51], v[204:207], v[164:167], v[48:51]
	v_mfma_f32_16x16x32_bf16 v[36:39], v[196:199], v[172:175], v[36:39]
	v_mfma_f32_16x16x32_bf16 v[32:35], v[204:207], v[172:175], v[32:35]
	v_mfma_f32_16x16x32_bf16 v[20:23], v[196:199], v[180:183], v[20:23]
	v_mfma_f32_16x16x32_bf16 v[16:19], v[204:207], v[180:183], v[16:19]
	v_mfma_f32_16x16x32_bf16 v[4:7], v[196:199], v[188:191], v[4:7]
	v_mfma_f32_16x16x32_bf16 v[0:3], v[204:207], v[188:191], v[0:3]
	v_mfma_f32_16x16x32_bf16 v[52:55], v[200:203], v[168:171], v[52:55]
	v_mfma_f32_16x16x32_bf16 v[48:51], v[208:211], v[168:171], v[48:51]
	v_mfma_f32_16x16x32_bf16 v[36:39], v[200:203], v[176:179], v[36:39]
	v_mfma_f32_16x16x32_bf16 v[32:35], v[208:211], v[176:179], v[32:35]
	v_mfma_f32_16x16x32_bf16 v[20:23], v[200:203], v[184:187], v[20:23]
	v_mfma_f32_16x16x32_bf16 v[16:19], v[208:211], v[184:187], v[16:19]
	v_mfma_f32_16x16x32_bf16 v[4:7], v[200:203], v[192:195], v[4:7]
	v_mfma_f32_16x16x32_bf16 v[0:3], v[208:211], v[192:195], v[0:3]
	s_add_i32 s47, s47, 2
	s_add_u32 s43, s43, 0x100
	s_addc_u32 s46, s46, 0
	s_cmp_gt_u32 s47, 29
	s_mov_b64 s[20:21], s[22:23]
	s_barrier
	s_cbranch_scc0 .LBB0_606
	v_mul_f32_e32 v150, 0xbfb8aa3b, v124
	v_mul_f32_e32 v151, 0xbfb8aa3b, v125
	v_exp_f32_e32 v150, v150
	v_exp_f32_e32 v151, v151
	s_lshl_b32 s11, s19, 7
	v_lshl_add_u32 v147, s18, 8, v142
	v_add_f32_e32 v150, 1.0, v150
	v_add_f32_e32 v151, 1.0, v151
	v_rcp_f32_e32 v150, v150
	v_rcp_f32_e32 v151, v151
	s_or_b32 s18, s11, s36
	s_ashr_i32 s19, s18, 31
	v_mad_i64_i32 v[148:149], s[20:21], v147, s40, v[132:133]
	v_pk_mul_f32 v[124:125], v[124:125], v[150:151]
	s_lshl_b64 s[18:19], s[18:19], 1
	v_pk_mul_f32 v[120:121], v[120:121], v[124:125]
	s_and_b64 vcc, exec, s[6:7]
	v_cvt_pk_bf16_f32 v120, v120, v121
	v_mul_f32_e32 v121, 0xbfb8aa3b, v126
	v_exp_f32_e32 v121, v121
	s_mov_b64 s[22:23], s[16:17]
	v_add_f32_e32 v121, 1.0, v121
	v_rcp_f32_e32 v124, v121
	v_mul_f32_e32 v121, 0xbfb8aa3b, v127
	v_exp_f32_e32 v121, v121
	s_nop 0
	v_add_f32_e32 v121, 1.0, v121
	v_rcp_f32_e32 v125, v121
	s_nop 0
	v_pk_mul_f32 v[124:125], v[126:127], v[124:125]
	s_nop 0
	v_pk_mul_f32 v[122:123], v[122:123], v[124:125]
	s_nop 0
	v_cvt_pk_bf16_f32 v121, v122, v123
	v_lshl_add_u64 v[122:123], v[148:149], 0, s[18:19]
	global_store_dwordx2 v[122:123], v[120:121], off
	v_mul_f32_e32 v120, 0xbfb8aa3b, v116
	v_mul_f32_e32 v121, 0xbfb8aa3b, v117
	v_exp_f32_e32 v120, v120
	v_exp_f32_e32 v121, v121
	v_add_f32_e32 v120, 1.0, v120
	v_add_f32_e32 v121, 1.0, v121
	v_rcp_f32_e32 v120, v120
	v_rcp_f32_e32 v121, v121
	s_nop 0
	v_pk_mul_f32 v[116:117], v[116:117], v[120:121]
	s_nop 0
	v_pk_mul_f32 v[112:113], v[112:113], v[116:117]
	s_nop 0
	v_cvt_pk_bf16_f32 v112, v112, v113
	v_mul_f32_e32 v113, 0xbfb8aa3b, v118
	v_exp_f32_e32 v113, v113
	s_nop 0
	v_add_f32_e32 v113, 1.0, v113
	v_rcp_f32_e32 v116, v113
	v_mul_f32_e32 v113, 0xbfb8aa3b, v119
	v_exp_f32_e32 v113, v113
	s_nop 0
	v_add_f32_e32 v113, 1.0, v113
	v_rcp_f32_e32 v117, v113
	s_nop 0
	v_pk_mul_f32 v[116:117], v[118:119], v[116:117]
	s_nop 0
	v_pk_mul_f32 v[114:115], v[114:115], v[116:117]
	s_nop 0
	v_cvt_pk_bf16_f32 v113, v114, v115
	v_mul_f32_e32 v114, 0xbfb8aa3b, v108
	v_mul_f32_e32 v115, 0xbfb8aa3b, v109
	v_exp_f32_e32 v114, v114
	v_exp_f32_e32 v115, v115
	global_store_dwordx2 v[122:123], v[112:113], off offset:128
	v_or_b32_e32 v112, 16, v147
	v_add_f32_e32 v114, 1.0, v114
	v_add_f32_e32 v115, 1.0, v115
	v_rcp_f32_e32 v114, v114
	v_rcp_f32_e32 v115, v115
	v_mad_i64_i32 v[112:113], s[20:21], v112, s40, v[132:133]
	v_pk_mul_f32 v[108:109], v[108:109], v[114:115]
	s_nop 0
	v_pk_mul_f32 v[104:105], v[104:105], v[108:109]
	s_nop 0
	v_cvt_pk_bf16_f32 v104, v104, v105
	v_mul_f32_e32 v105, 0xbfb8aa3b, v110
	v_exp_f32_e32 v105, v105
	s_nop 0
	v_add_f32_e32 v105, 1.0, v105
	v_rcp_f32_e32 v108, v105
	v_mul_f32_e32 v105, 0xbfb8aa3b, v111
	v_exp_f32_e32 v105, v105
	s_nop 0
	v_add_f32_e32 v105, 1.0, v105
	v_rcp_f32_e32 v109, v105
	s_nop 0
	v_pk_mul_f32 v[108:109], v[110:111], v[108:109]
	s_nop 0
	v_pk_mul_f32 v[106:107], v[106:107], v[108:109]
	s_nop 0
	v_cvt_pk_bf16_f32 v105, v106, v107
	v_lshl_add_u64 v[106:107], v[112:113], 0, s[18:19]
	global_store_dwordx2 v[106:107], v[104:105], off
	v_mul_f32_e32 v104, 0xbfb8aa3b, v100
	v_mul_f32_e32 v105, 0xbfb8aa3b, v101
	v_exp_f32_e32 v104, v104
	v_exp_f32_e32 v105, v105
	v_add_f32_e32 v104, 1.0, v104
	v_add_f32_e32 v105, 1.0, v105
	v_rcp_f32_e32 v104, v104
	v_rcp_f32_e32 v105, v105
	s_nop 0
	v_pk_mul_f32 v[100:101], v[100:101], v[104:105]
	s_nop 0
	v_pk_mul_f32 v[96:97], v[96:97], v[100:101]
	s_nop 0
	v_cvt_pk_bf16_f32 v96, v96, v97
	v_mul_f32_e32 v97, 0xbfb8aa3b, v102
	v_exp_f32_e32 v97, v97
	s_nop 0
	v_add_f32_e32 v97, 1.0, v97
	v_rcp_f32_e32 v100, v97
	v_mul_f32_e32 v97, 0xbfb8aa3b, v103
	v_exp_f32_e32 v97, v97
	s_nop 0
	v_add_f32_e32 v97, 1.0, v97
	v_rcp_f32_e32 v101, v97
	s_nop 0
	v_pk_mul_f32 v[100:101], v[102:103], v[100:101]
	s_nop 0
	v_pk_mul_f32 v[98:99], v[98:99], v[100:101]
	s_nop 0
	v_cvt_pk_bf16_f32 v97, v98, v99
	v_mul_f32_e32 v98, 0xbfb8aa3b, v92
	v_mul_f32_e32 v99, 0xbfb8aa3b, v93
	v_exp_f32_e32 v98, v98
	v_exp_f32_e32 v99, v99
	global_store_dwordx2 v[106:107], v[96:97], off offset:128
	v_or_b32_e32 v96, 32, v147
	v_add_f32_e32 v98, 1.0, v98
	v_add_f32_e32 v99, 1.0, v99
	v_rcp_f32_e32 v98, v98
	v_rcp_f32_e32 v99, v99
	v_mad_i64_i32 v[96:97], s[20:21], v96, s40, v[132:133]
	v_pk_mul_f32 v[92:93], v[92:93], v[98:99]
	s_nop 0
	v_pk_mul_f32 v[88:89], v[88:89], v[92:93]
	s_nop 0
	v_cvt_pk_bf16_f32 v88, v88, v89
	v_mul_f32_e32 v89, 0xbfb8aa3b, v94
	v_exp_f32_e32 v89, v89
	s_nop 0
	v_add_f32_e32 v89, 1.0, v89
	v_rcp_f32_e32 v92, v89
	v_mul_f32_e32 v89, 0xbfb8aa3b, v95
	v_exp_f32_e32 v89, v89
	s_nop 0
	v_add_f32_e32 v89, 1.0, v89
	v_rcp_f32_e32 v93, v89
	s_nop 0
	v_pk_mul_f32 v[92:93], v[94:95], v[92:93]
	s_nop 0
	v_pk_mul_f32 v[90:91], v[90:91], v[92:93]
	s_nop 0
	v_cvt_pk_bf16_f32 v89, v90, v91
	v_lshl_add_u64 v[90:91], v[96:97], 0, s[18:19]
	global_store_dwordx2 v[90:91], v[88:89], off
	v_mul_f32_e32 v88, 0xbfb8aa3b, v84
	v_mul_f32_e32 v89, 0xbfb8aa3b, v85
	v_exp_f32_e32 v88, v88
	v_exp_f32_e32 v89, v89
	v_add_f32_e32 v88, 1.0, v88
	v_add_f32_e32 v89, 1.0, v89
	v_rcp_f32_e32 v88, v88
	v_rcp_f32_e32 v89, v89
	s_nop 0
	v_pk_mul_f32 v[84:85], v[84:85], v[88:89]
	s_nop 0
	v_pk_mul_f32 v[80:81], v[80:81], v[84:85]
	s_nop 0
	v_cvt_pk_bf16_f32 v80, v80, v81
	v_mul_f32_e32 v81, 0xbfb8aa3b, v86
	v_exp_f32_e32 v81, v81
	s_nop 0
	v_add_f32_e32 v81, 1.0, v81
	v_rcp_f32_e32 v84, v81
	v_mul_f32_e32 v81, 0xbfb8aa3b, v87
	v_exp_f32_e32 v81, v81
	s_nop 0
	v_add_f32_e32 v81, 1.0, v81
	v_rcp_f32_e32 v85, v81
	s_nop 0
	v_pk_mul_f32 v[84:85], v[86:87], v[84:85]
	s_nop 0
	v_pk_mul_f32 v[82:83], v[82:83], v[84:85]
	s_nop 0
	v_cvt_pk_bf16_f32 v81, v82, v83
	v_mul_f32_e32 v82, 0xbfb8aa3b, v76
	v_mul_f32_e32 v83, 0xbfb8aa3b, v77
	v_exp_f32_e32 v82, v82
	v_exp_f32_e32 v83, v83
	global_store_dwordx2 v[90:91], v[80:81], off offset:128
	v_or_b32_e32 v80, 48, v147
	v_add_f32_e32 v82, 1.0, v82
	v_add_f32_e32 v83, 1.0, v83
	v_rcp_f32_e32 v82, v82
	v_rcp_f32_e32 v83, v83
	v_mad_i64_i32 v[80:81], s[20:21], v80, s40, v[132:133]
	v_pk_mul_f32 v[76:77], v[76:77], v[82:83]
	s_nop 0
	v_pk_mul_f32 v[72:73], v[72:73], v[76:77]
	s_nop 0
	v_cvt_pk_bf16_f32 v72, v72, v73
	v_mul_f32_e32 v73, 0xbfb8aa3b, v78
	v_exp_f32_e32 v73, v73
	s_nop 0
	v_add_f32_e32 v73, 1.0, v73
	v_rcp_f32_e32 v76, v73
	v_mul_f32_e32 v73, 0xbfb8aa3b, v79
	v_exp_f32_e32 v73, v73
	s_nop 0
	v_add_f32_e32 v73, 1.0, v73
	v_rcp_f32_e32 v77, v73
	s_nop 0
	v_pk_mul_f32 v[76:77], v[78:79], v[76:77]
	s_nop 0
	v_pk_mul_f32 v[74:75], v[74:75], v[76:77]
	s_nop 0
	v_cvt_pk_bf16_f32 v73, v74, v75
	v_lshl_add_u64 v[74:75], v[80:81], 0, s[18:19]
	global_store_dwordx2 v[74:75], v[72:73], off
	v_mul_f32_e32 v72, 0xbfb8aa3b, v68
	v_mul_f32_e32 v73, 0xbfb8aa3b, v69
	v_exp_f32_e32 v72, v72
	v_exp_f32_e32 v73, v73
	v_add_f32_e32 v72, 1.0, v72
	v_add_f32_e32 v73, 1.0, v73
	v_rcp_f32_e32 v72, v72
	v_rcp_f32_e32 v73, v73
	s_nop 0
	v_pk_mul_f32 v[68:69], v[68:69], v[72:73]
	s_nop 0
	v_pk_mul_f32 v[64:65], v[64:65], v[68:69]
	s_nop 0
	v_cvt_pk_bf16_f32 v64, v64, v65
	v_mul_f32_e32 v65, 0xbfb8aa3b, v70
	v_exp_f32_e32 v65, v65
	s_nop 0
	v_add_f32_e32 v65, 1.0, v65
	v_rcp_f32_e32 v68, v65
	v_mul_f32_e32 v65, 0xbfb8aa3b, v71
	v_exp_f32_e32 v65, v65
	s_nop 0
	v_add_f32_e32 v65, 1.0, v65
	v_rcp_f32_e32 v69, v65
	s_nop 0
	v_pk_mul_f32 v[68:69], v[70:71], v[68:69]
	s_nop 0
	v_pk_mul_f32 v[66:67], v[66:67], v[68:69]
	s_nop 0
	v_cvt_pk_bf16_f32 v65, v66, v67
	v_mul_f32_e32 v66, 0xbfb8aa3b, v60
	v_mul_f32_e32 v67, 0xbfb8aa3b, v61
	v_exp_f32_e32 v66, v66
	v_exp_f32_e32 v67, v67
	global_store_dwordx2 v[74:75], v[64:65], off offset:128
	v_add_u32_e32 v64, 0x80, v147
	v_add_f32_e32 v66, 1.0, v66
	v_add_f32_e32 v67, 1.0, v67
	v_rcp_f32_e32 v66, v66
	v_rcp_f32_e32 v67, v67
	v_mad_i64_i32 v[64:65], s[20:21], v64, s40, v[132:133]
	v_pk_mul_f32 v[60:61], v[60:61], v[66:67]
	s_nop 0
	v_pk_mul_f32 v[56:57], v[56:57], v[60:61]
	s_nop 0
	v_cvt_pk_bf16_f32 v56, v56, v57
	v_mul_f32_e32 v57, 0xbfb8aa3b, v62
	v_exp_f32_e32 v57, v57
	s_nop 0
	v_add_f32_e32 v57, 1.0, v57
	v_rcp_f32_e32 v60, v57
	v_mul_f32_e32 v57, 0xbfb8aa3b, v63
	v_exp_f32_e32 v57, v57
	s_nop 0
	v_add_f32_e32 v57, 1.0, v57
	v_rcp_f32_e32 v61, v57
	s_nop 0
	v_pk_mul_f32 v[60:61], v[62:63], v[60:61]
	s_nop 0
	v_pk_mul_f32 v[58:59], v[58:59], v[60:61]
	s_nop 0
	v_cvt_pk_bf16_f32 v57, v58, v59
	v_lshl_add_u64 v[58:59], v[64:65], 0, s[18:19]
	global_store_dwordx2 v[58:59], v[56:57], off
	v_mul_f32_e32 v56, 0xbfb8aa3b, v52
	v_mul_f32_e32 v57, 0xbfb8aa3b, v53
	v_exp_f32_e32 v56, v56
	v_exp_f32_e32 v57, v57
	v_add_f32_e32 v56, 1.0, v56
	v_add_f32_e32 v57, 1.0, v57
	v_rcp_f32_e32 v56, v56
	v_rcp_f32_e32 v57, v57
	s_nop 0
	v_pk_mul_f32 v[52:53], v[52:53], v[56:57]
	s_nop 0
	v_pk_mul_f32 v[48:49], v[48:49], v[52:53]
	s_nop 0
	v_cvt_pk_bf16_f32 v48, v48, v49
	v_mul_f32_e32 v49, 0xbfb8aa3b, v54
	v_exp_f32_e32 v49, v49
	s_nop 0
	v_add_f32_e32 v49, 1.0, v49
	v_rcp_f32_e32 v52, v49
	v_mul_f32_e32 v49, 0xbfb8aa3b, v55
	v_exp_f32_e32 v49, v49
	s_nop 0
	v_add_f32_e32 v49, 1.0, v49
	v_rcp_f32_e32 v53, v49
	s_nop 0
	v_pk_mul_f32 v[52:53], v[54:55], v[52:53]
	s_nop 0
	v_pk_mul_f32 v[50:51], v[50:51], v[52:53]
	s_nop 0
	v_cvt_pk_bf16_f32 v49, v50, v51
	v_mul_f32_e32 v50, 0xbfb8aa3b, v44
	v_mul_f32_e32 v51, 0xbfb8aa3b, v45
	v_exp_f32_e32 v50, v50
	v_exp_f32_e32 v51, v51
	global_store_dwordx2 v[58:59], v[48:49], off offset:128
	v_add_u32_e32 v48, 0x90, v147
	v_add_f32_e32 v50, 1.0, v50
	v_add_f32_e32 v51, 1.0, v51
	v_rcp_f32_e32 v50, v50
	v_rcp_f32_e32 v51, v51
	v_mad_i64_i32 v[48:49], s[20:21], v48, s40, v[132:133]
	v_pk_mul_f32 v[44:45], v[44:45], v[50:51]
	s_nop 0
	v_pk_mul_f32 v[40:41], v[40:41], v[44:45]
	s_nop 0
	v_cvt_pk_bf16_f32 v40, v40, v41
	v_mul_f32_e32 v41, 0xbfb8aa3b, v46
	v_exp_f32_e32 v41, v41
	s_nop 0
	v_add_f32_e32 v41, 1.0, v41
	v_rcp_f32_e32 v44, v41
	v_mul_f32_e32 v41, 0xbfb8aa3b, v47
	v_exp_f32_e32 v41, v41
	s_nop 0
	v_add_f32_e32 v41, 1.0, v41
	v_rcp_f32_e32 v45, v41
	s_nop 0
	v_pk_mul_f32 v[44:45], v[46:47], v[44:45]
	s_nop 0
	v_pk_mul_f32 v[42:43], v[42:43], v[44:45]
	s_nop 0
	v_cvt_pk_bf16_f32 v41, v42, v43
	v_lshl_add_u64 v[42:43], v[48:49], 0, s[18:19]
	global_store_dwordx2 v[42:43], v[40:41], off
	v_mul_f32_e32 v40, 0xbfb8aa3b, v36
	v_mul_f32_e32 v41, 0xbfb8aa3b, v37
	v_exp_f32_e32 v40, v40
	v_exp_f32_e32 v41, v41
	v_add_f32_e32 v40, 1.0, v40
	v_add_f32_e32 v41, 1.0, v41
	v_rcp_f32_e32 v40, v40
	v_rcp_f32_e32 v41, v41
	s_nop 0
	v_pk_mul_f32 v[36:37], v[36:37], v[40:41]
	s_nop 0
	v_pk_mul_f32 v[32:33], v[32:33], v[36:37]
	s_nop 0
	v_cvt_pk_bf16_f32 v32, v32, v33
	v_mul_f32_e32 v33, 0xbfb8aa3b, v38
	v_exp_f32_e32 v33, v33
	s_nop 0
	v_add_f32_e32 v33, 1.0, v33
	v_rcp_f32_e32 v36, v33
	v_mul_f32_e32 v33, 0xbfb8aa3b, v39
	v_exp_f32_e32 v33, v33
	s_nop 0
	v_add_f32_e32 v33, 1.0, v33
	v_rcp_f32_e32 v37, v33
	s_nop 0
	v_pk_mul_f32 v[36:37], v[38:39], v[36:37]
	s_nop 0
	v_pk_mul_f32 v[34:35], v[34:35], v[36:37]
	s_nop 0
	v_cvt_pk_bf16_f32 v33, v34, v35
	v_mul_f32_e32 v34, 0xbfb8aa3b, v28
	v_mul_f32_e32 v35, 0xbfb8aa3b, v29
	v_exp_f32_e32 v34, v34
	v_exp_f32_e32 v35, v35
	global_store_dwordx2 v[42:43], v[32:33], off offset:128
	v_add_u32_e32 v32, 0xa0, v147
	v_add_f32_e32 v34, 1.0, v34
	v_add_f32_e32 v35, 1.0, v35
	v_rcp_f32_e32 v34, v34
	v_rcp_f32_e32 v35, v35
	v_mad_i64_i32 v[32:33], s[20:21], v32, s40, v[132:133]
	v_pk_mul_f32 v[28:29], v[28:29], v[34:35]
	s_nop 0
	v_pk_mul_f32 v[24:25], v[24:25], v[28:29]
	s_nop 0
	v_cvt_pk_bf16_f32 v24, v24, v25
	v_mul_f32_e32 v25, 0xbfb8aa3b, v30
	v_exp_f32_e32 v25, v25
	s_nop 0
	v_add_f32_e32 v25, 1.0, v25
	v_rcp_f32_e32 v28, v25
	v_mul_f32_e32 v25, 0xbfb8aa3b, v31
	v_exp_f32_e32 v25, v25
	s_nop 0
	v_add_f32_e32 v25, 1.0, v25
	v_rcp_f32_e32 v29, v25
	s_nop 0
	v_pk_mul_f32 v[28:29], v[30:31], v[28:29]
	s_nop 0
	v_pk_mul_f32 v[26:27], v[26:27], v[28:29]
	s_nop 0
	v_cvt_pk_bf16_f32 v25, v26, v27
	v_lshl_add_u64 v[26:27], v[32:33], 0, s[18:19]
	global_store_dwordx2 v[26:27], v[24:25], off
	v_mul_f32_e32 v24, 0xbfb8aa3b, v20
	v_mul_f32_e32 v25, 0xbfb8aa3b, v21
	v_exp_f32_e32 v24, v24
	v_exp_f32_e32 v25, v25
	v_add_f32_e32 v24, 1.0, v24
	v_add_f32_e32 v25, 1.0, v25
	v_rcp_f32_e32 v24, v24
	v_rcp_f32_e32 v25, v25
	s_nop 0
	v_pk_mul_f32 v[20:21], v[20:21], v[24:25]
	s_nop 0
	v_pk_mul_f32 v[16:17], v[16:17], v[20:21]
	s_nop 0
	v_cvt_pk_bf16_f32 v16, v16, v17
	v_mul_f32_e32 v17, 0xbfb8aa3b, v22
	v_exp_f32_e32 v17, v17
	s_nop 0
	v_add_f32_e32 v17, 1.0, v17
	v_rcp_f32_e32 v20, v17
	v_mul_f32_e32 v17, 0xbfb8aa3b, v23
	v_exp_f32_e32 v17, v17
	s_nop 0
	v_add_f32_e32 v17, 1.0, v17
	v_rcp_f32_e32 v21, v17
	s_nop 0
	v_pk_mul_f32 v[20:21], v[22:23], v[20:21]
	s_nop 0
	v_pk_mul_f32 v[18:19], v[18:19], v[20:21]
	s_nop 0
	v_cvt_pk_bf16_f32 v17, v18, v19
	v_mul_f32_e32 v18, 0xbfb8aa3b, v12
	v_mul_f32_e32 v19, 0xbfb8aa3b, v13
	v_exp_f32_e32 v18, v18
	v_exp_f32_e32 v19, v19
	global_store_dwordx2 v[26:27], v[16:17], off offset:128
	v_add_u32_e32 v16, 0xb0, v147
	v_add_f32_e32 v18, 1.0, v18
	v_add_f32_e32 v19, 1.0, v19
	v_rcp_f32_e32 v18, v18
	v_rcp_f32_e32 v19, v19
	v_mad_i64_i32 v[16:17], s[20:21], v16, s40, v[132:133]
	s_mov_b64 s[20:21], s[14:15]
	v_pk_mul_f32 v[12:13], v[12:13], v[18:19]
	s_nop 0
	v_pk_mul_f32 v[8:9], v[8:9], v[12:13]
	s_nop 0
	v_cvt_pk_bf16_f32 v8, v8, v9
	v_mul_f32_e32 v9, 0xbfb8aa3b, v14
	v_exp_f32_e32 v9, v9
	s_nop 0
	v_add_f32_e32 v9, 1.0, v9
	v_rcp_f32_e32 v12, v9
	v_mul_f32_e32 v9, 0xbfb8aa3b, v15
	v_exp_f32_e32 v9, v9
	s_nop 0
	v_add_f32_e32 v9, 1.0, v9
	v_rcp_f32_e32 v13, v9
	s_nop 0
	v_pk_mul_f32 v[12:13], v[14:15], v[12:13]
	s_nop 0
	v_pk_mul_f32 v[10:11], v[10:11], v[12:13]
	s_nop 0
	v_cvt_pk_bf16_f32 v9, v10, v11
	v_lshl_add_u64 v[10:11], v[16:17], 0, s[18:19]
	global_store_dwordx2 v[10:11], v[8:9], off
	v_mul_f32_e32 v8, 0xbfb8aa3b, v4
	v_mul_f32_e32 v9, 0xbfb8aa3b, v5
	v_exp_f32_e32 v8, v8
	v_exp_f32_e32 v9, v9
	s_mov_b32 s19, s10
	s_mov_b32 s18, s12
	v_add_f32_e32 v8, 1.0, v8
	v_add_f32_e32 v9, 1.0, v9
	v_rcp_f32_e32 v8, v8
	v_rcp_f32_e32 v9, v9
	s_nop 0
	v_pk_mul_f32 v[4:5], v[4:5], v[8:9]
	s_nop 0
	v_pk_mul_f32 v[0:1], v[0:1], v[4:5]
	s_nop 0
	v_cvt_pk_bf16_f32 v0, v0, v1
	v_mul_f32_e32 v1, 0xbfb8aa3b, v6
	v_exp_f32_e32 v1, v1
	s_nop 0
	v_add_f32_e32 v1, 1.0, v1
	v_rcp_f32_e32 v4, v1
	v_mul_f32_e32 v1, 0xbfb8aa3b, v7
	v_exp_f32_e32 v1, v1
	s_nop 0
	v_add_f32_e32 v1, 1.0, v1
	v_rcp_f32_e32 v5, v1
	s_nop 0
	v_pk_mul_f32 v[4:5], v[6:7], v[4:5]
	s_nop 0
	v_pk_mul_f32 v[2:3], v[2:3], v[4:5]
	s_nop 0
	v_cvt_pk_bf16_f32 v1, v2, v3
	global_store_dwordx2 v[10:11], v[0:1], off offset:128
	s_cbranch_vccz .LBB0_603
	s_waitcnt vmcnt(0)
	s_cmpk_gt_u32 s1, 0xff
	s_cbranch_scc1 .LBB0_610
	s_barrier

.LBB0_682:
	ds_read_b128 v[128:131], v151
	ds_read_b128 v[144:147], v151 offset:1024
	ds_read_b128 v[154:157], v151 offset:2048
	ds_read_b128 v[158:161], v151 offset:3072
	s_add_u32 s16, s14, 0x100
	s_addc_u32 s17, s15, 0
	s_cmpk_eq_i32 s40, 0x54
	s_cselect_b32 s21, s9, s17
	s_cselect_b32 s20, s8, s16
	s_cselect_b32 s19, s11, s39
	s_cselect_b32 s18, s10, s38
	s_add_i32 m0, s4, 0xc000
	ds_read_b128 v[162:165], v152
	ds_read_b128 v[166:169], v152 offset:1024
	ds_read_b128 v[170:173], v152 offset:2048
	ds_read_b128 v[174:177], v152 offset:3072
	ds_read_b128 v[178:181], v152 offset:4096
	ds_read_b128 v[182:185], v152 offset:5120
	ds_read_b128 v[186:189], v152 offset:6144
	ds_read_b128 v[190:193], v152 offset:7168
	global_load_lds_dwordx4 v136, s[14:15]
	v_lshl_add_u64 v[194:195], s[14:15], 0, v[138:139]
	s_add_i32 m0, s4, 0xe000
	s_nop 0
	global_load_lds_dwordx4 v[194:195], off
	s_waitcnt lgkmcnt(8)
	s_barrier
	s_waitcnt lgkmcnt(0)
	s_waitcnt lgkmcnt(0)
	v_mfma_f32_16x16x32_bf16 v[124:127], v[128:131], v[162:165], v[124:127]
	v_mfma_f32_16x16x32_bf16 v[92:95], v[154:157], v[162:165], v[92:95]
	v_mfma_f32_16x16x32_bf16 v[120:123], v[128:131], v[170:173], v[120:123]
	v_mfma_f32_16x16x32_bf16 v[88:91], v[154:157], v[170:173], v[88:91]
	v_mfma_f32_16x16x32_bf16 v[116:119], v[128:131], v[178:181], v[116:119]
	v_mfma_f32_16x16x32_bf16 v[84:87], v[154:157], v[178:181], v[84:87]
	v_mfma_f32_16x16x32_bf16 v[112:115], v[128:131], v[186:189], v[112:115]
	v_mfma_f32_16x16x32_bf16 v[80:83], v[154:157], v[186:189], v[80:83]
	v_mfma_f32_16x16x32_bf16 v[124:127], v[144:147], v[166:169], v[124:127]
	v_mfma_f32_16x16x32_bf16 v[92:95], v[158:161], v[166:169], v[92:95]
	v_mfma_f32_16x16x32_bf16 v[120:123], v[144:147], v[174:177], v[120:123]
	v_mfma_f32_16x16x32_bf16 v[88:91], v[158:161], v[174:177], v[88:91]
	v_mfma_f32_16x16x32_bf16 v[116:119], v[144:147], v[182:185], v[116:119]
	v_mfma_f32_16x16x32_bf16 v[84:87], v[158:161], v[182:185], v[84:87]
	v_mfma_f32_16x16x32_bf16 v[112:115], v[144:147], v[190:193], v[112:115]
	v_mfma_f32_16x16x32_bf16 v[80:83], v[158:161], v[190:193], v[80:83]
	s_barrier
	s_add_i32 s14, s30, s3
	v_lshl_add_u64 v[210:211], s[18:19], 0, v[132:133]
	s_mov_b32 m0, s14
	ds_read_b128 v[194:197], v153
	ds_read_b128 v[198:201], v153 offset:1024
	ds_read_b128 v[202:205], v153 offset:2048
	ds_read_b128 v[206:209], v153 offset:3072
	global_load_lds_dwordx4 v[210:211], off
	s_add_i32 m0, s14, 0x2000
	s_nop 0
	global_load_lds_dwordx4 v134, s[18:19]
	s_barrier
	s_waitcnt lgkmcnt(0)
	s_waitcnt lgkmcnt(0)
	v_mfma_f32_16x16x32_bf16 v[76:79], v[194:197], v[162:165], v[76:79]
	v_mfma_f32_16x16x32_bf16 v[48:51], v[202:205], v[162:165], v[48:51]
	v_mfma_f32_16x16x32_bf16 v[68:71], v[194:197], v[170:173], v[68:71]
	v_mfma_f32_16x16x32_bf16 v[40:43], v[202:205], v[170:173], v[40:43]
	v_mfma_f32_16x16x32_bf16 v[60:63], v[194:197], v[178:181], v[60:63]
	v_mfma_f32_16x16x32_bf16 v[36:39], v[202:205], v[178:181], v[36:39]
	v_mfma_f32_16x16x32_bf16 v[52:55], v[194:197], v[186:189], v[52:55]
	v_mfma_f32_16x16x32_bf16 v[28:31], v[202:205], v[186:189], v[28:31]
	v_mfma_f32_16x16x32_bf16 v[76:79], v[198:201], v[166:169], v[76:79]
	v_mfma_f32_16x16x32_bf16 v[48:51], v[206:209], v[166:169], v[48:51]
	v_mfma_f32_16x16x32_bf16 v[68:71], v[198:201], v[174:177], v[68:71]
	v_mfma_f32_16x16x32_bf16 v[40:43], v[206:209], v[174:177], v[40:43]
	v_mfma_f32_16x16x32_bf16 v[60:63], v[198:201], v[182:185], v[60:63]
	v_mfma_f32_16x16x32_bf16 v[36:39], v[206:209], v[182:185], v[36:39]
	v_mfma_f32_16x16x32_bf16 v[52:55], v[198:201], v[190:193], v[52:55]
	v_mfma_f32_16x16x32_bf16 v[28:31], v[206:209], v[190:193], v[28:31]
	s_mov_b32 m0, s4
	v_lshl_add_u64 v[214:215], s[20:21], 0, v[132:133]
	s_barrier
	ds_read_b128 v[162:165], v152 offset:16384
	ds_read_b128 v[166:169], v152 offset:17408
	ds_read_b128 v[170:173], v152 offset:18432
	ds_read_b128 v[174:177], v152 offset:19456
	ds_read_b128 v[178:181], v152 offset:20480
	ds_read_b128 v[182:185], v152 offset:21504
	ds_read_b128 v[186:189], v152 offset:22528
	ds_read_b128 v[190:193], v152 offset:23552
	global_load_lds_dwordx4 v[214:215], off
	v_lshl_add_u64 v[216:217], s[20:21], 0, v[134:135]
	s_mov_b32 m0, s5
	s_nop 0
	global_load_lds_dwordx4 v134, s[20:21]
	s_barrier
	s_waitcnt lgkmcnt(0)
	s_waitcnt lgkmcnt(0)
	v_mfma_f32_16x16x32_bf16 v[108:111], v[128:131], v[162:165], v[108:111]
	v_mfma_f32_16x16x32_bf16 v[72:75], v[154:157], v[162:165], v[72:75]
	v_mfma_f32_16x16x32_bf16 v[104:107], v[128:131], v[170:173], v[104:107]
	v_mfma_f32_16x16x32_bf16 v[64:67], v[154:157], v[170:173], v[64:67]
	v_mfma_f32_16x16x32_bf16 v[100:103], v[128:131], v[178:181], v[100:103]
	v_mfma_f32_16x16x32_bf16 v[56:59], v[154:157], v[178:181], v[56:59]
	v_mfma_f32_16x16x32_bf16 v[96:99], v[128:131], v[186:189], v[96:99]
	v_mfma_f32_16x16x32_bf16 v[44:47], v[154:157], v[186:189], v[44:47]
	v_mfma_f32_16x16x32_bf16 v[108:111], v[144:147], v[166:169], v[108:111]
	v_mfma_f32_16x16x32_bf16 v[72:75], v[158:161], v[166:169], v[72:75]
	v_mfma_f32_16x16x32_bf16 v[104:107], v[144:147], v[174:177], v[104:107]
	v_mfma_f32_16x16x32_bf16 v[64:67], v[158:161], v[174:177], v[64:67]
	v_mfma_f32_16x16x32_bf16 v[100:103], v[144:147], v[182:185], v[100:103]
	v_mfma_f32_16x16x32_bf16 v[56:59], v[158:161], v[182:185], v[56:59]
	v_mfma_f32_16x16x32_bf16 v[96:99], v[144:147], v[190:193], v[96:99]
	v_mfma_f32_16x16x32_bf16 v[44:47], v[158:161], v[190:193], v[44:47]
	s_barrier
	s_add_u32 s14, s18, 0x160000
	s_addc_u32 s15, s19, 0
	s_add_i32 s41, s31, s3
	v_lshl_add_u64 v[128:129], s[14:15], 0, v[132:133]
	s_mov_b32 m0, s41
	s_nop 0
	global_load_lds_dwordx4 v[128:129], off
	s_add_i32 m0, s41, 0x2000
	s_nop 0
	global_load_lds_dwordx4 v134, s[14:15]
	s_waitcnt vmcnt(6)
	s_barrier
	v_mfma_f32_16x16x32_bf16 v[32:35], v[194:197], v[162:165], v[32:35]
	v_mfma_f32_16x16x32_bf16 v[12:15], v[202:205], v[162:165], v[12:15]
	v_mfma_f32_16x16x32_bf16 v[24:27], v[194:197], v[170:173], v[24:27]
	v_mfma_f32_16x16x32_bf16 v[8:11], v[202:205], v[170:173], v[8:11]
	v_mfma_f32_16x16x32_bf16 v[20:23], v[194:197], v[178:181], v[20:23]
	v_mfma_f32_16x16x32_bf16 v[4:7], v[202:205], v[178:181], v[4:7]
	v_mfma_f32_16x16x32_bf16 v[16:19], v[194:197], v[186:189], v[16:19]
	v_mfma_f32_16x16x32_bf16 v[0:3], v[202:205], v[186:189], v[0:3]
	v_mfma_f32_16x16x32_bf16 v[32:35], v[198:201], v[166:169], v[32:35]
	v_mfma_f32_16x16x32_bf16 v[12:15], v[206:209], v[166:169], v[12:15]
	v_mfma_f32_16x16x32_bf16 v[24:27], v[198:201], v[174:177], v[24:27]
	v_mfma_f32_16x16x32_bf16 v[8:11], v[206:209], v[174:177], v[8:11]
	v_mfma_f32_16x16x32_bf16 v[20:23], v[198:201], v[182:185], v[20:23]
	v_mfma_f32_16x16x32_bf16 v[4:7], v[206:209], v[182:185], v[4:7]
	v_mfma_f32_16x16x32_bf16 v[16:19], v[198:201], v[190:193], v[16:19]
	v_mfma_f32_16x16x32_bf16 v[0:3], v[206:209], v[190:193], v[0:3]
	s_add_i32 s41, 0, 0x18000
	v_add_u32_e32 v158, s41, v149
	s_barrier
	ds_read_b128 v[128:131], v158
	ds_read_b128 v[144:147], v158 offset:1024
	ds_read_b128 v[154:157], v158 offset:2048
	ds_read_b128 v[158:161], v158 offset:3072
	s_add_u32 s14, s20, 0x160000
	s_addc_u32 s15, s21, 0
	s_mov_b32 m0, s22
	v_lshl_add_u64 v[194:195], s[14:15], 0, v[132:133]
	ds_read_b128 v[162:165], v152 offset:32768
	ds_read_b128 v[166:169], v152 offset:33792
	ds_read_b128 v[170:173], v152 offset:34816
	ds_read_b128 v[174:177], v152 offset:35840
	ds_read_b128 v[178:181], v152 offset:36864
	ds_read_b128 v[182:185], v152 offset:37888
	ds_read_b128 v[186:189], v152 offset:38912
	ds_read_b128 v[190:193], v152 offset:39936
	global_load_lds_dwordx4 v[194:195], off
	s_mov_b32 m0, s23
	s_nop 0
	global_load_lds_dwordx4 v134, s[14:15]
	s_waitcnt lgkmcnt(8)
	s_barrier
	s_waitcnt lgkmcnt(0)
	s_waitcnt lgkmcnt(0)
	v_mfma_f32_16x16x32_bf16 v[124:127], v[128:131], v[162:165], v[124:127]
	v_mfma_f32_16x16x32_bf16 v[92:95], v[154:157], v[162:165], v[92:95]
	v_mfma_f32_16x16x32_bf16 v[120:123], v[128:131], v[170:173], v[120:123]
	v_mfma_f32_16x16x32_bf16 v[88:91], v[154:157], v[170:173], v[88:91]
	v_mfma_f32_16x16x32_bf16 v[116:119], v[128:131], v[178:181], v[116:119]
	v_mfma_f32_16x16x32_bf16 v[84:87], v[154:157], v[178:181], v[84:87]
	v_mfma_f32_16x16x32_bf16 v[112:115], v[128:131], v[186:189], v[112:115]
	v_mfma_f32_16x16x32_bf16 v[80:83], v[154:157], v[186:189], v[80:83]
	v_mfma_f32_16x16x32_bf16 v[124:127], v[144:147], v[166:169], v[124:127]
	v_mfma_f32_16x16x32_bf16 v[92:95], v[158:161], v[166:169], v[92:95]
	v_mfma_f32_16x16x32_bf16 v[120:123], v[144:147], v[174:177], v[120:123]
	v_mfma_f32_16x16x32_bf16 v[88:91], v[158:161], v[174:177], v[88:91]
	v_mfma_f32_16x16x32_bf16 v[116:119], v[144:147], v[182:185], v[116:119]
	v_mfma_f32_16x16x32_bf16 v[84:87], v[158:161], v[182:185], v[84:87]
	v_mfma_f32_16x16x32_bf16 v[112:115], v[144:147], v[190:193], v[112:115]
	v_mfma_f32_16x16x32_bf16 v[80:83], v[158:161], v[190:193], v[80:83]
	s_barrier
	s_add_i32 s20, 0, 0x1c000
	s_add_i32 s14, s41, s3
	v_add_u32_e32 v206, s20, v149
	v_lshl_add_u64 v[210:211], v[210:211], 0, s[12:13]
	s_mov_b32 m0, s14
	ds_read_b128 v[194:197], v206
	ds_read_b128 v[198:201], v206 offset:1024
	ds_read_b128 v[202:205], v206 offset:2048
	ds_read_b128 v[206:209], v206 offset:3072
	global_load_lds_dwordx4 v[210:211], off
	s_add_u32 s98, s18, s12
	s_addc_u32 s99, s19, s13
	s_add_i32 m0, s14, 0x2000
	s_nop 0
	global_load_lds_dwordx4 v134, s[98:99]
	s_barrier
	s_waitcnt lgkmcnt(0)
	s_waitcnt lgkmcnt(0)
	v_mfma_f32_16x16x32_bf16 v[76:79], v[194:197], v[162:165], v[76:79]
	v_mfma_f32_16x16x32_bf16 v[48:51], v[202:205], v[162:165], v[48:51]
	v_mfma_f32_16x16x32_bf16 v[68:71], v[194:197], v[170:173], v[68:71]
	v_mfma_f32_16x16x32_bf16 v[40:43], v[202:205], v[170:173], v[40:43]
	v_mfma_f32_16x16x32_bf16 v[60:63], v[194:197], v[178:181], v[60:63]
	v_mfma_f32_16x16x32_bf16 v[36:39], v[202:205], v[178:181], v[36:39]
	v_mfma_f32_16x16x32_bf16 v[52:55], v[194:197], v[186:189], v[52:55]
	v_mfma_f32_16x16x32_bf16 v[28:31], v[202:205], v[186:189], v[28:31]
	v_mfma_f32_16x16x32_bf16 v[76:79], v[198:201], v[166:169], v[76:79]
	v_mfma_f32_16x16x32_bf16 v[48:51], v[206:209], v[166:169], v[48:51]
	v_mfma_f32_16x16x32_bf16 v[68:71], v[198:201], v[174:177], v[68:71]
	v_mfma_f32_16x16x32_bf16 v[40:43], v[206:209], v[174:177], v[40:43]
	v_mfma_f32_16x16x32_bf16 v[60:63], v[198:201], v[182:185], v[60:63]
	v_mfma_f32_16x16x32_bf16 v[36:39], v[206:209], v[182:185], v[36:39]
	v_mfma_f32_16x16x32_bf16 v[52:55], v[198:201], v[190:193], v[52:55]
	v_mfma_f32_16x16x32_bf16 v[28:31], v[206:209], v[190:193], v[28:31]
	s_mov_b32 m0, s25
	v_lshl_add_u64 v[210:211], v[214:215], 0, s[12:13]
	s_barrier
	ds_read_b128 v[162:165], v152 offset:49152
	ds_read_b128 v[166:169], v152 offset:50176
	ds_read_b128 v[170:173], v152 offset:51200
	ds_read_b128 v[174:177], v152 offset:52224
	ds_read_b128 v[178:181], v152 offset:53248
	ds_read_b128 v[182:185], v152 offset:54272
	ds_read_b128 v[186:189], v152 offset:55296
	ds_read_b128 v[190:193], v152 offset:56320
	global_load_lds_dwordx4 v[210:211], off
	v_lshl_add_u64 v[210:211], v[216:217], 0, s[12:13]
	s_mov_b32 m0, s26
	s_nop 0
	global_load_lds_dwordx4 v[210:211], off
	s_barrier
	s_waitcnt lgkmcnt(0)
	s_waitcnt lgkmcnt(0)
	v_mfma_f32_16x16x32_bf16 v[108:111], v[128:131], v[162:165], v[108:111]
	v_mfma_f32_16x16x32_bf16 v[72:75], v[154:157], v[162:165], v[72:75]
	v_mfma_f32_16x16x32_bf16 v[104:107], v[128:131], v[170:173], v[104:107]
	v_mfma_f32_16x16x32_bf16 v[64:67], v[154:157], v[170:173], v[64:67]
	v_mfma_f32_16x16x32_bf16 v[100:103], v[128:131], v[178:181], v[100:103]
	v_mfma_f32_16x16x32_bf16 v[56:59], v[154:157], v[178:181], v[56:59]
	v_mfma_f32_16x16x32_bf16 v[96:99], v[128:131], v[186:189], v[96:99]
	v_mfma_f32_16x16x32_bf16 v[44:47], v[154:157], v[186:189], v[44:47]
	v_mfma_f32_16x16x32_bf16 v[108:111], v[144:147], v[166:169], v[108:111]
	v_mfma_f32_16x16x32_bf16 v[72:75], v[158:161], v[166:169], v[72:75]
	v_mfma_f32_16x16x32_bf16 v[104:107], v[144:147], v[174:177], v[104:107]
	v_mfma_f32_16x16x32_bf16 v[64:67], v[158:161], v[174:177], v[64:67]
	v_mfma_f32_16x16x32_bf16 v[100:103], v[144:147], v[182:185], v[100:103]
	v_mfma_f32_16x16x32_bf16 v[56:59], v[158:161], v[182:185], v[56:59]
	v_mfma_f32_16x16x32_bf16 v[96:99], v[144:147], v[190:193], v[96:99]
	v_mfma_f32_16x16x32_bf16 v[44:47], v[158:161], v[190:193], v[44:47]
	s_barrier
	s_add_u32 s14, s18, 0x160080
	s_addc_u32 s15, s19, 0
	s_add_i32 s18, s20, s3
	v_lshl_add_u64 v[128:129], s[14:15], 0, v[132:133]
	s_mov_b32 m0, s18
	s_nop 0
	global_load_lds_dwordx4 v[128:129], off
	s_add_i32 m0, s18, 0x2000
	s_nop 0
	global_load_lds_dwordx4 v134, s[14:15]
	s_waitcnt vmcnt(6)
	s_barrier
	v_mfma_f32_16x16x32_bf16 v[32:35], v[194:197], v[162:165], v[32:35]
	v_mfma_f32_16x16x32_bf16 v[12:15], v[202:205], v[162:165], v[12:15]
	v_mfma_f32_16x16x32_bf16 v[24:27], v[194:197], v[170:173], v[24:27]
	v_mfma_f32_16x16x32_bf16 v[8:11], v[202:205], v[170:173], v[8:11]
	v_mfma_f32_16x16x32_bf16 v[20:23], v[194:197], v[178:181], v[20:23]
	v_mfma_f32_16x16x32_bf16 v[4:7], v[202:205], v[178:181], v[4:7]
	v_mfma_f32_16x16x32_bf16 v[16:19], v[194:197], v[186:189], v[16:19]
	v_mfma_f32_16x16x32_bf16 v[0:3], v[202:205], v[186:189], v[0:3]
	v_mfma_f32_16x16x32_bf16 v[32:35], v[198:201], v[166:169], v[32:35]
	v_mfma_f32_16x16x32_bf16 v[12:15], v[206:209], v[166:169], v[12:15]
	v_mfma_f32_16x16x32_bf16 v[24:27], v[198:201], v[174:177], v[24:27]
	v_mfma_f32_16x16x32_bf16 v[8:11], v[206:209], v[174:177], v[8:11]
	v_mfma_f32_16x16x32_bf16 v[20:23], v[198:201], v[182:185], v[20:23]
	v_mfma_f32_16x16x32_bf16 v[4:7], v[206:209], v[182:185], v[4:7]
	v_mfma_f32_16x16x32_bf16 v[16:19], v[198:201], v[190:193], v[16:19]
	v_mfma_f32_16x16x32_bf16 v[0:3], v[206:209], v[190:193], v[0:3]
	s_add_i32 s40, s40, 2
	s_add_u32 s38, s38, 0x100
	s_addc_u32 s39, s39, 0
	s_cmpk_gt_u32 s40, 0x55
	s_mov_b64 s[14:15], s[16:17]
	s_barrier
	s_cbranch_scc0 .LBB0_682
	s_cmp_lt_u32 s36, 32
	s_movk_i32 s14, 0x3000
	s_cselect_b32 s14, s14, 0x6000
	s_cmp_gt_i32 s36, 15
	v_lshl_add_u32 v158, s36, 8, v148
	s_cselect_b32 s14, s14, 0
	v_lshl_or_b32 v128, s37, 8, v150
	s_lshl_b32 s14, s14, 2
	v_ashrrev_i32_e32 v159, 31, v158
	s_add_u32 s14, s28, s14
	v_ashrrev_i32_e32 v129, 31, v128
	v_lshlrev_b64 v[146:147], 13, v[158:159]
	s_addc_u32 s15, s29, 0
	v_lshlrev_b64 v[160:161], 2, v[128:129]
	v_lshl_add_u64 v[146:147], s[56:57], 0, v[146:147]
	v_lshl_add_u64 v[144:145], s[14:15], 0, v[160:161]
	v_lshl_add_u64 v[146:147], v[146:147], 0, v[160:161]
	s_mov_b64 s[14:15], 0x100000
	s_mov_b32 s37, s34
	s_mov_b32 s36, s35
	s_mov_b64 s[16:17], s[10:11]
	v_or_b32_e32 v162, 16, v158
	v_ashrrev_i32_e32 v163, 31, v162
	v_lshlrev_b64 v[164:165], 13, v[162:163]
	v_lshl_add_u64 v[162:163], s[56:57], 0, v[164:165]
	v_lshl_add_u64 v[164:165], v[162:163], 0, v[160:161]
	v_or_b32_e32 v162, 32, v158
	v_ashrrev_i32_e32 v163, 31, v162
	v_lshlrev_b64 v[166:167], 13, v[162:163]
	v_lshl_add_u64 v[162:163], s[56:57], 0, v[166:167]
	v_lshl_add_u64 v[166:167], v[162:163], 0, v[160:161]
	v_or_b32_e32 v162, 48, v158
	v_ashrrev_i32_e32 v163, 31, v162
	v_lshlrev_b64 v[168:169], 13, v[162:163]
	v_lshl_add_u64 v[162:163], s[56:57], 0, v[168:169]
	v_lshl_add_u64 v[168:169], v[162:163], 0, v[160:161]
	v_lshl_add_u64 v[162:163], v[146:147], 0, s[14:15]
	s_mov_b32 s14, 0x100000
	v_add_co_u32_e32 v170, vcc, s14, v146
	s_mov_b64 s[14:15], 0x120000
	s_nop 0
	v_addc_co_u32_e32 v171, vcc, 0, v147, vcc
	v_lshl_add_u64 v[172:173], v[146:147], 0, s[14:15]
	s_mov_b32 s14, 0x120000
	v_add_co_u32_e32 v174, vcc, s14, v146
	s_mov_b64 s[14:15], 0x140000
	s_nop 0
	v_addc_co_u32_e32 v175, vcc, 0, v147, vcc
	v_lshl_add_u64 v[176:177], v[146:147], 0, s[14:15]
	s_mov_b32 s14, 0x140000
	v_add_co_u32_e32 v178, vcc, s14, v146
	s_mov_b64 s[14:15], 0x160000
	s_nop 0
	v_addc_co_u32_e32 v179, vcc, 0, v147, vcc
	v_lshl_add_u64 v[180:181], v[146:147], 0, s[14:15]
	s_mov_b32 s14, 0x160000
	v_add_co_u32_e32 v182, vcc, s14, v146
	s_mov_b64 s[14:15], s[8:9]
	s_nop 0
	v_addc_co_u32_e32 v183, vcc, 0, v147, vcc
	s_and_b64 vcc, exec, s[6:7]
	global_load_dwordx4 v[184:187], v[144:145], off
	global_load_dwordx4 v[188:191], v[146:147], off
	v_pk_add_f32 v[126:127], v[126:127], 0 op_sel_hi:[1,0]
	v_pk_add_f32 v[124:125], v[124:125], 0 op_sel_hi:[1,0]
	v_pk_add_f32 v[122:123], v[122:123], 0 op_sel_hi:[1,0]
	v_pk_add_f32 v[120:121], v[120:121], 0 op_sel_hi:[1,0]
	v_pk_add_f32 v[118:119], v[118:119], 0 op_sel_hi:[1,0]
	v_pk_add_f32 v[116:117], v[116:117], 0 op_sel_hi:[1,0]
	v_pk_add_f32 v[114:115], v[114:115], 0 op_sel_hi:[1,0]
	v_pk_add_f32 v[112:113], v[112:113], 0 op_sel_hi:[1,0]
	v_pk_add_f32 v[110:111], v[110:111], 0 op_sel_hi:[1,0]
	v_pk_add_f32 v[108:109], v[108:109], 0 op_sel_hi:[1,0]
	v_pk_add_f32 v[106:107], v[106:107], 0 op_sel_hi:[1,0]
	v_pk_add_f32 v[104:105], v[104:105], 0 op_sel_hi:[1,0]
	v_pk_add_f32 v[102:103], v[102:103], 0 op_sel_hi:[1,0]
	v_pk_add_f32 v[100:101], v[100:101], 0 op_sel_hi:[1,0]
	v_pk_add_f32 v[98:99], v[98:99], 0 op_sel_hi:[1,0]
	v_pk_add_f32 v[96:97], v[96:97], 0 op_sel_hi:[1,0]
	v_pk_add_f32 v[94:95], v[94:95], 0 op_sel_hi:[1,0]
	v_pk_add_f32 v[92:93], v[92:93], 0 op_sel_hi:[1,0]
	v_pk_add_f32 v[90:91], v[90:91], 0 op_sel_hi:[1,0]
	v_pk_add_f32 v[88:89], v[88:89], 0 op_sel_hi:[1,0]
	v_pk_add_f32 v[86:87], v[86:87], 0 op_sel_hi:[1,0]
	v_pk_add_f32 v[84:85], v[84:85], 0 op_sel_hi:[1,0]
	v_pk_add_f32 v[82:83], v[82:83], 0 op_sel_hi:[1,0]
	v_pk_add_f32 v[80:81], v[80:81], 0 op_sel_hi:[1,0]
	v_pk_add_f32 v[74:75], v[74:75], 0 op_sel_hi:[1,0]
	v_pk_add_f32 v[72:73], v[72:73], 0 op_sel_hi:[1,0]
	v_pk_add_f32 v[66:67], v[66:67], 0 op_sel_hi:[1,0]
	v_pk_add_f32 v[64:65], v[64:65], 0 op_sel_hi:[1,0]
	v_pk_add_f32 v[58:59], v[58:59], 0 op_sel_hi:[1,0]
	v_pk_add_f32 v[56:57], v[56:57], 0 op_sel_hi:[1,0]
	v_pk_add_f32 v[46:47], v[46:47], 0 op_sel_hi:[1,0]
	v_pk_add_f32 v[44:45], v[44:45], 0 op_sel_hi:[1,0]
	v_pk_add_f32 v[62:63], v[62:63], 0 op_sel_hi:[1,0]
	v_pk_add_f32 v[60:61], v[60:61], 0 op_sel_hi:[1,0]
	v_pk_add_f32 v[54:55], v[54:55], 0 op_sel_hi:[1,0]
	v_pk_add_f32 v[52:53], v[52:53], 0 op_sel_hi:[1,0]
	v_pk_add_f32 v[34:35], v[34:35], 0 op_sel_hi:[1,0]
	v_pk_add_f32 v[32:33], v[32:33], 0 op_sel_hi:[1,0]
	v_pk_add_f32 v[26:27], v[26:27], 0 op_sel_hi:[1,0]
	v_pk_add_f32 v[24:25], v[24:25], 0 op_sel_hi:[1,0]
	v_pk_add_f32 v[22:23], v[22:23], 0 op_sel_hi:[1,0]
	v_pk_add_f32 v[20:21], v[20:21], 0 op_sel_hi:[1,0]
	v_pk_add_f32 v[18:19], v[18:19], 0 op_sel_hi:[1,0]
	v_pk_add_f32 v[16:17], v[16:17], 0 op_sel_hi:[1,0]
	v_pk_add_f32 v[14:15], v[14:15], 0 op_sel_hi:[1,0]
	v_pk_add_f32 v[12:13], v[12:13], 0 op_sel_hi:[1,0]
	v_pk_add_f32 v[10:11], v[10:11], 0 op_sel_hi:[1,0]
	v_pk_add_f32 v[8:9], v[8:9], 0 op_sel_hi:[1,0]
	v_pk_add_f32 v[6:7], v[6:7], 0 op_sel_hi:[1,0]
	v_pk_add_f32 v[4:5], v[4:5], 0 op_sel_hi:[1,0]
	v_pk_add_f32 v[2:3], v[2:3], 0 op_sel_hi:[1,0]
	v_pk_add_f32 v[0:1], v[0:1], 0 op_sel_hi:[1,0]
	s_waitcnt vmcnt(0)
	v_pk_fma_f32 v[126:127], v[126:127], v[186:187], v[190:191]
	v_pk_fma_f32 v[124:125], v[124:125], v[184:185], v[188:189]
	global_store_dwordx4 v[146:147], v[124:127], off
	global_load_dwordx4 v[188:191], v[164:165], off
	global_load_dwordx4 v[192:195], v[166:167], off
	global_load_dwordx4 v[196:199], v[168:169], off
	global_load_dwordx4 v[200:203], v[170:171], off
	global_load_dwordx4 v[204:207], v[174:175], off
	global_load_dwordx4 v[208:211], v[178:179], off
	global_load_dwordx4 v[212:215], v[182:183], off
	global_load_dwordx4 v[216:219], v[144:145], off offset:64
	global_load_dwordx4 v[220:223], v[146:147], off offset:64
	global_load_dwordx4 v[224:227], v[164:165], off offset:64
	global_load_dwordx4 v[228:231], v[166:167], off offset:64
	global_load_dwordx4 v[232:235], v[168:169], off offset:64
	s_waitcnt vmcnt(11)
	v_pk_fma_f32 v[122:123], v[122:123], v[186:187], v[190:191]
	v_pk_fma_f32 v[120:121], v[120:121], v[184:185], v[188:189]
	global_store_dwordx4 v[164:165], v[120:123], off
	global_load_dwordx4 v[188:191], v[162:163], off offset:64
	s_waitcnt vmcnt(12)
	v_pk_fma_f32 v[118:119], v[118:119], v[186:187], v[194:195]
	v_pk_fma_f32 v[116:117], v[116:117], v[184:185], v[192:193]
	global_store_dwordx4 v[166:167], v[116:119], off
	global_load_dwordx4 v[192:195], v[172:173], off offset:64
	s_waitcnt vmcnt(13)
	v_pk_fma_f32 v[114:115], v[114:115], v[186:187], v[198:199]
	v_pk_fma_f32 v[112:113], v[112:113], v[184:185], v[196:197]
	global_store_dwordx4 v[168:169], v[112:115], off
	global_load_dwordx4 v[196:199], v[176:177], off offset:64
	s_waitcnt vmcnt(14)
	v_pk_fma_f32 v[110:111], v[110:111], v[186:187], v[202:203]
	v_pk_fma_f32 v[108:109], v[108:109], v[184:185], v[200:201]
	global_store_dwordx4 v[170:171], v[108:111], off
	global_load_dwordx4 v[200:203], v[180:181], off offset:64
	s_waitcnt vmcnt(15)
	v_pk_fma_f32 v[106:107], v[106:107], v[186:187], v[206:207]
	v_pk_fma_f32 v[104:105], v[104:105], v[184:185], v[204:205]
	global_store_dwordx4 v[174:175], v[104:107], off
	global_load_dwordx4 v[204:207], v[144:145], off offset:512
	s_waitcnt vmcnt(16)
	v_pk_fma_f32 v[102:103], v[102:103], v[186:187], v[210:211]
	v_pk_fma_f32 v[100:101], v[100:101], v[184:185], v[208:209]
	global_store_dwordx4 v[178:179], v[100:103], off
	global_load_dwordx4 v[208:211], v[146:147], off offset:512
	s_waitcnt vmcnt(17)
	v_pk_fma_f32 v[98:99], v[98:99], v[186:187], v[214:215]
	v_pk_fma_f32 v[96:97], v[96:97], v[184:185], v[212:213]
	global_store_dwordx4 v[182:183], v[96:99], off
	global_load_dwordx4 v[184:187], v[164:165], off offset:512
	s_waitcnt vmcnt(17)
	v_pk_fma_f32 v[94:95], v[94:95], v[218:219], v[222:223]
	v_pk_fma_f32 v[92:93], v[92:93], v[216:217], v[220:221]
	global_store_dwordx4 v[146:147], v[92:95], off offset:64
	global_load_dwordx4 v[212:215], v[166:167], off offset:512
	global_load_dwordx4 v[220:223], v[168:169], off offset:512
	s_waitcnt vmcnt(19)
	v_pk_fma_f32 v[90:91], v[90:91], v[218:219], v[226:227]
	v_pk_fma_f32 v[88:89], v[88:89], v[216:217], v[224:225]
	global_store_dwordx4 v[164:165], v[88:91], off offset:64
	global_load_dwordx4 v[224:227], v[162:163], off offset:512
	s_waitcnt vmcnt(20)
	v_pk_fma_f32 v[86:87], v[86:87], v[218:219], v[230:231]
	v_pk_fma_f32 v[84:85], v[84:85], v[216:217], v[228:229]
	global_store_dwordx4 v[166:167], v[84:87], off offset:64
	global_load_dwordx4 v[228:231], v[172:173], off offset:512
	s_waitcnt vmcnt(21)
	v_pk_fma_f32 v[82:83], v[82:83], v[218:219], v[234:235]
	v_pk_fma_f32 v[80:81], v[80:81], v[216:217], v[232:233]
	global_store_dwordx4 v[168:169], v[80:83], off offset:64
	global_load_dwordx4 v[232:235], v[176:177], off offset:512
	s_waitcnt vmcnt(21)
	v_pk_fma_f32 v[74:75], v[74:75], v[218:219], v[190:191]
	v_pk_fma_f32 v[72:73], v[72:73], v[216:217], v[188:189]
	global_store_dwordx4 v[162:163], v[72:75], off offset:64
	global_load_dwordx4 v[188:191], v[180:181], off offset:512
	s_waitcnt vmcnt(21)
	v_pk_fma_f32 v[66:67], v[66:67], v[218:219], v[194:195]
	v_pk_fma_f32 v[64:65], v[64:65], v[216:217], v[192:193]
	global_store_dwordx4 v[172:173], v[64:67], off offset:64
	global_load_dwordx4 v[192:195], v[144:145], off offset:576
	s_waitcnt vmcnt(21)
	v_pk_fma_f32 v[58:59], v[58:59], v[218:219], v[198:199]
	v_pk_fma_f32 v[56:57], v[56:57], v[216:217], v[196:197]
	global_store_dwordx4 v[176:177], v[56:59], off offset:64
	global_load_dwordx4 v[196:199], v[146:147], off offset:576
	v_pk_add_f32 v[64:65], v[78:79], 0 op_sel_hi:[1,0]
	v_pk_add_f32 v[66:67], v[76:77], 0 op_sel_hi:[1,0]
	s_waitcnt vmcnt(21)
	v_pk_fma_f32 v[46:47], v[46:47], v[218:219], v[202:203]
	v_pk_fma_f32 v[44:45], v[44:45], v[216:217], v[200:201]
	global_store_dwordx4 v[180:181], v[44:47], off offset:64
	global_load_dwordx4 v[200:203], v[164:165], off offset:576
	s_waitcnt vmcnt(19)
	v_pk_fma_f32 v[58:59], v[64:65], v[206:207], v[210:211]
	v_pk_fma_f32 v[56:57], v[66:67], v[204:205], v[208:209]
	global_store_dwordx4 v[146:147], v[56:59], off offset:512
	global_load_dwordx4 v[208:211], v[166:167], off offset:576
	global_load_dwordx4 v[216:219], v[168:169], off offset:576
	v_pk_add_f32 v[64:65], v[70:71], 0 op_sel_hi:[1,0]
	v_pk_add_f32 v[66:67], v[68:69], 0 op_sel_hi:[1,0]
	s_waitcnt vmcnt(20)
	v_pk_fma_f32 v[58:59], v[64:65], v[206:207], v[186:187]
	v_pk_fma_f32 v[56:57], v[66:67], v[204:205], v[184:185]
	global_store_dwordx4 v[164:165], v[56:59], off offset:512
	global_load_dwordx4 v[184:187], v[162:163], off offset:576
	s_waitcnt vmcnt(20)
	v_pk_fma_f32 v[58:59], v[62:63], v[206:207], v[214:215]
	v_pk_fma_f32 v[56:57], v[60:61], v[204:205], v[212:213]
	global_store_dwordx4 v[166:167], v[56:59], off offset:512
	global_load_dwordx4 v[212:215], v[172:173], off offset:576
	s_waitcnt vmcnt(21)
	v_pk_fma_f32 v[54:55], v[54:55], v[206:207], v[222:223]
	v_pk_fma_f32 v[52:53], v[52:53], v[204:205], v[220:221]
	global_store_dwordx4 v[168:169], v[52:55], off offset:512
	global_load_dwordx4 v[220:223], v[176:177], off offset:576
	s_waitcnt vmcnt(21)
	v_pk_fma_f32 v[34:35], v[34:35], v[206:207], v[226:227]
	v_pk_fma_f32 v[32:33], v[32:33], v[204:205], v[224:225]
	global_store_dwordx4 v[162:163], v[32:35], off offset:512
	global_load_dwordx4 v[224:227], v[180:181], off offset:576
	s_waitcnt vmcnt(21)
	v_pk_fma_f32 v[26:27], v[26:27], v[206:207], v[230:231]
	v_pk_fma_f32 v[24:25], v[24:25], v[204:205], v[228:229]
	global_store_dwordx4 v[172:173], v[24:27], off offset:512
	s_waitcnt vmcnt(20)
	v_pk_fma_f32 v[22:23], v[22:23], v[206:207], v[234:235]
	v_pk_fma_f32 v[20:21], v[20:21], v[204:205], v[232:233]
	global_store_dwordx4 v[176:177], v[20:23], off offset:512
	v_pk_add_f32 v[24:25], v[50:51], 0 op_sel_hi:[1,0]
	v_pk_add_f32 v[26:27], v[48:49], 0 op_sel_hi:[1,0]
	s_waitcnt vmcnt(19)
	v_pk_fma_f32 v[18:19], v[18:19], v[206:207], v[190:191]
	v_pk_fma_f32 v[16:17], v[16:17], v[204:205], v[188:189]
	global_store_dwordx4 v[180:181], v[16:19], off offset:512
	s_waitcnt vmcnt(16)
	v_pk_fma_f32 v[22:23], v[24:25], v[194:195], v[198:199]
	v_pk_fma_f32 v[20:21], v[26:27], v[192:193], v[196:197]
	global_store_dwordx4 v[146:147], v[20:23], off offset:576
	v_pk_add_f32 v[24:25], v[42:43], 0 op_sel_hi:[1,0]
	v_pk_add_f32 v[26:27], v[40:41], 0 op_sel_hi:[1,0]
	s_waitcnt vmcnt(15)
	v_pk_fma_f32 v[22:23], v[24:25], v[194:195], v[202:203]
	v_pk_fma_f32 v[20:21], v[26:27], v[192:193], v[200:201]
	global_store_dwordx4 v[164:165], v[20:23], off offset:576
	v_pk_add_f32 v[24:25], v[38:39], 0 op_sel_hi:[1,0]
	v_pk_add_f32 v[26:27], v[36:37], 0 op_sel_hi:[1,0]
	s_waitcnt vmcnt(14)
	v_pk_fma_f32 v[22:23], v[24:25], v[194:195], v[210:211]
	v_pk_fma_f32 v[20:21], v[26:27], v[192:193], v[208:209]
	global_store_dwordx4 v[166:167], v[20:23], off offset:576
	v_pk_add_f32 v[24:25], v[30:31], 0 op_sel_hi:[1,0]
	v_pk_add_f32 v[26:27], v[28:29], 0 op_sel_hi:[1,0]
	s_waitcnt vmcnt(14)
	v_pk_fma_f32 v[22:23], v[24:25], v[194:195], v[218:219]
	v_pk_fma_f32 v[20:21], v[26:27], v[192:193], v[216:217]
	global_store_dwordx4 v[168:169], v[20:23], off offset:576
	s_waitcnt vmcnt(13)
	v_pk_fma_f32 v[14:15], v[14:15], v[194:195], v[186:187]
	v_pk_fma_f32 v[12:13], v[12:13], v[192:193], v[184:185]
	global_store_dwordx4 v[162:163], v[12:15], off offset:576
	s_waitcnt vmcnt(12)
	v_pk_fma_f32 v[10:11], v[10:11], v[194:195], v[214:215]
	v_pk_fma_f32 v[8:9], v[8:9], v[192:193], v[212:213]
	global_store_dwordx4 v[172:173], v[8:11], off offset:576
	s_waitcnt vmcnt(11)
	v_pk_fma_f32 v[6:7], v[6:7], v[194:195], v[222:223]
	v_pk_fma_f32 v[4:5], v[4:5], v[192:193], v[220:221]
	global_store_dwordx4 v[176:177], v[4:7], off offset:576
	s_waitcnt vmcnt(10)
	v_pk_fma_f32 v[2:3], v[2:3], v[194:195], v[226:227]
	v_pk_fma_f32 v[0:1], v[0:1], v[192:193], v[224:225]
	global_store_dwordx4 v[180:181], v[0:3], off offset:576
	s_cbranch_vccz .LBB0_671
	s_waitcnt vmcnt(0)
	s_cmpk_gt_u32 s1, 0xff
	s_cbranch_scc1 .LBB0_686
	s_barrier

.LBB0_698:
	ds_read_b128 v[144:147], v139
	ds_read_b128 v[148:151], v139 offset:1024
	ds_read_b128 v[152:155], v139 offset:2048
	ds_read_b128 v[156:159], v139 offset:3072
	s_add_u32 s16, s14, 0x100
	s_addc_u32 s17, s15, 0
	s_cmp_eq_u32 s43, 4
	s_cselect_b32 s21, s13, s17
	s_cselect_b32 s20, s12, s16
	s_cselect_b32 s19, s7, s42
	s_cselect_b32 s18, s6, s41
	s_mov_b32 m0, s29
	v_lshl_add_u64 v[192:193], s[14:15], 0, v[132:133]
	ds_read_b128 v[160:163], v140
	ds_read_b128 v[164:167], v140 offset:1024
	ds_read_b128 v[168:171], v140 offset:2048
	ds_read_b128 v[172:175], v140 offset:3072
	ds_read_b128 v[176:179], v140 offset:4096
	ds_read_b128 v[180:183], v140 offset:5120
	ds_read_b128 v[184:187], v140 offset:6144
	ds_read_b128 v[188:191], v140 offset:7168
	global_load_lds_dwordx4 v[192:193], off
	s_mov_b32 m0, s30
	s_nop 0
	global_load_lds_dwordx4 v134, s[14:15]
	s_waitcnt lgkmcnt(8)
	s_barrier
	s_waitcnt lgkmcnt(0)
	s_waitcnt lgkmcnt(0)
	v_mfma_f32_16x16x32_bf16 v[124:127], v[144:147], v[160:163], v[124:127]
	v_mfma_f32_16x16x32_bf16 v[120:123], v[152:155], v[160:163], v[120:123]
	v_mfma_f32_16x16x32_bf16 v[116:119], v[144:147], v[168:171], v[116:119]
	v_mfma_f32_16x16x32_bf16 v[112:115], v[152:155], v[168:171], v[112:115]
	v_mfma_f32_16x16x32_bf16 v[100:103], v[144:147], v[176:179], v[100:103]
	v_mfma_f32_16x16x32_bf16 v[96:99], v[152:155], v[176:179], v[96:99]
	v_mfma_f32_16x16x32_bf16 v[84:87], v[144:147], v[184:187], v[84:87]
	v_mfma_f32_16x16x32_bf16 v[80:83], v[152:155], v[184:187], v[80:83]
	v_mfma_f32_16x16x32_bf16 v[124:127], v[148:151], v[164:167], v[124:127]
	v_mfma_f32_16x16x32_bf16 v[120:123], v[156:159], v[164:167], v[120:123]
	v_mfma_f32_16x16x32_bf16 v[116:119], v[148:151], v[172:175], v[116:119]
	v_mfma_f32_16x16x32_bf16 v[112:115], v[156:159], v[172:175], v[112:115]
	v_mfma_f32_16x16x32_bf16 v[100:103], v[148:151], v[180:183], v[100:103]
	v_mfma_f32_16x16x32_bf16 v[96:99], v[156:159], v[180:183], v[96:99]
	v_mfma_f32_16x16x32_bf16 v[84:87], v[148:151], v[188:191], v[84:87]
	v_mfma_f32_16x16x32_bf16 v[80:83], v[156:159], v[188:191], v[80:83]
	s_barrier
	s_mov_b32 m0, s31
	ds_read_b128 v[192:195], v141
	ds_read_b128 v[196:199], v141 offset:1024
	ds_read_b128 v[200:203], v141 offset:2048
	ds_read_b128 v[204:207], v141 offset:3072
	global_load_lds_dwordx4 v130, s[18:19]
	s_mov_b32 m0, s34
	s_nop 0
	global_load_lds_dwordx4 v128, s[18:19]
	s_barrier
	s_waitcnt lgkmcnt(0)
	s_waitcnt lgkmcnt(0)
	v_mfma_f32_16x16x32_bf16 v[108:111], v[192:195], v[160:163], v[108:111]
	v_mfma_f32_16x16x32_bf16 v[104:107], v[200:203], v[160:163], v[104:107]
	v_mfma_f32_16x16x32_bf16 v[92:95], v[192:195], v[168:171], v[92:95]
	v_mfma_f32_16x16x32_bf16 v[88:91], v[200:203], v[168:171], v[88:91]
	v_mfma_f32_16x16x32_bf16 v[76:79], v[192:195], v[176:179], v[76:79]
	v_mfma_f32_16x16x32_bf16 v[72:75], v[200:203], v[176:179], v[72:75]
	v_mfma_f32_16x16x32_bf16 v[68:71], v[192:195], v[184:187], v[68:71]
	v_mfma_f32_16x16x32_bf16 v[64:67], v[200:203], v[184:187], v[64:67]
	v_mfma_f32_16x16x32_bf16 v[108:111], v[196:199], v[164:167], v[108:111]
	v_mfma_f32_16x16x32_bf16 v[104:107], v[204:207], v[164:167], v[104:107]
	v_mfma_f32_16x16x32_bf16 v[92:95], v[196:199], v[172:175], v[92:95]
	v_mfma_f32_16x16x32_bf16 v[88:91], v[204:207], v[172:175], v[88:91]
	v_mfma_f32_16x16x32_bf16 v[76:79], v[196:199], v[180:183], v[76:79]
	v_mfma_f32_16x16x32_bf16 v[72:75], v[204:207], v[180:183], v[72:75]
	v_mfma_f32_16x16x32_bf16 v[68:71], v[196:199], v[188:191], v[68:71]
	v_mfma_f32_16x16x32_bf16 v[64:67], v[204:207], v[188:191], v[64:67]
	s_mov_b32 m0, s3
	v_lshl_add_u64 v[212:213], s[20:21], 0, v[130:131]
	s_barrier
	ds_read_b128 v[160:163], v140 offset:16384
	ds_read_b128 v[164:167], v140 offset:17408
	ds_read_b128 v[168:171], v140 offset:18432
	ds_read_b128 v[172:175], v140 offset:19456
	ds_read_b128 v[176:179], v140 offset:20480
	ds_read_b128 v[180:183], v140 offset:21504
	ds_read_b128 v[184:187], v140 offset:22528
	ds_read_b128 v[188:191], v140 offset:23552
	global_load_lds_dwordx4 v130, s[20:21]
	v_lshl_add_u64 v[214:215], s[20:21], 0, v[128:129]
	s_mov_b32 m0, s4
	s_nop 0
	global_load_lds_dwordx4 v128, s[20:21]
	s_barrier
	s_waitcnt lgkmcnt(0)
	s_waitcnt lgkmcnt(0)
	v_mfma_f32_16x16x32_bf16 v[60:63], v[144:147], v[160:163], v[60:63]
	v_mfma_f32_16x16x32_bf16 v[56:59], v[152:155], v[160:163], v[56:59]
	v_mfma_f32_16x16x32_bf16 v[52:55], v[144:147], v[168:171], v[52:55]
	v_mfma_f32_16x16x32_bf16 v[48:51], v[152:155], v[168:171], v[48:51]
	v_mfma_f32_16x16x32_bf16 v[36:39], v[144:147], v[176:179], v[36:39]
	v_mfma_f32_16x16x32_bf16 v[32:35], v[152:155], v[176:179], v[32:35]
	v_mfma_f32_16x16x32_bf16 v[20:23], v[144:147], v[184:187], v[20:23]
	v_mfma_f32_16x16x32_bf16 v[16:19], v[152:155], v[184:187], v[16:19]
	v_mfma_f32_16x16x32_bf16 v[60:63], v[148:151], v[164:167], v[60:63]
	v_mfma_f32_16x16x32_bf16 v[56:59], v[156:159], v[164:167], v[56:59]
	v_mfma_f32_16x16x32_bf16 v[52:55], v[148:151], v[172:175], v[52:55]
	v_mfma_f32_16x16x32_bf16 v[48:51], v[156:159], v[172:175], v[48:51]
	v_mfma_f32_16x16x32_bf16 v[36:39], v[148:151], v[180:183], v[36:39]
	v_mfma_f32_16x16x32_bf16 v[32:35], v[156:159], v[180:183], v[32:35]
	v_mfma_f32_16x16x32_bf16 v[20:23], v[148:151], v[188:191], v[20:23]
	v_mfma_f32_16x16x32_bf16 v[16:19], v[156:159], v[188:191], v[16:19]
	s_barrier
	s_add_u32 s14, s18, 0x160000
	s_addc_u32 s15, s19, 0
	s_mov_b32 m0, s35
	global_load_lds_dwordx4 v130, s[14:15]
	s_mov_b32 m0, s36
	s_nop 0
	global_load_lds_dwordx4 v128, s[14:15]
	s_waitcnt vmcnt(6)
	s_barrier
	v_mfma_f32_16x16x32_bf16 v[44:47], v[192:195], v[160:163], v[44:47]
	v_mfma_f32_16x16x32_bf16 v[40:43], v[200:203], v[160:163], v[40:43]
	v_mfma_f32_16x16x32_bf16 v[28:31], v[192:195], v[168:171], v[28:31]
	v_mfma_f32_16x16x32_bf16 v[24:27], v[200:203], v[168:171], v[24:27]
	v_mfma_f32_16x16x32_bf16 v[12:15], v[192:195], v[176:179], v[12:15]
	v_mfma_f32_16x16x32_bf16 v[8:11], v[200:203], v[176:179], v[8:11]
	v_mfma_f32_16x16x32_bf16 v[4:7], v[192:195], v[184:187], v[4:7]
	v_mfma_f32_16x16x32_bf16 v[0:3], v[200:203], v[184:187], v[0:3]
	v_mfma_f32_16x16x32_bf16 v[44:47], v[196:199], v[164:167], v[44:47]
	v_mfma_f32_16x16x32_bf16 v[40:43], v[204:207], v[164:167], v[40:43]
	v_mfma_f32_16x16x32_bf16 v[28:31], v[196:199], v[172:175], v[28:31]
	v_mfma_f32_16x16x32_bf16 v[24:27], v[204:207], v[172:175], v[24:27]
	v_mfma_f32_16x16x32_bf16 v[12:15], v[196:199], v[180:183], v[12:15]
	v_mfma_f32_16x16x32_bf16 v[8:11], v[204:207], v[180:183], v[8:11]
	v_mfma_f32_16x16x32_bf16 v[4:7], v[196:199], v[188:191], v[4:7]
	v_mfma_f32_16x16x32_bf16 v[0:3], v[204:207], v[188:191], v[0:3]
	s_barrier
	ds_read_b128 v[144:147], v142
	ds_read_b128 v[148:151], v142 offset:1024
	ds_read_b128 v[152:155], v142 offset:2048
	ds_read_b128 v[156:159], v142 offset:3072
	s_add_u32 s14, s20, 0x160000
	s_addc_u32 s15, s21, 0
	s_mov_b32 m0, s5
	ds_read_b128 v[160:163], v140 offset:32768
	ds_read_b128 v[164:167], v140 offset:33792
	ds_read_b128 v[168:171], v140 offset:34816
	ds_read_b128 v[172:175], v140 offset:35840
	ds_read_b128 v[176:179], v140 offset:36864
	ds_read_b128 v[180:183], v140 offset:37888
	ds_read_b128 v[184:187], v140 offset:38912
	ds_read_b128 v[188:191], v140 offset:39936
	global_load_lds_dwordx4 v130, s[14:15]
	s_mov_b32 m0, s22
	s_nop 0
	global_load_lds_dwordx4 v128, s[14:15]
	s_waitcnt lgkmcnt(8)
	s_barrier
	s_waitcnt lgkmcnt(0)
	s_waitcnt lgkmcnt(0)
	v_mfma_f32_16x16x32_bf16 v[124:127], v[144:147], v[160:163], v[124:127]
	v_mfma_f32_16x16x32_bf16 v[120:123], v[152:155], v[160:163], v[120:123]
	v_mfma_f32_16x16x32_bf16 v[116:119], v[144:147], v[168:171], v[116:119]
	v_mfma_f32_16x16x32_bf16 v[112:115], v[152:155], v[168:171], v[112:115]
	v_mfma_f32_16x16x32_bf16 v[100:103], v[144:147], v[176:179], v[100:103]
	v_mfma_f32_16x16x32_bf16 v[96:99], v[152:155], v[176:179], v[96:99]
	v_mfma_f32_16x16x32_bf16 v[84:87], v[144:147], v[184:187], v[84:87]
	v_mfma_f32_16x16x32_bf16 v[80:83], v[152:155], v[184:187], v[80:83]
	v_mfma_f32_16x16x32_bf16 v[124:127], v[148:151], v[164:167], v[124:127]
	v_mfma_f32_16x16x32_bf16 v[120:123], v[156:159], v[164:167], v[120:123]
	v_mfma_f32_16x16x32_bf16 v[116:119], v[148:151], v[172:175], v[116:119]
	v_mfma_f32_16x16x32_bf16 v[112:115], v[156:159], v[172:175], v[112:115]
	v_mfma_f32_16x16x32_bf16 v[100:103], v[148:151], v[180:183], v[100:103]
	v_mfma_f32_16x16x32_bf16 v[96:99], v[156:159], v[180:183], v[96:99]
	v_mfma_f32_16x16x32_bf16 v[84:87], v[148:151], v[188:191], v[84:87]
	v_mfma_f32_16x16x32_bf16 v[80:83], v[156:159], v[188:191], v[80:83]
	s_barrier
	s_add_i32 s20, 0, 0x1c000
	s_add_i32 s14, s37, s2
	v_add_u32_e32 v143, s20, v137
	s_add_u32 s98, s18, s8
	s_addc_u32 s99, s19, s9
	s_mov_b32 m0, s14
	ds_read_b128 v[192:195], v143
	ds_read_b128 v[196:199], v143 offset:1024
	ds_read_b128 v[200:203], v143 offset:2048
	ds_read_b128 v[204:207], v143 offset:3072
	global_load_lds_dwordx4 v130, s[98:99]
	s_add_i32 m0, s14, 0x2000
	s_nop 0
	global_load_lds_dwordx4 v128, s[98:99]
	s_barrier
	s_waitcnt lgkmcnt(0)
	s_waitcnt lgkmcnt(0)
	v_mfma_f32_16x16x32_bf16 v[108:111], v[192:195], v[160:163], v[108:111]
	v_mfma_f32_16x16x32_bf16 v[104:107], v[200:203], v[160:163], v[104:107]
	v_mfma_f32_16x16x32_bf16 v[92:95], v[192:195], v[168:171], v[92:95]
	v_mfma_f32_16x16x32_bf16 v[88:91], v[200:203], v[168:171], v[88:91]
	v_mfma_f32_16x16x32_bf16 v[76:79], v[192:195], v[176:179], v[76:79]
	v_mfma_f32_16x16x32_bf16 v[72:75], v[200:203], v[176:179], v[72:75]
	v_mfma_f32_16x16x32_bf16 v[68:71], v[192:195], v[184:187], v[68:71]
	v_mfma_f32_16x16x32_bf16 v[64:67], v[200:203], v[184:187], v[64:67]
	v_mfma_f32_16x16x32_bf16 v[108:111], v[196:199], v[164:167], v[108:111]
	v_mfma_f32_16x16x32_bf16 v[104:107], v[204:207], v[164:167], v[104:107]
	v_mfma_f32_16x16x32_bf16 v[92:95], v[196:199], v[172:175], v[92:95]
	v_mfma_f32_16x16x32_bf16 v[88:91], v[204:207], v[172:175], v[88:91]
	v_mfma_f32_16x16x32_bf16 v[76:79], v[196:199], v[180:183], v[76:79]
	v_mfma_f32_16x16x32_bf16 v[72:75], v[204:207], v[180:183], v[72:75]
	v_mfma_f32_16x16x32_bf16 v[68:71], v[196:199], v[188:191], v[68:71]
	v_mfma_f32_16x16x32_bf16 v[64:67], v[204:207], v[188:191], v[64:67]
	s_mov_b32 m0, s27
	v_lshl_add_u64 v[208:209], v[212:213], 0, s[8:9]
	s_barrier
	ds_read_b128 v[160:163], v140 offset:49152
	ds_read_b128 v[164:167], v140 offset:50176
	ds_read_b128 v[168:171], v140 offset:51200
	ds_read_b128 v[172:175], v140 offset:52224
	ds_read_b128 v[176:179], v140 offset:53248
	ds_read_b128 v[180:183], v140 offset:54272
	ds_read_b128 v[184:187], v140 offset:55296
	ds_read_b128 v[188:191], v140 offset:56320
	global_load_lds_dwordx4 v[208:209], off
	v_lshl_add_u64 v[208:209], v[214:215], 0, s[8:9]
	s_mov_b32 m0, s28
	s_nop 0
	global_load_lds_dwordx4 v[208:209], off
	s_barrier
	s_waitcnt lgkmcnt(0)
	s_waitcnt lgkmcnt(0)
	v_mfma_f32_16x16x32_bf16 v[60:63], v[144:147], v[160:163], v[60:63]
	v_mfma_f32_16x16x32_bf16 v[56:59], v[152:155], v[160:163], v[56:59]
	v_mfma_f32_16x16x32_bf16 v[52:55], v[144:147], v[168:171], v[52:55]
	v_mfma_f32_16x16x32_bf16 v[48:51], v[152:155], v[168:171], v[48:51]
	v_mfma_f32_16x16x32_bf16 v[36:39], v[144:147], v[176:179], v[36:39]
	v_mfma_f32_16x16x32_bf16 v[32:35], v[152:155], v[176:179], v[32:35]
	v_mfma_f32_16x16x32_bf16 v[20:23], v[144:147], v[184:187], v[20:23]
	v_mfma_f32_16x16x32_bf16 v[16:19], v[152:155], v[184:187], v[16:19]
	v_mfma_f32_16x16x32_bf16 v[60:63], v[148:151], v[164:167], v[60:63]
	v_mfma_f32_16x16x32_bf16 v[56:59], v[156:159], v[164:167], v[56:59]
	v_mfma_f32_16x16x32_bf16 v[52:55], v[148:151], v[172:175], v[52:55]
	v_mfma_f32_16x16x32_bf16 v[48:51], v[156:159], v[172:175], v[48:51]
	v_mfma_f32_16x16x32_bf16 v[36:39], v[148:151], v[180:183], v[36:39]
	v_mfma_f32_16x16x32_bf16 v[32:35], v[156:159], v[180:183], v[32:35]
	v_mfma_f32_16x16x32_bf16 v[20:23], v[148:151], v[188:191], v[20:23]
	v_mfma_f32_16x16x32_bf16 v[16:19], v[156:159], v[188:191], v[16:19]
	s_barrier
	s_add_u32 s14, s18, 0x160080
	s_addc_u32 s15, s19, 0
	s_add_i32 s18, s20, s2
	s_mov_b32 m0, s18
	s_nop 0
	global_load_lds_dwordx4 v130, s[14:15]
	s_add_i32 m0, s18, 0x2000
	s_nop 0
	global_load_lds_dwordx4 v128, s[14:15]
	s_waitcnt vmcnt(6)
	s_barrier
	v_mfma_f32_16x16x32_bf16 v[44:47], v[192:195], v[160:163], v[44:47]
	v_mfma_f32_16x16x32_bf16 v[40:43], v[200:203], v[160:163], v[40:43]
	v_mfma_f32_16x16x32_bf16 v[28:31], v[192:195], v[168:171], v[28:31]
	v_mfma_f32_16x16x32_bf16 v[24:27], v[200:203], v[168:171], v[24:27]
	v_mfma_f32_16x16x32_bf16 v[12:15], v[192:195], v[176:179], v[12:15]
	v_mfma_f32_16x16x32_bf16 v[8:11], v[200:203], v[176:179], v[8:11]
	v_mfma_f32_16x16x32_bf16 v[4:7], v[192:195], v[184:187], v[4:7]
	v_mfma_f32_16x16x32_bf16 v[0:3], v[200:203], v[184:187], v[0:3]
	v_mfma_f32_16x16x32_bf16 v[44:47], v[196:199], v[164:167], v[44:47]
	v_mfma_f32_16x16x32_bf16 v[40:43], v[204:207], v[164:167], v[40:43]
	v_mfma_f32_16x16x32_bf16 v[28:31], v[196:199], v[172:175], v[28:31]
	v_mfma_f32_16x16x32_bf16 v[24:27], v[204:207], v[172:175], v[24:27]
	v_mfma_f32_16x16x32_bf16 v[12:15], v[196:199], v[180:183], v[12:15]
	v_mfma_f32_16x16x32_bf16 v[8:11], v[204:207], v[180:183], v[8:11]
	v_mfma_f32_16x16x32_bf16 v[4:7], v[196:199], v[188:191], v[4:7]
	v_mfma_f32_16x16x32_bf16 v[0:3], v[204:207], v[188:191], v[0:3]
	s_add_i32 s43, s43, 2
	s_add_u32 s41, s41, 0x100
	s_addc_u32 s42, s42, 0
	s_cmp_gt_u32 s43, 5
	s_mov_b64 s[14:15], s[16:17]
	s_barrier
	s_cbranch_scc0 .LBB0_698
	s_ashr_i32 s14, s26, 1
	s_and_b32 s14, s14, 0xfffffe00
	s_lshl_b32 s15, s25, 8
	s_add_i32 s15, s15, s14
	v_add_u32_e32 v146, s15, v136
	v_lshl_or_b32 v144, s24, 8, v138
	v_ashrrev_i32_e32 v147, 31, v146
	v_ashrrev_i32_e32 v145, 31, v144
	v_lshlrev_b64 v[148:149], 13, v[146:147]
	v_lshl_add_u64 v[148:149], s[66:67], 0, v[148:149]
	v_lshlrev_b64 v[144:145], 2, v[144:145]
	v_lshl_add_u64 v[148:149], v[148:149], 0, v[144:145]
	global_store_dwordx4 v[148:149], v[124:127], off
	global_store_dwordx4 v[148:149], v[120:123], off offset:64
	global_store_dwordx4 v[148:149], v[108:111], off offset:512
	global_store_dwordx4 v[148:149], v[104:107], off offset:576
	s_mov_b64 s[14:15], 0x100000
	s_mov_b32 s26, s39
	v_or_b32_e32 v104, 16, v146
	v_ashrrev_i32_e32 v105, 31, v104
	v_lshlrev_b64 v[104:105], 13, v[104:105]
	v_lshl_add_u64 v[104:105], s[66:67], 0, v[104:105]
	v_lshl_add_u64 v[104:105], v[104:105], 0, v[144:145]
	global_store_dwordx4 v[104:105], v[116:119], off
	global_store_dwordx4 v[104:105], v[112:115], off offset:64
	global_store_dwordx4 v[104:105], v[92:95], off offset:512
	global_store_dwordx4 v[104:105], v[88:91], off offset:576
	s_mov_b32 s24, s38
	s_mov_b32 s25, s40
	v_or_b32_e32 v88, 32, v146
	v_ashrrev_i32_e32 v89, 31, v88
	v_lshlrev_b64 v[88:89], 13, v[88:89]
	v_lshl_add_u64 v[88:89], s[66:67], 0, v[88:89]
	v_lshl_add_u64 v[88:89], v[88:89], 0, v[144:145]
	global_store_dwordx4 v[88:89], v[100:103], off
	global_store_dwordx4 v[88:89], v[96:99], off offset:64
	global_store_dwordx4 v[88:89], v[76:79], off offset:512
	global_store_dwordx4 v[88:89], v[72:75], off offset:576
	s_mov_b64 s[16:17], s[6:7]
	s_nop 0
	v_or_b32_e32 v72, 48, v146
	v_ashrrev_i32_e32 v73, 31, v72
	v_lshlrev_b64 v[72:73], 13, v[72:73]
	v_lshl_add_u64 v[72:73], s[66:67], 0, v[72:73]
	v_lshl_add_u64 v[72:73], v[72:73], 0, v[144:145]
	global_store_dwordx4 v[72:73], v[84:87], off
	global_store_dwordx4 v[72:73], v[80:83], off offset:64
	global_store_dwordx4 v[72:73], v[68:71], off offset:512
	global_store_dwordx4 v[72:73], v[64:67], off offset:576
	s_nop 1
	v_lshl_add_u64 v[64:65], v[148:149], 0, s[14:15]
	s_mov_b32 s14, 0x100000
	v_add_co_u32_e32 v66, vcc, s14, v148
	s_mov_b64 s[14:15], 0x120000
	s_nop 0
	v_addc_co_u32_e32 v67, vcc, 0, v149, vcc
	global_store_dwordx4 v[66:67], v[60:63], off
	global_store_dwordx4 v[64:65], v[56:59], off offset:64
	global_store_dwordx4 v[64:65], v[44:47], off offset:512
	global_store_dwordx4 v[64:65], v[40:43], off offset:576
	s_nop 1
	v_lshl_add_u64 v[40:41], v[148:149], 0, s[14:15]
	s_mov_b32 s14, 0x120000
	v_add_co_u32_e32 v42, vcc, s14, v148
	s_mov_b64 s[14:15], 0x140000
	s_nop 0
	v_addc_co_u32_e32 v43, vcc, 0, v149, vcc
	global_store_dwordx4 v[42:43], v[52:55], off
	global_store_dwordx4 v[40:41], v[48:51], off offset:64
	global_store_dwordx4 v[40:41], v[28:31], off offset:512
	global_store_dwordx4 v[40:41], v[24:27], off offset:576
	s_nop 1
	v_lshl_add_u64 v[24:25], v[148:149], 0, s[14:15]
	s_mov_b32 s14, 0x140000
	v_add_co_u32_e32 v26, vcc, s14, v148
	s_mov_b64 s[14:15], 0x160000
	s_nop 0
	v_addc_co_u32_e32 v27, vcc, 0, v149, vcc
	global_store_dwordx4 v[26:27], v[36:39], off
	global_store_dwordx4 v[24:25], v[32:35], off offset:64
	global_store_dwordx4 v[24:25], v[12:15], off offset:512
	global_store_dwordx4 v[24:25], v[8:11], off offset:576
	s_nop 1
	v_add_co_u32_e32 v10, vcc, 0x160000, v148
	v_lshl_add_u64 v[8:9], v[148:149], 0, s[14:15]
	s_nop 0
	v_addc_co_u32_e32 v11, vcc, 0, v149, vcc
	s_and_b64 vcc, exec, s[10:11]
	s_mov_b64 s[14:15], s[12:13]
	global_store_dwordx4 v[10:11], v[20:23], off
	global_store_dwordx4 v[8:9], v[16:19], off offset:64
	global_store_dwordx4 v[8:9], v[4:7], off offset:512
	global_store_dwordx4 v[8:9], v[0:3], off offset:576
	s_cbranch_vccz .LBB0_691
	s_waitcnt vmcnt(0)
	s_cmpk_gt_u32 s1, 0xff
	s_cbranch_scc1 .LBB0_702
	s_barrier

.LBB0_924:
	s_add_u32 s21, s12, s20
	s_addc_u32 s29, s13, 0
	s_add_u32 s24, s21, 0x100
	s_addc_u32 s25, s29, 0
	s_and_b64 s[22:23], s[18:19], exec
	s_cselect_b32 s25, s9, s25
	s_cselect_b32 s24, s17, s24
	s_add_u32 s20, s10, s20
	s_addc_u32 s22, s11, 0
	s_add_u32 s20, s20, 0x100
	s_addc_u32 s22, s22, 0
	s_and_b64 s[18:19], s[18:19], exec
	s_cselect_b32 s27, s30, s22
	s_cselect_b32 s26, s31, s20
	s_add_u32 s28, s21, 0x10080
	s_addc_u32 s29, s29, 0
	s_add_i32 s67, s75, s3
	s_add_i32 m0, s4, 0xc000
	s_add_i32 s72, s4, 0xe000
	s_add_i32 s65, s67, 0x2000
	s_add_u32 s22, s26, 0x10000
	s_addc_u32 s23, s27, 0
	s_add_i32 s41, s2, s3
	ds_read_b128 v[144:147], v141
	ds_read_b128 v[148:151], v141 offset:1024
	ds_read_b128 v[152:155], v141 offset:2048
	ds_read_b128 v[156:159], v141 offset:3072
	s_add_i32 s40, s41, 0x2000
	s_add_i32 s39, 0, 0x18000
	s_add_u32 s20, s24, 0x10000
	s_addc_u32 s21, s25, 0
	s_add_i32 s38, s39, s3
	s_add_i32 s37, 0, 0x1c000
	s_add_i32 s36, s38, 0x2000
	s_add_u32 s18, s26, 0x10080
	s_addc_u32 s19, s27, 0
	s_add_i32 s35, s37, s3
	s_add_i32 s34, s35, 0x2000
	v_lshl_add_u64 v[136:137], s[28:29], 0, v[128:129]
	ds_read_b128 v[160:163], v142
	ds_read_b128 v[164:167], v142 offset:1024
	ds_read_b128 v[168:171], v142 offset:2048
	ds_read_b128 v[172:175], v142 offset:3072
	ds_read_b128 v[176:179], v142 offset:4096
	ds_read_b128 v[180:183], v142 offset:5120
	ds_read_b128 v[184:187], v142 offset:6144
	ds_read_b128 v[188:191], v142 offset:7168
	global_load_lds_dwordx4 v128, s[28:29]
	s_mov_b32 m0, s72
	s_nop 0
	global_load_lds_dwordx4 v130, s[28:29]
	s_waitcnt lgkmcnt(8)
	s_barrier
	s_waitcnt lgkmcnt(0)
	s_waitcnt lgkmcnt(0)
	v_mfma_f32_16x16x32_bf16 v[124:127], v[144:147], v[160:163], v[124:127]
	v_mfma_f32_16x16x32_bf16 v[120:123], v[152:155], v[160:163], v[120:123]
	v_mfma_f32_16x16x32_bf16 v[108:111], v[144:147], v[168:171], v[108:111]
	v_mfma_f32_16x16x32_bf16 v[104:107], v[152:155], v[168:171], v[104:107]
	v_mfma_f32_16x16x32_bf16 v[92:95], v[144:147], v[176:179], v[92:95]
	v_mfma_f32_16x16x32_bf16 v[88:91], v[152:155], v[176:179], v[88:91]
	v_mfma_f32_16x16x32_bf16 v[76:79], v[144:147], v[184:187], v[76:79]
	v_mfma_f32_16x16x32_bf16 v[72:75], v[152:155], v[184:187], v[72:75]
	v_mfma_f32_16x16x32_bf16 v[124:127], v[148:151], v[164:167], v[124:127]
	v_mfma_f32_16x16x32_bf16 v[120:123], v[156:159], v[164:167], v[120:123]
	v_mfma_f32_16x16x32_bf16 v[108:111], v[148:151], v[172:175], v[108:111]
	v_mfma_f32_16x16x32_bf16 v[104:107], v[156:159], v[172:175], v[104:107]
	v_mfma_f32_16x16x32_bf16 v[92:95], v[148:151], v[180:183], v[92:95]
	v_mfma_f32_16x16x32_bf16 v[88:91], v[156:159], v[180:183], v[88:91]
	v_mfma_f32_16x16x32_bf16 v[76:79], v[148:151], v[188:191], v[76:79]
	v_mfma_f32_16x16x32_bf16 v[72:75], v[156:159], v[188:191], v[72:75]
	s_barrier
	s_mov_b32 m0, s67
	ds_read_b128 v[192:195], v143
	ds_read_b128 v[196:199], v143 offset:1024
	ds_read_b128 v[200:203], v143 offset:2048
	ds_read_b128 v[204:207], v143 offset:3072
	global_load_lds_dwordx4 v128, s[26:27]
	s_mov_b32 m0, s65
	s_nop 0
	global_load_lds_dwordx4 v130, s[26:27]
	s_barrier
	s_waitcnt lgkmcnt(0)
	s_waitcnt lgkmcnt(0)
	v_mfma_f32_16x16x32_bf16 v[116:119], v[192:195], v[160:163], v[116:119]
	v_mfma_f32_16x16x32_bf16 v[112:115], v[200:203], v[160:163], v[112:115]
	v_mfma_f32_16x16x32_bf16 v[100:103], v[192:195], v[168:171], v[100:103]
	v_mfma_f32_16x16x32_bf16 v[96:99], v[200:203], v[168:171], v[96:99]
	v_mfma_f32_16x16x32_bf16 v[84:87], v[192:195], v[176:179], v[84:87]
	v_mfma_f32_16x16x32_bf16 v[80:83], v[200:203], v[176:179], v[80:83]
	v_mfma_f32_16x16x32_bf16 v[68:71], v[192:195], v[184:187], v[68:71]
	v_mfma_f32_16x16x32_bf16 v[64:67], v[200:203], v[184:187], v[64:67]
	v_mfma_f32_16x16x32_bf16 v[116:119], v[196:199], v[164:167], v[116:119]
	v_mfma_f32_16x16x32_bf16 v[112:115], v[204:207], v[164:167], v[112:115]
	v_mfma_f32_16x16x32_bf16 v[100:103], v[196:199], v[172:175], v[100:103]
	v_mfma_f32_16x16x32_bf16 v[96:99], v[204:207], v[172:175], v[96:99]
	v_mfma_f32_16x16x32_bf16 v[84:87], v[196:199], v[180:183], v[84:87]
	v_mfma_f32_16x16x32_bf16 v[80:83], v[204:207], v[180:183], v[80:83]
	v_mfma_f32_16x16x32_bf16 v[68:71], v[196:199], v[188:191], v[68:71]
	v_mfma_f32_16x16x32_bf16 v[64:67], v[204:207], v[188:191], v[64:67]
	s_mov_b32 m0, s4
	s_barrier
	ds_read_b128 v[160:163], v142 offset:16384
	ds_read_b128 v[164:167], v142 offset:17408
	ds_read_b128 v[168:171], v142 offset:18432
	ds_read_b128 v[172:175], v142 offset:19456
	ds_read_b128 v[176:179], v142 offset:20480
	ds_read_b128 v[180:183], v142 offset:21504
	ds_read_b128 v[184:187], v142 offset:22528
	ds_read_b128 v[188:191], v142 offset:23552
	global_load_lds_dwordx4 v128, s[24:25]
	s_mov_b32 m0, s5
	s_nop 0
	global_load_lds_dwordx4 v130, s[24:25]
	s_barrier
	s_waitcnt lgkmcnt(0)
	s_waitcnt lgkmcnt(0)
	v_mfma_f32_16x16x32_bf16 v[60:63], v[144:147], v[160:163], v[60:63]
	v_mfma_f32_16x16x32_bf16 v[56:59], v[152:155], v[160:163], v[56:59]
	v_mfma_f32_16x16x32_bf16 v[44:47], v[144:147], v[168:171], v[44:47]
	v_mfma_f32_16x16x32_bf16 v[40:43], v[152:155], v[168:171], v[40:43]
	v_mfma_f32_16x16x32_bf16 v[28:31], v[144:147], v[176:179], v[28:31]
	v_mfma_f32_16x16x32_bf16 v[24:27], v[152:155], v[176:179], v[24:27]
	v_mfma_f32_16x16x32_bf16 v[12:15], v[144:147], v[184:187], v[12:15]
	v_mfma_f32_16x16x32_bf16 v[8:11], v[152:155], v[184:187], v[8:11]
	v_mfma_f32_16x16x32_bf16 v[60:63], v[148:151], v[164:167], v[60:63]
	v_mfma_f32_16x16x32_bf16 v[56:59], v[156:159], v[164:167], v[56:59]
	v_mfma_f32_16x16x32_bf16 v[44:47], v[148:151], v[172:175], v[44:47]
	v_mfma_f32_16x16x32_bf16 v[40:43], v[156:159], v[172:175], v[40:43]
	v_mfma_f32_16x16x32_bf16 v[28:31], v[148:151], v[180:183], v[28:31]
	v_mfma_f32_16x16x32_bf16 v[24:27], v[156:159], v[180:183], v[24:27]
	v_mfma_f32_16x16x32_bf16 v[12:15], v[148:151], v[188:191], v[12:15]
	v_mfma_f32_16x16x32_bf16 v[8:11], v[156:159], v[188:191], v[8:11]
	s_barrier
	s_mov_b32 m0, s41
	global_load_lds_dwordx4 v128, s[22:23]
	s_mov_b32 m0, s40
	s_nop 0
	global_load_lds_dwordx4 v130, s[22:23]
	s_waitcnt vmcnt(6)
	s_barrier
	v_mfma_f32_16x16x32_bf16 v[52:55], v[192:195], v[160:163], v[52:55]
	v_mfma_f32_16x16x32_bf16 v[48:51], v[200:203], v[160:163], v[48:51]
	v_mfma_f32_16x16x32_bf16 v[36:39], v[192:195], v[168:171], v[36:39]
	v_mfma_f32_16x16x32_bf16 v[32:35], v[200:203], v[168:171], v[32:35]
	v_mfma_f32_16x16x32_bf16 v[20:23], v[192:195], v[176:179], v[20:23]
	v_mfma_f32_16x16x32_bf16 v[16:19], v[200:203], v[176:179], v[16:19]
	v_mfma_f32_16x16x32_bf16 v[4:7], v[192:195], v[184:187], v[4:7]
	v_mfma_f32_16x16x32_bf16 v[0:3], v[200:203], v[184:187], v[0:3]
	v_mfma_f32_16x16x32_bf16 v[52:55], v[196:199], v[164:167], v[52:55]
	v_mfma_f32_16x16x32_bf16 v[48:51], v[204:207], v[164:167], v[48:51]
	v_mfma_f32_16x16x32_bf16 v[36:39], v[196:199], v[172:175], v[36:39]
	v_mfma_f32_16x16x32_bf16 v[32:35], v[204:207], v[172:175], v[32:35]
	v_mfma_f32_16x16x32_bf16 v[20:23], v[196:199], v[180:183], v[20:23]
	v_mfma_f32_16x16x32_bf16 v[16:19], v[204:207], v[180:183], v[16:19]
	v_mfma_f32_16x16x32_bf16 v[4:7], v[196:199], v[188:191], v[4:7]
	v_mfma_f32_16x16x32_bf16 v[0:3], v[204:207], v[188:191], v[0:3]
	v_add_u32_e32 v156, s39, v139
	s_barrier
	ds_read_b128 v[144:147], v156
	ds_read_b128 v[148:151], v156 offset:1024
	ds_read_b128 v[152:155], v156 offset:2048
	ds_read_b128 v[156:159], v156 offset:3072
	s_mov_b32 m0, s42
	ds_read_b128 v[160:163], v142 offset:32768
	ds_read_b128 v[164:167], v142 offset:33792
	ds_read_b128 v[168:171], v142 offset:34816
	ds_read_b128 v[172:175], v142 offset:35840
	ds_read_b128 v[176:179], v142 offset:36864
	ds_read_b128 v[180:183], v142 offset:37888
	ds_read_b128 v[184:187], v142 offset:38912
	ds_read_b128 v[188:191], v142 offset:39936
	global_load_lds_dwordx4 v128, s[20:21]
	s_mov_b32 m0, s43
	s_nop 0
	global_load_lds_dwordx4 v130, s[20:21]
	s_waitcnt lgkmcnt(8)
	s_barrier
	s_waitcnt lgkmcnt(0)
	s_waitcnt lgkmcnt(0)
	v_mfma_f32_16x16x32_bf16 v[124:127], v[144:147], v[160:163], v[124:127]
	v_mfma_f32_16x16x32_bf16 v[120:123], v[152:155], v[160:163], v[120:123]
	v_mfma_f32_16x16x32_bf16 v[108:111], v[144:147], v[168:171], v[108:111]
	v_mfma_f32_16x16x32_bf16 v[104:107], v[152:155], v[168:171], v[104:107]
	v_mfma_f32_16x16x32_bf16 v[92:95], v[144:147], v[176:179], v[92:95]
	v_mfma_f32_16x16x32_bf16 v[88:91], v[152:155], v[176:179], v[88:91]
	v_mfma_f32_16x16x32_bf16 v[76:79], v[144:147], v[184:187], v[76:79]
	v_mfma_f32_16x16x32_bf16 v[72:75], v[152:155], v[184:187], v[72:75]
	v_mfma_f32_16x16x32_bf16 v[124:127], v[148:151], v[164:167], v[124:127]
	v_mfma_f32_16x16x32_bf16 v[120:123], v[156:159], v[164:167], v[120:123]
	v_mfma_f32_16x16x32_bf16 v[108:111], v[148:151], v[172:175], v[108:111]
	v_mfma_f32_16x16x32_bf16 v[104:107], v[156:159], v[172:175], v[104:107]
	v_mfma_f32_16x16x32_bf16 v[92:95], v[148:151], v[180:183], v[92:95]
	v_mfma_f32_16x16x32_bf16 v[88:91], v[156:159], v[180:183], v[88:91]
	v_mfma_f32_16x16x32_bf16 v[76:79], v[148:151], v[188:191], v[76:79]
	v_mfma_f32_16x16x32_bf16 v[72:75], v[156:159], v[188:191], v[72:75]
	s_barrier
	s_mov_b32 m0, s38
	v_add_u32_e32 v204, s37, v139
	s_add_u32 s98, s26, s62
	s_addc_u32 s99, s27, s63
	ds_read_b128 v[192:195], v204
	ds_read_b128 v[196:199], v204 offset:1024
	ds_read_b128 v[200:203], v204 offset:2048
	ds_read_b128 v[204:207], v204 offset:3072
	global_load_lds_dwordx4 v128, s[98:99]
	s_mov_b32 m0, s36
	s_nop 0
	global_load_lds_dwordx4 v130, s[98:99]
	s_barrier
	s_waitcnt lgkmcnt(0)
	s_waitcnt lgkmcnt(0)
	v_mfma_f32_16x16x32_bf16 v[116:119], v[192:195], v[160:163], v[116:119]
	v_mfma_f32_16x16x32_bf16 v[112:115], v[200:203], v[160:163], v[112:115]
	v_mfma_f32_16x16x32_bf16 v[100:103], v[192:195], v[168:171], v[100:103]
	v_mfma_f32_16x16x32_bf16 v[96:99], v[200:203], v[168:171], v[96:99]
	v_mfma_f32_16x16x32_bf16 v[84:87], v[192:195], v[176:179], v[84:87]
	v_mfma_f32_16x16x32_bf16 v[80:83], v[200:203], v[176:179], v[80:83]
	v_mfma_f32_16x16x32_bf16 v[68:71], v[192:195], v[184:187], v[68:71]
	v_mfma_f32_16x16x32_bf16 v[64:67], v[200:203], v[184:187], v[64:67]
	v_mfma_f32_16x16x32_bf16 v[116:119], v[196:199], v[164:167], v[116:119]
	v_mfma_f32_16x16x32_bf16 v[112:115], v[204:207], v[164:167], v[112:115]
	v_mfma_f32_16x16x32_bf16 v[100:103], v[196:199], v[172:175], v[100:103]
	v_mfma_f32_16x16x32_bf16 v[96:99], v[204:207], v[172:175], v[96:99]
	v_mfma_f32_16x16x32_bf16 v[84:87], v[196:199], v[180:183], v[84:87]
	v_mfma_f32_16x16x32_bf16 v[80:83], v[204:207], v[180:183], v[80:83]
	v_mfma_f32_16x16x32_bf16 v[68:71], v[196:199], v[188:191], v[68:71]
	v_mfma_f32_16x16x32_bf16 v[64:67], v[204:207], v[188:191], v[64:67]
	s_mov_b32 m0, s47
	s_add_u32 s98, s24, s62
	s_addc_u32 s99, s25, s63
	s_barrier
	ds_read_b128 v[160:163], v142 offset:49152
	ds_read_b128 v[164:167], v142 offset:50176
	ds_read_b128 v[168:171], v142 offset:51200
	ds_read_b128 v[172:175], v142 offset:52224
	ds_read_b128 v[176:179], v142 offset:53248
	ds_read_b128 v[180:183], v142 offset:54272
	ds_read_b128 v[184:187], v142 offset:55296
	ds_read_b128 v[188:191], v142 offset:56320
	global_load_lds_dwordx4 v128, s[98:99]
	s_mov_b32 m0, s74
	s_nop 0
	global_load_lds_dwordx4 v130, s[98:99]
	s_barrier
	s_waitcnt lgkmcnt(0)
	s_waitcnt lgkmcnt(0)
	v_mfma_f32_16x16x32_bf16 v[60:63], v[144:147], v[160:163], v[60:63]
	v_mfma_f32_16x16x32_bf16 v[56:59], v[152:155], v[160:163], v[56:59]
	v_mfma_f32_16x16x32_bf16 v[44:47], v[144:147], v[168:171], v[44:47]
	v_mfma_f32_16x16x32_bf16 v[40:43], v[152:155], v[168:171], v[40:43]
	v_mfma_f32_16x16x32_bf16 v[28:31], v[144:147], v[176:179], v[28:31]
	v_mfma_f32_16x16x32_bf16 v[24:27], v[152:155], v[176:179], v[24:27]
	v_mfma_f32_16x16x32_bf16 v[12:15], v[144:147], v[184:187], v[12:15]
	v_mfma_f32_16x16x32_bf16 v[8:11], v[152:155], v[184:187], v[8:11]
	v_mfma_f32_16x16x32_bf16 v[60:63], v[148:151], v[164:167], v[60:63]
	v_mfma_f32_16x16x32_bf16 v[56:59], v[156:159], v[164:167], v[56:59]
	v_mfma_f32_16x16x32_bf16 v[44:47], v[148:151], v[172:175], v[44:47]
	v_mfma_f32_16x16x32_bf16 v[40:43], v[156:159], v[172:175], v[40:43]
	v_mfma_f32_16x16x32_bf16 v[28:31], v[148:151], v[180:183], v[28:31]
	v_mfma_f32_16x16x32_bf16 v[24:27], v[156:159], v[180:183], v[24:27]
	v_mfma_f32_16x16x32_bf16 v[12:15], v[148:151], v[188:191], v[12:15]
	v_mfma_f32_16x16x32_bf16 v[8:11], v[156:159], v[188:191], v[8:11]
	s_barrier
	s_mov_b32 m0, s35
	global_load_lds_dwordx4 v128, s[18:19]
	s_mov_b32 m0, s34
	s_nop 0
	global_load_lds_dwordx4 v130, s[18:19]
	s_waitcnt vmcnt(6)
	s_barrier
	v_mfma_f32_16x16x32_bf16 v[52:55], v[192:195], v[160:163], v[52:55]
	v_mfma_f32_16x16x32_bf16 v[48:51], v[200:203], v[160:163], v[48:51]
	v_mfma_f32_16x16x32_bf16 v[36:39], v[192:195], v[168:171], v[36:39]
	v_mfma_f32_16x16x32_bf16 v[32:35], v[200:203], v[168:171], v[32:35]
	v_mfma_f32_16x16x32_bf16 v[20:23], v[192:195], v[176:179], v[20:23]
	v_mfma_f32_16x16x32_bf16 v[16:19], v[200:203], v[176:179], v[16:19]
	v_mfma_f32_16x16x32_bf16 v[4:7], v[192:195], v[184:187], v[4:7]
	v_mfma_f32_16x16x32_bf16 v[0:3], v[200:203], v[184:187], v[0:3]
	v_mfma_f32_16x16x32_bf16 v[52:55], v[196:199], v[164:167], v[52:55]
	v_mfma_f32_16x16x32_bf16 v[48:51], v[204:207], v[164:167], v[48:51]
	v_mfma_f32_16x16x32_bf16 v[36:39], v[196:199], v[172:175], v[36:39]
	v_mfma_f32_16x16x32_bf16 v[32:35], v[204:207], v[172:175], v[32:35]
	v_mfma_f32_16x16x32_bf16 v[20:23], v[196:199], v[180:183], v[20:23]
	v_mfma_f32_16x16x32_bf16 v[16:19], v[204:207], v[180:183], v[16:19]
	v_mfma_f32_16x16x32_bf16 v[4:7], v[196:199], v[188:191], v[4:7]
	v_mfma_f32_16x16x32_bf16 v[0:3], v[204:207], v[188:191], v[0:3]
	s_movk_i32 s20, 0x100
	s_andn2_b64 vcc, exec, s[14:15]
	s_mov_b64 s[18:19], -1
	s_mov_b64 s[14:15], 0
	s_barrier
	s_cbranch_vccz .LBB0_924
	v_lshl_or_b32 v136, s8, 8, v140
	v_ashrrev_i32_e32 v137, 31, v136
	v_cmp_lt_i32_e64 s[8:9], s1, v136
	v_add_u32_e32 v148, 0xfffff000, v136
	s_and_saveexec_b64 s[10:11], s[8:9]
	s_xor_b64 s[10:11], exec, s[10:11]
	v_cvt_f32_u32_e32 v144, v148
	v_mul_f32_e32 v147, 0x3b808081, v144
	s_or_saveexec_b64 s[10:11], s[10:11]
	v_cvt_f32_i32_e32 v150, v136
	s_xor_b64 exec, exec, s[10:11]
	v_mul_f32_e32 v147, 0x39800801, v150
	s_or_b64 exec, exec, s[10:11]
	v_or_b32_e32 v144, 1, v136
	v_cmp_lt_i32_e64 s[10:11], s1, v144
	v_add_u32_e32 v149, 0xfffff001, v136
	s_and_saveexec_b64 s[12:13], s[10:11]
	s_xor_b64 s[12:13], exec, s[12:13]
	v_cvt_f32_u32_e32 v145, v149
	v_mul_f32_e32 v153, 0x3b808081, v145
	s_or_saveexec_b64 s[12:13], s[12:13]
	v_cvt_f32_i32_e32 v167, v144
	v_mul_f32_e32 v144, 0x39800801, v167
	s_xor_b64 exec, exec, s[12:13]
	v_mul_f32_e32 v153, 0x39800801, v167
	s_or_b64 exec, exec, s[12:13]
	v_or_b32_e32 v145, 2, v136
	v_cmp_lt_i32_e64 s[12:13], s1, v145
	v_add_u32_e32 v151, 0xfffff002, v136
	s_and_saveexec_b64 s[14:15], s[12:13]
	s_xor_b64 s[14:15], exec, s[14:15]
	v_cvt_f32_u32_e32 v146, v151
	v_mul_f32_e32 v154, 0x3b808081, v146
	s_or_saveexec_b64 s[14:15], s[14:15]
	v_cvt_f32_i32_e32 v168, v145
	v_mul_f32_e32 v145, 0x39800801, v168
	s_xor_b64 exec, exec, s[14:15]
	v_mul_f32_e32 v154, 0x39800801, v168
	s_or_b64 exec, exec, s[14:15]
	v_or_b32_e32 v146, 3, v136
	v_cmp_lt_i32_e64 s[14:15], s1, v146
	v_add_u32_e32 v152, 0xfffff003, v136
	s_and_saveexec_b64 s[18:19], s[14:15]
	s_xor_b64 s[18:19], exec, s[18:19]
	v_cvt_f32_u32_e32 v155, v152
	v_mul_f32_e32 v155, 0x3b808081, v155
	s_or_saveexec_b64 s[18:19], s[18:19]
	v_cvt_f32_i32_e32 v169, v146
	v_mul_f32_e32 v146, 0x39800801, v169
	s_xor_b64 exec, exec, s[18:19]
	v_mul_f32_e32 v155, 0x39800801, v169
	s_or_b64 exec, exec, s[18:19]
	v_lshl_add_u32 v156, s16, 8, v138
	v_and_b32_e32 v157, 0x7cf, v156
	v_cvt_f32_u32_e32 v157, v157
	v_mul_f32_e32 v157, 0xc1447cbd, v157
	v_div_scale_f32 v158, s[16:17], s60, s60, v157
	v_rcp_f32_e32 v159, v158
	v_div_scale_f32 v160, vcc, v157, s60, v157
	v_fma_f32 v161, -v158, v159, 1.0
	v_fmac_f32_e32 v159, v161, v159
	v_mul_f32_e32 v161, v160, v159
	v_fma_f32 v162, -v158, v161, v160
	v_fmac_f32_e32 v161, v162, v159
	v_fma_f32 v158, -v158, v161, v160
	v_div_fmas_f32 v158, v158, v159, v161
	v_div_fixup_f32 v157, v158, s60, v157
	v_add_f32_e32 v182, 0xc0447cbd, v157
	v_mul_f32_e64 v154, |v182|, -v154
	v_mul_f32_e32 v154, 0x3fb8aa3b, v154
	v_exp_f32_e32 v154, v154
	v_mul_f32_e64 v147, |v182|, -v147
	v_mul_f32_e64 v153, |v182|, -v153
	v_mul_f32_e32 v147, 0x3fb8aa3b, v147
	v_mul_f32_e32 v153, 0x3fb8aa3b, v153
	v_mul_f32_e32 v160, v126, v154
	v_mul_f32_e64 v126, |v182|, -v155
	v_exp_f32_e32 v147, v147
	v_exp_f32_e32 v153, v153
	v_mul_f32_e32 v126, 0x3fb8aa3b, v126
	v_exp_f32_e32 v126, v126
	v_mul_f32_e32 v158, v124, v147
	v_mul_f32_e32 v159, v125, v153
	v_mov_b64_e32 v[124:125], s[92:93]
	v_mad_i64_i32 v[124:125], s[16:17], v156, s61, v[124:125]
	v_mul_f32_e32 v161, v127, v126
	v_or_b32_e32 v126, 16, v136
	v_lshl_add_u64 v[124:125], v[136:137], 2, v[124:125]
	v_cmp_lt_i32_e64 s[16:17], s1, v126
	v_add_u32_e32 v153, 0xfffff010, v136
	global_store_dwordx4 v[124:125], v[158:161], off
	s_and_saveexec_b64 s[18:19], s[16:17]
	s_xor_b64 s[18:19], exec, s[18:19]
	v_cvt_f32_u32_e32 v127, v153
	v_mul_f32_e32 v159, 0x3b808081, v127
	s_or_saveexec_b64 s[18:19], s[18:19]
	v_cvt_f32_i32_e32 v170, v126
	v_mul_f32_e32 v126, 0x39800801, v170
	s_xor_b64 exec, exec, s[18:19]
	v_mul_f32_e32 v159, 0x39800801, v170
	s_or_b64 exec, exec, s[18:19]
	v_or_b32_e32 v127, 17, v136
	v_cmp_lt_i32_e64 s[18:19], s1, v127
	v_add_u32_e32 v155, 0xfffff011, v136
	s_and_saveexec_b64 s[20:21], s[18:19]
	s_xor_b64 s[20:21], exec, s[20:21]
	v_cvt_f32_u32_e32 v147, v155
	v_mul_f32_e32 v160, 0x3b808081, v147
	s_or_saveexec_b64 s[20:21], s[20:21]
	v_cvt_f32_i32_e32 v171, v127
	v_mul_f32_e32 v127, 0x39800801, v171
	s_xor_b64 exec, exec, s[20:21]
	v_mul_f32_e32 v160, 0x39800801, v171
	s_or_b64 exec, exec, s[20:21]
	v_or_b32_e32 v147, 18, v136
	v_cmp_lt_i32_e64 s[20:21], s1, v147
	v_add_u32_e32 v157, 0xfffff012, v136
	s_and_saveexec_b64 s[22:23], s[20:21]
	s_xor_b64 s[22:23], exec, s[22:23]
	v_cvt_f32_u32_e32 v154, v157
	v_mul_f32_e32 v161, 0x3b808081, v154
	s_or_saveexec_b64 s[22:23], s[22:23]
	v_cvt_f32_i32_e32 v172, v147
	v_mul_f32_e32 v147, 0x39800801, v172
	s_xor_b64 exec, exec, s[22:23]
	v_mul_f32_e32 v161, 0x39800801, v172
	s_or_b64 exec, exec, s[22:23]
	v_or_b32_e32 v154, 19, v136
	v_cmp_lt_i32_e64 s[22:23], s1, v154
	v_add_u32_e32 v158, 0xfffff013, v136
	s_and_saveexec_b64 s[24:25], s[22:23]
	s_xor_b64 s[24:25], exec, s[24:25]
	v_cvt_f32_u32_e32 v162, v158
	v_mul_f32_e32 v162, 0x3b808081, v162
	s_or_saveexec_b64 s[24:25], s[24:25]
	v_cvt_f32_i32_e32 v173, v154
	v_mul_f32_e32 v154, 0x39800801, v173
	s_xor_b64 exec, exec, s[24:25]
	v_mul_f32_e32 v162, 0x39800801, v173
	s_or_b64 exec, exec, s[24:25]
	v_mul_f32_e64 v159, |v182|, -v159
	v_mul_f32_e64 v160, |v182|, -v160
	v_mul_f32_e64 v161, |v182|, -v161
	v_mul_f32_e64 v162, |v182|, -v162
	v_mul_f32_e32 v159, 0x3fb8aa3b, v159
	v_mul_f32_e32 v160, 0x3fb8aa3b, v160
	v_mul_f32_e32 v161, 0x3fb8aa3b, v161
	v_mul_f32_e32 v162, 0x3fb8aa3b, v162
	v_exp_f32_e32 v159, v159
	v_exp_f32_e32 v160, v160
	v_exp_f32_e32 v161, v161
	v_exp_f32_e32 v162, v162
	v_mul_f32_e32 v120, v120, v159
	v_mul_f32_e32 v121, v121, v160
	v_mul_f32_e32 v122, v122, v161
	v_mul_f32_e32 v123, v123, v162
	global_store_dwordx4 v[124:125], v[120:123], off offset:64
	s_nop 1
	v_or_b32_e32 v120, 0x80, v136
	v_cmp_lt_i32_e64 s[24:25], s1, v120
	v_add_u32_e32 v123, 0xfffff080, v136
	s_and_saveexec_b64 s[26:27], s[24:25]
	s_xor_b64 s[26:27], exec, s[26:27]
	v_cvt_f32_u32_e32 v121, v123
	v_mul_f32_e32 v163, 0x3b808081, v121
	s_or_saveexec_b64 s[26:27], s[26:27]
	v_cvt_f32_i32_e32 v174, v120
	v_mul_f32_e32 v120, 0x39800801, v174
	s_xor_b64 exec, exec, s[26:27]
	v_mul_f32_e32 v163, 0x39800801, v174
	s_or_b64 exec, exec, s[26:27]
	v_or_b32_e32 v121, 0x81, v136
	v_cmp_lt_i32_e64 s[26:27], s1, v121
	v_add_u32_e32 v160, 0xfffff081, v136
	s_and_saveexec_b64 s[28:29], s[26:27]
	s_xor_b64 s[28:29], exec, s[28:29]
	v_cvt_f32_u32_e32 v122, v160
	v_mul_f32_e32 v164, 0x3b808081, v122
	s_or_saveexec_b64 s[28:29], s[28:29]
	v_cvt_f32_i32_e32 v175, v121
	v_mul_f32_e32 v121, 0x39800801, v175
	s_xor_b64 exec, exec, s[28:29]
	v_mul_f32_e32 v164, 0x39800801, v175
	s_or_b64 exec, exec, s[28:29]
	v_or_b32_e32 v122, 0x82, v136
	v_cmp_lt_i32_e64 s[28:29], s1, v122
	v_add_u32_e32 v161, 0xfffff082, v136
	s_and_saveexec_b64 s[30:31], s[28:29]
	s_xor_b64 s[30:31], exec, s[30:31]
	v_cvt_f32_u32_e32 v159, v161
	v_mul_f32_e32 v165, 0x3b808081, v159
	s_or_saveexec_b64 s[30:31], s[30:31]
	v_cvt_f32_i32_e32 v176, v122
	v_mul_f32_e32 v122, 0x39800801, v176
	s_xor_b64 exec, exec, s[30:31]
	v_mul_f32_e32 v165, 0x39800801, v176
	s_or_b64 exec, exec, s[30:31]
	v_or_b32_e32 v159, 0x83, v136
	v_cmp_lt_i32_e64 s[30:31], s1, v159
	v_add_u32_e32 v162, 0xfffff083, v136
	s_and_saveexec_b64 s[34:35], s[30:31]
	s_xor_b64 s[34:35], exec, s[34:35]
	v_cvt_f32_u32_e32 v166, v162
	v_mul_f32_e32 v166, 0x3b808081, v166
	s_or_saveexec_b64 s[34:35], s[34:35]
	v_cvt_f32_i32_e32 v177, v159
	v_mul_f32_e32 v159, 0x39800801, v177
	s_xor_b64 exec, exec, s[34:35]
	v_mul_f32_e32 v166, 0x39800801, v177
	s_or_b64 exec, exec, s[34:35]
	v_mul_f32_e64 v163, |v182|, -v163
	v_mul_f32_e64 v164, |v182|, -v164
	v_mul_f32_e64 v165, |v182|, -v165
	v_mul_f32_e64 v166, |v182|, -v166
	v_mul_f32_e32 v163, 0x3fb8aa3b, v163
	v_mul_f32_e32 v164, 0x3fb8aa3b, v164
	v_mul_f32_e32 v165, 0x3fb8aa3b, v165
	v_mul_f32_e32 v166, 0x3fb8aa3b, v166
	v_exp_f32_e32 v163, v163
	v_exp_f32_e32 v164, v164
	v_exp_f32_e32 v165, v165
	v_exp_f32_e32 v166, v166
	v_mul_f32_e32 v116, v116, v163
	v_mul_f32_e32 v117, v117, v164
	v_mul_f32_e32 v118, v118, v165
	v_mul_f32_e32 v119, v119, v166
	global_store_dwordx4 v[124:125], v[116:119], off offset:512
	s_nop 1
	v_or_b32_e32 v116, 0x90, v136
	v_cmp_lt_i32_e64 s[34:35], s1, v116
	v_add_u32_e32 v119, 0xfffff090, v136
	s_and_saveexec_b64 s[36:37], s[34:35]
	s_xor_b64 s[36:37], exec, s[36:37]
	v_cvt_f32_u32_e32 v117, v119
	v_mul_f32_e32 v183, 0x3b808081, v117
	s_or_saveexec_b64 s[36:37], s[36:37]
	v_cvt_f32_i32_e32 v178, v116
	v_mul_f32_e32 v116, 0x39800801, v178
	s_xor_b64 exec, exec, s[36:37]
	v_mul_f32_e32 v183, 0x39800801, v178
	s_or_b64 exec, exec, s[36:37]
	v_or_b32_e32 v117, 0x91, v136
	v_cmp_lt_i32_e64 s[36:37], s1, v117
	v_add_u32_e32 v164, 0xfffff091, v136
	s_and_saveexec_b64 s[38:39], s[36:37]
	s_xor_b64 s[38:39], exec, s[38:39]
	v_cvt_f32_u32_e32 v118, v164
	v_mul_f32_e32 v184, 0x3b808081, v118
	s_or_saveexec_b64 s[38:39], s[38:39]
	v_cvt_f32_i32_e32 v179, v117
	v_mul_f32_e32 v117, 0x39800801, v179
	s_xor_b64 exec, exec, s[38:39]
	v_mul_f32_e32 v184, 0x39800801, v179
	s_or_b64 exec, exec, s[38:39]
	v_or_b32_e32 v118, 0x92, v136
	v_cmp_lt_i32_e64 s[38:39], s1, v118
	v_add_u32_e32 v165, 0xfffff092, v136
	s_and_saveexec_b64 s[40:41], s[38:39]
	s_xor_b64 s[40:41], exec, s[40:41]
	v_cvt_f32_u32_e32 v163, v165
	v_mul_f32_e32 v185, 0x3b808081, v163
	s_or_saveexec_b64 s[40:41], s[40:41]
	v_cvt_f32_i32_e32 v180, v118
	v_mul_f32_e32 v118, 0x39800801, v180
	s_xor_b64 exec, exec, s[40:41]
	v_mul_f32_e32 v185, 0x39800801, v180
	s_or_b64 exec, exec, s[40:41]
	v_or_b32_e32 v163, 0x93, v136
	v_cmp_lt_i32_e64 s[40:41], s1, v163
	v_add_u32_e32 v166, 0xfffff093, v136
	s_and_saveexec_b64 s[72:73], s[40:41]
	s_xor_b64 s[72:73], exec, s[72:73]
	v_cvt_f32_u32_e32 v181, v166
	v_mul_f32_e32 v186, 0x3b808081, v181
	s_or_saveexec_b64 s[72:73], s[72:73]
	v_cvt_f32_i32_e32 v181, v163
	v_mul_f32_e32 v163, 0x39800801, v181
	s_xor_b64 exec, exec, s[72:73]
	v_mul_f32_e32 v186, 0x39800801, v181
	s_or_b64 exec, exec, s[72:73]
	v_mul_f32_e64 v183, |v182|, -v183
	v_mul_f32_e64 v184, |v182|, -v184
	v_mul_f32_e64 v185, |v182|, -v185
	v_mul_f32_e64 v182, |v182|, -v186
	v_mul_f32_e32 v183, 0x3fb8aa3b, v183
	v_mul_f32_e32 v184, 0x3fb8aa3b, v184
	v_mul_f32_e32 v185, 0x3fb8aa3b, v185
	v_mul_f32_e32 v182, 0x3fb8aa3b, v182
	v_exp_f32_e32 v183, v183
	v_exp_f32_e32 v184, v184
	v_exp_f32_e32 v185, v185
	v_exp_f32_e32 v182, v182
	v_mul_f32_e32 v112, v112, v183
	v_mul_f32_e32 v113, v113, v184
	v_mul_f32_e32 v114, v114, v185
	v_mul_f32_e32 v115, v115, v182
	global_store_dwordx4 v[124:125], v[112:115], off offset:576
	s_and_saveexec_b64 s[72:73], s[8:9]
	s_xor_b64 s[72:73], exec, s[72:73]
	s_cbranch_execz .LBB0_991
	v_cvt_f32_u32_e32 v112, v148
	v_mul_f32_e32 v113, 0x3b808081, v112
	s_andn2_saveexec_b64 s[72:73], s[72:73]
	s_branch .LBB0_992

.LBB0_1417:
	ds_read_b128 v[140:143], v151
	ds_read_b128 v[144:147], v151 offset:1024
	ds_read_b128 v[154:157], v151 offset:2048
	ds_read_b128 v[158:161], v151 offset:3072
	s_add_u32 s22, s20, 0x100
	s_addc_u32 s23, s21, 0
	s_cmp_eq_u32 s46, 28
	s_cselect_b32 s27, s13, s23
	s_cselect_b32 s26, s40, s22
	s_cselect_b32 s25, s11, s43
	s_cselect_b32 s24, s41, s42
	v_lshl_add_u64 v[194:195], s[20:21], 0, v[132:133]
	s_add_i32 m0, s5, 0xc000
	ds_read_b128 v[162:165], v152
	ds_read_b128 v[166:169], v152 offset:1024
	ds_read_b128 v[170:173], v152 offset:2048
	ds_read_b128 v[174:177], v152 offset:3072
	ds_read_b128 v[178:181], v152 offset:4096
	ds_read_b128 v[182:185], v152 offset:5120
	ds_read_b128 v[186:189], v152 offset:6144
	ds_read_b128 v[190:193], v152 offset:7168
	global_load_lds_dwordx4 v[194:195], off
	s_add_i32 m0, s5, 0xe000
	s_nop 0
	global_load_lds_dwordx4 v134, s[20:21]
	s_waitcnt lgkmcnt(8)
	s_barrier
	s_waitcnt lgkmcnt(0)
	s_waitcnt lgkmcnt(0)
	v_mfma_f32_16x16x32_bf16 v[124:127], v[140:143], v[162:165], v[124:127]
	v_mfma_f32_16x16x32_bf16 v[120:123], v[154:157], v[162:165], v[120:123]
	v_mfma_f32_16x16x32_bf16 v[108:111], v[140:143], v[170:173], v[108:111]
	v_mfma_f32_16x16x32_bf16 v[104:107], v[154:157], v[170:173], v[104:107]
	v_mfma_f32_16x16x32_bf16 v[92:95], v[140:143], v[178:181], v[92:95]
	v_mfma_f32_16x16x32_bf16 v[88:91], v[154:157], v[178:181], v[88:91]
	v_mfma_f32_16x16x32_bf16 v[76:79], v[140:143], v[186:189], v[76:79]
	v_mfma_f32_16x16x32_bf16 v[72:75], v[154:157], v[186:189], v[72:75]
	v_mfma_f32_16x16x32_bf16 v[124:127], v[144:147], v[166:169], v[124:127]
	v_mfma_f32_16x16x32_bf16 v[120:123], v[158:161], v[166:169], v[120:123]
	v_mfma_f32_16x16x32_bf16 v[108:111], v[144:147], v[174:177], v[108:111]
	v_mfma_f32_16x16x32_bf16 v[104:107], v[158:161], v[174:177], v[104:107]
	v_mfma_f32_16x16x32_bf16 v[92:95], v[144:147], v[182:185], v[92:95]
	v_mfma_f32_16x16x32_bf16 v[88:91], v[158:161], v[182:185], v[88:91]
	v_mfma_f32_16x16x32_bf16 v[76:79], v[144:147], v[190:193], v[76:79]
	v_mfma_f32_16x16x32_bf16 v[72:75], v[158:161], v[190:193], v[72:75]
	s_barrier
	s_add_i32 s20, s36, s2
	s_mov_b32 m0, s20
	ds_read_b128 v[194:197], v153
	ds_read_b128 v[198:201], v153 offset:1024
	ds_read_b128 v[202:205], v153 offset:2048
	ds_read_b128 v[206:209], v153 offset:3072
	global_load_lds_dwordx4 v130, s[24:25]
	s_add_i32 m0, s20, 0x2000
	s_nop 0
	global_load_lds_dwordx4 v128, s[24:25]
	s_barrier
	s_waitcnt lgkmcnt(0)
	s_waitcnt lgkmcnt(0)
	v_mfma_f32_16x16x32_bf16 v[116:119], v[194:197], v[162:165], v[116:119]
	v_mfma_f32_16x16x32_bf16 v[112:115], v[202:205], v[162:165], v[112:115]
	v_mfma_f32_16x16x32_bf16 v[100:103], v[194:197], v[170:173], v[100:103]
	v_mfma_f32_16x16x32_bf16 v[96:99], v[202:205], v[170:173], v[96:99]
	v_mfma_f32_16x16x32_bf16 v[84:87], v[194:197], v[178:181], v[84:87]
	v_mfma_f32_16x16x32_bf16 v[80:83], v[202:205], v[178:181], v[80:83]
	v_mfma_f32_16x16x32_bf16 v[68:71], v[194:197], v[186:189], v[68:71]
	v_mfma_f32_16x16x32_bf16 v[64:67], v[202:205], v[186:189], v[64:67]
	v_mfma_f32_16x16x32_bf16 v[116:119], v[198:201], v[166:169], v[116:119]
	v_mfma_f32_16x16x32_bf16 v[112:115], v[206:209], v[166:169], v[112:115]
	v_mfma_f32_16x16x32_bf16 v[100:103], v[198:201], v[174:177], v[100:103]
	v_mfma_f32_16x16x32_bf16 v[96:99], v[206:209], v[174:177], v[96:99]
	v_mfma_f32_16x16x32_bf16 v[84:87], v[198:201], v[182:185], v[84:87]
	v_mfma_f32_16x16x32_bf16 v[80:83], v[206:209], v[182:185], v[80:83]
	v_mfma_f32_16x16x32_bf16 v[68:71], v[198:201], v[190:193], v[68:71]
	v_mfma_f32_16x16x32_bf16 v[64:67], v[206:209], v[190:193], v[64:67]
	s_mov_b32 m0, s5
	v_lshl_add_u64 v[214:215], s[26:27], 0, v[130:131]
	s_barrier
	ds_read_b128 v[162:165], v152 offset:16384
	ds_read_b128 v[166:169], v152 offset:17408
	ds_read_b128 v[170:173], v152 offset:18432
	ds_read_b128 v[174:177], v152 offset:19456
	ds_read_b128 v[178:181], v152 offset:20480
	ds_read_b128 v[182:185], v152 offset:21504
	ds_read_b128 v[186:189], v152 offset:22528
	ds_read_b128 v[190:193], v152 offset:23552
	global_load_lds_dwordx4 v130, s[26:27]
	v_lshl_add_u64 v[216:217], s[26:27], 0, v[128:129]
	s_mov_b32 m0, s19
	s_nop 0
	global_load_lds_dwordx4 v128, s[26:27]
	s_barrier
	s_waitcnt lgkmcnt(0)
	s_waitcnt lgkmcnt(0)
	v_mfma_f32_16x16x32_bf16 v[60:63], v[140:143], v[162:165], v[60:63]
	v_mfma_f32_16x16x32_bf16 v[56:59], v[154:157], v[162:165], v[56:59]
	v_mfma_f32_16x16x32_bf16 v[44:47], v[140:143], v[170:173], v[44:47]
	v_mfma_f32_16x16x32_bf16 v[40:43], v[154:157], v[170:173], v[40:43]
	v_mfma_f32_16x16x32_bf16 v[28:31], v[140:143], v[178:181], v[28:31]
	v_mfma_f32_16x16x32_bf16 v[24:27], v[154:157], v[178:181], v[24:27]
	v_mfma_f32_16x16x32_bf16 v[12:15], v[140:143], v[186:189], v[12:15]
	v_mfma_f32_16x16x32_bf16 v[8:11], v[154:157], v[186:189], v[8:11]
	v_mfma_f32_16x16x32_bf16 v[60:63], v[144:147], v[166:169], v[60:63]
	v_mfma_f32_16x16x32_bf16 v[56:59], v[158:161], v[166:169], v[56:59]
	v_mfma_f32_16x16x32_bf16 v[44:47], v[144:147], v[174:177], v[44:47]
	v_mfma_f32_16x16x32_bf16 v[40:43], v[158:161], v[174:177], v[40:43]
	v_mfma_f32_16x16x32_bf16 v[28:31], v[144:147], v[182:185], v[28:31]
	v_mfma_f32_16x16x32_bf16 v[24:27], v[158:161], v[182:185], v[24:27]
	v_mfma_f32_16x16x32_bf16 v[12:15], v[144:147], v[190:193], v[12:15]
	v_mfma_f32_16x16x32_bf16 v[8:11], v[158:161], v[190:193], v[8:11]
	s_barrier
	s_add_u32 s20, s24, 0x80000
	s_addc_u32 s21, s25, 0
	s_add_i32 s47, s37, s2
	s_mov_b32 m0, s47
	s_nop 0
	global_load_lds_dwordx4 v130, s[20:21]
	s_add_i32 m0, s47, 0x2000
	s_nop 0
	global_load_lds_dwordx4 v128, s[20:21]
	s_waitcnt vmcnt(6)
	s_barrier
	v_mfma_f32_16x16x32_bf16 v[52:55], v[194:197], v[162:165], v[52:55]
	v_mfma_f32_16x16x32_bf16 v[48:51], v[202:205], v[162:165], v[48:51]
	v_mfma_f32_16x16x32_bf16 v[36:39], v[194:197], v[170:173], v[36:39]
	v_mfma_f32_16x16x32_bf16 v[32:35], v[202:205], v[170:173], v[32:35]
	v_mfma_f32_16x16x32_bf16 v[20:23], v[194:197], v[178:181], v[20:23]
	v_mfma_f32_16x16x32_bf16 v[16:19], v[202:205], v[178:181], v[16:19]
	v_mfma_f32_16x16x32_bf16 v[4:7], v[194:197], v[186:189], v[4:7]
	v_mfma_f32_16x16x32_bf16 v[0:3], v[202:205], v[186:189], v[0:3]
	v_mfma_f32_16x16x32_bf16 v[52:55], v[198:201], v[166:169], v[52:55]
	v_mfma_f32_16x16x32_bf16 v[48:51], v[206:209], v[166:169], v[48:51]
	v_mfma_f32_16x16x32_bf16 v[36:39], v[198:201], v[174:177], v[36:39]
	v_mfma_f32_16x16x32_bf16 v[32:35], v[206:209], v[174:177], v[32:35]
	v_mfma_f32_16x16x32_bf16 v[20:23], v[198:201], v[182:185], v[20:23]
	v_mfma_f32_16x16x32_bf16 v[16:19], v[206:209], v[182:185], v[16:19]
	v_mfma_f32_16x16x32_bf16 v[4:7], v[198:201], v[190:193], v[4:7]
	v_mfma_f32_16x16x32_bf16 v[0:3], v[206:209], v[190:193], v[0:3]
	s_add_i32 s47, 0, 0x18000
	v_add_u32_e32 v158, s47, v149
	s_barrier
	ds_read_b128 v[140:143], v158
	ds_read_b128 v[144:147], v158 offset:1024
	ds_read_b128 v[154:157], v158 offset:2048
	ds_read_b128 v[158:161], v158 offset:3072
	s_add_u32 s20, s26, 0x80000
	s_addc_u32 s21, s27, 0
	s_mov_b32 m0, s28
	ds_read_b128 v[162:165], v152 offset:32768
	ds_read_b128 v[166:169], v152 offset:33792
	ds_read_b128 v[170:173], v152 offset:34816
	ds_read_b128 v[174:177], v152 offset:35840
	ds_read_b128 v[178:181], v152 offset:36864
	ds_read_b128 v[182:185], v152 offset:37888
	ds_read_b128 v[186:189], v152 offset:38912
	ds_read_b128 v[190:193], v152 offset:39936
	global_load_lds_dwordx4 v130, s[20:21]
	s_mov_b32 m0, s29
	s_nop 0
	global_load_lds_dwordx4 v128, s[20:21]
	s_waitcnt lgkmcnt(8)
	s_barrier
	s_waitcnt lgkmcnt(0)
	s_waitcnt lgkmcnt(0)
	v_mfma_f32_16x16x32_bf16 v[124:127], v[140:143], v[162:165], v[124:127]
	v_mfma_f32_16x16x32_bf16 v[120:123], v[154:157], v[162:165], v[120:123]
	v_mfma_f32_16x16x32_bf16 v[108:111], v[140:143], v[170:173], v[108:111]
	v_mfma_f32_16x16x32_bf16 v[104:107], v[154:157], v[170:173], v[104:107]
	v_mfma_f32_16x16x32_bf16 v[92:95], v[140:143], v[178:181], v[92:95]
	v_mfma_f32_16x16x32_bf16 v[88:91], v[154:157], v[178:181], v[88:91]
	v_mfma_f32_16x16x32_bf16 v[76:79], v[140:143], v[186:189], v[76:79]
	v_mfma_f32_16x16x32_bf16 v[72:75], v[154:157], v[186:189], v[72:75]
	v_mfma_f32_16x16x32_bf16 v[124:127], v[144:147], v[166:169], v[124:127]
	v_mfma_f32_16x16x32_bf16 v[120:123], v[158:161], v[166:169], v[120:123]
	v_mfma_f32_16x16x32_bf16 v[108:111], v[144:147], v[174:177], v[108:111]
	v_mfma_f32_16x16x32_bf16 v[104:107], v[158:161], v[174:177], v[104:107]
	v_mfma_f32_16x16x32_bf16 v[92:95], v[144:147], v[182:185], v[92:95]
	v_mfma_f32_16x16x32_bf16 v[88:91], v[158:161], v[182:185], v[88:91]
	v_mfma_f32_16x16x32_bf16 v[76:79], v[144:147], v[190:193], v[76:79]
	v_mfma_f32_16x16x32_bf16 v[72:75], v[158:161], v[190:193], v[72:75]
	s_barrier
	s_add_i32 s26, 0, 0x1c000
	s_add_i32 s20, s47, s2
	v_add_u32_e32 v206, s26, v149
	s_add_u32 s98, s24, s8
	s_addc_u32 s99, s25, s9
	s_mov_b32 m0, s20
	ds_read_b128 v[194:197], v206
	ds_read_b128 v[198:201], v206 offset:1024
	ds_read_b128 v[202:205], v206 offset:2048
	ds_read_b128 v[206:209], v206 offset:3072
	global_load_lds_dwordx4 v130, s[98:99]
	s_add_i32 m0, s20, 0x2000
	s_nop 0
	global_load_lds_dwordx4 v128, s[98:99]
	s_barrier
	s_waitcnt lgkmcnt(0)
	s_waitcnt lgkmcnt(0)
	v_mfma_f32_16x16x32_bf16 v[116:119], v[194:197], v[162:165], v[116:119]
	v_mfma_f32_16x16x32_bf16 v[112:115], v[202:205], v[162:165], v[112:115]
	v_mfma_f32_16x16x32_bf16 v[100:103], v[194:197], v[170:173], v[100:103]
	v_mfma_f32_16x16x32_bf16 v[96:99], v[202:205], v[170:173], v[96:99]
	v_mfma_f32_16x16x32_bf16 v[84:87], v[194:197], v[178:181], v[84:87]
	v_mfma_f32_16x16x32_bf16 v[80:83], v[202:205], v[178:181], v[80:83]
	v_mfma_f32_16x16x32_bf16 v[68:71], v[194:197], v[186:189], v[68:71]
	v_mfma_f32_16x16x32_bf16 v[64:67], v[202:205], v[186:189], v[64:67]
	v_mfma_f32_16x16x32_bf16 v[116:119], v[198:201], v[166:169], v[116:119]
	v_mfma_f32_16x16x32_bf16 v[112:115], v[206:209], v[166:169], v[112:115]
	v_mfma_f32_16x16x32_bf16 v[100:103], v[198:201], v[174:177], v[100:103]
	v_mfma_f32_16x16x32_bf16 v[96:99], v[206:209], v[174:177], v[96:99]
	v_mfma_f32_16x16x32_bf16 v[84:87], v[198:201], v[182:185], v[84:87]
	v_mfma_f32_16x16x32_bf16 v[80:83], v[206:209], v[182:185], v[80:83]
	v_mfma_f32_16x16x32_bf16 v[68:71], v[198:201], v[190:193], v[68:71]
	v_mfma_f32_16x16x32_bf16 v[64:67], v[206:209], v[190:193], v[64:67]
	s_mov_b32 m0, s31
	v_lshl_add_u64 v[210:211], v[214:215], 0, s[8:9]
	s_barrier
	ds_read_b128 v[162:165], v152 offset:49152
	ds_read_b128 v[166:169], v152 offset:50176
	ds_read_b128 v[170:173], v152 offset:51200
	ds_read_b128 v[174:177], v152 offset:52224
	ds_read_b128 v[178:181], v152 offset:53248
	ds_read_b128 v[182:185], v152 offset:54272
	ds_read_b128 v[186:189], v152 offset:55296
	ds_read_b128 v[190:193], v152 offset:56320
	global_load_lds_dwordx4 v[210:211], off
	v_lshl_add_u64 v[210:211], v[216:217], 0, s[8:9]
	s_mov_b32 m0, s34
	s_nop 0
	global_load_lds_dwordx4 v[210:211], off
	s_barrier
	s_waitcnt lgkmcnt(0)
	s_waitcnt lgkmcnt(0)
	v_mfma_f32_16x16x32_bf16 v[60:63], v[140:143], v[162:165], v[60:63]
	v_mfma_f32_16x16x32_bf16 v[56:59], v[154:157], v[162:165], v[56:59]
	v_mfma_f32_16x16x32_bf16 v[44:47], v[140:143], v[170:173], v[44:47]
	v_mfma_f32_16x16x32_bf16 v[40:43], v[154:157], v[170:173], v[40:43]
	v_mfma_f32_16x16x32_bf16 v[28:31], v[140:143], v[178:181], v[28:31]
	v_mfma_f32_16x16x32_bf16 v[24:27], v[154:157], v[178:181], v[24:27]
	v_mfma_f32_16x16x32_bf16 v[12:15], v[140:143], v[186:189], v[12:15]
	v_mfma_f32_16x16x32_bf16 v[8:11], v[154:157], v[186:189], v[8:11]
	v_mfma_f32_16x16x32_bf16 v[60:63], v[144:147], v[166:169], v[60:63]
	v_mfma_f32_16x16x32_bf16 v[56:59], v[158:161], v[166:169], v[56:59]
	v_mfma_f32_16x16x32_bf16 v[44:47], v[144:147], v[174:177], v[44:47]
	v_mfma_f32_16x16x32_bf16 v[40:43], v[158:161], v[174:177], v[40:43]
	v_mfma_f32_16x16x32_bf16 v[28:31], v[144:147], v[182:185], v[28:31]
	v_mfma_f32_16x16x32_bf16 v[24:27], v[158:161], v[182:185], v[24:27]
	v_mfma_f32_16x16x32_bf16 v[12:15], v[144:147], v[190:193], v[12:15]
	v_mfma_f32_16x16x32_bf16 v[8:11], v[158:161], v[190:193], v[8:11]
	s_barrier
	s_add_u32 s20, s24, 0x80080
	s_addc_u32 s21, s25, 0
	s_add_i32 s24, s26, s2
	s_mov_b32 m0, s24
	s_nop 0
	global_load_lds_dwordx4 v130, s[20:21]
	s_add_i32 m0, s24, 0x2000
	s_nop 0
	global_load_lds_dwordx4 v128, s[20:21]
	s_waitcnt vmcnt(6)
	s_barrier
	v_mfma_f32_16x16x32_bf16 v[52:55], v[194:197], v[162:165], v[52:55]
	v_mfma_f32_16x16x32_bf16 v[48:51], v[202:205], v[162:165], v[48:51]
	v_mfma_f32_16x16x32_bf16 v[36:39], v[194:197], v[170:173], v[36:39]
	v_mfma_f32_16x16x32_bf16 v[32:35], v[202:205], v[170:173], v[32:35]
	v_mfma_f32_16x16x32_bf16 v[20:23], v[194:197], v[178:181], v[20:23]
	v_mfma_f32_16x16x32_bf16 v[16:19], v[202:205], v[178:181], v[16:19]
	v_mfma_f32_16x16x32_bf16 v[4:7], v[194:197], v[186:189], v[4:7]
	v_mfma_f32_16x16x32_bf16 v[0:3], v[202:205], v[186:189], v[0:3]
	v_mfma_f32_16x16x32_bf16 v[52:55], v[198:201], v[166:169], v[52:55]
	v_mfma_f32_16x16x32_bf16 v[48:51], v[206:209], v[166:169], v[48:51]
	v_mfma_f32_16x16x32_bf16 v[36:39], v[198:201], v[174:177], v[36:39]
	v_mfma_f32_16x16x32_bf16 v[32:35], v[206:209], v[174:177], v[32:35]
	v_mfma_f32_16x16x32_bf16 v[20:23], v[198:201], v[182:185], v[20:23]
	v_mfma_f32_16x16x32_bf16 v[16:19], v[206:209], v[182:185], v[16:19]
	v_mfma_f32_16x16x32_bf16 v[4:7], v[198:201], v[190:193], v[4:7]
	v_mfma_f32_16x16x32_bf16 v[0:3], v[206:209], v[190:193], v[0:3]
	s_add_i32 s46, s46, 2
	s_add_u32 s42, s42, 0x100
	s_addc_u32 s43, s43, 0
	s_cmp_gt_u32 s46, 29
	s_mov_b64 s[20:21], s[22:23]
	s_barrier
	s_cbranch_scc0 .LBB0_1417
	v_lshl_or_b32 v144, s39, 8, v150
	v_lshl_add_u32 v140, s18, 8, v148
	v_ashrrev_i32_e32 v145, 31, v144
	v_mov_b64_e32 v[142:143], s[52:53]
	v_readlane_b32 s60, v240, 49
	v_ashrrev_i32_e32 v141, 31, v140
	v_mad_i64_i32 v[146:147], s[20:21], v140, s38, v[142:143]
	v_lshlrev_b64 v[144:145], 2, v[144:145]
	v_readlane_b32 s72, v240, 61
	v_readlane_b32 s73, v240, 62
	v_lshl_add_u64 v[154:155], v[146:147], 0, v[144:145]
	s_and_b64 vcc, exec, s[6:7]
	v_lshl_add_u64 v[146:147], v[140:141], 2, s[72:73]
	global_load_dword v156, v[146:147], off
	s_mov_b32 s39, s10
	s_mov_b32 s18, s12
	s_mov_b64 s[22:23], s[16:17]
	v_readlane_b32 s61, v240, 50
	v_readlane_b32 s62, v240, 51
	v_readlane_b32 s63, v240, 52
	v_readlane_b32 s64, v240, 53
	v_readlane_b32 s65, v240, 54
	v_readlane_b32 s66, v240, 55
	v_readlane_b32 s67, v240, 56
	v_readlane_b32 s68, v240, 57
	v_readlane_b32 s69, v240, 58
	v_readlane_b32 s70, v240, 59
	v_readlane_b32 s71, v240, 60
	v_readlane_b32 s74, v240, 63
	v_readlane_b32 s75, v239, 0
	s_waitcnt vmcnt(0)
	v_pk_add_f32 v[126:127], v[126:127], v[156:157] op_sel_hi:[1,0]
	v_pk_add_f32 v[124:125], v[124:125], v[156:157] op_sel_hi:[1,0]
	v_pk_add_f32 v[122:123], v[122:123], v[156:157] op_sel_hi:[1,0]
	v_pk_add_f32 v[120:121], v[120:121], v[156:157] op_sel_hi:[1,0]
	v_pk_add_f32 v[118:119], v[118:119], v[156:157] op_sel_hi:[1,0]
	v_pk_add_f32 v[116:117], v[116:117], v[156:157] op_sel_hi:[1,0]
	v_pk_add_f32 v[114:115], v[114:115], v[156:157] op_sel_hi:[1,0]
	v_pk_add_f32 v[112:113], v[112:113], v[156:157] op_sel_hi:[1,0]
	global_store_dwordx4 v[154:155], v[124:127], off
	global_store_dwordx4 v[154:155], v[120:123], off offset:64
	global_store_dwordx4 v[154:155], v[116:119], off offset:512
	global_store_dwordx4 v[154:155], v[112:115], off offset:576
	global_load_dword v114, v[146:147], off offset:64
	s_waitcnt vmcnt(0)
	v_pk_add_f32 v[110:111], v[110:111], v[114:115] op_sel_hi:[1,0]
	v_or_b32_e32 v112, 16, v140
	v_mad_i64_i32 v[112:113], s[20:21], v112, s38, v[142:143]
	v_lshl_add_u64 v[112:113], v[112:113], 0, v[144:145]
	v_pk_add_f32 v[108:109], v[108:109], v[114:115] op_sel_hi:[1,0]
	v_pk_add_f32 v[106:107], v[106:107], v[114:115] op_sel_hi:[1,0]
	v_pk_add_f32 v[104:105], v[104:105], v[114:115] op_sel_hi:[1,0]
	v_pk_add_f32 v[102:103], v[102:103], v[114:115] op_sel_hi:[1,0]
	v_pk_add_f32 v[100:101], v[100:101], v[114:115] op_sel_hi:[1,0]
	v_pk_add_f32 v[98:99], v[98:99], v[114:115] op_sel_hi:[1,0]
	v_pk_add_f32 v[96:97], v[96:97], v[114:115] op_sel_hi:[1,0]
	global_store_dwordx4 v[112:113], v[108:111], off
	global_store_dwordx4 v[112:113], v[104:107], off offset:64
	global_store_dwordx4 v[112:113], v[100:103], off offset:512
	global_store_dwordx4 v[112:113], v[96:99], off offset:576
	global_load_dword v98, v[146:147], off offset:128
	s_waitcnt vmcnt(0)
	v_pk_add_f32 v[94:95], v[94:95], v[98:99] op_sel_hi:[1,0]
	v_or_b32_e32 v96, 32, v140
	v_mad_i64_i32 v[96:97], s[20:21], v96, s38, v[142:143]
	v_lshl_add_u64 v[96:97], v[96:97], 0, v[144:145]
	v_pk_add_f32 v[92:93], v[92:93], v[98:99] op_sel_hi:[1,0]
	v_pk_add_f32 v[90:91], v[90:91], v[98:99] op_sel_hi:[1,0]
	v_pk_add_f32 v[88:89], v[88:89], v[98:99] op_sel_hi:[1,0]
	v_pk_add_f32 v[86:87], v[86:87], v[98:99] op_sel_hi:[1,0]
	v_pk_add_f32 v[84:85], v[84:85], v[98:99] op_sel_hi:[1,0]
	v_pk_add_f32 v[82:83], v[82:83], v[98:99] op_sel_hi:[1,0]
	v_pk_add_f32 v[80:81], v[80:81], v[98:99] op_sel_hi:[1,0]
	global_store_dwordx4 v[96:97], v[92:95], off
	global_store_dwordx4 v[96:97], v[88:91], off offset:64
	global_store_dwordx4 v[96:97], v[84:87], off offset:512
	global_store_dwordx4 v[96:97], v[80:83], off offset:576
	global_load_dword v82, v[146:147], off offset:192
	s_waitcnt vmcnt(0)
	v_pk_add_f32 v[78:79], v[78:79], v[82:83] op_sel_hi:[1,0]
	v_or_b32_e32 v80, 48, v140
	v_mad_i64_i32 v[80:81], s[20:21], v80, s38, v[142:143]
	v_lshl_add_u64 v[80:81], v[80:81], 0, v[144:145]
	v_pk_add_f32 v[76:77], v[76:77], v[82:83] op_sel_hi:[1,0]
	v_pk_add_f32 v[74:75], v[74:75], v[82:83] op_sel_hi:[1,0]
	v_pk_add_f32 v[72:73], v[72:73], v[82:83] op_sel_hi:[1,0]
	v_pk_add_f32 v[70:71], v[70:71], v[82:83] op_sel_hi:[1,0]
	v_pk_add_f32 v[68:69], v[68:69], v[82:83] op_sel_hi:[1,0]
	v_pk_add_f32 v[66:67], v[66:67], v[82:83] op_sel_hi:[1,0]
	v_pk_add_f32 v[64:65], v[64:65], v[82:83] op_sel_hi:[1,0]
	global_store_dwordx4 v[80:81], v[76:79], off
	global_store_dwordx4 v[80:81], v[72:75], off offset:64
	global_store_dwordx4 v[80:81], v[68:71], off offset:512
	global_store_dwordx4 v[80:81], v[64:67], off offset:576
	global_load_dword v66, v[146:147], off offset:512
	s_waitcnt vmcnt(0)
	v_pk_add_f32 v[62:63], v[62:63], v[66:67] op_sel_hi:[1,0]
	v_add_u32_e32 v64, 0x80, v140
	v_mad_i64_i32 v[64:65], s[20:21], v64, s38, v[142:143]
	v_lshl_add_u64 v[64:65], v[64:65], 0, v[144:145]
	v_pk_add_f32 v[60:61], v[60:61], v[66:67] op_sel_hi:[1,0]
	v_pk_add_f32 v[58:59], v[58:59], v[66:67] op_sel_hi:[1,0]
	v_pk_add_f32 v[56:57], v[56:57], v[66:67] op_sel_hi:[1,0]
	v_pk_add_f32 v[54:55], v[54:55], v[66:67] op_sel_hi:[1,0]
	v_pk_add_f32 v[52:53], v[52:53], v[66:67] op_sel_hi:[1,0]
	v_pk_add_f32 v[50:51], v[50:51], v[66:67] op_sel_hi:[1,0]
	v_pk_add_f32 v[48:49], v[48:49], v[66:67] op_sel_hi:[1,0]
	global_store_dwordx4 v[64:65], v[60:63], off
	global_store_dwordx4 v[64:65], v[56:59], off offset:64
	global_store_dwordx4 v[64:65], v[52:55], off offset:512
	global_store_dwordx4 v[64:65], v[48:51], off offset:576
	global_load_dword v50, v[146:147], off offset:576
	s_waitcnt vmcnt(0)
	v_pk_add_f32 v[46:47], v[46:47], v[50:51] op_sel_hi:[1,0]
	v_add_u32_e32 v48, 0x90, v140
	v_mad_i64_i32 v[48:49], s[20:21], v48, s38, v[142:143]
	v_lshl_add_u64 v[48:49], v[48:49], 0, v[144:145]
	v_pk_add_f32 v[44:45], v[44:45], v[50:51] op_sel_hi:[1,0]
	v_pk_add_f32 v[42:43], v[42:43], v[50:51] op_sel_hi:[1,0]
	v_pk_add_f32 v[40:41], v[40:41], v[50:51] op_sel_hi:[1,0]
	v_pk_add_f32 v[38:39], v[38:39], v[50:51] op_sel_hi:[1,0]
	v_pk_add_f32 v[36:37], v[36:37], v[50:51] op_sel_hi:[1,0]
	v_pk_add_f32 v[34:35], v[34:35], v[50:51] op_sel_hi:[1,0]
	v_pk_add_f32 v[32:33], v[32:33], v[50:51] op_sel_hi:[1,0]
	global_store_dwordx4 v[48:49], v[44:47], off
	global_store_dwordx4 v[48:49], v[40:43], off offset:64
	global_store_dwordx4 v[48:49], v[36:39], off offset:512
	global_store_dwordx4 v[48:49], v[32:35], off offset:576
	global_load_dword v34, v[146:147], off offset:640
	s_waitcnt vmcnt(0)
	v_pk_add_f32 v[30:31], v[30:31], v[34:35] op_sel_hi:[1,0]
	v_add_u32_e32 v32, 0xa0, v140
	v_mad_i64_i32 v[32:33], s[20:21], v32, s38, v[142:143]
	v_lshl_add_u64 v[32:33], v[32:33], 0, v[144:145]
	v_pk_add_f32 v[28:29], v[28:29], v[34:35] op_sel_hi:[1,0]
	v_pk_add_f32 v[26:27], v[26:27], v[34:35] op_sel_hi:[1,0]
	v_pk_add_f32 v[24:25], v[24:25], v[34:35] op_sel_hi:[1,0]
	v_pk_add_f32 v[22:23], v[22:23], v[34:35] op_sel_hi:[1,0]
	v_pk_add_f32 v[20:21], v[20:21], v[34:35] op_sel_hi:[1,0]
	v_pk_add_f32 v[18:19], v[18:19], v[34:35] op_sel_hi:[1,0]
	v_pk_add_f32 v[16:17], v[16:17], v[34:35] op_sel_hi:[1,0]
	global_store_dwordx4 v[32:33], v[28:31], off
	global_store_dwordx4 v[32:33], v[24:27], off offset:64
	global_store_dwordx4 v[32:33], v[20:23], off offset:512
	global_store_dwordx4 v[32:33], v[16:19], off offset:576
	global_load_dword v18, v[146:147], off offset:704
	s_waitcnt vmcnt(0)
	v_pk_add_f32 v[14:15], v[14:15], v[18:19] op_sel_hi:[1,0]
	v_add_u32_e32 v16, 0xb0, v140
	v_mad_i64_i32 v[16:17], s[20:21], v16, s38, v[142:143]
	v_lshl_add_u64 v[16:17], v[16:17], 0, v[144:145]
	v_pk_add_f32 v[12:13], v[12:13], v[18:19] op_sel_hi:[1,0]
	v_pk_add_f32 v[10:11], v[10:11], v[18:19] op_sel_hi:[1,0]
	v_pk_add_f32 v[8:9], v[8:9], v[18:19] op_sel_hi:[1,0]
	v_pk_add_f32 v[6:7], v[6:7], v[18:19] op_sel_hi:[1,0]
	v_pk_add_f32 v[4:5], v[4:5], v[18:19] op_sel_hi:[1,0]
	v_pk_add_f32 v[2:3], v[2:3], v[18:19] op_sel_hi:[1,0]
	v_pk_add_f32 v[0:1], v[0:1], v[18:19] op_sel_hi:[1,0]
	s_mov_b64 s[20:21], s[14:15]
	global_store_dwordx4 v[16:17], v[12:15], off
	global_store_dwordx4 v[16:17], v[8:11], off offset:64
	global_store_dwordx4 v[16:17], v[4:7], off offset:512
	global_store_dwordx4 v[16:17], v[0:3], off offset:576
	s_cbranch_vccz .LBB0_1414
	s_waitcnt vmcnt(0)
	s_cmpk_gt_u32 s1, 0xff
	s_cbranch_scc1 .LBB0_1421
	s_barrier

.LBB0_1865:
	ds_read_b128 v[142:145], v139
	ds_read_b128 v[146:149], v139 offset:1024
	ds_read_b128 v[150:153], v139 offset:2048
	ds_read_b128 v[154:157], v139 offset:3072
	s_add_u32 s24, s22, 0x100
	s_addc_u32 s25, s23, 0
	s_cmp_eq_u32 s46, 4
	s_cselect_b32 s29, s15, s25
	s_cselect_b32 s28, s40, s24
	s_cselect_b32 s27, s13, s43
	s_cselect_b32 s26, s41, s42
	v_lshl_add_u64 v[190:191], s[22:23], 0, v[132:133]
	s_add_i32 m0, s5, 0xc000
	ds_read_b128 v[158:161], v140
	ds_read_b128 v[162:165], v140 offset:1024
	ds_read_b128 v[166:169], v140 offset:2048
	ds_read_b128 v[170:173], v140 offset:3072
	ds_read_b128 v[174:177], v140 offset:4096
	ds_read_b128 v[178:181], v140 offset:5120
	ds_read_b128 v[182:185], v140 offset:6144
	ds_read_b128 v[186:189], v140 offset:7168
	global_load_lds_dwordx4 v[190:191], off
	s_add_i32 m0, s5, 0xe000
	s_nop 0
	global_load_lds_dwordx4 v134, s[22:23]
	s_waitcnt lgkmcnt(8)
	s_barrier
	s_waitcnt lgkmcnt(0)
	s_waitcnt lgkmcnt(0)
	v_mfma_f32_16x16x32_bf16 v[124:127], v[142:145], v[158:161], v[124:127]
	v_mfma_f32_16x16x32_bf16 v[120:123], v[150:153], v[158:161], v[120:123]
	v_mfma_f32_16x16x32_bf16 v[116:119], v[142:145], v[166:169], v[116:119]
	v_mfma_f32_16x16x32_bf16 v[112:115], v[150:153], v[166:169], v[112:115]
	v_mfma_f32_16x16x32_bf16 v[100:103], v[142:145], v[174:177], v[100:103]
	v_mfma_f32_16x16x32_bf16 v[96:99], v[150:153], v[174:177], v[96:99]
	v_mfma_f32_16x16x32_bf16 v[84:87], v[142:145], v[182:185], v[84:87]
	v_mfma_f32_16x16x32_bf16 v[80:83], v[150:153], v[182:185], v[80:83]
	v_mfma_f32_16x16x32_bf16 v[124:127], v[146:149], v[162:165], v[124:127]
	v_mfma_f32_16x16x32_bf16 v[120:123], v[154:157], v[162:165], v[120:123]
	v_mfma_f32_16x16x32_bf16 v[116:119], v[146:149], v[170:173], v[116:119]
	v_mfma_f32_16x16x32_bf16 v[112:115], v[154:157], v[170:173], v[112:115]
	v_mfma_f32_16x16x32_bf16 v[100:103], v[146:149], v[178:181], v[100:103]
	v_mfma_f32_16x16x32_bf16 v[96:99], v[154:157], v[178:181], v[96:99]
	v_mfma_f32_16x16x32_bf16 v[84:87], v[146:149], v[186:189], v[84:87]
	v_mfma_f32_16x16x32_bf16 v[80:83], v[154:157], v[186:189], v[80:83]
	s_barrier
	s_add_i32 s22, s37, s4
	s_mov_b32 m0, s22
	ds_read_b128 v[190:193], v141
	ds_read_b128 v[194:197], v141 offset:1024
	ds_read_b128 v[198:201], v141 offset:2048
	ds_read_b128 v[202:205], v141 offset:3072
	global_load_lds_dwordx4 v130, s[26:27]
	s_add_i32 m0, s22, 0x2000
	s_nop 0
	global_load_lds_dwordx4 v128, s[26:27]
	s_barrier
	s_waitcnt lgkmcnt(0)
	s_waitcnt lgkmcnt(0)
	v_mfma_f32_16x16x32_bf16 v[108:111], v[190:193], v[158:161], v[108:111]
	v_mfma_f32_16x16x32_bf16 v[104:107], v[198:201], v[158:161], v[104:107]
	v_mfma_f32_16x16x32_bf16 v[92:95], v[190:193], v[166:169], v[92:95]
	v_mfma_f32_16x16x32_bf16 v[88:91], v[198:201], v[166:169], v[88:91]
	v_mfma_f32_16x16x32_bf16 v[76:79], v[190:193], v[174:177], v[76:79]
	v_mfma_f32_16x16x32_bf16 v[72:75], v[198:201], v[174:177], v[72:75]
	v_mfma_f32_16x16x32_bf16 v[68:71], v[190:193], v[182:185], v[68:71]
	v_mfma_f32_16x16x32_bf16 v[64:67], v[198:201], v[182:185], v[64:67]
	v_mfma_f32_16x16x32_bf16 v[108:111], v[194:197], v[162:165], v[108:111]
	v_mfma_f32_16x16x32_bf16 v[104:107], v[202:205], v[162:165], v[104:107]
	v_mfma_f32_16x16x32_bf16 v[92:95], v[194:197], v[170:173], v[92:95]
	v_mfma_f32_16x16x32_bf16 v[88:91], v[202:205], v[170:173], v[88:91]
	v_mfma_f32_16x16x32_bf16 v[76:79], v[194:197], v[178:181], v[76:79]
	v_mfma_f32_16x16x32_bf16 v[72:75], v[202:205], v[178:181], v[72:75]
	v_mfma_f32_16x16x32_bf16 v[68:71], v[194:197], v[186:189], v[68:71]
	v_mfma_f32_16x16x32_bf16 v[64:67], v[202:205], v[186:189], v[64:67]
	s_mov_b32 m0, s5
	v_lshl_add_u64 v[210:211], s[28:29], 0, v[130:131]
	s_barrier
	ds_read_b128 v[158:161], v140 offset:16384
	ds_read_b128 v[162:165], v140 offset:17408
	ds_read_b128 v[166:169], v140 offset:18432
	ds_read_b128 v[170:173], v140 offset:19456
	ds_read_b128 v[174:177], v140 offset:20480
	ds_read_b128 v[178:181], v140 offset:21504
	ds_read_b128 v[182:185], v140 offset:22528
	ds_read_b128 v[186:189], v140 offset:23552
	global_load_lds_dwordx4 v130, s[28:29]
	v_lshl_add_u64 v[212:213], s[28:29], 0, v[128:129]
	s_mov_b32 m0, s7
	s_nop 0
	global_load_lds_dwordx4 v128, s[28:29]
	s_barrier
	s_waitcnt lgkmcnt(0)
	s_waitcnt lgkmcnt(0)
	v_mfma_f32_16x16x32_bf16 v[60:63], v[142:145], v[158:161], v[60:63]
	v_mfma_f32_16x16x32_bf16 v[56:59], v[150:153], v[158:161], v[56:59]
	v_mfma_f32_16x16x32_bf16 v[52:55], v[142:145], v[166:169], v[52:55]
	v_mfma_f32_16x16x32_bf16 v[48:51], v[150:153], v[166:169], v[48:51]
	v_mfma_f32_16x16x32_bf16 v[36:39], v[142:145], v[174:177], v[36:39]
	v_mfma_f32_16x16x32_bf16 v[32:35], v[150:153], v[174:177], v[32:35]
	v_mfma_f32_16x16x32_bf16 v[20:23], v[142:145], v[182:185], v[20:23]
	v_mfma_f32_16x16x32_bf16 v[16:19], v[150:153], v[182:185], v[16:19]
	v_mfma_f32_16x16x32_bf16 v[60:63], v[146:149], v[162:165], v[60:63]
	v_mfma_f32_16x16x32_bf16 v[56:59], v[154:157], v[162:165], v[56:59]
	v_mfma_f32_16x16x32_bf16 v[52:55], v[146:149], v[170:173], v[52:55]
	v_mfma_f32_16x16x32_bf16 v[48:51], v[154:157], v[170:173], v[48:51]
	v_mfma_f32_16x16x32_bf16 v[36:39], v[146:149], v[178:181], v[36:39]
	v_mfma_f32_16x16x32_bf16 v[32:35], v[154:157], v[178:181], v[32:35]
	v_mfma_f32_16x16x32_bf16 v[20:23], v[146:149], v[186:189], v[20:23]
	v_mfma_f32_16x16x32_bf16 v[16:19], v[154:157], v[186:189], v[16:19]
	s_barrier
	s_add_u32 s22, s26, 0x80000
	s_addc_u32 s23, s27, 0
	s_add_i32 s47, s38, s4
	s_mov_b32 m0, s47
	s_nop 0
	global_load_lds_dwordx4 v130, s[22:23]
	s_add_i32 m0, s47, 0x2000
	s_nop 0
	global_load_lds_dwordx4 v128, s[22:23]
	s_waitcnt vmcnt(6)
	s_barrier
	v_mfma_f32_16x16x32_bf16 v[44:47], v[190:193], v[158:161], v[44:47]
	v_mfma_f32_16x16x32_bf16 v[40:43], v[198:201], v[158:161], v[40:43]
	v_mfma_f32_16x16x32_bf16 v[28:31], v[190:193], v[166:169], v[28:31]
	v_mfma_f32_16x16x32_bf16 v[24:27], v[198:201], v[166:169], v[24:27]
	v_mfma_f32_16x16x32_bf16 v[12:15], v[190:193], v[174:177], v[12:15]
	v_mfma_f32_16x16x32_bf16 v[8:11], v[198:201], v[174:177], v[8:11]
	v_mfma_f32_16x16x32_bf16 v[4:7], v[190:193], v[182:185], v[4:7]
	v_mfma_f32_16x16x32_bf16 v[0:3], v[198:201], v[182:185], v[0:3]
	v_mfma_f32_16x16x32_bf16 v[44:47], v[194:197], v[162:165], v[44:47]
	v_mfma_f32_16x16x32_bf16 v[40:43], v[202:205], v[162:165], v[40:43]
	v_mfma_f32_16x16x32_bf16 v[28:31], v[194:197], v[170:173], v[28:31]
	v_mfma_f32_16x16x32_bf16 v[24:27], v[202:205], v[170:173], v[24:27]
	v_mfma_f32_16x16x32_bf16 v[12:15], v[194:197], v[178:181], v[12:15]
	v_mfma_f32_16x16x32_bf16 v[8:11], v[202:205], v[178:181], v[8:11]
	v_mfma_f32_16x16x32_bf16 v[4:7], v[194:197], v[186:189], v[4:7]
	v_mfma_f32_16x16x32_bf16 v[0:3], v[202:205], v[186:189], v[0:3]
	s_add_i32 s47, 0, 0x18000
	v_add_u32_e32 v154, s47, v137
	s_barrier
	ds_read_b128 v[142:145], v154
	ds_read_b128 v[146:149], v154 offset:1024
	ds_read_b128 v[150:153], v154 offset:2048
	ds_read_b128 v[154:157], v154 offset:3072
	s_add_u32 s22, s28, 0x80000
	s_addc_u32 s23, s29, 0
	s_mov_b32 m0, s9
	ds_read_b128 v[158:161], v140 offset:32768
	ds_read_b128 v[162:165], v140 offset:33792
	ds_read_b128 v[166:169], v140 offset:34816
	ds_read_b128 v[170:173], v140 offset:35840
	ds_read_b128 v[174:177], v140 offset:36864
	ds_read_b128 v[178:181], v140 offset:37888
	ds_read_b128 v[182:185], v140 offset:38912
	ds_read_b128 v[186:189], v140 offset:39936
	global_load_lds_dwordx4 v130, s[22:23]
	s_mov_b32 m0, s30
	s_nop 0
	global_load_lds_dwordx4 v128, s[22:23]
	s_waitcnt lgkmcnt(8)
	s_barrier
	s_waitcnt lgkmcnt(0)
	s_waitcnt lgkmcnt(0)
	v_mfma_f32_16x16x32_bf16 v[124:127], v[142:145], v[158:161], v[124:127]
	v_mfma_f32_16x16x32_bf16 v[120:123], v[150:153], v[158:161], v[120:123]
	v_mfma_f32_16x16x32_bf16 v[116:119], v[142:145], v[166:169], v[116:119]
	v_mfma_f32_16x16x32_bf16 v[112:115], v[150:153], v[166:169], v[112:115]
	v_mfma_f32_16x16x32_bf16 v[100:103], v[142:145], v[174:177], v[100:103]
	v_mfma_f32_16x16x32_bf16 v[96:99], v[150:153], v[174:177], v[96:99]
	v_mfma_f32_16x16x32_bf16 v[84:87], v[142:145], v[182:185], v[84:87]
	v_mfma_f32_16x16x32_bf16 v[80:83], v[150:153], v[182:185], v[80:83]
	v_mfma_f32_16x16x32_bf16 v[124:127], v[146:149], v[162:165], v[124:127]
	v_mfma_f32_16x16x32_bf16 v[120:123], v[154:157], v[162:165], v[120:123]
	v_mfma_f32_16x16x32_bf16 v[116:119], v[146:149], v[170:173], v[116:119]
	v_mfma_f32_16x16x32_bf16 v[112:115], v[154:157], v[170:173], v[112:115]
	v_mfma_f32_16x16x32_bf16 v[100:103], v[146:149], v[178:181], v[100:103]
	v_mfma_f32_16x16x32_bf16 v[96:99], v[154:157], v[178:181], v[96:99]
	v_mfma_f32_16x16x32_bf16 v[84:87], v[146:149], v[186:189], v[84:87]
	v_mfma_f32_16x16x32_bf16 v[80:83], v[154:157], v[186:189], v[80:83]
	s_barrier
	s_add_i32 s28, 0, 0x1c000
	s_add_i32 s22, s47, s4
	v_add_u32_e32 v202, s28, v137
	s_add_u32 s98, s26, s10
	s_addc_u32 s99, s27, s11
	s_mov_b32 m0, s22
	ds_read_b128 v[190:193], v202
	ds_read_b128 v[194:197], v202 offset:1024
	ds_read_b128 v[198:201], v202 offset:2048
	ds_read_b128 v[202:205], v202 offset:3072
	global_load_lds_dwordx4 v130, s[98:99]
	s_add_i32 m0, s22, 0x2000
	s_nop 0
	global_load_lds_dwordx4 v128, s[98:99]
	s_barrier
	s_waitcnt lgkmcnt(0)
	s_waitcnt lgkmcnt(0)
	v_mfma_f32_16x16x32_bf16 v[108:111], v[190:193], v[158:161], v[108:111]
	v_mfma_f32_16x16x32_bf16 v[104:107], v[198:201], v[158:161], v[104:107]
	v_mfma_f32_16x16x32_bf16 v[92:95], v[190:193], v[166:169], v[92:95]
	v_mfma_f32_16x16x32_bf16 v[88:91], v[198:201], v[166:169], v[88:91]
	v_mfma_f32_16x16x32_bf16 v[76:79], v[190:193], v[174:177], v[76:79]
	v_mfma_f32_16x16x32_bf16 v[72:75], v[198:201], v[174:177], v[72:75]
	v_mfma_f32_16x16x32_bf16 v[68:71], v[190:193], v[182:185], v[68:71]
	v_mfma_f32_16x16x32_bf16 v[64:67], v[198:201], v[182:185], v[64:67]
	v_mfma_f32_16x16x32_bf16 v[108:111], v[194:197], v[162:165], v[108:111]
	v_mfma_f32_16x16x32_bf16 v[104:107], v[202:205], v[162:165], v[104:107]
	v_mfma_f32_16x16x32_bf16 v[92:95], v[194:197], v[170:173], v[92:95]
	v_mfma_f32_16x16x32_bf16 v[88:91], v[202:205], v[170:173], v[88:91]
	v_mfma_f32_16x16x32_bf16 v[76:79], v[194:197], v[178:181], v[76:79]
	v_mfma_f32_16x16x32_bf16 v[72:75], v[202:205], v[178:181], v[72:75]
	v_mfma_f32_16x16x32_bf16 v[68:71], v[194:197], v[186:189], v[68:71]
	v_mfma_f32_16x16x32_bf16 v[64:67], v[202:205], v[186:189], v[64:67]
	s_mov_b32 m0, s35
	v_lshl_add_u64 v[206:207], v[210:211], 0, s[10:11]
	s_barrier
	ds_read_b128 v[158:161], v140 offset:49152
	ds_read_b128 v[162:165], v140 offset:50176
	ds_read_b128 v[166:169], v140 offset:51200
	ds_read_b128 v[170:173], v140 offset:52224
	ds_read_b128 v[174:177], v140 offset:53248
	ds_read_b128 v[178:181], v140 offset:54272
	ds_read_b128 v[182:185], v140 offset:55296
	ds_read_b128 v[186:189], v140 offset:56320
	global_load_lds_dwordx4 v[206:207], off
	v_lshl_add_u64 v[206:207], v[212:213], 0, s[10:11]
	s_mov_b32 m0, s36
	s_nop 0
	global_load_lds_dwordx4 v[206:207], off
	s_barrier
	s_waitcnt lgkmcnt(0)
	s_waitcnt lgkmcnt(0)
	v_mfma_f32_16x16x32_bf16 v[60:63], v[142:145], v[158:161], v[60:63]
	v_mfma_f32_16x16x32_bf16 v[56:59], v[150:153], v[158:161], v[56:59]
	v_mfma_f32_16x16x32_bf16 v[52:55], v[142:145], v[166:169], v[52:55]
	v_mfma_f32_16x16x32_bf16 v[48:51], v[150:153], v[166:169], v[48:51]
	v_mfma_f32_16x16x32_bf16 v[36:39], v[142:145], v[174:177], v[36:39]
	v_mfma_f32_16x16x32_bf16 v[32:35], v[150:153], v[174:177], v[32:35]
	v_mfma_f32_16x16x32_bf16 v[20:23], v[142:145], v[182:185], v[20:23]
	v_mfma_f32_16x16x32_bf16 v[16:19], v[150:153], v[182:185], v[16:19]
	v_mfma_f32_16x16x32_bf16 v[60:63], v[146:149], v[162:165], v[60:63]
	v_mfma_f32_16x16x32_bf16 v[56:59], v[154:157], v[162:165], v[56:59]
	v_mfma_f32_16x16x32_bf16 v[52:55], v[146:149], v[170:173], v[52:55]
	v_mfma_f32_16x16x32_bf16 v[48:51], v[154:157], v[170:173], v[48:51]
	v_mfma_f32_16x16x32_bf16 v[36:39], v[146:149], v[178:181], v[36:39]
	v_mfma_f32_16x16x32_bf16 v[32:35], v[154:157], v[178:181], v[32:35]
	v_mfma_f32_16x16x32_bf16 v[20:23], v[146:149], v[186:189], v[20:23]
	v_mfma_f32_16x16x32_bf16 v[16:19], v[154:157], v[186:189], v[16:19]
	s_barrier
	s_add_u32 s22, s26, 0x80080
	s_addc_u32 s23, s27, 0
	s_add_i32 s26, s28, s4
	s_mov_b32 m0, s26
	s_nop 0
	global_load_lds_dwordx4 v130, s[22:23]
	s_add_i32 m0, s26, 0x2000
	s_nop 0
	global_load_lds_dwordx4 v128, s[22:23]
	s_waitcnt vmcnt(6)
	s_barrier
	v_mfma_f32_16x16x32_bf16 v[44:47], v[190:193], v[158:161], v[44:47]
	v_mfma_f32_16x16x32_bf16 v[40:43], v[198:201], v[158:161], v[40:43]
	v_mfma_f32_16x16x32_bf16 v[28:31], v[190:193], v[166:169], v[28:31]
	v_mfma_f32_16x16x32_bf16 v[24:27], v[198:201], v[166:169], v[24:27]
	v_mfma_f32_16x16x32_bf16 v[12:15], v[190:193], v[174:177], v[12:15]
	v_mfma_f32_16x16x32_bf16 v[8:11], v[198:201], v[174:177], v[8:11]
	v_mfma_f32_16x16x32_bf16 v[4:7], v[190:193], v[182:185], v[4:7]
	v_mfma_f32_16x16x32_bf16 v[0:3], v[198:201], v[182:185], v[0:3]
	v_mfma_f32_16x16x32_bf16 v[44:47], v[194:197], v[162:165], v[44:47]
	v_mfma_f32_16x16x32_bf16 v[40:43], v[202:205], v[162:165], v[40:43]
	v_mfma_f32_16x16x32_bf16 v[28:31], v[194:197], v[170:173], v[28:31]
	v_mfma_f32_16x16x32_bf16 v[24:27], v[202:205], v[170:173], v[24:27]
	v_mfma_f32_16x16x32_bf16 v[12:15], v[194:197], v[178:181], v[12:15]
	v_mfma_f32_16x16x32_bf16 v[8:11], v[202:205], v[178:181], v[8:11]
	v_mfma_f32_16x16x32_bf16 v[4:7], v[194:197], v[186:189], v[4:7]
	v_mfma_f32_16x16x32_bf16 v[0:3], v[202:205], v[186:189], v[0:3]
	s_add_i32 s46, s46, 2
	s_add_u32 s42, s42, 0x100
	s_addc_u32 s43, s43, 0
	s_cmp_gt_u32 s46, 5
	s_mov_b64 s[22:23], s[24:25]
	s_barrier
	s_cbranch_scc0 .LBB0_1865
	s_ashr_i32 s13, s34, 1
	s_and_b32 s13, s13, 0xfffffe00
	s_lshl_b32 s8, s8, 8
	s_add_i32 s8, s8, s13
	v_add_u32_e32 v144, s8, v136
	v_lshl_or_b32 v142, s6, 8, v138
	v_ashrrev_i32_e32 v145, 31, v144
	v_ashrrev_i32_e32 v143, 31, v142
	v_lshlrev_b64 v[146:147], 13, v[144:145]
	v_lshl_add_u64 v[146:147], s[66:67], 0, v[146:147]
	v_lshlrev_b64 v[142:143], 2, v[142:143]
	v_lshl_add_u64 v[146:147], v[146:147], 0, v[142:143]
	global_store_dwordx4 v[146:147], v[124:127], off
	global_store_dwordx4 v[146:147], v[120:123], off offset:64
	global_store_dwordx4 v[146:147], v[108:111], off offset:512
	global_store_dwordx4 v[146:147], v[104:107], off offset:576
	s_mov_b32 s6, 0x100000
	s_mov_b64 s[22:23], 0x100000
	v_or_b32_e32 v104, 16, v144
	v_ashrrev_i32_e32 v105, 31, v104
	v_lshlrev_b64 v[104:105], 13, v[104:105]
	v_lshl_add_u64 v[104:105], s[66:67], 0, v[104:105]
	v_lshl_add_u64 v[104:105], v[104:105], 0, v[142:143]
	global_store_dwordx4 v[104:105], v[116:119], off
	global_store_dwordx4 v[104:105], v[112:115], off offset:64
	global_store_dwordx4 v[104:105], v[92:95], off offset:512
	global_store_dwordx4 v[104:105], v[88:91], off offset:576
	s_mov_b32 s34, s39
	s_mov_b32 s8, s14
	v_or_b32_e32 v88, 32, v144
	v_ashrrev_i32_e32 v89, 31, v88
	v_lshlrev_b64 v[88:89], 13, v[88:89]
	v_lshl_add_u64 v[88:89], s[66:67], 0, v[88:89]
	v_lshl_add_u64 v[88:89], v[88:89], 0, v[142:143]
	global_store_dwordx4 v[88:89], v[100:103], off
	global_store_dwordx4 v[88:89], v[96:99], off offset:64
	global_store_dwordx4 v[88:89], v[76:79], off offset:512
	global_store_dwordx4 v[88:89], v[72:75], off offset:576
	s_mov_b64 s[24:25], s[20:21]
	s_nop 0
	v_or_b32_e32 v72, 48, v144
	v_ashrrev_i32_e32 v73, 31, v72
	v_lshlrev_b64 v[72:73], 13, v[72:73]
	v_lshl_add_u64 v[72:73], s[66:67], 0, v[72:73]
	v_lshl_add_u64 v[72:73], v[72:73], 0, v[142:143]
	global_store_dwordx4 v[72:73], v[84:87], off
	global_store_dwordx4 v[72:73], v[80:83], off offset:64
	global_store_dwordx4 v[72:73], v[68:71], off offset:512
	global_store_dwordx4 v[72:73], v[64:67], off offset:576
	s_nop 1
	v_add_co_u32_e32 v66, vcc, s6, v146
	s_mov_b32 s6, 0x120000
	s_nop 0
	v_addc_co_u32_e32 v67, vcc, 0, v147, vcc
	v_lshl_add_u64 v[64:65], v[146:147], 0, s[22:23]
	global_store_dwordx4 v[66:67], v[60:63], off
	global_store_dwordx4 v[64:65], v[56:59], off offset:64
	global_store_dwordx4 v[64:65], v[44:47], off offset:512
	global_store_dwordx4 v[64:65], v[40:43], off offset:576
	s_mov_b64 s[22:23], 0x120000
	s_nop 0
	v_add_co_u32_e32 v42, vcc, s6, v146
	s_mov_b32 s6, 0x140000
	s_nop 0
	v_addc_co_u32_e32 v43, vcc, 0, v147, vcc
	v_lshl_add_u64 v[40:41], v[146:147], 0, s[22:23]
	global_store_dwordx4 v[42:43], v[52:55], off
	global_store_dwordx4 v[40:41], v[48:51], off offset:64
	global_store_dwordx4 v[40:41], v[28:31], off offset:512
	global_store_dwordx4 v[40:41], v[24:27], off offset:576
	s_mov_b64 s[22:23], 0x140000
	s_nop 0
	v_add_co_u32_e32 v26, vcc, s6, v146
	v_lshl_add_u64 v[24:25], v[146:147], 0, s[22:23]
	s_nop 0
	v_addc_co_u32_e32 v27, vcc, 0, v147, vcc
	global_store_dwordx4 v[26:27], v[36:39], off
	global_store_dwordx4 v[24:25], v[32:35], off offset:64
	global_store_dwordx4 v[24:25], v[12:15], off offset:512
	global_store_dwordx4 v[24:25], v[8:11], off offset:576
	s_mov_b64 s[22:23], 0x160000
	s_mov_b32 s6, s12
	v_add_co_u32_e32 v10, vcc, 0x160000, v146
	v_lshl_add_u64 v[8:9], v[146:147], 0, s[22:23]
	s_nop 0
	v_addc_co_u32_e32 v11, vcc, 0, v147, vcc
	s_and_b64 vcc, exec, s[16:17]
	s_mov_b64 s[22:23], s[18:19]
	global_store_dwordx4 v[10:11], v[20:23], off
	global_store_dwordx4 v[8:9], v[16:19], off offset:64
	global_store_dwordx4 v[8:9], v[4:7], off offset:512
	global_store_dwordx4 v[8:9], v[0:3], off offset:576
	s_cbranch_vccz .LBB0_1862
	s_waitcnt vmcnt(0)
	s_cmpk_gt_u32 s1, 0xff
	s_cbranch_scc1 .LBB0_1869
	s_barrier

.LBB0_2005:
	ds_read_b128 v[148:151], v144
	ds_read_b128 v[152:155], v144 offset:1024
	ds_read_b128 v[156:159], v144 offset:2048
	ds_read_b128 v[160:163], v144 offset:3072
	s_add_u32 s24, s22, 0x100
	s_addc_u32 s25, s23, 0
	s_cmp_eq_u32 s61, 28
	s_cselect_b32 s29, s15, s25
	s_cselect_b32 s28, s43, s24
	s_cselect_b32 s27, s13, s60
	s_cselect_b32 s26, s46, s47
	s_add_i32 m0, s5, 0xc000
	ds_read_b128 v[164:167], v145
	ds_read_b128 v[168:171], v145 offset:1024
	ds_read_b128 v[172:175], v145 offset:2048
	ds_read_b128 v[176:179], v145 offset:3072
	ds_read_b128 v[180:183], v145 offset:4096
	ds_read_b128 v[184:187], v145 offset:5120
	ds_read_b128 v[188:191], v145 offset:6144
	ds_read_b128 v[192:195], v145 offset:7168
	global_load_lds_dwordx4 v134, s[22:23]
	s_add_i32 m0, s5, 0xe000
	s_nop 0
	global_load_lds_dwordx4 v136, s[22:23]
	s_waitcnt lgkmcnt(8)
	s_barrier
	s_waitcnt lgkmcnt(0)
	s_waitcnt lgkmcnt(0)
	v_mfma_f32_16x16x32_bf16 v[124:127], v[148:151], v[164:167], v[124:127]
	v_mfma_f32_16x16x32_bf16 v[120:123], v[156:159], v[164:167], v[120:123]
	v_mfma_f32_16x16x32_bf16 v[108:111], v[148:151], v[172:175], v[108:111]
	v_mfma_f32_16x16x32_bf16 v[104:107], v[156:159], v[172:175], v[104:107]
	v_mfma_f32_16x16x32_bf16 v[92:95], v[148:151], v[180:183], v[92:95]
	v_mfma_f32_16x16x32_bf16 v[88:91], v[156:159], v[180:183], v[88:91]
	v_mfma_f32_16x16x32_bf16 v[76:79], v[148:151], v[188:191], v[76:79]
	v_mfma_f32_16x16x32_bf16 v[72:75], v[156:159], v[188:191], v[72:75]
	v_mfma_f32_16x16x32_bf16 v[124:127], v[152:155], v[168:171], v[124:127]
	v_mfma_f32_16x16x32_bf16 v[120:123], v[160:163], v[168:171], v[120:123]
	v_mfma_f32_16x16x32_bf16 v[108:111], v[152:155], v[176:179], v[108:111]
	v_mfma_f32_16x16x32_bf16 v[104:107], v[160:163], v[176:179], v[104:107]
	v_mfma_f32_16x16x32_bf16 v[92:95], v[152:155], v[184:187], v[92:95]
	v_mfma_f32_16x16x32_bf16 v[88:91], v[160:163], v[184:187], v[88:91]
	v_mfma_f32_16x16x32_bf16 v[76:79], v[152:155], v[192:195], v[76:79]
	v_mfma_f32_16x16x32_bf16 v[72:75], v[160:163], v[192:195], v[72:75]
	s_barrier
	s_add_i32 s22, s40, s2
	s_mov_b32 m0, s22
	ds_read_b128 v[196:199], v146
	ds_read_b128 v[200:203], v146 offset:1024
	ds_read_b128 v[204:207], v146 offset:2048
	ds_read_b128 v[208:211], v146 offset:3072
	global_load_lds_dwordx4 v130, s[26:27]
	s_add_i32 m0, s22, 0x2000
	s_nop 0
	global_load_lds_dwordx4 v128, s[26:27]
	s_barrier
	s_waitcnt lgkmcnt(0)
	s_waitcnt lgkmcnt(0)
	v_mfma_f32_16x16x32_bf16 v[116:119], v[196:199], v[164:167], v[116:119]
	v_mfma_f32_16x16x32_bf16 v[112:115], v[204:207], v[164:167], v[112:115]
	v_mfma_f32_16x16x32_bf16 v[100:103], v[196:199], v[172:175], v[100:103]
	v_mfma_f32_16x16x32_bf16 v[96:99], v[204:207], v[172:175], v[96:99]
	v_mfma_f32_16x16x32_bf16 v[84:87], v[196:199], v[180:183], v[84:87]
	v_mfma_f32_16x16x32_bf16 v[80:83], v[204:207], v[180:183], v[80:83]
	v_mfma_f32_16x16x32_bf16 v[68:71], v[196:199], v[188:191], v[68:71]
	v_mfma_f32_16x16x32_bf16 v[64:67], v[204:207], v[188:191], v[64:67]
	v_mfma_f32_16x16x32_bf16 v[116:119], v[200:203], v[168:171], v[116:119]
	v_mfma_f32_16x16x32_bf16 v[112:115], v[208:211], v[168:171], v[112:115]
	v_mfma_f32_16x16x32_bf16 v[100:103], v[200:203], v[176:179], v[100:103]
	v_mfma_f32_16x16x32_bf16 v[96:99], v[208:211], v[176:179], v[96:99]
	v_mfma_f32_16x16x32_bf16 v[84:87], v[200:203], v[184:187], v[84:87]
	v_mfma_f32_16x16x32_bf16 v[80:83], v[208:211], v[184:187], v[80:83]
	v_mfma_f32_16x16x32_bf16 v[68:71], v[200:203], v[192:195], v[68:71]
	v_mfma_f32_16x16x32_bf16 v[64:67], v[208:211], v[192:195], v[64:67]
	s_mov_b32 m0, s5
	v_lshl_add_u64 v[216:217], s[28:29], 0, v[130:131]
	s_barrier
	ds_read_b128 v[164:167], v145 offset:16384
	ds_read_b128 v[168:171], v145 offset:17408
	ds_read_b128 v[172:175], v145 offset:18432
	ds_read_b128 v[176:179], v145 offset:19456
	ds_read_b128 v[180:183], v145 offset:20480
	ds_read_b128 v[184:187], v145 offset:21504
	ds_read_b128 v[188:191], v145 offset:22528
	ds_read_b128 v[192:195], v145 offset:23552
	global_load_lds_dwordx4 v130, s[28:29]
	v_lshl_add_u64 v[218:219], s[28:29], 0, v[128:129]
	s_mov_b32 m0, s30
	s_nop 0
	global_load_lds_dwordx4 v128, s[28:29]
	s_barrier
	s_waitcnt lgkmcnt(0)
	s_waitcnt lgkmcnt(0)
	v_mfma_f32_16x16x32_bf16 v[60:63], v[148:151], v[164:167], v[60:63]
	v_mfma_f32_16x16x32_bf16 v[56:59], v[156:159], v[164:167], v[56:59]
	v_mfma_f32_16x16x32_bf16 v[44:47], v[148:151], v[172:175], v[44:47]
	v_mfma_f32_16x16x32_bf16 v[40:43], v[156:159], v[172:175], v[40:43]
	v_mfma_f32_16x16x32_bf16 v[28:31], v[148:151], v[180:183], v[28:31]
	v_mfma_f32_16x16x32_bf16 v[24:27], v[156:159], v[180:183], v[24:27]
	v_mfma_f32_16x16x32_bf16 v[12:15], v[148:151], v[188:191], v[12:15]
	v_mfma_f32_16x16x32_bf16 v[8:11], v[156:159], v[188:191], v[8:11]
	v_mfma_f32_16x16x32_bf16 v[60:63], v[152:155], v[168:171], v[60:63]
	v_mfma_f32_16x16x32_bf16 v[56:59], v[160:163], v[168:171], v[56:59]
	v_mfma_f32_16x16x32_bf16 v[44:47], v[152:155], v[176:179], v[44:47]
	v_mfma_f32_16x16x32_bf16 v[40:43], v[160:163], v[176:179], v[40:43]
	v_mfma_f32_16x16x32_bf16 v[28:31], v[152:155], v[184:187], v[28:31]
	v_mfma_f32_16x16x32_bf16 v[24:27], v[160:163], v[184:187], v[24:27]
	v_mfma_f32_16x16x32_bf16 v[12:15], v[152:155], v[192:195], v[12:15]
	v_mfma_f32_16x16x32_bf16 v[8:11], v[160:163], v[192:195], v[8:11]
	s_barrier
	s_add_u32 s22, s26, 0x80000
	s_addc_u32 s23, s27, 0
	s_add_i32 s62, s41, s2
	s_mov_b32 m0, s62
	s_nop 0
	global_load_lds_dwordx4 v130, s[22:23]
	s_add_i32 m0, s62, 0x2000
	s_nop 0
	global_load_lds_dwordx4 v128, s[22:23]
	s_waitcnt vmcnt(6)
	s_barrier
	v_mfma_f32_16x16x32_bf16 v[52:55], v[196:199], v[164:167], v[52:55]
	v_mfma_f32_16x16x32_bf16 v[48:51], v[204:207], v[164:167], v[48:51]
	v_mfma_f32_16x16x32_bf16 v[36:39], v[196:199], v[172:175], v[36:39]
	v_mfma_f32_16x16x32_bf16 v[32:35], v[204:207], v[172:175], v[32:35]
	v_mfma_f32_16x16x32_bf16 v[20:23], v[196:199], v[180:183], v[20:23]
	v_mfma_f32_16x16x32_bf16 v[16:19], v[204:207], v[180:183], v[16:19]
	v_mfma_f32_16x16x32_bf16 v[4:7], v[196:199], v[188:191], v[4:7]
	v_mfma_f32_16x16x32_bf16 v[0:3], v[204:207], v[188:191], v[0:3]
	v_mfma_f32_16x16x32_bf16 v[52:55], v[200:203], v[168:171], v[52:55]
	v_mfma_f32_16x16x32_bf16 v[48:51], v[208:211], v[168:171], v[48:51]
	v_mfma_f32_16x16x32_bf16 v[36:39], v[200:203], v[176:179], v[36:39]
	v_mfma_f32_16x16x32_bf16 v[32:35], v[208:211], v[176:179], v[32:35]
	v_mfma_f32_16x16x32_bf16 v[20:23], v[200:203], v[184:187], v[20:23]
	v_mfma_f32_16x16x32_bf16 v[16:19], v[208:211], v[184:187], v[16:19]
	v_mfma_f32_16x16x32_bf16 v[4:7], v[200:203], v[192:195], v[4:7]
	v_mfma_f32_16x16x32_bf16 v[0:3], v[208:211], v[192:195], v[0:3]
	s_add_i32 s62, 0, 0x18000
	v_add_u32_e32 v147, s62, v143
	s_barrier
	ds_read_b128 v[148:151], v147
	ds_read_b128 v[152:155], v147 offset:1024
	ds_read_b128 v[156:159], v147 offset:2048
	ds_read_b128 v[160:163], v147 offset:3072
	s_add_u32 s22, s28, 0x80000
	s_addc_u32 s23, s29, 0
	s_mov_b32 m0, s31
	ds_read_b128 v[164:167], v145 offset:32768
	ds_read_b128 v[168:171], v145 offset:33792
	ds_read_b128 v[172:175], v145 offset:34816
	ds_read_b128 v[176:179], v145 offset:35840
	ds_read_b128 v[180:183], v145 offset:36864
	ds_read_b128 v[184:187], v145 offset:37888
	ds_read_b128 v[188:191], v145 offset:38912
	ds_read_b128 v[192:195], v145 offset:39936
	global_load_lds_dwordx4 v130, s[22:23]
	s_mov_b32 m0, s34
	s_nop 0
	global_load_lds_dwordx4 v128, s[22:23]
	s_waitcnt lgkmcnt(8)
	s_barrier
	s_waitcnt lgkmcnt(0)
	s_waitcnt lgkmcnt(0)
	v_mfma_f32_16x16x32_bf16 v[124:127], v[148:151], v[164:167], v[124:127]
	v_mfma_f32_16x16x32_bf16 v[120:123], v[156:159], v[164:167], v[120:123]
	v_mfma_f32_16x16x32_bf16 v[108:111], v[148:151], v[172:175], v[108:111]
	v_mfma_f32_16x16x32_bf16 v[104:107], v[156:159], v[172:175], v[104:107]
	v_mfma_f32_16x16x32_bf16 v[92:95], v[148:151], v[180:183], v[92:95]
	v_mfma_f32_16x16x32_bf16 v[88:91], v[156:159], v[180:183], v[88:91]
	v_mfma_f32_16x16x32_bf16 v[76:79], v[148:151], v[188:191], v[76:79]
	v_mfma_f32_16x16x32_bf16 v[72:75], v[156:159], v[188:191], v[72:75]
	v_mfma_f32_16x16x32_bf16 v[124:127], v[152:155], v[168:171], v[124:127]
	v_mfma_f32_16x16x32_bf16 v[120:123], v[160:163], v[168:171], v[120:123]
	v_mfma_f32_16x16x32_bf16 v[108:111], v[152:155], v[176:179], v[108:111]
	v_mfma_f32_16x16x32_bf16 v[104:107], v[160:163], v[176:179], v[104:107]
	v_mfma_f32_16x16x32_bf16 v[92:95], v[152:155], v[184:187], v[92:95]
	v_mfma_f32_16x16x32_bf16 v[88:91], v[160:163], v[184:187], v[88:91]
	v_mfma_f32_16x16x32_bf16 v[76:79], v[152:155], v[192:195], v[76:79]
	v_mfma_f32_16x16x32_bf16 v[72:75], v[160:163], v[192:195], v[72:75]
	s_barrier
	s_add_i32 s28, 0, 0x1c000
	s_add_i32 s22, s62, s2
	v_add_u32_e32 v147, s28, v143
	s_add_u32 s98, s26, s10
	s_addc_u32 s99, s27, s11
	s_mov_b32 m0, s22
	ds_read_b128 v[196:199], v147
	ds_read_b128 v[200:203], v147 offset:1024
	ds_read_b128 v[204:207], v147 offset:2048
	ds_read_b128 v[208:211], v147 offset:3072
	global_load_lds_dwordx4 v130, s[98:99]
	s_add_i32 m0, s22, 0x2000
	s_nop 0
	global_load_lds_dwordx4 v128, s[98:99]
	s_barrier
	s_waitcnt lgkmcnt(0)
	s_waitcnt lgkmcnt(0)
	v_mfma_f32_16x16x32_bf16 v[116:119], v[196:199], v[164:167], v[116:119]
	v_mfma_f32_16x16x32_bf16 v[112:115], v[204:207], v[164:167], v[112:115]
	v_mfma_f32_16x16x32_bf16 v[100:103], v[196:199], v[172:175], v[100:103]
	v_mfma_f32_16x16x32_bf16 v[96:99], v[204:207], v[172:175], v[96:99]
	v_mfma_f32_16x16x32_bf16 v[84:87], v[196:199], v[180:183], v[84:87]
	v_mfma_f32_16x16x32_bf16 v[80:83], v[204:207], v[180:183], v[80:83]
	v_mfma_f32_16x16x32_bf16 v[68:71], v[196:199], v[188:191], v[68:71]
	v_mfma_f32_16x16x32_bf16 v[64:67], v[204:207], v[188:191], v[64:67]
	v_mfma_f32_16x16x32_bf16 v[116:119], v[200:203], v[168:171], v[116:119]
	v_mfma_f32_16x16x32_bf16 v[112:115], v[208:211], v[168:171], v[112:115]
	v_mfma_f32_16x16x32_bf16 v[100:103], v[200:203], v[176:179], v[100:103]
	v_mfma_f32_16x16x32_bf16 v[96:99], v[208:211], v[176:179], v[96:99]
	v_mfma_f32_16x16x32_bf16 v[84:87], v[200:203], v[184:187], v[84:87]
	v_mfma_f32_16x16x32_bf16 v[80:83], v[208:211], v[184:187], v[80:83]
	v_mfma_f32_16x16x32_bf16 v[68:71], v[200:203], v[192:195], v[68:71]
	v_mfma_f32_16x16x32_bf16 v[64:67], v[208:211], v[192:195], v[64:67]
	s_mov_b32 m0, s36
	v_lshl_add_u64 v[212:213], v[216:217], 0, s[10:11]
	s_barrier
	ds_read_b128 v[164:167], v145 offset:49152
	ds_read_b128 v[168:171], v145 offset:50176
	ds_read_b128 v[172:175], v145 offset:51200
	ds_read_b128 v[176:179], v145 offset:52224
	ds_read_b128 v[180:183], v145 offset:53248
	ds_read_b128 v[184:187], v145 offset:54272
	ds_read_b128 v[188:191], v145 offset:55296
	ds_read_b128 v[192:195], v145 offset:56320
	global_load_lds_dwordx4 v[212:213], off
	v_lshl_add_u64 v[212:213], v[218:219], 0, s[10:11]
	s_mov_b32 m0, s37
	s_nop 0
	global_load_lds_dwordx4 v[212:213], off
	s_barrier
	s_waitcnt lgkmcnt(0)
	s_waitcnt lgkmcnt(0)
	v_mfma_f32_16x16x32_bf16 v[60:63], v[148:151], v[164:167], v[60:63]
	v_mfma_f32_16x16x32_bf16 v[56:59], v[156:159], v[164:167], v[56:59]
	v_mfma_f32_16x16x32_bf16 v[44:47], v[148:151], v[172:175], v[44:47]
	v_mfma_f32_16x16x32_bf16 v[40:43], v[156:159], v[172:175], v[40:43]
	v_mfma_f32_16x16x32_bf16 v[28:31], v[148:151], v[180:183], v[28:31]
	v_mfma_f32_16x16x32_bf16 v[24:27], v[156:159], v[180:183], v[24:27]
	v_mfma_f32_16x16x32_bf16 v[12:15], v[148:151], v[188:191], v[12:15]
	v_mfma_f32_16x16x32_bf16 v[8:11], v[156:159], v[188:191], v[8:11]
	v_mfma_f32_16x16x32_bf16 v[60:63], v[152:155], v[168:171], v[60:63]
	v_mfma_f32_16x16x32_bf16 v[56:59], v[160:163], v[168:171], v[56:59]
	v_mfma_f32_16x16x32_bf16 v[44:47], v[152:155], v[176:179], v[44:47]
	v_mfma_f32_16x16x32_bf16 v[40:43], v[160:163], v[176:179], v[40:43]
	v_mfma_f32_16x16x32_bf16 v[28:31], v[152:155], v[184:187], v[28:31]
	v_mfma_f32_16x16x32_bf16 v[24:27], v[160:163], v[184:187], v[24:27]
	v_mfma_f32_16x16x32_bf16 v[12:15], v[152:155], v[192:195], v[12:15]
	v_mfma_f32_16x16x32_bf16 v[8:11], v[160:163], v[192:195], v[8:11]
	s_barrier
	s_add_u32 s22, s26, 0x80080
	s_addc_u32 s23, s27, 0
	s_add_i32 s26, s28, s2
	s_mov_b32 m0, s26
	s_nop 0
	global_load_lds_dwordx4 v130, s[22:23]
	s_add_i32 m0, s26, 0x2000
	s_nop 0
	global_load_lds_dwordx4 v128, s[22:23]
	s_waitcnt vmcnt(6)
	s_barrier
	v_mfma_f32_16x16x32_bf16 v[52:55], v[196:199], v[164:167], v[52:55]
	v_mfma_f32_16x16x32_bf16 v[48:51], v[204:207], v[164:167], v[48:51]
	v_mfma_f32_16x16x32_bf16 v[36:39], v[196:199], v[172:175], v[36:39]
	v_mfma_f32_16x16x32_bf16 v[32:35], v[204:207], v[172:175], v[32:35]
	v_mfma_f32_16x16x32_bf16 v[20:23], v[196:199], v[180:183], v[20:23]
	v_mfma_f32_16x16x32_bf16 v[16:19], v[204:207], v[180:183], v[16:19]
	v_mfma_f32_16x16x32_bf16 v[4:7], v[196:199], v[188:191], v[4:7]
	v_mfma_f32_16x16x32_bf16 v[0:3], v[204:207], v[188:191], v[0:3]
	v_mfma_f32_16x16x32_bf16 v[52:55], v[200:203], v[168:171], v[52:55]
	v_mfma_f32_16x16x32_bf16 v[48:51], v[208:211], v[168:171], v[48:51]
	v_mfma_f32_16x16x32_bf16 v[36:39], v[200:203], v[176:179], v[36:39]
	v_mfma_f32_16x16x32_bf16 v[32:35], v[208:211], v[176:179], v[32:35]
	v_mfma_f32_16x16x32_bf16 v[20:23], v[200:203], v[184:187], v[20:23]
	v_mfma_f32_16x16x32_bf16 v[16:19], v[208:211], v[184:187], v[16:19]
	v_mfma_f32_16x16x32_bf16 v[4:7], v[200:203], v[192:195], v[4:7]
	v_mfma_f32_16x16x32_bf16 v[0:3], v[208:211], v[192:195], v[0:3]
	s_add_i32 s61, s61, 2
	s_add_u32 s47, s47, 0x100
	s_addc_u32 s60, s60, 0
	s_cmp_gt_u32 s61, 29
	s_mov_b64 s[22:23], s[24:25]
	s_barrier
	s_cbranch_scc0 .LBB0_2005
	v_mul_f32_e32 v150, 0xbfb8aa3b, v124
	v_mul_f32_e32 v151, 0xbfb8aa3b, v125
	v_exp_f32_e32 v150, v150
	v_exp_f32_e32 v151, v151
	s_lshl_b32 s13, s21, 7
	v_lshl_add_u32 v147, s20, 8, v142
	v_add_f32_e32 v150, 1.0, v150
	v_add_f32_e32 v151, 1.0, v151
	v_rcp_f32_e32 v150, v150
	v_rcp_f32_e32 v151, v151
	s_or_b32 s20, s13, s38
	s_ashr_i32 s21, s20, 31
	v_mad_i64_i32 v[148:149], s[22:23], v147, s42, v[132:133]
	v_pk_mul_f32 v[124:125], v[124:125], v[150:151]
	s_lshl_b64 s[20:21], s[20:21], 1
	v_pk_mul_f32 v[120:121], v[120:121], v[124:125]
	s_and_b64 vcc, exec, s[6:7]
	v_cvt_pk_bf16_f32 v120, v120, v121
	v_mul_f32_e32 v121, 0xbfb8aa3b, v126
	v_exp_f32_e32 v121, v121
	s_mov_b64 s[24:25], s[18:19]
	v_add_f32_e32 v121, 1.0, v121
	v_rcp_f32_e32 v124, v121
	v_mul_f32_e32 v121, 0xbfb8aa3b, v127
	v_exp_f32_e32 v121, v121
	s_nop 0
	v_add_f32_e32 v121, 1.0, v121
	v_rcp_f32_e32 v125, v121
	s_nop 0
	v_pk_mul_f32 v[124:125], v[126:127], v[124:125]
	s_nop 0
	v_pk_mul_f32 v[122:123], v[122:123], v[124:125]
	s_nop 0
	v_cvt_pk_bf16_f32 v121, v122, v123
	v_lshl_add_u64 v[122:123], v[148:149], 0, s[20:21]
	global_store_dwordx2 v[122:123], v[120:121], off
	v_mul_f32_e32 v120, 0xbfb8aa3b, v116
	v_mul_f32_e32 v121, 0xbfb8aa3b, v117
	v_exp_f32_e32 v120, v120
	v_exp_f32_e32 v121, v121
	v_add_f32_e32 v120, 1.0, v120
	v_add_f32_e32 v121, 1.0, v121
	v_rcp_f32_e32 v120, v120
	v_rcp_f32_e32 v121, v121
	s_nop 0
	v_pk_mul_f32 v[116:117], v[116:117], v[120:121]
	s_nop 0
	v_pk_mul_f32 v[112:113], v[112:113], v[116:117]
	s_nop 0
	v_cvt_pk_bf16_f32 v112, v112, v113
	v_mul_f32_e32 v113, 0xbfb8aa3b, v118
	v_exp_f32_e32 v113, v113
	s_nop 0
	v_add_f32_e32 v113, 1.0, v113
	v_rcp_f32_e32 v116, v113
	v_mul_f32_e32 v113, 0xbfb8aa3b, v119
	v_exp_f32_e32 v113, v113
	s_nop 0
	v_add_f32_e32 v113, 1.0, v113
	v_rcp_f32_e32 v117, v113
	s_nop 0
	v_pk_mul_f32 v[116:117], v[118:119], v[116:117]
	s_nop 0
	v_pk_mul_f32 v[114:115], v[114:115], v[116:117]
	s_nop 0
	v_cvt_pk_bf16_f32 v113, v114, v115
	v_mul_f32_e32 v114, 0xbfb8aa3b, v108
	v_mul_f32_e32 v115, 0xbfb8aa3b, v109
	v_exp_f32_e32 v114, v114
	v_exp_f32_e32 v115, v115
	global_store_dwordx2 v[122:123], v[112:113], off offset:128
	v_or_b32_e32 v112, 16, v147
	v_add_f32_e32 v114, 1.0, v114
	v_add_f32_e32 v115, 1.0, v115
	v_rcp_f32_e32 v114, v114
	v_rcp_f32_e32 v115, v115
	v_mad_i64_i32 v[112:113], s[22:23], v112, s42, v[132:133]
	v_pk_mul_f32 v[108:109], v[108:109], v[114:115]
	s_nop 0
	v_pk_mul_f32 v[104:105], v[104:105], v[108:109]
	s_nop 0
	v_cvt_pk_bf16_f32 v104, v104, v105
	v_mul_f32_e32 v105, 0xbfb8aa3b, v110
	v_exp_f32_e32 v105, v105
	s_nop 0
	v_add_f32_e32 v105, 1.0, v105
	v_rcp_f32_e32 v108, v105
	v_mul_f32_e32 v105, 0xbfb8aa3b, v111
	v_exp_f32_e32 v105, v105
	s_nop 0
	v_add_f32_e32 v105, 1.0, v105
	v_rcp_f32_e32 v109, v105
	s_nop 0
	v_pk_mul_f32 v[108:109], v[110:111], v[108:109]
	s_nop 0
	v_pk_mul_f32 v[106:107], v[106:107], v[108:109]
	s_nop 0
	v_cvt_pk_bf16_f32 v105, v106, v107
	v_lshl_add_u64 v[106:107], v[112:113], 0, s[20:21]
	global_store_dwordx2 v[106:107], v[104:105], off
	v_mul_f32_e32 v104, 0xbfb8aa3b, v100
	v_mul_f32_e32 v105, 0xbfb8aa3b, v101
	v_exp_f32_e32 v104, v104
	v_exp_f32_e32 v105, v105
	v_add_f32_e32 v104, 1.0, v104
	v_add_f32_e32 v105, 1.0, v105
	v_rcp_f32_e32 v104, v104
	v_rcp_f32_e32 v105, v105
	s_nop 0
	v_pk_mul_f32 v[100:101], v[100:101], v[104:105]
	s_nop 0
	v_pk_mul_f32 v[96:97], v[96:97], v[100:101]
	s_nop 0
	v_cvt_pk_bf16_f32 v96, v96, v97
	v_mul_f32_e32 v97, 0xbfb8aa3b, v102
	v_exp_f32_e32 v97, v97
	s_nop 0
	v_add_f32_e32 v97, 1.0, v97
	v_rcp_f32_e32 v100, v97
	v_mul_f32_e32 v97, 0xbfb8aa3b, v103
	v_exp_f32_e32 v97, v97
	s_nop 0
	v_add_f32_e32 v97, 1.0, v97
	v_rcp_f32_e32 v101, v97
	s_nop 0
	v_pk_mul_f32 v[100:101], v[102:103], v[100:101]
	s_nop 0
	v_pk_mul_f32 v[98:99], v[98:99], v[100:101]
	s_nop 0
	v_cvt_pk_bf16_f32 v97, v98, v99
	v_mul_f32_e32 v98, 0xbfb8aa3b, v92
	v_mul_f32_e32 v99, 0xbfb8aa3b, v93
	v_exp_f32_e32 v98, v98
	v_exp_f32_e32 v99, v99
	global_store_dwordx2 v[106:107], v[96:97], off offset:128
	v_or_b32_e32 v96, 32, v147
	v_add_f32_e32 v98, 1.0, v98
	v_add_f32_e32 v99, 1.0, v99
	v_rcp_f32_e32 v98, v98
	v_rcp_f32_e32 v99, v99
	v_mad_i64_i32 v[96:97], s[22:23], v96, s42, v[132:133]
	v_pk_mul_f32 v[92:93], v[92:93], v[98:99]
	s_nop 0
	v_pk_mul_f32 v[88:89], v[88:89], v[92:93]
	s_nop 0
	v_cvt_pk_bf16_f32 v88, v88, v89
	v_mul_f32_e32 v89, 0xbfb8aa3b, v94
	v_exp_f32_e32 v89, v89
	s_nop 0
	v_add_f32_e32 v89, 1.0, v89
	v_rcp_f32_e32 v92, v89
	v_mul_f32_e32 v89, 0xbfb8aa3b, v95
	v_exp_f32_e32 v89, v89
	s_nop 0
	v_add_f32_e32 v89, 1.0, v89
	v_rcp_f32_e32 v93, v89
	s_nop 0
	v_pk_mul_f32 v[92:93], v[94:95], v[92:93]
	s_nop 0
	v_pk_mul_f32 v[90:91], v[90:91], v[92:93]
	s_nop 0
	v_cvt_pk_bf16_f32 v89, v90, v91
	v_lshl_add_u64 v[90:91], v[96:97], 0, s[20:21]
	global_store_dwordx2 v[90:91], v[88:89], off
	v_mul_f32_e32 v88, 0xbfb8aa3b, v84
	v_mul_f32_e32 v89, 0xbfb8aa3b, v85
	v_exp_f32_e32 v88, v88
	v_exp_f32_e32 v89, v89
	v_add_f32_e32 v88, 1.0, v88
	v_add_f32_e32 v89, 1.0, v89
	v_rcp_f32_e32 v88, v88
	v_rcp_f32_e32 v89, v89
	s_nop 0
	v_pk_mul_f32 v[84:85], v[84:85], v[88:89]
	s_nop 0
	v_pk_mul_f32 v[80:81], v[80:81], v[84:85]
	s_nop 0
	v_cvt_pk_bf16_f32 v80, v80, v81
	v_mul_f32_e32 v81, 0xbfb8aa3b, v86
	v_exp_f32_e32 v81, v81
	s_nop 0
	v_add_f32_e32 v81, 1.0, v81
	v_rcp_f32_e32 v84, v81
	v_mul_f32_e32 v81, 0xbfb8aa3b, v87
	v_exp_f32_e32 v81, v81
	s_nop 0
	v_add_f32_e32 v81, 1.0, v81
	v_rcp_f32_e32 v85, v81
	s_nop 0
	v_pk_mul_f32 v[84:85], v[86:87], v[84:85]
	s_nop 0
	v_pk_mul_f32 v[82:83], v[82:83], v[84:85]
	s_nop 0
	v_cvt_pk_bf16_f32 v81, v82, v83
	v_mul_f32_e32 v82, 0xbfb8aa3b, v76
	v_mul_f32_e32 v83, 0xbfb8aa3b, v77
	v_exp_f32_e32 v82, v82
	v_exp_f32_e32 v83, v83
	global_store_dwordx2 v[90:91], v[80:81], off offset:128
	v_or_b32_e32 v80, 48, v147
	v_add_f32_e32 v82, 1.0, v82
	v_add_f32_e32 v83, 1.0, v83
	v_rcp_f32_e32 v82, v82
	v_rcp_f32_e32 v83, v83
	v_mad_i64_i32 v[80:81], s[22:23], v80, s42, v[132:133]
	v_pk_mul_f32 v[76:77], v[76:77], v[82:83]
	s_nop 0
	v_pk_mul_f32 v[72:73], v[72:73], v[76:77]
	s_nop 0
	v_cvt_pk_bf16_f32 v72, v72, v73
	v_mul_f32_e32 v73, 0xbfb8aa3b, v78
	v_exp_f32_e32 v73, v73
	s_nop 0
	v_add_f32_e32 v73, 1.0, v73
	v_rcp_f32_e32 v76, v73
	v_mul_f32_e32 v73, 0xbfb8aa3b, v79
	v_exp_f32_e32 v73, v73
	s_nop 0
	v_add_f32_e32 v73, 1.0, v73
	v_rcp_f32_e32 v77, v73
	s_nop 0
	v_pk_mul_f32 v[76:77], v[78:79], v[76:77]
	s_nop 0
	v_pk_mul_f32 v[74:75], v[74:75], v[76:77]
	s_nop 0
	v_cvt_pk_bf16_f32 v73, v74, v75
	v_lshl_add_u64 v[74:75], v[80:81], 0, s[20:21]
	global_store_dwordx2 v[74:75], v[72:73], off
	v_mul_f32_e32 v72, 0xbfb8aa3b, v68
	v_mul_f32_e32 v73, 0xbfb8aa3b, v69
	v_exp_f32_e32 v72, v72
	v_exp_f32_e32 v73, v73
	v_add_f32_e32 v72, 1.0, v72
	v_add_f32_e32 v73, 1.0, v73
	v_rcp_f32_e32 v72, v72
	v_rcp_f32_e32 v73, v73
	s_nop 0
	v_pk_mul_f32 v[68:69], v[68:69], v[72:73]
	s_nop 0
	v_pk_mul_f32 v[64:65], v[64:65], v[68:69]
	s_nop 0
	v_cvt_pk_bf16_f32 v64, v64, v65
	v_mul_f32_e32 v65, 0xbfb8aa3b, v70
	v_exp_f32_e32 v65, v65
	s_nop 0
	v_add_f32_e32 v65, 1.0, v65
	v_rcp_f32_e32 v68, v65
	v_mul_f32_e32 v65, 0xbfb8aa3b, v71
	v_exp_f32_e32 v65, v65
	s_nop 0
	v_add_f32_e32 v65, 1.0, v65
	v_rcp_f32_e32 v69, v65
	s_nop 0
	v_pk_mul_f32 v[68:69], v[70:71], v[68:69]
	s_nop 0
	v_pk_mul_f32 v[66:67], v[66:67], v[68:69]
	s_nop 0
	v_cvt_pk_bf16_f32 v65, v66, v67
	v_mul_f32_e32 v66, 0xbfb8aa3b, v60
	v_mul_f32_e32 v67, 0xbfb8aa3b, v61
	v_exp_f32_e32 v66, v66
	v_exp_f32_e32 v67, v67
	global_store_dwordx2 v[74:75], v[64:65], off offset:128
	v_add_u32_e32 v64, 0x80, v147
	v_add_f32_e32 v66, 1.0, v66
	v_add_f32_e32 v67, 1.0, v67
	v_rcp_f32_e32 v66, v66
	v_rcp_f32_e32 v67, v67
	v_mad_i64_i32 v[64:65], s[22:23], v64, s42, v[132:133]
	v_pk_mul_f32 v[60:61], v[60:61], v[66:67]
	s_nop 0
	v_pk_mul_f32 v[56:57], v[56:57], v[60:61]
	s_nop 0
	v_cvt_pk_bf16_f32 v56, v56, v57
	v_mul_f32_e32 v57, 0xbfb8aa3b, v62
	v_exp_f32_e32 v57, v57
	s_nop 0
	v_add_f32_e32 v57, 1.0, v57
	v_rcp_f32_e32 v60, v57
	v_mul_f32_e32 v57, 0xbfb8aa3b, v63
	v_exp_f32_e32 v57, v57
	s_nop 0
	v_add_f32_e32 v57, 1.0, v57
	v_rcp_f32_e32 v61, v57
	s_nop 0
	v_pk_mul_f32 v[60:61], v[62:63], v[60:61]
	s_nop 0
	v_pk_mul_f32 v[58:59], v[58:59], v[60:61]
	s_nop 0
	v_cvt_pk_bf16_f32 v57, v58, v59
	v_lshl_add_u64 v[58:59], v[64:65], 0, s[20:21]
	global_store_dwordx2 v[58:59], v[56:57], off
	v_mul_f32_e32 v56, 0xbfb8aa3b, v52
	v_mul_f32_e32 v57, 0xbfb8aa3b, v53
	v_exp_f32_e32 v56, v56
	v_exp_f32_e32 v57, v57
	v_add_f32_e32 v56, 1.0, v56
	v_add_f32_e32 v57, 1.0, v57
	v_rcp_f32_e32 v56, v56
	v_rcp_f32_e32 v57, v57
	s_nop 0
	v_pk_mul_f32 v[52:53], v[52:53], v[56:57]
	s_nop 0
	v_pk_mul_f32 v[48:49], v[48:49], v[52:53]
	s_nop 0
	v_cvt_pk_bf16_f32 v48, v48, v49
	v_mul_f32_e32 v49, 0xbfb8aa3b, v54
	v_exp_f32_e32 v49, v49
	s_nop 0
	v_add_f32_e32 v49, 1.0, v49
	v_rcp_f32_e32 v52, v49
	v_mul_f32_e32 v49, 0xbfb8aa3b, v55
	v_exp_f32_e32 v49, v49
	s_nop 0
	v_add_f32_e32 v49, 1.0, v49
	v_rcp_f32_e32 v53, v49
	s_nop 0
	v_pk_mul_f32 v[52:53], v[54:55], v[52:53]
	s_nop 0
	v_pk_mul_f32 v[50:51], v[50:51], v[52:53]
	s_nop 0
	v_cvt_pk_bf16_f32 v49, v50, v51
	v_mul_f32_e32 v50, 0xbfb8aa3b, v44
	v_mul_f32_e32 v51, 0xbfb8aa3b, v45
	v_exp_f32_e32 v50, v50
	v_exp_f32_e32 v51, v51
	global_store_dwordx2 v[58:59], v[48:49], off offset:128
	v_add_u32_e32 v48, 0x90, v147
	v_add_f32_e32 v50, 1.0, v50
	v_add_f32_e32 v51, 1.0, v51
	v_rcp_f32_e32 v50, v50
	v_rcp_f32_e32 v51, v51
	v_mad_i64_i32 v[48:49], s[22:23], v48, s42, v[132:133]
	v_pk_mul_f32 v[44:45], v[44:45], v[50:51]
	s_nop 0
	v_pk_mul_f32 v[40:41], v[40:41], v[44:45]
	s_nop 0
	v_cvt_pk_bf16_f32 v40, v40, v41
	v_mul_f32_e32 v41, 0xbfb8aa3b, v46
	v_exp_f32_e32 v41, v41
	s_nop 0
	v_add_f32_e32 v41, 1.0, v41
	v_rcp_f32_e32 v44, v41
	v_mul_f32_e32 v41, 0xbfb8aa3b, v47
	v_exp_f32_e32 v41, v41
	s_nop 0
	v_add_f32_e32 v41, 1.0, v41
	v_rcp_f32_e32 v45, v41
	s_nop 0
	v_pk_mul_f32 v[44:45], v[46:47], v[44:45]
	s_nop 0
	v_pk_mul_f32 v[42:43], v[42:43], v[44:45]
	s_nop 0
	v_cvt_pk_bf16_f32 v41, v42, v43
	v_lshl_add_u64 v[42:43], v[48:49], 0, s[20:21]
	global_store_dwordx2 v[42:43], v[40:41], off
	v_mul_f32_e32 v40, 0xbfb8aa3b, v36
	v_mul_f32_e32 v41, 0xbfb8aa3b, v37
	v_exp_f32_e32 v40, v40
	v_exp_f32_e32 v41, v41
	v_add_f32_e32 v40, 1.0, v40
	v_add_f32_e32 v41, 1.0, v41
	v_rcp_f32_e32 v40, v40
	v_rcp_f32_e32 v41, v41
	s_nop 0
	v_pk_mul_f32 v[36:37], v[36:37], v[40:41]
	s_nop 0
	v_pk_mul_f32 v[32:33], v[32:33], v[36:37]
	s_nop 0
	v_cvt_pk_bf16_f32 v32, v32, v33
	v_mul_f32_e32 v33, 0xbfb8aa3b, v38
	v_exp_f32_e32 v33, v33
	s_nop 0
	v_add_f32_e32 v33, 1.0, v33
	v_rcp_f32_e32 v36, v33
	v_mul_f32_e32 v33, 0xbfb8aa3b, v39
	v_exp_f32_e32 v33, v33
	s_nop 0
	v_add_f32_e32 v33, 1.0, v33
	v_rcp_f32_e32 v37, v33
	s_nop 0
	v_pk_mul_f32 v[36:37], v[38:39], v[36:37]
	s_nop 0
	v_pk_mul_f32 v[34:35], v[34:35], v[36:37]
	s_nop 0
	v_cvt_pk_bf16_f32 v33, v34, v35
	v_mul_f32_e32 v34, 0xbfb8aa3b, v28
	v_mul_f32_e32 v35, 0xbfb8aa3b, v29
	v_exp_f32_e32 v34, v34
	v_exp_f32_e32 v35, v35
	global_store_dwordx2 v[42:43], v[32:33], off offset:128
	v_add_u32_e32 v32, 0xa0, v147
	v_add_f32_e32 v34, 1.0, v34
	v_add_f32_e32 v35, 1.0, v35
	v_rcp_f32_e32 v34, v34
	v_rcp_f32_e32 v35, v35
	v_mad_i64_i32 v[32:33], s[22:23], v32, s42, v[132:133]
	v_pk_mul_f32 v[28:29], v[28:29], v[34:35]
	s_nop 0
	v_pk_mul_f32 v[24:25], v[24:25], v[28:29]
	s_nop 0
	v_cvt_pk_bf16_f32 v24, v24, v25
	v_mul_f32_e32 v25, 0xbfb8aa3b, v30
	v_exp_f32_e32 v25, v25
	s_nop 0
	v_add_f32_e32 v25, 1.0, v25
	v_rcp_f32_e32 v28, v25
	v_mul_f32_e32 v25, 0xbfb8aa3b, v31
	v_exp_f32_e32 v25, v25
	s_nop 0
	v_add_f32_e32 v25, 1.0, v25
	v_rcp_f32_e32 v29, v25
	s_nop 0
	v_pk_mul_f32 v[28:29], v[30:31], v[28:29]
	s_nop 0
	v_pk_mul_f32 v[26:27], v[26:27], v[28:29]
	s_nop 0
	v_cvt_pk_bf16_f32 v25, v26, v27
	v_lshl_add_u64 v[26:27], v[32:33], 0, s[20:21]
	global_store_dwordx2 v[26:27], v[24:25], off
	v_mul_f32_e32 v24, 0xbfb8aa3b, v20
	v_mul_f32_e32 v25, 0xbfb8aa3b, v21
	v_exp_f32_e32 v24, v24
	v_exp_f32_e32 v25, v25
	v_add_f32_e32 v24, 1.0, v24
	v_add_f32_e32 v25, 1.0, v25
	v_rcp_f32_e32 v24, v24
	v_rcp_f32_e32 v25, v25
	s_nop 0
	v_pk_mul_f32 v[20:21], v[20:21], v[24:25]
	s_nop 0
	v_pk_mul_f32 v[16:17], v[16:17], v[20:21]
	s_nop 0
	v_cvt_pk_bf16_f32 v16, v16, v17
	v_mul_f32_e32 v17, 0xbfb8aa3b, v22
	v_exp_f32_e32 v17, v17
	s_nop 0
	v_add_f32_e32 v17, 1.0, v17
	v_rcp_f32_e32 v20, v17
	v_mul_f32_e32 v17, 0xbfb8aa3b, v23
	v_exp_f32_e32 v17, v17
	s_nop 0
	v_add_f32_e32 v17, 1.0, v17
	v_rcp_f32_e32 v21, v17
	s_nop 0
	v_pk_mul_f32 v[20:21], v[22:23], v[20:21]
	s_nop 0
	v_pk_mul_f32 v[18:19], v[18:19], v[20:21]
	s_nop 0
	v_cvt_pk_bf16_f32 v17, v18, v19
	v_mul_f32_e32 v18, 0xbfb8aa3b, v12
	v_mul_f32_e32 v19, 0xbfb8aa3b, v13
	v_exp_f32_e32 v18, v18
	v_exp_f32_e32 v19, v19
	global_store_dwordx2 v[26:27], v[16:17], off offset:128
	v_add_u32_e32 v16, 0xb0, v147
	v_add_f32_e32 v18, 1.0, v18
	v_add_f32_e32 v19, 1.0, v19
	v_rcp_f32_e32 v18, v18
	v_rcp_f32_e32 v19, v19
	v_mad_i64_i32 v[16:17], s[22:23], v16, s42, v[132:133]
	s_mov_b64 s[22:23], s[16:17]
	v_pk_mul_f32 v[12:13], v[12:13], v[18:19]
	s_nop 0
	v_pk_mul_f32 v[8:9], v[8:9], v[12:13]
	s_nop 0
	v_cvt_pk_bf16_f32 v8, v8, v9
	v_mul_f32_e32 v9, 0xbfb8aa3b, v14
	v_exp_f32_e32 v9, v9
	s_nop 0
	v_add_f32_e32 v9, 1.0, v9
	v_rcp_f32_e32 v12, v9
	v_mul_f32_e32 v9, 0xbfb8aa3b, v15
	v_exp_f32_e32 v9, v9
	s_nop 0
	v_add_f32_e32 v9, 1.0, v9
	v_rcp_f32_e32 v13, v9
	s_nop 0
	v_pk_mul_f32 v[12:13], v[14:15], v[12:13]
	s_nop 0
	v_pk_mul_f32 v[10:11], v[10:11], v[12:13]
	s_nop 0
	v_cvt_pk_bf16_f32 v9, v10, v11
	v_lshl_add_u64 v[10:11], v[16:17], 0, s[20:21]
	global_store_dwordx2 v[10:11], v[8:9], off
	v_mul_f32_e32 v8, 0xbfb8aa3b, v4
	v_mul_f32_e32 v9, 0xbfb8aa3b, v5
	v_exp_f32_e32 v8, v8
	v_exp_f32_e32 v9, v9
	s_mov_b32 s21, s12
	s_mov_b32 s20, s14
	v_add_f32_e32 v8, 1.0, v8
	v_add_f32_e32 v9, 1.0, v9
	v_rcp_f32_e32 v8, v8
	v_rcp_f32_e32 v9, v9
	s_nop 0
	v_pk_mul_f32 v[4:5], v[4:5], v[8:9]
	s_nop 0
	v_pk_mul_f32 v[0:1], v[0:1], v[4:5]
	s_nop 0
	v_cvt_pk_bf16_f32 v0, v0, v1
	v_mul_f32_e32 v1, 0xbfb8aa3b, v6
	v_exp_f32_e32 v1, v1
	s_nop 0
	v_add_f32_e32 v1, 1.0, v1
	v_rcp_f32_e32 v4, v1
	v_mul_f32_e32 v1, 0xbfb8aa3b, v7
	v_exp_f32_e32 v1, v1
	s_nop 0
	v_add_f32_e32 v1, 1.0, v1
	v_rcp_f32_e32 v5, v1
	s_nop 0
	v_pk_mul_f32 v[4:5], v[6:7], v[4:5]
	s_nop 0
	v_pk_mul_f32 v[2:3], v[2:3], v[4:5]
	s_nop 0
	v_cvt_pk_bf16_f32 v1, v2, v3
	global_store_dwordx2 v[10:11], v[0:1], off offset:128
	s_cbranch_vccz .LBB0_2002
	s_waitcnt vmcnt(0)
	s_cmpk_gt_u32 s1, 0xff
	s_cbranch_scc1 .LBB0_2009
	s_barrier

.LBB0_2081:
	ds_read_b128 v[128:131], v151
	ds_read_b128 v[144:147], v151 offset:1024
	ds_read_b128 v[154:157], v151 offset:2048
	ds_read_b128 v[158:161], v151 offset:3072
	s_add_u32 s18, s16, 0x100
	s_addc_u32 s19, s17, 0
	s_cmpk_eq_i32 s42, 0x54
	s_cselect_b32 s23, s11, s19
	s_cselect_b32 s22, s10, s18
	s_cselect_b32 s21, s13, s41
	s_cselect_b32 s20, s12, s40
	s_add_i32 m0, s4, 0xc000
	ds_read_b128 v[162:165], v152
	ds_read_b128 v[166:169], v152 offset:1024
	ds_read_b128 v[170:173], v152 offset:2048
	ds_read_b128 v[174:177], v152 offset:3072
	ds_read_b128 v[178:181], v152 offset:4096
	ds_read_b128 v[182:185], v152 offset:5120
	ds_read_b128 v[186:189], v152 offset:6144
	ds_read_b128 v[190:193], v152 offset:7168
	global_load_lds_dwordx4 v136, s[16:17]
	v_lshl_add_u64 v[194:195], s[16:17], 0, v[138:139]
	s_add_i32 m0, s4, 0xe000
	s_nop 0
	global_load_lds_dwordx4 v[194:195], off
	s_waitcnt lgkmcnt(8)
	s_barrier
	s_waitcnt lgkmcnt(0)
	s_waitcnt lgkmcnt(0)
	v_mfma_f32_16x16x32_bf16 v[124:127], v[128:131], v[162:165], v[124:127]
	v_mfma_f32_16x16x32_bf16 v[92:95], v[154:157], v[162:165], v[92:95]
	v_mfma_f32_16x16x32_bf16 v[120:123], v[128:131], v[170:173], v[120:123]
	v_mfma_f32_16x16x32_bf16 v[88:91], v[154:157], v[170:173], v[88:91]
	v_mfma_f32_16x16x32_bf16 v[116:119], v[128:131], v[178:181], v[116:119]
	v_mfma_f32_16x16x32_bf16 v[84:87], v[154:157], v[178:181], v[84:87]
	v_mfma_f32_16x16x32_bf16 v[112:115], v[128:131], v[186:189], v[112:115]
	v_mfma_f32_16x16x32_bf16 v[80:83], v[154:157], v[186:189], v[80:83]
	v_mfma_f32_16x16x32_bf16 v[124:127], v[144:147], v[166:169], v[124:127]
	v_mfma_f32_16x16x32_bf16 v[92:95], v[158:161], v[166:169], v[92:95]
	v_mfma_f32_16x16x32_bf16 v[120:123], v[144:147], v[174:177], v[120:123]
	v_mfma_f32_16x16x32_bf16 v[88:91], v[158:161], v[174:177], v[88:91]
	v_mfma_f32_16x16x32_bf16 v[116:119], v[144:147], v[182:185], v[116:119]
	v_mfma_f32_16x16x32_bf16 v[84:87], v[158:161], v[182:185], v[84:87]
	v_mfma_f32_16x16x32_bf16 v[112:115], v[144:147], v[190:193], v[112:115]
	v_mfma_f32_16x16x32_bf16 v[80:83], v[158:161], v[190:193], v[80:83]
	s_barrier
	s_add_i32 s16, s34, s3
	v_lshl_add_u64 v[210:211], s[20:21], 0, v[132:133]
	s_mov_b32 m0, s16
	ds_read_b128 v[194:197], v153
	ds_read_b128 v[198:201], v153 offset:1024
	ds_read_b128 v[202:205], v153 offset:2048
	ds_read_b128 v[206:209], v153 offset:3072
	global_load_lds_dwordx4 v[210:211], off
	s_add_i32 m0, s16, 0x2000
	s_nop 0
	global_load_lds_dwordx4 v134, s[20:21]
	s_barrier
	s_waitcnt lgkmcnt(0)
	s_waitcnt lgkmcnt(0)
	v_mfma_f32_16x16x32_bf16 v[76:79], v[194:197], v[162:165], v[76:79]
	v_mfma_f32_16x16x32_bf16 v[48:51], v[202:205], v[162:165], v[48:51]
	v_mfma_f32_16x16x32_bf16 v[68:71], v[194:197], v[170:173], v[68:71]
	v_mfma_f32_16x16x32_bf16 v[40:43], v[202:205], v[170:173], v[40:43]
	v_mfma_f32_16x16x32_bf16 v[60:63], v[194:197], v[178:181], v[60:63]
	v_mfma_f32_16x16x32_bf16 v[36:39], v[202:205], v[178:181], v[36:39]
	v_mfma_f32_16x16x32_bf16 v[52:55], v[194:197], v[186:189], v[52:55]
	v_mfma_f32_16x16x32_bf16 v[28:31], v[202:205], v[186:189], v[28:31]
	v_mfma_f32_16x16x32_bf16 v[76:79], v[198:201], v[166:169], v[76:79]
	v_mfma_f32_16x16x32_bf16 v[48:51], v[206:209], v[166:169], v[48:51]
	v_mfma_f32_16x16x32_bf16 v[68:71], v[198:201], v[174:177], v[68:71]
	v_mfma_f32_16x16x32_bf16 v[40:43], v[206:209], v[174:177], v[40:43]
	v_mfma_f32_16x16x32_bf16 v[60:63], v[198:201], v[182:185], v[60:63]
	v_mfma_f32_16x16x32_bf16 v[36:39], v[206:209], v[182:185], v[36:39]
	v_mfma_f32_16x16x32_bf16 v[52:55], v[198:201], v[190:193], v[52:55]
	v_mfma_f32_16x16x32_bf16 v[28:31], v[206:209], v[190:193], v[28:31]
	s_mov_b32 m0, s4
	v_lshl_add_u64 v[214:215], s[22:23], 0, v[132:133]
	s_barrier
	ds_read_b128 v[162:165], v152 offset:16384
	ds_read_b128 v[166:169], v152 offset:17408
	ds_read_b128 v[170:173], v152 offset:18432
	ds_read_b128 v[174:177], v152 offset:19456
	ds_read_b128 v[178:181], v152 offset:20480
	ds_read_b128 v[182:185], v152 offset:21504
	ds_read_b128 v[186:189], v152 offset:22528
	ds_read_b128 v[190:193], v152 offset:23552
	global_load_lds_dwordx4 v[214:215], off
	v_lshl_add_u64 v[216:217], s[22:23], 0, v[134:135]
	s_mov_b32 m0, s5
	s_nop 0
	global_load_lds_dwordx4 v134, s[22:23]
	s_barrier
	s_waitcnt lgkmcnt(0)
	s_waitcnt lgkmcnt(0)
	v_mfma_f32_16x16x32_bf16 v[108:111], v[128:131], v[162:165], v[108:111]
	v_mfma_f32_16x16x32_bf16 v[72:75], v[154:157], v[162:165], v[72:75]
	v_mfma_f32_16x16x32_bf16 v[104:107], v[128:131], v[170:173], v[104:107]
	v_mfma_f32_16x16x32_bf16 v[64:67], v[154:157], v[170:173], v[64:67]
	v_mfma_f32_16x16x32_bf16 v[100:103], v[128:131], v[178:181], v[100:103]
	v_mfma_f32_16x16x32_bf16 v[56:59], v[154:157], v[178:181], v[56:59]
	v_mfma_f32_16x16x32_bf16 v[96:99], v[128:131], v[186:189], v[96:99]
	v_mfma_f32_16x16x32_bf16 v[44:47], v[154:157], v[186:189], v[44:47]
	v_mfma_f32_16x16x32_bf16 v[108:111], v[144:147], v[166:169], v[108:111]
	v_mfma_f32_16x16x32_bf16 v[72:75], v[158:161], v[166:169], v[72:75]
	v_mfma_f32_16x16x32_bf16 v[104:107], v[144:147], v[174:177], v[104:107]
	v_mfma_f32_16x16x32_bf16 v[64:67], v[158:161], v[174:177], v[64:67]
	v_mfma_f32_16x16x32_bf16 v[100:103], v[144:147], v[182:185], v[100:103]
	v_mfma_f32_16x16x32_bf16 v[56:59], v[158:161], v[182:185], v[56:59]
	v_mfma_f32_16x16x32_bf16 v[96:99], v[144:147], v[190:193], v[96:99]
	v_mfma_f32_16x16x32_bf16 v[44:47], v[158:161], v[190:193], v[44:47]
	s_barrier
	s_add_u32 s16, s20, 0x160000
	s_addc_u32 s17, s21, 0
	s_add_i32 s43, s35, s3
	v_lshl_add_u64 v[128:129], s[16:17], 0, v[132:133]
	s_mov_b32 m0, s43
	s_nop 0
	global_load_lds_dwordx4 v[128:129], off
	s_add_i32 m0, s43, 0x2000
	s_nop 0
	global_load_lds_dwordx4 v134, s[16:17]
	s_waitcnt vmcnt(6)
	s_barrier
	v_mfma_f32_16x16x32_bf16 v[32:35], v[194:197], v[162:165], v[32:35]
	v_mfma_f32_16x16x32_bf16 v[12:15], v[202:205], v[162:165], v[12:15]
	v_mfma_f32_16x16x32_bf16 v[24:27], v[194:197], v[170:173], v[24:27]
	v_mfma_f32_16x16x32_bf16 v[8:11], v[202:205], v[170:173], v[8:11]
	v_mfma_f32_16x16x32_bf16 v[20:23], v[194:197], v[178:181], v[20:23]
	v_mfma_f32_16x16x32_bf16 v[4:7], v[202:205], v[178:181], v[4:7]
	v_mfma_f32_16x16x32_bf16 v[16:19], v[194:197], v[186:189], v[16:19]
	v_mfma_f32_16x16x32_bf16 v[0:3], v[202:205], v[186:189], v[0:3]
	v_mfma_f32_16x16x32_bf16 v[32:35], v[198:201], v[166:169], v[32:35]
	v_mfma_f32_16x16x32_bf16 v[12:15], v[206:209], v[166:169], v[12:15]
	v_mfma_f32_16x16x32_bf16 v[24:27], v[198:201], v[174:177], v[24:27]
	v_mfma_f32_16x16x32_bf16 v[8:11], v[206:209], v[174:177], v[8:11]
	v_mfma_f32_16x16x32_bf16 v[20:23], v[198:201], v[182:185], v[20:23]
	v_mfma_f32_16x16x32_bf16 v[4:7], v[206:209], v[182:185], v[4:7]
	v_mfma_f32_16x16x32_bf16 v[16:19], v[198:201], v[190:193], v[16:19]
	v_mfma_f32_16x16x32_bf16 v[0:3], v[206:209], v[190:193], v[0:3]
	s_add_i32 s43, 0, 0x18000
	v_add_u32_e32 v158, s43, v149
	s_barrier
	ds_read_b128 v[128:131], v158
	ds_read_b128 v[144:147], v158 offset:1024
	ds_read_b128 v[154:157], v158 offset:2048
	ds_read_b128 v[158:161], v158 offset:3072
	s_add_u32 s16, s22, 0x160000
	s_addc_u32 s17, s23, 0
	s_mov_b32 m0, s24
	v_lshl_add_u64 v[194:195], s[16:17], 0, v[132:133]
	ds_read_b128 v[162:165], v152 offset:32768
	ds_read_b128 v[166:169], v152 offset:33792
	ds_read_b128 v[170:173], v152 offset:34816
	ds_read_b128 v[174:177], v152 offset:35840
	ds_read_b128 v[178:181], v152 offset:36864
	ds_read_b128 v[182:185], v152 offset:37888
	ds_read_b128 v[186:189], v152 offset:38912
	ds_read_b128 v[190:193], v152 offset:39936
	global_load_lds_dwordx4 v[194:195], off
	s_mov_b32 m0, s25
	s_nop 0
	global_load_lds_dwordx4 v134, s[16:17]
	s_waitcnt lgkmcnt(8)
	s_barrier
	s_waitcnt lgkmcnt(0)
	s_waitcnt lgkmcnt(0)
	v_mfma_f32_16x16x32_bf16 v[124:127], v[128:131], v[162:165], v[124:127]
	v_mfma_f32_16x16x32_bf16 v[92:95], v[154:157], v[162:165], v[92:95]
	v_mfma_f32_16x16x32_bf16 v[120:123], v[128:131], v[170:173], v[120:123]
	v_mfma_f32_16x16x32_bf16 v[88:91], v[154:157], v[170:173], v[88:91]
	v_mfma_f32_16x16x32_bf16 v[116:119], v[128:131], v[178:181], v[116:119]
	v_mfma_f32_16x16x32_bf16 v[84:87], v[154:157], v[178:181], v[84:87]
	v_mfma_f32_16x16x32_bf16 v[112:115], v[128:131], v[186:189], v[112:115]
	v_mfma_f32_16x16x32_bf16 v[80:83], v[154:157], v[186:189], v[80:83]
	v_mfma_f32_16x16x32_bf16 v[124:127], v[144:147], v[166:169], v[124:127]
	v_mfma_f32_16x16x32_bf16 v[92:95], v[158:161], v[166:169], v[92:95]
	v_mfma_f32_16x16x32_bf16 v[120:123], v[144:147], v[174:177], v[120:123]
	v_mfma_f32_16x16x32_bf16 v[88:91], v[158:161], v[174:177], v[88:91]
	v_mfma_f32_16x16x32_bf16 v[116:119], v[144:147], v[182:185], v[116:119]
	v_mfma_f32_16x16x32_bf16 v[84:87], v[158:161], v[182:185], v[84:87]
	v_mfma_f32_16x16x32_bf16 v[112:115], v[144:147], v[190:193], v[112:115]
	v_mfma_f32_16x16x32_bf16 v[80:83], v[158:161], v[190:193], v[80:83]
	s_barrier
	s_add_i32 s22, 0, 0x1c000
	s_add_i32 s16, s43, s3
	v_add_u32_e32 v206, s22, v149
	v_lshl_add_u64 v[210:211], v[210:211], 0, s[14:15]
	s_mov_b32 m0, s16
	ds_read_b128 v[194:197], v206
	ds_read_b128 v[198:201], v206 offset:1024
	ds_read_b128 v[202:205], v206 offset:2048
	ds_read_b128 v[206:209], v206 offset:3072
	global_load_lds_dwordx4 v[210:211], off
	s_add_u32 s98, s20, s14
	s_addc_u32 s99, s21, s15
	s_add_i32 m0, s16, 0x2000
	s_nop 0
	global_load_lds_dwordx4 v134, s[98:99]
	s_barrier
	s_waitcnt lgkmcnt(0)
	s_waitcnt lgkmcnt(0)
	v_mfma_f32_16x16x32_bf16 v[76:79], v[194:197], v[162:165], v[76:79]
	v_mfma_f32_16x16x32_bf16 v[48:51], v[202:205], v[162:165], v[48:51]
	v_mfma_f32_16x16x32_bf16 v[68:71], v[194:197], v[170:173], v[68:71]
	v_mfma_f32_16x16x32_bf16 v[40:43], v[202:205], v[170:173], v[40:43]
	v_mfma_f32_16x16x32_bf16 v[60:63], v[194:197], v[178:181], v[60:63]
	v_mfma_f32_16x16x32_bf16 v[36:39], v[202:205], v[178:181], v[36:39]
	v_mfma_f32_16x16x32_bf16 v[52:55], v[194:197], v[186:189], v[52:55]
	v_mfma_f32_16x16x32_bf16 v[28:31], v[202:205], v[186:189], v[28:31]
	v_mfma_f32_16x16x32_bf16 v[76:79], v[198:201], v[166:169], v[76:79]
	v_mfma_f32_16x16x32_bf16 v[48:51], v[206:209], v[166:169], v[48:51]
	v_mfma_f32_16x16x32_bf16 v[68:71], v[198:201], v[174:177], v[68:71]
	v_mfma_f32_16x16x32_bf16 v[40:43], v[206:209], v[174:177], v[40:43]
	v_mfma_f32_16x16x32_bf16 v[60:63], v[198:201], v[182:185], v[60:63]
	v_mfma_f32_16x16x32_bf16 v[36:39], v[206:209], v[182:185], v[36:39]
	v_mfma_f32_16x16x32_bf16 v[52:55], v[198:201], v[190:193], v[52:55]
	v_mfma_f32_16x16x32_bf16 v[28:31], v[206:209], v[190:193], v[28:31]
	s_mov_b32 m0, s27
	v_lshl_add_u64 v[210:211], v[214:215], 0, s[14:15]
	s_barrier
	ds_read_b128 v[162:165], v152 offset:49152
	ds_read_b128 v[166:169], v152 offset:50176
	ds_read_b128 v[170:173], v152 offset:51200
	ds_read_b128 v[174:177], v152 offset:52224
	ds_read_b128 v[178:181], v152 offset:53248
	ds_read_b128 v[182:185], v152 offset:54272
	ds_read_b128 v[186:189], v152 offset:55296
	ds_read_b128 v[190:193], v152 offset:56320
	global_load_lds_dwordx4 v[210:211], off
	v_lshl_add_u64 v[210:211], v[216:217], 0, s[14:15]
	s_mov_b32 m0, s28
	s_nop 0
	global_load_lds_dwordx4 v[210:211], off
	s_barrier
	s_waitcnt lgkmcnt(0)
	s_waitcnt lgkmcnt(0)
	v_mfma_f32_16x16x32_bf16 v[108:111], v[128:131], v[162:165], v[108:111]
	v_mfma_f32_16x16x32_bf16 v[72:75], v[154:157], v[162:165], v[72:75]
	v_mfma_f32_16x16x32_bf16 v[104:107], v[128:131], v[170:173], v[104:107]
	v_mfma_f32_16x16x32_bf16 v[64:67], v[154:157], v[170:173], v[64:67]
	v_mfma_f32_16x16x32_bf16 v[100:103], v[128:131], v[178:181], v[100:103]
	v_mfma_f32_16x16x32_bf16 v[56:59], v[154:157], v[178:181], v[56:59]
	v_mfma_f32_16x16x32_bf16 v[96:99], v[128:131], v[186:189], v[96:99]
	v_mfma_f32_16x16x32_bf16 v[44:47], v[154:157], v[186:189], v[44:47]
	v_mfma_f32_16x16x32_bf16 v[108:111], v[144:147], v[166:169], v[108:111]
	v_mfma_f32_16x16x32_bf16 v[72:75], v[158:161], v[166:169], v[72:75]
	v_mfma_f32_16x16x32_bf16 v[104:107], v[144:147], v[174:177], v[104:107]
	v_mfma_f32_16x16x32_bf16 v[64:67], v[158:161], v[174:177], v[64:67]
	v_mfma_f32_16x16x32_bf16 v[100:103], v[144:147], v[182:185], v[100:103]
	v_mfma_f32_16x16x32_bf16 v[56:59], v[158:161], v[182:185], v[56:59]
	v_mfma_f32_16x16x32_bf16 v[96:99], v[144:147], v[190:193], v[96:99]
	v_mfma_f32_16x16x32_bf16 v[44:47], v[158:161], v[190:193], v[44:47]
	s_barrier
	s_add_u32 s16, s20, 0x160080
	s_addc_u32 s17, s21, 0
	s_add_i32 s20, s22, s3
	v_lshl_add_u64 v[128:129], s[16:17], 0, v[132:133]
	s_mov_b32 m0, s20
	s_nop 0
	global_load_lds_dwordx4 v[128:129], off
	s_add_i32 m0, s20, 0x2000
	s_nop 0
	global_load_lds_dwordx4 v134, s[16:17]
	s_waitcnt vmcnt(6)
	s_barrier
	v_mfma_f32_16x16x32_bf16 v[32:35], v[194:197], v[162:165], v[32:35]
	v_mfma_f32_16x16x32_bf16 v[12:15], v[202:205], v[162:165], v[12:15]
	v_mfma_f32_16x16x32_bf16 v[24:27], v[194:197], v[170:173], v[24:27]
	v_mfma_f32_16x16x32_bf16 v[8:11], v[202:205], v[170:173], v[8:11]
	v_mfma_f32_16x16x32_bf16 v[20:23], v[194:197], v[178:181], v[20:23]
	v_mfma_f32_16x16x32_bf16 v[4:7], v[202:205], v[178:181], v[4:7]
	v_mfma_f32_16x16x32_bf16 v[16:19], v[194:197], v[186:189], v[16:19]
	v_mfma_f32_16x16x32_bf16 v[0:3], v[202:205], v[186:189], v[0:3]
	v_mfma_f32_16x16x32_bf16 v[32:35], v[198:201], v[166:169], v[32:35]
	v_mfma_f32_16x16x32_bf16 v[12:15], v[206:209], v[166:169], v[12:15]
	v_mfma_f32_16x16x32_bf16 v[24:27], v[198:201], v[174:177], v[24:27]
	v_mfma_f32_16x16x32_bf16 v[8:11], v[206:209], v[174:177], v[8:11]
	v_mfma_f32_16x16x32_bf16 v[20:23], v[198:201], v[182:185], v[20:23]
	v_mfma_f32_16x16x32_bf16 v[4:7], v[206:209], v[182:185], v[4:7]
	v_mfma_f32_16x16x32_bf16 v[16:19], v[198:201], v[190:193], v[16:19]
	v_mfma_f32_16x16x32_bf16 v[0:3], v[206:209], v[190:193], v[0:3]
	s_add_i32 s42, s42, 2
	s_add_u32 s40, s40, 0x100
	s_addc_u32 s41, s41, 0
	s_cmpk_gt_u32 s42, 0x55
	s_mov_b64 s[16:17], s[18:19]
	s_barrier
	s_cbranch_scc0 .LBB0_2081
	s_cmp_lt_u32 s38, 32
	s_movk_i32 s16, 0x3000
	s_cselect_b32 s16, s16, 0x6000
	s_cmp_gt_i32 s38, 15
	v_lshl_add_u32 v158, s38, 8, v148
	s_cselect_b32 s16, s16, 0
	v_lshl_or_b32 v128, s39, 8, v150
	s_lshl_b32 s16, s16, 2
	v_ashrrev_i32_e32 v159, 31, v158
	s_add_u32 s16, s30, s16
	v_ashrrev_i32_e32 v129, 31, v128
	v_lshlrev_b64 v[146:147], 13, v[158:159]
	s_addc_u32 s17, s31, 0
	v_lshlrev_b64 v[160:161], 2, v[128:129]
	v_lshl_add_u64 v[146:147], s[56:57], 0, v[146:147]
	v_lshl_add_u64 v[144:145], s[16:17], 0, v[160:161]
	v_lshl_add_u64 v[146:147], v[146:147], 0, v[160:161]
	s_mov_b64 s[16:17], 0x100000
	s_mov_b32 s39, s36
	s_mov_b32 s38, s37
	s_mov_b64 s[18:19], s[12:13]
	v_or_b32_e32 v162, 16, v158
	v_ashrrev_i32_e32 v163, 31, v162
	v_lshlrev_b64 v[164:165], 13, v[162:163]
	v_lshl_add_u64 v[162:163], s[56:57], 0, v[164:165]
	v_lshl_add_u64 v[164:165], v[162:163], 0, v[160:161]
	v_or_b32_e32 v162, 32, v158
	v_ashrrev_i32_e32 v163, 31, v162
	v_lshlrev_b64 v[166:167], 13, v[162:163]
	v_lshl_add_u64 v[162:163], s[56:57], 0, v[166:167]
	v_lshl_add_u64 v[166:167], v[162:163], 0, v[160:161]
	v_or_b32_e32 v162, 48, v158
	v_ashrrev_i32_e32 v163, 31, v162
	v_lshlrev_b64 v[168:169], 13, v[162:163]
	v_lshl_add_u64 v[162:163], s[56:57], 0, v[168:169]
	v_lshl_add_u64 v[168:169], v[162:163], 0, v[160:161]
	v_lshl_add_u64 v[162:163], v[146:147], 0, s[16:17]
	s_mov_b32 s16, 0x100000
	v_add_co_u32_e32 v170, vcc, s16, v146
	s_mov_b64 s[16:17], 0x120000
	s_nop 0
	v_addc_co_u32_e32 v171, vcc, 0, v147, vcc
	v_lshl_add_u64 v[172:173], v[146:147], 0, s[16:17]
	s_mov_b32 s16, 0x120000
	v_add_co_u32_e32 v174, vcc, s16, v146
	s_mov_b64 s[16:17], 0x140000
	s_nop 0
	v_addc_co_u32_e32 v175, vcc, 0, v147, vcc
	v_lshl_add_u64 v[176:177], v[146:147], 0, s[16:17]
	s_mov_b32 s16, 0x140000
	v_add_co_u32_e32 v178, vcc, s16, v146
	s_mov_b64 s[16:17], 0x160000
	s_nop 0
	v_addc_co_u32_e32 v179, vcc, 0, v147, vcc
	v_lshl_add_u64 v[180:181], v[146:147], 0, s[16:17]
	s_mov_b32 s16, 0x160000
	v_add_co_u32_e32 v182, vcc, s16, v146
	s_mov_b64 s[16:17], s[10:11]
	s_nop 0
	v_addc_co_u32_e32 v183, vcc, 0, v147, vcc
	s_and_b64 vcc, exec, s[6:7]
	global_load_dwordx4 v[184:187], v[144:145], off
	global_load_dwordx4 v[188:191], v[146:147], off
	v_pk_add_f32 v[126:127], v[126:127], 0 op_sel_hi:[1,0]
	v_pk_add_f32 v[124:125], v[124:125], 0 op_sel_hi:[1,0]
	v_pk_add_f32 v[122:123], v[122:123], 0 op_sel_hi:[1,0]
	v_pk_add_f32 v[120:121], v[120:121], 0 op_sel_hi:[1,0]
	v_pk_add_f32 v[118:119], v[118:119], 0 op_sel_hi:[1,0]
	v_pk_add_f32 v[116:117], v[116:117], 0 op_sel_hi:[1,0]
	v_pk_add_f32 v[114:115], v[114:115], 0 op_sel_hi:[1,0]
	v_pk_add_f32 v[112:113], v[112:113], 0 op_sel_hi:[1,0]
	v_pk_add_f32 v[110:111], v[110:111], 0 op_sel_hi:[1,0]
	v_pk_add_f32 v[108:109], v[108:109], 0 op_sel_hi:[1,0]
	v_pk_add_f32 v[106:107], v[106:107], 0 op_sel_hi:[1,0]
	v_pk_add_f32 v[104:105], v[104:105], 0 op_sel_hi:[1,0]
	v_pk_add_f32 v[102:103], v[102:103], 0 op_sel_hi:[1,0]
	v_pk_add_f32 v[100:101], v[100:101], 0 op_sel_hi:[1,0]
	v_pk_add_f32 v[98:99], v[98:99], 0 op_sel_hi:[1,0]
	v_pk_add_f32 v[96:97], v[96:97], 0 op_sel_hi:[1,0]
	v_pk_add_f32 v[94:95], v[94:95], 0 op_sel_hi:[1,0]
	v_pk_add_f32 v[92:93], v[92:93], 0 op_sel_hi:[1,0]
	v_pk_add_f32 v[90:91], v[90:91], 0 op_sel_hi:[1,0]
	v_pk_add_f32 v[88:89], v[88:89], 0 op_sel_hi:[1,0]
	v_pk_add_f32 v[86:87], v[86:87], 0 op_sel_hi:[1,0]
	v_pk_add_f32 v[84:85], v[84:85], 0 op_sel_hi:[1,0]
	v_pk_add_f32 v[82:83], v[82:83], 0 op_sel_hi:[1,0]
	v_pk_add_f32 v[80:81], v[80:81], 0 op_sel_hi:[1,0]
	v_pk_add_f32 v[74:75], v[74:75], 0 op_sel_hi:[1,0]
	v_pk_add_f32 v[72:73], v[72:73], 0 op_sel_hi:[1,0]
	v_pk_add_f32 v[66:67], v[66:67], 0 op_sel_hi:[1,0]
	v_pk_add_f32 v[64:65], v[64:65], 0 op_sel_hi:[1,0]
	v_pk_add_f32 v[58:59], v[58:59], 0 op_sel_hi:[1,0]
	v_pk_add_f32 v[56:57], v[56:57], 0 op_sel_hi:[1,0]
	v_pk_add_f32 v[46:47], v[46:47], 0 op_sel_hi:[1,0]
	v_pk_add_f32 v[44:45], v[44:45], 0 op_sel_hi:[1,0]
	v_pk_add_f32 v[62:63], v[62:63], 0 op_sel_hi:[1,0]
	v_pk_add_f32 v[60:61], v[60:61], 0 op_sel_hi:[1,0]
	v_pk_add_f32 v[54:55], v[54:55], 0 op_sel_hi:[1,0]
	v_pk_add_f32 v[52:53], v[52:53], 0 op_sel_hi:[1,0]
	v_pk_add_f32 v[34:35], v[34:35], 0 op_sel_hi:[1,0]
	v_pk_add_f32 v[32:33], v[32:33], 0 op_sel_hi:[1,0]
	v_pk_add_f32 v[26:27], v[26:27], 0 op_sel_hi:[1,0]
	v_pk_add_f32 v[24:25], v[24:25], 0 op_sel_hi:[1,0]
	v_pk_add_f32 v[22:23], v[22:23], 0 op_sel_hi:[1,0]
	v_pk_add_f32 v[20:21], v[20:21], 0 op_sel_hi:[1,0]
	v_pk_add_f32 v[18:19], v[18:19], 0 op_sel_hi:[1,0]
	v_pk_add_f32 v[16:17], v[16:17], 0 op_sel_hi:[1,0]
	v_pk_add_f32 v[14:15], v[14:15], 0 op_sel_hi:[1,0]
	v_pk_add_f32 v[12:13], v[12:13], 0 op_sel_hi:[1,0]
	v_pk_add_f32 v[10:11], v[10:11], 0 op_sel_hi:[1,0]
	v_pk_add_f32 v[8:9], v[8:9], 0 op_sel_hi:[1,0]
	v_pk_add_f32 v[6:7], v[6:7], 0 op_sel_hi:[1,0]
	v_pk_add_f32 v[4:5], v[4:5], 0 op_sel_hi:[1,0]
	v_pk_add_f32 v[2:3], v[2:3], 0 op_sel_hi:[1,0]
	v_pk_add_f32 v[0:1], v[0:1], 0 op_sel_hi:[1,0]
	s_waitcnt vmcnt(0)
	v_pk_fma_f32 v[126:127], v[126:127], v[186:187], v[190:191]
	v_pk_fma_f32 v[124:125], v[124:125], v[184:185], v[188:189]
	global_store_dwordx4 v[146:147], v[124:127], off
	global_load_dwordx4 v[188:191], v[164:165], off
	global_load_dwordx4 v[192:195], v[166:167], off
	global_load_dwordx4 v[196:199], v[168:169], off
	global_load_dwordx4 v[200:203], v[170:171], off
	global_load_dwordx4 v[204:207], v[174:175], off
	global_load_dwordx4 v[208:211], v[178:179], off
	global_load_dwordx4 v[212:215], v[182:183], off
	global_load_dwordx4 v[216:219], v[144:145], off offset:64
	global_load_dwordx4 v[220:223], v[146:147], off offset:64
	global_load_dwordx4 v[224:227], v[164:165], off offset:64
	global_load_dwordx4 v[228:231], v[166:167], off offset:64
	global_load_dwordx4 v[232:235], v[168:169], off offset:64
	s_waitcnt vmcnt(11)
	v_pk_fma_f32 v[122:123], v[122:123], v[186:187], v[190:191]
	v_pk_fma_f32 v[120:121], v[120:121], v[184:185], v[188:189]
	global_store_dwordx4 v[164:165], v[120:123], off
	global_load_dwordx4 v[188:191], v[162:163], off offset:64
	s_waitcnt vmcnt(12)
	v_pk_fma_f32 v[118:119], v[118:119], v[186:187], v[194:195]
	v_pk_fma_f32 v[116:117], v[116:117], v[184:185], v[192:193]
	global_store_dwordx4 v[166:167], v[116:119], off
	global_load_dwordx4 v[192:195], v[172:173], off offset:64
	s_waitcnt vmcnt(13)
	v_pk_fma_f32 v[114:115], v[114:115], v[186:187], v[198:199]
	v_pk_fma_f32 v[112:113], v[112:113], v[184:185], v[196:197]
	global_store_dwordx4 v[168:169], v[112:115], off
	global_load_dwordx4 v[196:199], v[176:177], off offset:64
	s_waitcnt vmcnt(14)
	v_pk_fma_f32 v[110:111], v[110:111], v[186:187], v[202:203]
	v_pk_fma_f32 v[108:109], v[108:109], v[184:185], v[200:201]
	global_store_dwordx4 v[170:171], v[108:111], off
	global_load_dwordx4 v[200:203], v[180:181], off offset:64
	s_waitcnt vmcnt(15)
	v_pk_fma_f32 v[106:107], v[106:107], v[186:187], v[206:207]
	v_pk_fma_f32 v[104:105], v[104:105], v[184:185], v[204:205]
	global_store_dwordx4 v[174:175], v[104:107], off
	global_load_dwordx4 v[204:207], v[144:145], off offset:512
	s_waitcnt vmcnt(16)
	v_pk_fma_f32 v[102:103], v[102:103], v[186:187], v[210:211]
	v_pk_fma_f32 v[100:101], v[100:101], v[184:185], v[208:209]
	global_store_dwordx4 v[178:179], v[100:103], off
	global_load_dwordx4 v[208:211], v[146:147], off offset:512
	s_waitcnt vmcnt(17)
	v_pk_fma_f32 v[98:99], v[98:99], v[186:187], v[214:215]
	v_pk_fma_f32 v[96:97], v[96:97], v[184:185], v[212:213]
	global_store_dwordx4 v[182:183], v[96:99], off
	global_load_dwordx4 v[184:187], v[164:165], off offset:512
	s_waitcnt vmcnt(17)
	v_pk_fma_f32 v[94:95], v[94:95], v[218:219], v[222:223]
	v_pk_fma_f32 v[92:93], v[92:93], v[216:217], v[220:221]
	global_store_dwordx4 v[146:147], v[92:95], off offset:64
	global_load_dwordx4 v[212:215], v[166:167], off offset:512
	global_load_dwordx4 v[220:223], v[168:169], off offset:512
	s_waitcnt vmcnt(19)
	v_pk_fma_f32 v[90:91], v[90:91], v[218:219], v[226:227]
	v_pk_fma_f32 v[88:89], v[88:89], v[216:217], v[224:225]
	global_store_dwordx4 v[164:165], v[88:91], off offset:64
	global_load_dwordx4 v[224:227], v[162:163], off offset:512
	s_waitcnt vmcnt(20)
	v_pk_fma_f32 v[86:87], v[86:87], v[218:219], v[230:231]
	v_pk_fma_f32 v[84:85], v[84:85], v[216:217], v[228:229]
	global_store_dwordx4 v[166:167], v[84:87], off offset:64
	global_load_dwordx4 v[228:231], v[172:173], off offset:512
	s_waitcnt vmcnt(21)
	v_pk_fma_f32 v[82:83], v[82:83], v[218:219], v[234:235]
	v_pk_fma_f32 v[80:81], v[80:81], v[216:217], v[232:233]
	global_store_dwordx4 v[168:169], v[80:83], off offset:64
	global_load_dwordx4 v[232:235], v[176:177], off offset:512
	s_waitcnt vmcnt(21)
	v_pk_fma_f32 v[74:75], v[74:75], v[218:219], v[190:191]
	v_pk_fma_f32 v[72:73], v[72:73], v[216:217], v[188:189]
	global_store_dwordx4 v[162:163], v[72:75], off offset:64
	global_load_dwordx4 v[188:191], v[180:181], off offset:512
	s_waitcnt vmcnt(21)
	v_pk_fma_f32 v[66:67], v[66:67], v[218:219], v[194:195]
	v_pk_fma_f32 v[64:65], v[64:65], v[216:217], v[192:193]
	global_store_dwordx4 v[172:173], v[64:67], off offset:64
	global_load_dwordx4 v[192:195], v[144:145], off offset:576
	s_waitcnt vmcnt(21)
	v_pk_fma_f32 v[58:59], v[58:59], v[218:219], v[198:199]
	v_pk_fma_f32 v[56:57], v[56:57], v[216:217], v[196:197]
	global_store_dwordx4 v[176:177], v[56:59], off offset:64
	global_load_dwordx4 v[196:199], v[146:147], off offset:576
	v_pk_add_f32 v[64:65], v[78:79], 0 op_sel_hi:[1,0]
	v_pk_add_f32 v[66:67], v[76:77], 0 op_sel_hi:[1,0]
	s_waitcnt vmcnt(21)
	v_pk_fma_f32 v[46:47], v[46:47], v[218:219], v[202:203]
	v_pk_fma_f32 v[44:45], v[44:45], v[216:217], v[200:201]
	global_store_dwordx4 v[180:181], v[44:47], off offset:64
	global_load_dwordx4 v[200:203], v[164:165], off offset:576
	s_waitcnt vmcnt(19)
	v_pk_fma_f32 v[58:59], v[64:65], v[206:207], v[210:211]
	v_pk_fma_f32 v[56:57], v[66:67], v[204:205], v[208:209]
	global_store_dwordx4 v[146:147], v[56:59], off offset:512
	global_load_dwordx4 v[208:211], v[166:167], off offset:576
	global_load_dwordx4 v[216:219], v[168:169], off offset:576
	v_pk_add_f32 v[64:65], v[70:71], 0 op_sel_hi:[1,0]
	v_pk_add_f32 v[66:67], v[68:69], 0 op_sel_hi:[1,0]
	s_waitcnt vmcnt(20)
	v_pk_fma_f32 v[58:59], v[64:65], v[206:207], v[186:187]
	v_pk_fma_f32 v[56:57], v[66:67], v[204:205], v[184:185]
	global_store_dwordx4 v[164:165], v[56:59], off offset:512
	global_load_dwordx4 v[184:187], v[162:163], off offset:576
	s_waitcnt vmcnt(20)
	v_pk_fma_f32 v[58:59], v[62:63], v[206:207], v[214:215]
	v_pk_fma_f32 v[56:57], v[60:61], v[204:205], v[212:213]
	global_store_dwordx4 v[166:167], v[56:59], off offset:512
	global_load_dwordx4 v[212:215], v[172:173], off offset:576
	s_waitcnt vmcnt(21)
	v_pk_fma_f32 v[54:55], v[54:55], v[206:207], v[222:223]
	v_pk_fma_f32 v[52:53], v[52:53], v[204:205], v[220:221]
	global_store_dwordx4 v[168:169], v[52:55], off offset:512
	global_load_dwordx4 v[220:223], v[176:177], off offset:576
	s_waitcnt vmcnt(21)
	v_pk_fma_f32 v[34:35], v[34:35], v[206:207], v[226:227]
	v_pk_fma_f32 v[32:33], v[32:33], v[204:205], v[224:225]
	global_store_dwordx4 v[162:163], v[32:35], off offset:512
	global_load_dwordx4 v[224:227], v[180:181], off offset:576
	s_waitcnt vmcnt(21)
	v_pk_fma_f32 v[26:27], v[26:27], v[206:207], v[230:231]
	v_pk_fma_f32 v[24:25], v[24:25], v[204:205], v[228:229]
	global_store_dwordx4 v[172:173], v[24:27], off offset:512
	s_waitcnt vmcnt(20)
	v_pk_fma_f32 v[22:23], v[22:23], v[206:207], v[234:235]
	v_pk_fma_f32 v[20:21], v[20:21], v[204:205], v[232:233]
	global_store_dwordx4 v[176:177], v[20:23], off offset:512
	v_pk_add_f32 v[24:25], v[50:51], 0 op_sel_hi:[1,0]
	v_pk_add_f32 v[26:27], v[48:49], 0 op_sel_hi:[1,0]
	s_waitcnt vmcnt(19)
	v_pk_fma_f32 v[18:19], v[18:19], v[206:207], v[190:191]
	v_pk_fma_f32 v[16:17], v[16:17], v[204:205], v[188:189]
	global_store_dwordx4 v[180:181], v[16:19], off offset:512
	s_waitcnt vmcnt(16)
	v_pk_fma_f32 v[22:23], v[24:25], v[194:195], v[198:199]
	v_pk_fma_f32 v[20:21], v[26:27], v[192:193], v[196:197]
	global_store_dwordx4 v[146:147], v[20:23], off offset:576
	v_pk_add_f32 v[24:25], v[42:43], 0 op_sel_hi:[1,0]
	v_pk_add_f32 v[26:27], v[40:41], 0 op_sel_hi:[1,0]
	s_waitcnt vmcnt(15)
	v_pk_fma_f32 v[22:23], v[24:25], v[194:195], v[202:203]
	v_pk_fma_f32 v[20:21], v[26:27], v[192:193], v[200:201]
	global_store_dwordx4 v[164:165], v[20:23], off offset:576
	v_pk_add_f32 v[24:25], v[38:39], 0 op_sel_hi:[1,0]
	v_pk_add_f32 v[26:27], v[36:37], 0 op_sel_hi:[1,0]
	s_waitcnt vmcnt(14)
	v_pk_fma_f32 v[22:23], v[24:25], v[194:195], v[210:211]
	v_pk_fma_f32 v[20:21], v[26:27], v[192:193], v[208:209]
	global_store_dwordx4 v[166:167], v[20:23], off offset:576
	v_pk_add_f32 v[24:25], v[30:31], 0 op_sel_hi:[1,0]
	v_pk_add_f32 v[26:27], v[28:29], 0 op_sel_hi:[1,0]
	s_waitcnt vmcnt(14)
	v_pk_fma_f32 v[22:23], v[24:25], v[194:195], v[218:219]
	v_pk_fma_f32 v[20:21], v[26:27], v[192:193], v[216:217]
	global_store_dwordx4 v[168:169], v[20:23], off offset:576
	s_waitcnt vmcnt(13)
	v_pk_fma_f32 v[14:15], v[14:15], v[194:195], v[186:187]
	v_pk_fma_f32 v[12:13], v[12:13], v[192:193], v[184:185]
	global_store_dwordx4 v[162:163], v[12:15], off offset:576
	s_waitcnt vmcnt(12)
	v_pk_fma_f32 v[10:11], v[10:11], v[194:195], v[214:215]
	v_pk_fma_f32 v[8:9], v[8:9], v[192:193], v[212:213]
	global_store_dwordx4 v[172:173], v[8:11], off offset:576
	s_waitcnt vmcnt(11)
	v_pk_fma_f32 v[6:7], v[6:7], v[194:195], v[222:223]
	v_pk_fma_f32 v[4:5], v[4:5], v[192:193], v[220:221]
	global_store_dwordx4 v[176:177], v[4:7], off offset:576
	s_waitcnt vmcnt(10)
	v_pk_fma_f32 v[2:3], v[2:3], v[194:195], v[226:227]
	v_pk_fma_f32 v[0:1], v[0:1], v[192:193], v[224:225]
	global_store_dwordx4 v[180:181], v[0:3], off offset:576
	s_cbranch_vccz .LBB0_2070
	s_waitcnt vmcnt(0)
	s_cmpk_gt_u32 s1, 0xff
	s_cbranch_scc1 .LBB0_2085
	s_barrier

.LBB0_2097:
	ds_read_b128 v[144:147], v139
	ds_read_b128 v[148:151], v139 offset:1024
	ds_read_b128 v[152:155], v139 offset:2048
	ds_read_b128 v[156:159], v139 offset:3072
	s_add_u32 s20, s18, 0x100
	s_addc_u32 s21, s19, 0
	s_cmp_eq_u32 s61, 4
	s_cselect_b32 s25, s17, s21
	s_cselect_b32 s24, s16, s20
	s_cselect_b32 s23, s11, s60
	s_cselect_b32 s22, s10, s47
	s_mov_b32 m0, s35
	v_lshl_add_u64 v[192:193], s[18:19], 0, v[132:133]
	ds_read_b128 v[160:163], v140
	ds_read_b128 v[164:167], v140 offset:1024
	ds_read_b128 v[168:171], v140 offset:2048
	ds_read_b128 v[172:175], v140 offset:3072
	ds_read_b128 v[176:179], v140 offset:4096
	ds_read_b128 v[180:183], v140 offset:5120
	ds_read_b128 v[184:187], v140 offset:6144
	ds_read_b128 v[188:191], v140 offset:7168
	global_load_lds_dwordx4 v[192:193], off
	s_mov_b32 m0, s36
	s_nop 0
	global_load_lds_dwordx4 v134, s[18:19]
	s_waitcnt lgkmcnt(8)
	s_barrier
	s_waitcnt lgkmcnt(0)
	s_waitcnt lgkmcnt(0)
	v_mfma_f32_16x16x32_bf16 v[124:127], v[144:147], v[160:163], v[124:127]
	v_mfma_f32_16x16x32_bf16 v[120:123], v[152:155], v[160:163], v[120:123]
	v_mfma_f32_16x16x32_bf16 v[116:119], v[144:147], v[168:171], v[116:119]
	v_mfma_f32_16x16x32_bf16 v[112:115], v[152:155], v[168:171], v[112:115]
	v_mfma_f32_16x16x32_bf16 v[100:103], v[144:147], v[176:179], v[100:103]
	v_mfma_f32_16x16x32_bf16 v[96:99], v[152:155], v[176:179], v[96:99]
	v_mfma_f32_16x16x32_bf16 v[84:87], v[144:147], v[184:187], v[84:87]
	v_mfma_f32_16x16x32_bf16 v[80:83], v[152:155], v[184:187], v[80:83]
	v_mfma_f32_16x16x32_bf16 v[124:127], v[148:151], v[164:167], v[124:127]
	v_mfma_f32_16x16x32_bf16 v[120:123], v[156:159], v[164:167], v[120:123]
	v_mfma_f32_16x16x32_bf16 v[116:119], v[148:151], v[172:175], v[116:119]
	v_mfma_f32_16x16x32_bf16 v[112:115], v[156:159], v[172:175], v[112:115]
	v_mfma_f32_16x16x32_bf16 v[100:103], v[148:151], v[180:183], v[100:103]
	v_mfma_f32_16x16x32_bf16 v[96:99], v[156:159], v[180:183], v[96:99]
	v_mfma_f32_16x16x32_bf16 v[84:87], v[148:151], v[188:191], v[84:87]
	v_mfma_f32_16x16x32_bf16 v[80:83], v[156:159], v[188:191], v[80:83]
	s_barrier
	s_mov_b32 m0, s37
	ds_read_b128 v[192:195], v141
	ds_read_b128 v[196:199], v141 offset:1024
	ds_read_b128 v[200:203], v141 offset:2048
	ds_read_b128 v[204:207], v141 offset:3072
	global_load_lds_dwordx4 v130, s[22:23]
	s_mov_b32 m0, s38
	s_nop 0
	global_load_lds_dwordx4 v128, s[22:23]
	s_barrier
	s_waitcnt lgkmcnt(0)
	s_waitcnt lgkmcnt(0)
	v_mfma_f32_16x16x32_bf16 v[108:111], v[192:195], v[160:163], v[108:111]
	v_mfma_f32_16x16x32_bf16 v[104:107], v[200:203], v[160:163], v[104:107]
	v_mfma_f32_16x16x32_bf16 v[92:95], v[192:195], v[168:171], v[92:95]
	v_mfma_f32_16x16x32_bf16 v[88:91], v[200:203], v[168:171], v[88:91]
	v_mfma_f32_16x16x32_bf16 v[76:79], v[192:195], v[176:179], v[76:79]
	v_mfma_f32_16x16x32_bf16 v[72:75], v[200:203], v[176:179], v[72:75]
	v_mfma_f32_16x16x32_bf16 v[68:71], v[192:195], v[184:187], v[68:71]
	v_mfma_f32_16x16x32_bf16 v[64:67], v[200:203], v[184:187], v[64:67]
	v_mfma_f32_16x16x32_bf16 v[108:111], v[196:199], v[164:167], v[108:111]
	v_mfma_f32_16x16x32_bf16 v[104:107], v[204:207], v[164:167], v[104:107]
	v_mfma_f32_16x16x32_bf16 v[92:95], v[196:199], v[172:175], v[92:95]
	v_mfma_f32_16x16x32_bf16 v[88:91], v[204:207], v[172:175], v[88:91]
	v_mfma_f32_16x16x32_bf16 v[76:79], v[196:199], v[180:183], v[76:79]
	v_mfma_f32_16x16x32_bf16 v[72:75], v[204:207], v[180:183], v[72:75]
	v_mfma_f32_16x16x32_bf16 v[68:71], v[196:199], v[188:191], v[68:71]
	v_mfma_f32_16x16x32_bf16 v[64:67], v[204:207], v[188:191], v[64:67]
	s_mov_b32 m0, s3
	v_lshl_add_u64 v[212:213], s[24:25], 0, v[130:131]
	s_barrier
	ds_read_b128 v[160:163], v140 offset:16384
	ds_read_b128 v[164:167], v140 offset:17408
	ds_read_b128 v[168:171], v140 offset:18432
	ds_read_b128 v[172:175], v140 offset:19456
	ds_read_b128 v[176:179], v140 offset:20480
	ds_read_b128 v[180:183], v140 offset:21504
	ds_read_b128 v[184:187], v140 offset:22528
	ds_read_b128 v[188:191], v140 offset:23552
	global_load_lds_dwordx4 v130, s[24:25]
	v_lshl_add_u64 v[214:215], s[24:25], 0, v[128:129]
	s_mov_b32 m0, s4
	s_nop 0
	global_load_lds_dwordx4 v128, s[24:25]
	s_barrier
	s_waitcnt lgkmcnt(0)
	s_waitcnt lgkmcnt(0)
	v_mfma_f32_16x16x32_bf16 v[60:63], v[144:147], v[160:163], v[60:63]
	v_mfma_f32_16x16x32_bf16 v[56:59], v[152:155], v[160:163], v[56:59]
	v_mfma_f32_16x16x32_bf16 v[52:55], v[144:147], v[168:171], v[52:55]
	v_mfma_f32_16x16x32_bf16 v[48:51], v[152:155], v[168:171], v[48:51]
	v_mfma_f32_16x16x32_bf16 v[36:39], v[144:147], v[176:179], v[36:39]
	v_mfma_f32_16x16x32_bf16 v[32:35], v[152:155], v[176:179], v[32:35]
	v_mfma_f32_16x16x32_bf16 v[20:23], v[144:147], v[184:187], v[20:23]
	v_mfma_f32_16x16x32_bf16 v[16:19], v[152:155], v[184:187], v[16:19]
	v_mfma_f32_16x16x32_bf16 v[60:63], v[148:151], v[164:167], v[60:63]
	v_mfma_f32_16x16x32_bf16 v[56:59], v[156:159], v[164:167], v[56:59]
	v_mfma_f32_16x16x32_bf16 v[52:55], v[148:151], v[172:175], v[52:55]
	v_mfma_f32_16x16x32_bf16 v[48:51], v[156:159], v[172:175], v[48:51]
	v_mfma_f32_16x16x32_bf16 v[36:39], v[148:151], v[180:183], v[36:39]
	v_mfma_f32_16x16x32_bf16 v[32:35], v[156:159], v[180:183], v[32:35]
	v_mfma_f32_16x16x32_bf16 v[20:23], v[148:151], v[188:191], v[20:23]
	v_mfma_f32_16x16x32_bf16 v[16:19], v[156:159], v[188:191], v[16:19]
	s_barrier
	s_add_u32 s18, s22, 0x160000
	s_addc_u32 s19, s23, 0
	s_mov_b32 m0, s39
	global_load_lds_dwordx4 v130, s[18:19]
	s_mov_b32 m0, s40
	s_nop 0
	global_load_lds_dwordx4 v128, s[18:19]
	s_waitcnt vmcnt(6)
	s_barrier
	v_mfma_f32_16x16x32_bf16 v[44:47], v[192:195], v[160:163], v[44:47]
	v_mfma_f32_16x16x32_bf16 v[40:43], v[200:203], v[160:163], v[40:43]
	v_mfma_f32_16x16x32_bf16 v[28:31], v[192:195], v[168:171], v[28:31]
	v_mfma_f32_16x16x32_bf16 v[24:27], v[200:203], v[168:171], v[24:27]
	v_mfma_f32_16x16x32_bf16 v[12:15], v[192:195], v[176:179], v[12:15]
	v_mfma_f32_16x16x32_bf16 v[8:11], v[200:203], v[176:179], v[8:11]
	v_mfma_f32_16x16x32_bf16 v[4:7], v[192:195], v[184:187], v[4:7]
	v_mfma_f32_16x16x32_bf16 v[0:3], v[200:203], v[184:187], v[0:3]
	v_mfma_f32_16x16x32_bf16 v[44:47], v[196:199], v[164:167], v[44:47]
	v_mfma_f32_16x16x32_bf16 v[40:43], v[204:207], v[164:167], v[40:43]
	v_mfma_f32_16x16x32_bf16 v[28:31], v[196:199], v[172:175], v[28:31]
	v_mfma_f32_16x16x32_bf16 v[24:27], v[204:207], v[172:175], v[24:27]
	v_mfma_f32_16x16x32_bf16 v[12:15], v[196:199], v[180:183], v[12:15]
	v_mfma_f32_16x16x32_bf16 v[8:11], v[204:207], v[180:183], v[8:11]
	v_mfma_f32_16x16x32_bf16 v[4:7], v[196:199], v[188:191], v[4:7]
	v_mfma_f32_16x16x32_bf16 v[0:3], v[204:207], v[188:191], v[0:3]
	s_barrier
	ds_read_b128 v[144:147], v142
	ds_read_b128 v[148:151], v142 offset:1024
	ds_read_b128 v[152:155], v142 offset:2048
	ds_read_b128 v[156:159], v142 offset:3072
	s_add_u32 s18, s24, 0x160000
	s_addc_u32 s19, s25, 0
	s_mov_b32 m0, s5
	ds_read_b128 v[160:163], v140 offset:32768
	ds_read_b128 v[164:167], v140 offset:33792
	ds_read_b128 v[168:171], v140 offset:34816
	ds_read_b128 v[172:175], v140 offset:35840
	ds_read_b128 v[176:179], v140 offset:36864
	ds_read_b128 v[180:183], v140 offset:37888
	ds_read_b128 v[184:187], v140 offset:38912
	ds_read_b128 v[188:191], v140 offset:39936
	global_load_lds_dwordx4 v130, s[18:19]
	s_mov_b32 m0, s26
	s_nop 0
	global_load_lds_dwordx4 v128, s[18:19]
	s_waitcnt lgkmcnt(8)
	s_barrier
	s_waitcnt lgkmcnt(0)
	s_waitcnt lgkmcnt(0)
	v_mfma_f32_16x16x32_bf16 v[124:127], v[144:147], v[160:163], v[124:127]
	v_mfma_f32_16x16x32_bf16 v[120:123], v[152:155], v[160:163], v[120:123]
	v_mfma_f32_16x16x32_bf16 v[116:119], v[144:147], v[168:171], v[116:119]
	v_mfma_f32_16x16x32_bf16 v[112:115], v[152:155], v[168:171], v[112:115]
	v_mfma_f32_16x16x32_bf16 v[100:103], v[144:147], v[176:179], v[100:103]
	v_mfma_f32_16x16x32_bf16 v[96:99], v[152:155], v[176:179], v[96:99]
	v_mfma_f32_16x16x32_bf16 v[84:87], v[144:147], v[184:187], v[84:87]
	v_mfma_f32_16x16x32_bf16 v[80:83], v[152:155], v[184:187], v[80:83]
	v_mfma_f32_16x16x32_bf16 v[124:127], v[148:151], v[164:167], v[124:127]
	v_mfma_f32_16x16x32_bf16 v[120:123], v[156:159], v[164:167], v[120:123]
	v_mfma_f32_16x16x32_bf16 v[116:119], v[148:151], v[172:175], v[116:119]
	v_mfma_f32_16x16x32_bf16 v[112:115], v[156:159], v[172:175], v[112:115]
	v_mfma_f32_16x16x32_bf16 v[100:103], v[148:151], v[180:183], v[100:103]
	v_mfma_f32_16x16x32_bf16 v[96:99], v[156:159], v[180:183], v[96:99]
	v_mfma_f32_16x16x32_bf16 v[84:87], v[148:151], v[188:191], v[84:87]
	v_mfma_f32_16x16x32_bf16 v[80:83], v[156:159], v[188:191], v[80:83]
	s_barrier
	s_add_i32 s24, 0, 0x1c000
	s_add_i32 s18, s41, s2
	v_add_u32_e32 v143, s24, v137
	s_add_u32 s98, s22, s12
	s_addc_u32 s99, s23, s13
	s_mov_b32 m0, s18
	ds_read_b128 v[192:195], v143
	ds_read_b128 v[196:199], v143 offset:1024
	ds_read_b128 v[200:203], v143 offset:2048
	ds_read_b128 v[204:207], v143 offset:3072
	global_load_lds_dwordx4 v130, s[98:99]
	s_add_i32 m0, s18, 0x2000
	s_nop 0
	global_load_lds_dwordx4 v128, s[98:99]
	s_barrier
	s_waitcnt lgkmcnt(0)
	s_waitcnt lgkmcnt(0)
	v_mfma_f32_16x16x32_bf16 v[108:111], v[192:195], v[160:163], v[108:111]
	v_mfma_f32_16x16x32_bf16 v[104:107], v[200:203], v[160:163], v[104:107]
	v_mfma_f32_16x16x32_bf16 v[92:95], v[192:195], v[168:171], v[92:95]
	v_mfma_f32_16x16x32_bf16 v[88:91], v[200:203], v[168:171], v[88:91]
	v_mfma_f32_16x16x32_bf16 v[76:79], v[192:195], v[176:179], v[76:79]
	v_mfma_f32_16x16x32_bf16 v[72:75], v[200:203], v[176:179], v[72:75]
	v_mfma_f32_16x16x32_bf16 v[68:71], v[192:195], v[184:187], v[68:71]
	v_mfma_f32_16x16x32_bf16 v[64:67], v[200:203], v[184:187], v[64:67]
	v_mfma_f32_16x16x32_bf16 v[108:111], v[196:199], v[164:167], v[108:111]
	v_mfma_f32_16x16x32_bf16 v[104:107], v[204:207], v[164:167], v[104:107]
	v_mfma_f32_16x16x32_bf16 v[92:95], v[196:199], v[172:175], v[92:95]
	v_mfma_f32_16x16x32_bf16 v[88:91], v[204:207], v[172:175], v[88:91]
	v_mfma_f32_16x16x32_bf16 v[76:79], v[196:199], v[180:183], v[76:79]
	v_mfma_f32_16x16x32_bf16 v[72:75], v[204:207], v[180:183], v[72:75]
	v_mfma_f32_16x16x32_bf16 v[68:71], v[196:199], v[188:191], v[68:71]
	v_mfma_f32_16x16x32_bf16 v[64:67], v[204:207], v[188:191], v[64:67]
	s_mov_b32 m0, s31
	v_lshl_add_u64 v[208:209], v[212:213], 0, s[12:13]
	s_barrier
	ds_read_b128 v[160:163], v140 offset:49152
	ds_read_b128 v[164:167], v140 offset:50176
	ds_read_b128 v[168:171], v140 offset:51200
	ds_read_b128 v[172:175], v140 offset:52224
	ds_read_b128 v[176:179], v140 offset:53248
	ds_read_b128 v[180:183], v140 offset:54272
	ds_read_b128 v[184:187], v140 offset:55296
	ds_read_b128 v[188:191], v140 offset:56320
	global_load_lds_dwordx4 v[208:209], off
	v_lshl_add_u64 v[208:209], v[214:215], 0, s[12:13]
	s_mov_b32 m0, s34
	s_nop 0
	global_load_lds_dwordx4 v[208:209], off
	s_barrier
	s_waitcnt lgkmcnt(0)
	s_waitcnt lgkmcnt(0)
	v_mfma_f32_16x16x32_bf16 v[60:63], v[144:147], v[160:163], v[60:63]
	v_mfma_f32_16x16x32_bf16 v[56:59], v[152:155], v[160:163], v[56:59]
	v_mfma_f32_16x16x32_bf16 v[52:55], v[144:147], v[168:171], v[52:55]
	v_mfma_f32_16x16x32_bf16 v[48:51], v[152:155], v[168:171], v[48:51]
	v_mfma_f32_16x16x32_bf16 v[36:39], v[144:147], v[176:179], v[36:39]
	v_mfma_f32_16x16x32_bf16 v[32:35], v[152:155], v[176:179], v[32:35]
	v_mfma_f32_16x16x32_bf16 v[20:23], v[144:147], v[184:187], v[20:23]
	v_mfma_f32_16x16x32_bf16 v[16:19], v[152:155], v[184:187], v[16:19]
	v_mfma_f32_16x16x32_bf16 v[60:63], v[148:151], v[164:167], v[60:63]
	v_mfma_f32_16x16x32_bf16 v[56:59], v[156:159], v[164:167], v[56:59]
	v_mfma_f32_16x16x32_bf16 v[52:55], v[148:151], v[172:175], v[52:55]
	v_mfma_f32_16x16x32_bf16 v[48:51], v[156:159], v[172:175], v[48:51]
	v_mfma_f32_16x16x32_bf16 v[36:39], v[148:151], v[180:183], v[36:39]
	v_mfma_f32_16x16x32_bf16 v[32:35], v[156:159], v[180:183], v[32:35]
	v_mfma_f32_16x16x32_bf16 v[20:23], v[148:151], v[188:191], v[20:23]
	v_mfma_f32_16x16x32_bf16 v[16:19], v[156:159], v[188:191], v[16:19]
	s_barrier
	s_add_u32 s18, s22, 0x160080
	s_addc_u32 s19, s23, 0
	s_add_i32 s22, s24, s2
	s_mov_b32 m0, s22
	s_nop 0
	global_load_lds_dwordx4 v130, s[18:19]
	s_add_i32 m0, s22, 0x2000
	s_nop 0
	global_load_lds_dwordx4 v128, s[18:19]
	s_waitcnt vmcnt(6)
	s_barrier
	v_mfma_f32_16x16x32_bf16 v[44:47], v[192:195], v[160:163], v[44:47]
	v_mfma_f32_16x16x32_bf16 v[40:43], v[200:203], v[160:163], v[40:43]
	v_mfma_f32_16x16x32_bf16 v[28:31], v[192:195], v[168:171], v[28:31]
	v_mfma_f32_16x16x32_bf16 v[24:27], v[200:203], v[168:171], v[24:27]
	v_mfma_f32_16x16x32_bf16 v[12:15], v[192:195], v[176:179], v[12:15]
	v_mfma_f32_16x16x32_bf16 v[8:11], v[200:203], v[176:179], v[8:11]
	v_mfma_f32_16x16x32_bf16 v[4:7], v[192:195], v[184:187], v[4:7]
	v_mfma_f32_16x16x32_bf16 v[0:3], v[200:203], v[184:187], v[0:3]
	v_mfma_f32_16x16x32_bf16 v[44:47], v[196:199], v[164:167], v[44:47]
	v_mfma_f32_16x16x32_bf16 v[40:43], v[204:207], v[164:167], v[40:43]
	v_mfma_f32_16x16x32_bf16 v[28:31], v[196:199], v[172:175], v[28:31]
	v_mfma_f32_16x16x32_bf16 v[24:27], v[204:207], v[172:175], v[24:27]
	v_mfma_f32_16x16x32_bf16 v[12:15], v[196:199], v[180:183], v[12:15]
	v_mfma_f32_16x16x32_bf16 v[8:11], v[204:207], v[180:183], v[8:11]
	v_mfma_f32_16x16x32_bf16 v[4:7], v[196:199], v[188:191], v[4:7]
	v_mfma_f32_16x16x32_bf16 v[0:3], v[204:207], v[188:191], v[0:3]
	s_add_i32 s61, s61, 2
	s_add_u32 s47, s47, 0x100
	s_addc_u32 s60, s60, 0
	s_cmp_gt_u32 s61, 5
	s_mov_b64 s[18:19], s[20:21]
	s_barrier
	s_cbranch_scc0 .LBB0_2097
	s_ashr_i32 s18, s30, 1
	s_and_b32 s18, s18, 0xfffffe00
	s_lshl_b32 s19, s29, 8
	s_add_i32 s19, s19, s18
	v_add_u32_e32 v146, s19, v136
	v_lshl_or_b32 v144, s28, 8, v138
	v_ashrrev_i32_e32 v147, 31, v146
	v_readlane_b32 s52, v240, 22
	v_ashrrev_i32_e32 v145, 31, v144
	v_lshlrev_b64 v[148:149], 13, v[146:147]
	v_readlane_b32 s66, v240, 36
	v_readlane_b32 s67, v240, 37
	v_lshlrev_b64 v[144:145], 2, v[144:145]
	s_mov_b64 s[18:19], 0x100000
	v_lshl_add_u64 v[148:149], s[66:67], 0, v[148:149]
	v_lshl_add_u64 v[148:149], v[148:149], 0, v[144:145]
	global_store_dwordx4 v[148:149], v[124:127], off
	global_store_dwordx4 v[148:149], v[120:123], off offset:64
	global_store_dwordx4 v[148:149], v[108:111], off offset:512
	global_store_dwordx4 v[148:149], v[104:107], off offset:576
	v_readlane_b32 s53, v240, 23
	v_readlane_b32 s56, v240, 26
	v_or_b32_e32 v104, 16, v146
	v_ashrrev_i32_e32 v105, 31, v104
	v_lshlrev_b64 v[104:105], 13, v[104:105]
	v_lshl_add_u64 v[104:105], s[66:67], 0, v[104:105]
	v_lshl_add_u64 v[104:105], v[104:105], 0, v[144:145]
	global_store_dwordx4 v[104:105], v[116:119], off
	global_store_dwordx4 v[104:105], v[112:115], off offset:64
	global_store_dwordx4 v[104:105], v[92:95], off offset:512
	global_store_dwordx4 v[104:105], v[88:91], off offset:576
	v_readlane_b32 s57, v240, 27
	v_readlane_b32 s60, v240, 30
	v_or_b32_e32 v88, 32, v146
	v_ashrrev_i32_e32 v89, 31, v88
	v_lshlrev_b64 v[88:89], 13, v[88:89]
	v_lshl_add_u64 v[88:89], s[66:67], 0, v[88:89]
	v_lshl_add_u64 v[88:89], v[88:89], 0, v[144:145]
	global_store_dwordx4 v[88:89], v[100:103], off
	global_store_dwordx4 v[88:89], v[96:99], off offset:64
	global_store_dwordx4 v[88:89], v[76:79], off offset:512
	global_store_dwordx4 v[88:89], v[72:75], off offset:576
	v_readlane_b32 s61, v240, 31
	v_readlane_b32 s62, v240, 32
	v_or_b32_e32 v72, 48, v146
	v_ashrrev_i32_e32 v73, 31, v72
	v_lshlrev_b64 v[72:73], 13, v[72:73]
	v_lshl_add_u64 v[72:73], s[66:67], 0, v[72:73]
	v_lshl_add_u64 v[72:73], v[72:73], 0, v[144:145]
	global_store_dwordx4 v[72:73], v[84:87], off
	global_store_dwordx4 v[72:73], v[80:83], off offset:64
	global_store_dwordx4 v[72:73], v[68:71], off offset:512
	global_store_dwordx4 v[72:73], v[64:67], off offset:576
	v_readlane_b32 s63, v240, 33
	s_mov_b32 s30, s43
	v_lshl_add_u64 v[64:65], v[148:149], 0, s[18:19]
	s_mov_b32 s18, 0x100000
	v_add_co_u32_e32 v66, vcc, s18, v148
	s_mov_b64 s[18:19], 0x120000
	s_nop 0
	v_addc_co_u32_e32 v67, vcc, 0, v149, vcc
	global_store_dwordx4 v[66:67], v[60:63], off
	global_store_dwordx4 v[64:65], v[56:59], off offset:64
	global_store_dwordx4 v[64:65], v[44:47], off offset:512
	global_store_dwordx4 v[64:65], v[40:43], off offset:576
	s_mov_b32 s28, s42
	s_mov_b32 s29, s46
	v_lshl_add_u64 v[40:41], v[148:149], 0, s[18:19]
	s_mov_b32 s18, 0x120000
	v_add_co_u32_e32 v42, vcc, s18, v148
	s_mov_b64 s[18:19], 0x140000
	s_nop 0
	v_addc_co_u32_e32 v43, vcc, 0, v149, vcc
	global_store_dwordx4 v[42:43], v[52:55], off
	global_store_dwordx4 v[40:41], v[48:51], off offset:64
	global_store_dwordx4 v[40:41], v[28:31], off offset:512
	global_store_dwordx4 v[40:41], v[24:27], off offset:576
	s_mov_b64 s[20:21], s[10:11]
	v_readlane_b32 s54, v240, 24
	v_lshl_add_u64 v[24:25], v[148:149], 0, s[18:19]
	s_mov_b32 s18, 0x140000
	v_add_co_u32_e32 v26, vcc, s18, v148
	s_mov_b64 s[18:19], 0x160000
	s_nop 0
	v_addc_co_u32_e32 v27, vcc, 0, v149, vcc
	global_store_dwordx4 v[26:27], v[36:39], off
	global_store_dwordx4 v[24:25], v[32:35], off offset:64
	global_store_dwordx4 v[24:25], v[12:15], off offset:512
	global_store_dwordx4 v[24:25], v[8:11], off offset:576
	v_readlane_b32 s55, v240, 25
	v_readlane_b32 s58, v240, 28
	v_add_co_u32_e32 v10, vcc, 0x160000, v148
	v_lshl_add_u64 v[8:9], v[148:149], 0, s[18:19]
	s_nop 0
	v_addc_co_u32_e32 v11, vcc, 0, v149, vcc
	s_and_b64 vcc, exec, s[14:15]
	s_mov_b64 s[18:19], s[16:17]
	v_readlane_b32 s59, v240, 29
	v_readlane_b32 s64, v240, 34
	v_readlane_b32 s65, v240, 35
	global_store_dwordx4 v[10:11], v[20:23], off
	global_store_dwordx4 v[8:9], v[16:19], off offset:64
	global_store_dwordx4 v[8:9], v[4:7], off offset:512
	global_store_dwordx4 v[8:9], v[0:3], off offset:576
	s_cbranch_vccz .LBB0_2090
	s_waitcnt vmcnt(0)
	s_cmpk_gt_u32 s1, 0xff
	s_cbranch_scc1 .LBB0_2101
	s_barrier

.LBB0_2281:
	ds_read_b128 v[140:143], v157
	ds_read_b128 v[144:147], v157 offset:1024
	ds_read_b128 v[148:151], v157 offset:2048
	ds_read_b128 v[160:163], v157 offset:3072
	s_add_u32 s30, s28, 0x100
	s_addc_u32 s31, s29, 0
	s_cmp_eq_u32 s69, 28
	s_cselect_b32 s37, s19, s31
	s_cselect_b32 s36, s65, s30
	s_cselect_b32 s35, s17, s68
	s_cselect_b32 s34, s66, s67
	v_lshl_add_u64 v[152:153], s[28:29], 0, v[132:133]
	s_add_i32 m0, s4, 0xc000
	ds_read_b128 v[164:167], v158
	ds_read_b128 v[168:171], v158 offset:1024
	ds_read_b128 v[172:175], v158 offset:2048
	ds_read_b128 v[176:179], v158 offset:3072
	ds_read_b128 v[180:183], v158 offset:4096
	ds_read_b128 v[184:187], v158 offset:5120
	ds_read_b128 v[188:191], v158 offset:6144
	ds_read_b128 v[192:195], v158 offset:7168
	global_load_lds_dwordx4 v[152:153], off
	s_add_i32 m0, s4, 0xe000
	s_nop 0
	global_load_lds_dwordx4 v134, s[28:29]
	s_waitcnt lgkmcnt(8)
	s_barrier
	s_waitcnt lgkmcnt(0)
	s_waitcnt lgkmcnt(0)
	v_mfma_f32_16x16x32_bf16 v[124:127], v[140:143], v[164:167], v[124:127]
	v_mfma_f32_16x16x32_bf16 v[120:123], v[148:151], v[164:167], v[120:123]
	v_mfma_f32_16x16x32_bf16 v[116:119], v[140:143], v[172:175], v[116:119]
	v_mfma_f32_16x16x32_bf16 v[108:111], v[148:151], v[172:175], v[108:111]
	v_mfma_f32_16x16x32_bf16 v[100:103], v[140:143], v[180:183], v[100:103]
	v_mfma_f32_16x16x32_bf16 v[92:95], v[148:151], v[180:183], v[92:95]
	v_mfma_f32_16x16x32_bf16 v[84:87], v[140:143], v[188:191], v[84:87]
	v_mfma_f32_16x16x32_bf16 v[76:79], v[148:151], v[188:191], v[76:79]
	v_mfma_f32_16x16x32_bf16 v[124:127], v[144:147], v[168:171], v[124:127]
	v_mfma_f32_16x16x32_bf16 v[120:123], v[160:163], v[168:171], v[120:123]
	v_mfma_f32_16x16x32_bf16 v[116:119], v[144:147], v[176:179], v[116:119]
	v_mfma_f32_16x16x32_bf16 v[108:111], v[160:163], v[176:179], v[108:111]
	v_mfma_f32_16x16x32_bf16 v[100:103], v[144:147], v[184:187], v[100:103]
	v_mfma_f32_16x16x32_bf16 v[92:95], v[160:163], v[184:187], v[92:95]
	v_mfma_f32_16x16x32_bf16 v[84:87], v[144:147], v[192:195], v[84:87]
	v_mfma_f32_16x16x32_bf16 v[76:79], v[160:163], v[192:195], v[76:79]
	s_barrier
	s_add_i32 s28, s47, s3
	s_mov_b32 m0, s28
	ds_read_b128 v[196:199], v159
	ds_read_b128 v[200:203], v159 offset:1024
	ds_read_b128 v[204:207], v159 offset:2048
	ds_read_b128 v[208:211], v159 offset:3072
	global_load_lds_dwordx4 v128, s[34:35]
	s_add_i32 m0, s28, 0x2000
	s_nop 0
	global_load_lds_dwordx4 v130, s[34:35]
	s_barrier
	s_waitcnt lgkmcnt(0)
	s_waitcnt lgkmcnt(0)
	v_mfma_f32_16x16x32_bf16 v[112:115], v[196:199], v[164:167], v[112:115]
	v_mfma_f32_16x16x32_bf16 v[104:107], v[204:207], v[164:167], v[104:107]
	v_mfma_f32_16x16x32_bf16 v[96:99], v[196:199], v[172:175], v[96:99]
	v_mfma_f32_16x16x32_bf16 v[88:91], v[204:207], v[172:175], v[88:91]
	v_mfma_f32_16x16x32_bf16 v[80:83], v[196:199], v[180:183], v[80:83]
	v_mfma_f32_16x16x32_bf16 v[72:75], v[204:207], v[180:183], v[72:75]
	v_mfma_f32_16x16x32_bf16 v[68:71], v[196:199], v[188:191], v[68:71]
	v_mfma_f32_16x16x32_bf16 v[64:67], v[204:207], v[188:191], v[64:67]
	v_mfma_f32_16x16x32_bf16 v[112:115], v[200:203], v[168:171], v[112:115]
	v_mfma_f32_16x16x32_bf16 v[104:107], v[208:211], v[168:171], v[104:107]
	v_mfma_f32_16x16x32_bf16 v[96:99], v[200:203], v[176:179], v[96:99]
	v_mfma_f32_16x16x32_bf16 v[88:91], v[208:211], v[176:179], v[88:91]
	v_mfma_f32_16x16x32_bf16 v[80:83], v[200:203], v[184:187], v[80:83]
	v_mfma_f32_16x16x32_bf16 v[72:75], v[208:211], v[184:187], v[72:75]
	v_mfma_f32_16x16x32_bf16 v[68:71], v[200:203], v[192:195], v[68:71]
	v_mfma_f32_16x16x32_bf16 v[64:67], v[208:211], v[192:195], v[64:67]
	s_mov_b32 m0, s4
	v_lshl_add_u64 v[214:215], s[36:37], 0, v[128:129]
	s_barrier
	ds_read_b128 v[164:167], v158 offset:16384
	ds_read_b128 v[168:171], v158 offset:17408
	ds_read_b128 v[172:175], v158 offset:18432
	ds_read_b128 v[176:179], v158 offset:19456
	ds_read_b128 v[180:183], v158 offset:20480
	ds_read_b128 v[184:187], v158 offset:21504
	ds_read_b128 v[188:191], v158 offset:22528
	ds_read_b128 v[192:195], v158 offset:23552
	global_load_lds_dwordx4 v128, s[36:37]
	v_lshl_add_u64 v[216:217], s[36:37], 0, v[130:131]
	s_mov_b32 m0, s5
	s_nop 0
	global_load_lds_dwordx4 v130, s[36:37]
	s_barrier
	s_waitcnt lgkmcnt(0)
	s_waitcnt lgkmcnt(0)
	v_mfma_f32_16x16x32_bf16 v[60:63], v[140:143], v[164:167], v[60:63]
	v_mfma_f32_16x16x32_bf16 v[56:59], v[148:151], v[164:167], v[56:59]
	v_mfma_f32_16x16x32_bf16 v[52:55], v[140:143], v[172:175], v[52:55]
	v_mfma_f32_16x16x32_bf16 v[48:51], v[148:151], v[172:175], v[48:51]
	v_mfma_f32_16x16x32_bf16 v[40:43], v[140:143], v[180:183], v[40:43]
	v_mfma_f32_16x16x32_bf16 v[32:35], v[148:151], v[180:183], v[32:35]
	v_mfma_f32_16x16x32_bf16 v[24:27], v[140:143], v[188:191], v[24:27]
	v_mfma_f32_16x16x32_bf16 v[16:19], v[148:151], v[188:191], v[16:19]
	v_mfma_f32_16x16x32_bf16 v[60:63], v[144:147], v[168:171], v[60:63]
	v_mfma_f32_16x16x32_bf16 v[56:59], v[160:163], v[168:171], v[56:59]
	v_mfma_f32_16x16x32_bf16 v[52:55], v[144:147], v[176:179], v[52:55]
	v_mfma_f32_16x16x32_bf16 v[48:51], v[160:163], v[176:179], v[48:51]
	v_mfma_f32_16x16x32_bf16 v[40:43], v[144:147], v[184:187], v[40:43]
	v_mfma_f32_16x16x32_bf16 v[32:35], v[160:163], v[184:187], v[32:35]
	v_mfma_f32_16x16x32_bf16 v[24:27], v[144:147], v[192:195], v[24:27]
	v_mfma_f32_16x16x32_bf16 v[16:19], v[160:163], v[192:195], v[16:19]
	s_barrier
	s_add_u32 s28, s34, 0x80000
	s_addc_u32 s29, s35, 0
	s_add_i32 s70, s62, s3
	s_mov_b32 m0, s70
	s_nop 0
	global_load_lds_dwordx4 v128, s[28:29]
	s_add_i32 m0, s70, 0x2000
	s_nop 0
	global_load_lds_dwordx4 v130, s[28:29]
	s_waitcnt vmcnt(6)
	s_barrier
	v_mfma_f32_16x16x32_bf16 v[44:47], v[196:199], v[164:167], v[44:47]
	v_mfma_f32_16x16x32_bf16 v[36:39], v[204:207], v[164:167], v[36:39]
	v_mfma_f32_16x16x32_bf16 v[28:31], v[196:199], v[172:175], v[28:31]
	v_mfma_f32_16x16x32_bf16 v[20:23], v[204:207], v[172:175], v[20:23]
	v_mfma_f32_16x16x32_bf16 v[12:15], v[196:199], v[180:183], v[12:15]
	v_mfma_f32_16x16x32_bf16 v[8:11], v[204:207], v[180:183], v[8:11]
	v_mfma_f32_16x16x32_bf16 v[4:7], v[196:199], v[188:191], v[4:7]
	v_mfma_f32_16x16x32_bf16 v[0:3], v[204:207], v[188:191], v[0:3]
	v_mfma_f32_16x16x32_bf16 v[44:47], v[200:203], v[168:171], v[44:47]
	v_mfma_f32_16x16x32_bf16 v[36:39], v[208:211], v[168:171], v[36:39]
	v_mfma_f32_16x16x32_bf16 v[28:31], v[200:203], v[176:179], v[28:31]
	v_mfma_f32_16x16x32_bf16 v[20:23], v[208:211], v[176:179], v[20:23]
	v_mfma_f32_16x16x32_bf16 v[12:15], v[200:203], v[184:187], v[12:15]
	v_mfma_f32_16x16x32_bf16 v[8:11], v[208:211], v[184:187], v[8:11]
	v_mfma_f32_16x16x32_bf16 v[4:7], v[200:203], v[192:195], v[4:7]
	v_mfma_f32_16x16x32_bf16 v[0:3], v[208:211], v[192:195], v[0:3]
	s_add_i32 s70, 0, 0x18000
	v_add_u32_e32 v160, s70, v155
	s_barrier
	ds_read_b128 v[140:143], v160
	ds_read_b128 v[144:147], v160 offset:1024
	ds_read_b128 v[148:151], v160 offset:2048
	ds_read_b128 v[160:163], v160 offset:3072
	s_add_u32 s28, s36, 0x80000
	s_addc_u32 s29, s37, 0
	s_mov_b32 m0, s38
	ds_read_b128 v[164:167], v158 offset:32768
	ds_read_b128 v[168:171], v158 offset:33792
	ds_read_b128 v[172:175], v158 offset:34816
	ds_read_b128 v[176:179], v158 offset:35840
	ds_read_b128 v[180:183], v158 offset:36864
	ds_read_b128 v[184:187], v158 offset:37888
	ds_read_b128 v[188:191], v158 offset:38912
	ds_read_b128 v[192:195], v158 offset:39936
	global_load_lds_dwordx4 v128, s[28:29]
	s_mov_b32 m0, s39
	s_nop 0
	global_load_lds_dwordx4 v130, s[28:29]
	s_waitcnt lgkmcnt(8)
	s_barrier
	s_waitcnt lgkmcnt(0)
	s_waitcnt lgkmcnt(0)
	v_mfma_f32_16x16x32_bf16 v[124:127], v[140:143], v[164:167], v[124:127]
	v_mfma_f32_16x16x32_bf16 v[120:123], v[148:151], v[164:167], v[120:123]
	v_mfma_f32_16x16x32_bf16 v[116:119], v[140:143], v[172:175], v[116:119]
	v_mfma_f32_16x16x32_bf16 v[108:111], v[148:151], v[172:175], v[108:111]
	v_mfma_f32_16x16x32_bf16 v[100:103], v[140:143], v[180:183], v[100:103]
	v_mfma_f32_16x16x32_bf16 v[92:95], v[148:151], v[180:183], v[92:95]
	v_mfma_f32_16x16x32_bf16 v[84:87], v[140:143], v[188:191], v[84:87]
	v_mfma_f32_16x16x32_bf16 v[76:79], v[148:151], v[188:191], v[76:79]
	v_mfma_f32_16x16x32_bf16 v[124:127], v[144:147], v[168:171], v[124:127]
	v_mfma_f32_16x16x32_bf16 v[120:123], v[160:163], v[168:171], v[120:123]
	v_mfma_f32_16x16x32_bf16 v[116:119], v[144:147], v[176:179], v[116:119]
	v_mfma_f32_16x16x32_bf16 v[108:111], v[160:163], v[176:179], v[108:111]
	v_mfma_f32_16x16x32_bf16 v[100:103], v[144:147], v[184:187], v[100:103]
	v_mfma_f32_16x16x32_bf16 v[92:95], v[160:163], v[184:187], v[92:95]
	v_mfma_f32_16x16x32_bf16 v[84:87], v[144:147], v[192:195], v[84:87]
	v_mfma_f32_16x16x32_bf16 v[76:79], v[160:163], v[192:195], v[76:79]
	s_barrier
	s_add_i32 s36, 0, 0x1c000
	s_add_i32 s28, s70, s3
	v_add_u32_e32 v208, s36, v155
	s_add_u32 s98, s34, s12
	s_addc_u32 s99, s35, s13
	s_mov_b32 m0, s28
	ds_read_b128 v[196:199], v208
	ds_read_b128 v[200:203], v208 offset:1024
	ds_read_b128 v[204:207], v208 offset:2048
	ds_read_b128 v[208:211], v208 offset:3072
	global_load_lds_dwordx4 v128, s[98:99]
	s_add_i32 m0, s28, 0x2000
	s_nop 0
	global_load_lds_dwordx4 v130, s[98:99]
	s_barrier
	s_waitcnt lgkmcnt(0)
	s_waitcnt lgkmcnt(0)
	v_mfma_f32_16x16x32_bf16 v[112:115], v[196:199], v[164:167], v[112:115]
	v_mfma_f32_16x16x32_bf16 v[104:107], v[204:207], v[164:167], v[104:107]
	v_mfma_f32_16x16x32_bf16 v[96:99], v[196:199], v[172:175], v[96:99]
	v_mfma_f32_16x16x32_bf16 v[88:91], v[204:207], v[172:175], v[88:91]
	v_mfma_f32_16x16x32_bf16 v[80:83], v[196:199], v[180:183], v[80:83]
	v_mfma_f32_16x16x32_bf16 v[72:75], v[204:207], v[180:183], v[72:75]
	v_mfma_f32_16x16x32_bf16 v[68:71], v[196:199], v[188:191], v[68:71]
	v_mfma_f32_16x16x32_bf16 v[64:67], v[204:207], v[188:191], v[64:67]
	v_mfma_f32_16x16x32_bf16 v[112:115], v[200:203], v[168:171], v[112:115]
	v_mfma_f32_16x16x32_bf16 v[104:107], v[208:211], v[168:171], v[104:107]
	v_mfma_f32_16x16x32_bf16 v[96:99], v[200:203], v[176:179], v[96:99]
	v_mfma_f32_16x16x32_bf16 v[88:91], v[208:211], v[176:179], v[88:91]
	v_mfma_f32_16x16x32_bf16 v[80:83], v[200:203], v[184:187], v[80:83]
	v_mfma_f32_16x16x32_bf16 v[72:75], v[208:211], v[184:187], v[72:75]
	v_mfma_f32_16x16x32_bf16 v[68:71], v[200:203], v[192:195], v[68:71]
	v_mfma_f32_16x16x32_bf16 v[64:67], v[208:211], v[192:195], v[64:67]
	s_mov_b32 m0, s42
	v_lshl_add_u64 v[152:153], v[214:215], 0, s[12:13]
	s_barrier
	ds_read_b128 v[164:167], v158 offset:49152
	ds_read_b128 v[168:171], v158 offset:50176
	ds_read_b128 v[172:175], v158 offset:51200
	ds_read_b128 v[176:179], v158 offset:52224
	ds_read_b128 v[180:183], v158 offset:53248
	ds_read_b128 v[184:187], v158 offset:54272
	ds_read_b128 v[188:191], v158 offset:55296
	ds_read_b128 v[192:195], v158 offset:56320
	global_load_lds_dwordx4 v[152:153], off
	v_lshl_add_u64 v[152:153], v[216:217], 0, s[12:13]
	s_mov_b32 m0, s43
	s_nop 0
	global_load_lds_dwordx4 v[152:153], off
	s_barrier
	s_waitcnt lgkmcnt(0)
	s_waitcnt lgkmcnt(0)
	v_mfma_f32_16x16x32_bf16 v[60:63], v[140:143], v[164:167], v[60:63]
	v_mfma_f32_16x16x32_bf16 v[56:59], v[148:151], v[164:167], v[56:59]
	v_mfma_f32_16x16x32_bf16 v[52:55], v[140:143], v[172:175], v[52:55]
	v_mfma_f32_16x16x32_bf16 v[48:51], v[148:151], v[172:175], v[48:51]
	v_mfma_f32_16x16x32_bf16 v[40:43], v[140:143], v[180:183], v[40:43]
	v_mfma_f32_16x16x32_bf16 v[32:35], v[148:151], v[180:183], v[32:35]
	v_mfma_f32_16x16x32_bf16 v[24:27], v[140:143], v[188:191], v[24:27]
	v_mfma_f32_16x16x32_bf16 v[16:19], v[148:151], v[188:191], v[16:19]
	v_mfma_f32_16x16x32_bf16 v[60:63], v[144:147], v[168:171], v[60:63]
	v_mfma_f32_16x16x32_bf16 v[56:59], v[160:163], v[168:171], v[56:59]
	v_mfma_f32_16x16x32_bf16 v[52:55], v[144:147], v[176:179], v[52:55]
	v_mfma_f32_16x16x32_bf16 v[48:51], v[160:163], v[176:179], v[48:51]
	v_mfma_f32_16x16x32_bf16 v[40:43], v[144:147], v[184:187], v[40:43]
	v_mfma_f32_16x16x32_bf16 v[32:35], v[160:163], v[184:187], v[32:35]
	v_mfma_f32_16x16x32_bf16 v[24:27], v[144:147], v[192:195], v[24:27]
	v_mfma_f32_16x16x32_bf16 v[16:19], v[160:163], v[192:195], v[16:19]
	s_barrier
	s_add_u32 s28, s34, 0x80080
	s_addc_u32 s29, s35, 0
	s_add_i32 s34, s36, s3
	s_mov_b32 m0, s34
	s_nop 0
	global_load_lds_dwordx4 v128, s[28:29]
	s_add_i32 m0, s34, 0x2000
	s_nop 0
	global_load_lds_dwordx4 v130, s[28:29]
	s_waitcnt vmcnt(6)
	s_barrier
	v_mfma_f32_16x16x32_bf16 v[44:47], v[196:199], v[164:167], v[44:47]
	v_mfma_f32_16x16x32_bf16 v[36:39], v[204:207], v[164:167], v[36:39]
	v_mfma_f32_16x16x32_bf16 v[28:31], v[196:199], v[172:175], v[28:31]
	v_mfma_f32_16x16x32_bf16 v[20:23], v[204:207], v[172:175], v[20:23]
	v_mfma_f32_16x16x32_bf16 v[12:15], v[196:199], v[180:183], v[12:15]
	v_mfma_f32_16x16x32_bf16 v[8:11], v[204:207], v[180:183], v[8:11]
	v_mfma_f32_16x16x32_bf16 v[4:7], v[196:199], v[188:191], v[4:7]
	v_mfma_f32_16x16x32_bf16 v[0:3], v[204:207], v[188:191], v[0:3]
	v_mfma_f32_16x16x32_bf16 v[44:47], v[200:203], v[168:171], v[44:47]
	v_mfma_f32_16x16x32_bf16 v[36:39], v[208:211], v[168:171], v[36:39]
	v_mfma_f32_16x16x32_bf16 v[28:31], v[200:203], v[176:179], v[28:31]
	v_mfma_f32_16x16x32_bf16 v[20:23], v[208:211], v[176:179], v[20:23]
	v_mfma_f32_16x16x32_bf16 v[12:15], v[200:203], v[184:187], v[12:15]
	v_mfma_f32_16x16x32_bf16 v[8:11], v[208:211], v[184:187], v[8:11]
	v_mfma_f32_16x16x32_bf16 v[4:7], v[200:203], v[192:195], v[4:7]
	v_mfma_f32_16x16x32_bf16 v[0:3], v[208:211], v[192:195], v[0:3]
	s_add_i32 s69, s69, 2
	s_add_u32 s67, s67, 0x100
	s_addc_u32 s68, s68, 0
	s_cmp_gt_u32 s69, 29
	s_mov_b64 s[28:29], s[30:31]
	s_barrier
	s_cbranch_scc0 .LBB0_2281
	v_lshl_add_u32 v148, s26, 8, v154
	v_lshl_or_b32 v146, s27, 8, v156
	s_cmp_eq_u32 s27, 48
	v_ashrrev_i32_e32 v149, 31, v148
	s_mov_b64 s[26:27], -1
	v_or_b32_e32 v144, 16, v148
	v_or_b32_e32 v142, 32, v148
	v_or_b32_e32 v140, 48, v148
	s_cbranch_scc1 .LBB0_2284
	v_readlane_b32 s64, v240, 22
	v_readlane_b32 s72, v240, 30
	v_readlane_b32 s73, v240, 31
	v_ashrrev_i32_e32 v147, 31, v146
	v_lshlrev_b64 v[152:153], 1, v[146:147]
	v_mov_b64_e32 v[150:151], s[72:73]
	v_mad_i64_i32 v[160:161], s[26:27], v148, s41, v[150:151]
	v_pk_add_f32 v[162:163], v[126:127], 0 op_sel_hi:[1,0]
	v_pk_add_f32 v[164:165], v[124:125], 0 op_sel_hi:[1,0]
	v_lshl_add_u64 v[160:161], v[160:161], 0, v[152:153]
	v_cvt_pk_bf16_f32 v164, v164, v165
	v_cvt_pk_bf16_f32 v165, v162, v163
	global_store_dwordx2 v[160:161], v[164:165], off
	v_pk_add_f32 v[162:163], v[122:123], 0 op_sel_hi:[1,0]
	v_pk_add_f32 v[164:165], v[120:121], 0 op_sel_hi:[1,0]
	v_add_u32_e32 v141, 0x80, v148
	v_cvt_pk_bf16_f32 v164, v164, v165
	v_cvt_pk_bf16_f32 v165, v162, v163
	global_store_dwordx2 v[160:161], v[164:165], off offset:32
	v_pk_add_f32 v[162:163], v[114:115], 0 op_sel_hi:[1,0]
	v_pk_add_f32 v[164:165], v[112:113], 0 op_sel_hi:[1,0]
	v_readlane_b32 s65, v240, 23
	v_cvt_pk_bf16_f32 v164, v164, v165
	v_cvt_pk_bf16_f32 v165, v162, v163
	global_store_dwordx2 v[160:161], v[164:165], off offset:256
	v_pk_add_f32 v[162:163], v[106:107], 0 op_sel_hi:[1,0]
	v_pk_add_f32 v[164:165], v[104:105], 0 op_sel_hi:[1,0]
	v_readlane_b32 s66, v240, 24
	v_cvt_pk_bf16_f32 v164, v164, v165
	v_cvt_pk_bf16_f32 v165, v162, v163
	global_store_dwordx2 v[160:161], v[164:165], off offset:288
	v_mad_i64_i32 v[160:161], s[26:27], v144, s41, v[150:151]
	v_pk_add_f32 v[162:163], v[118:119], 0 op_sel_hi:[1,0]
	v_pk_add_f32 v[164:165], v[116:117], 0 op_sel_hi:[1,0]
	v_lshl_add_u64 v[160:161], v[160:161], 0, v[152:153]
	v_cvt_pk_bf16_f32 v164, v164, v165
	v_cvt_pk_bf16_f32 v165, v162, v163
	global_store_dwordx2 v[160:161], v[164:165], off
	v_pk_add_f32 v[162:163], v[110:111], 0 op_sel_hi:[1,0]
	v_pk_add_f32 v[164:165], v[108:109], 0 op_sel_hi:[1,0]
	v_readlane_b32 s67, v240, 25
	v_cvt_pk_bf16_f32 v164, v164, v165
	v_cvt_pk_bf16_f32 v165, v162, v163
	global_store_dwordx2 v[160:161], v[164:165], off offset:32
	v_pk_add_f32 v[162:163], v[98:99], 0 op_sel_hi:[1,0]
	v_pk_add_f32 v[164:165], v[96:97], 0 op_sel_hi:[1,0]
	v_readlane_b32 s68, v240, 26
	v_cvt_pk_bf16_f32 v164, v164, v165
	v_cvt_pk_bf16_f32 v165, v162, v163
	global_store_dwordx2 v[160:161], v[164:165], off offset:256
	v_pk_add_f32 v[162:163], v[90:91], 0 op_sel_hi:[1,0]
	v_pk_add_f32 v[164:165], v[88:89], 0 op_sel_hi:[1,0]
	v_readlane_b32 s69, v240, 27
	v_cvt_pk_bf16_f32 v164, v164, v165
	v_cvt_pk_bf16_f32 v165, v162, v163
	global_store_dwordx2 v[160:161], v[164:165], off offset:288
	v_mad_i64_i32 v[160:161], s[26:27], v142, s41, v[150:151]
	v_pk_add_f32 v[162:163], v[102:103], 0 op_sel_hi:[1,0]
	v_pk_add_f32 v[164:165], v[100:101], 0 op_sel_hi:[1,0]
	v_lshl_add_u64 v[160:161], v[160:161], 0, v[152:153]
	v_cvt_pk_bf16_f32 v164, v164, v165
	v_cvt_pk_bf16_f32 v165, v162, v163
	global_store_dwordx2 v[160:161], v[164:165], off
	v_pk_add_f32 v[162:163], v[94:95], 0 op_sel_hi:[1,0]
	v_pk_add_f32 v[164:165], v[92:93], 0 op_sel_hi:[1,0]
	v_readlane_b32 s70, v240, 28
	v_cvt_pk_bf16_f32 v164, v164, v165
	v_cvt_pk_bf16_f32 v165, v162, v163
	global_store_dwordx2 v[160:161], v[164:165], off offset:32
	v_pk_add_f32 v[162:163], v[82:83], 0 op_sel_hi:[1,0]
	v_pk_add_f32 v[164:165], v[80:81], 0 op_sel_hi:[1,0]
	v_readlane_b32 s71, v240, 29
	v_cvt_pk_bf16_f32 v164, v164, v165
	v_cvt_pk_bf16_f32 v165, v162, v163
	global_store_dwordx2 v[160:161], v[164:165], off offset:256
	v_pk_add_f32 v[162:163], v[74:75], 0 op_sel_hi:[1,0]
	v_pk_add_f32 v[164:165], v[72:73], 0 op_sel_hi:[1,0]
	v_readlane_b32 s74, v240, 32
	v_cvt_pk_bf16_f32 v164, v164, v165
	v_cvt_pk_bf16_f32 v165, v162, v163
	global_store_dwordx2 v[160:161], v[164:165], off offset:288
	v_mad_i64_i32 v[160:161], s[26:27], v140, s41, v[150:151]
	v_pk_add_f32 v[162:163], v[86:87], 0 op_sel_hi:[1,0]
	v_pk_add_f32 v[164:165], v[84:85], 0 op_sel_hi:[1,0]
	v_lshl_add_u64 v[160:161], v[160:161], 0, v[152:153]
	v_cvt_pk_bf16_f32 v164, v164, v165
	v_cvt_pk_bf16_f32 v165, v162, v163
	global_store_dwordx2 v[160:161], v[164:165], off
	v_pk_add_f32 v[162:163], v[78:79], 0 op_sel_hi:[1,0]
	v_pk_add_f32 v[164:165], v[76:77], 0 op_sel_hi:[1,0]
	v_readlane_b32 s75, v240, 33
	v_cvt_pk_bf16_f32 v164, v164, v165
	v_cvt_pk_bf16_f32 v165, v162, v163
	global_store_dwordx2 v[160:161], v[164:165], off offset:32
	v_pk_add_f32 v[162:163], v[70:71], 0 op_sel_hi:[1,0]
	v_pk_add_f32 v[164:165], v[68:69], 0 op_sel_hi:[1,0]
	v_readlane_b32 s76, v240, 34
	v_cvt_pk_bf16_f32 v164, v164, v165
	v_cvt_pk_bf16_f32 v165, v162, v163
	global_store_dwordx2 v[160:161], v[164:165], off offset:256
	v_pk_add_f32 v[162:163], v[66:67], 0 op_sel_hi:[1,0]
	v_pk_add_f32 v[164:165], v[64:65], 0 op_sel_hi:[1,0]
	v_readlane_b32 s77, v240, 35
	v_cvt_pk_bf16_f32 v164, v164, v165
	v_cvt_pk_bf16_f32 v165, v162, v163
	global_store_dwordx2 v[160:161], v[164:165], off offset:288
	v_mad_i64_i32 v[160:161], s[26:27], v141, s41, v[150:151]
	v_pk_add_f32 v[162:163], v[62:63], 0 op_sel_hi:[1,0]
	v_pk_add_f32 v[164:165], v[60:61], 0 op_sel_hi:[1,0]
	v_lshl_add_u64 v[160:161], v[160:161], 0, v[152:153]
	v_cvt_pk_bf16_f32 v164, v164, v165
	v_cvt_pk_bf16_f32 v165, v162, v163
	global_store_dwordx2 v[160:161], v[164:165], off
	v_pk_add_f32 v[162:163], v[58:59], 0 op_sel_hi:[1,0]
	v_pk_add_f32 v[164:165], v[56:57], 0 op_sel_hi:[1,0]
	v_add_u32_e32 v141, 0x90, v148
	v_cvt_pk_bf16_f32 v164, v164, v165
	v_cvt_pk_bf16_f32 v165, v162, v163
	global_store_dwordx2 v[160:161], v[164:165], off offset:32
	v_pk_add_f32 v[162:163], v[46:47], 0 op_sel_hi:[1,0]
	v_pk_add_f32 v[164:165], v[44:45], 0 op_sel_hi:[1,0]
	v_readlane_b32 s78, v240, 36
	v_cvt_pk_bf16_f32 v164, v164, v165
	v_cvt_pk_bf16_f32 v165, v162, v163
	global_store_dwordx2 v[160:161], v[164:165], off offset:256
	v_pk_add_f32 v[162:163], v[38:39], 0 op_sel_hi:[1,0]
	v_pk_add_f32 v[164:165], v[36:37], 0 op_sel_hi:[1,0]
	v_readlane_b32 s79, v240, 37
	v_cvt_pk_bf16_f32 v164, v164, v165
	v_cvt_pk_bf16_f32 v165, v162, v163
	global_store_dwordx2 v[160:161], v[164:165], off offset:288
	v_mad_i64_i32 v[160:161], s[26:27], v141, s41, v[150:151]
	v_pk_add_f32 v[162:163], v[54:55], 0 op_sel_hi:[1,0]
	v_pk_add_f32 v[164:165], v[52:53], 0 op_sel_hi:[1,0]
	v_lshl_add_u64 v[160:161], v[160:161], 0, v[152:153]
	v_cvt_pk_bf16_f32 v164, v164, v165
	v_cvt_pk_bf16_f32 v165, v162, v163
	global_store_dwordx2 v[160:161], v[164:165], off
	v_pk_add_f32 v[162:163], v[50:51], 0 op_sel_hi:[1,0]
	v_pk_add_f32 v[164:165], v[48:49], 0 op_sel_hi:[1,0]
	v_add_u32_e32 v141, 0xa0, v148
	v_cvt_pk_bf16_f32 v164, v164, v165
	v_cvt_pk_bf16_f32 v165, v162, v163
	global_store_dwordx2 v[160:161], v[164:165], off offset:32
	v_pk_add_f32 v[162:163], v[30:31], 0 op_sel_hi:[1,0]
	v_pk_add_f32 v[164:165], v[28:29], 0 op_sel_hi:[1,0]
	s_nop 0
	v_cvt_pk_bf16_f32 v164, v164, v165
	v_cvt_pk_bf16_f32 v165, v162, v163
	global_store_dwordx2 v[160:161], v[164:165], off offset:256
	v_pk_add_f32 v[162:163], v[22:23], 0 op_sel_hi:[1,0]
	v_pk_add_f32 v[164:165], v[20:21], 0 op_sel_hi:[1,0]
	s_nop 0
	v_cvt_pk_bf16_f32 v164, v164, v165
	v_cvt_pk_bf16_f32 v165, v162, v163
	global_store_dwordx2 v[160:161], v[164:165], off offset:288
	v_mad_i64_i32 v[160:161], s[26:27], v141, s41, v[150:151]
	v_pk_add_f32 v[162:163], v[42:43], 0 op_sel_hi:[1,0]
	v_pk_add_f32 v[164:165], v[40:41], 0 op_sel_hi:[1,0]
	v_lshl_add_u64 v[160:161], v[160:161], 0, v[152:153]
	v_cvt_pk_bf16_f32 v164, v164, v165
	v_cvt_pk_bf16_f32 v165, v162, v163
	global_store_dwordx2 v[160:161], v[164:165], off
	v_pk_add_f32 v[162:163], v[34:35], 0 op_sel_hi:[1,0]
	v_pk_add_f32 v[164:165], v[32:33], 0 op_sel_hi:[1,0]
	v_add_u32_e32 v141, 0xb0, v148
	v_cvt_pk_bf16_f32 v164, v164, v165
	v_cvt_pk_bf16_f32 v165, v162, v163
	global_store_dwordx2 v[160:161], v[164:165], off offset:32
	v_pk_add_f32 v[162:163], v[14:15], 0 op_sel_hi:[1,0]
	v_pk_add_f32 v[164:165], v[12:13], 0 op_sel_hi:[1,0]
	v_mad_i64_i32 v[150:151], s[26:27], v141, s41, v[150:151]
	v_cvt_pk_bf16_f32 v164, v164, v165
	v_cvt_pk_bf16_f32 v165, v162, v163
	global_store_dwordx2 v[160:161], v[164:165], off offset:256
	v_pk_add_f32 v[162:163], v[10:11], 0 op_sel_hi:[1,0]
	v_pk_add_f32 v[164:165], v[8:9], 0 op_sel_hi:[1,0]
	v_lshl_add_u64 v[150:151], v[150:151], 0, v[152:153]
	v_cvt_pk_bf16_f32 v164, v164, v165
	v_cvt_pk_bf16_f32 v165, v162, v163
	global_store_dwordx2 v[160:161], v[164:165], off offset:288
	v_pk_add_f32 v[152:153], v[26:27], 0 op_sel_hi:[1,0]
	v_pk_add_f32 v[160:161], v[24:25], 0 op_sel_hi:[1,0]
	s_mov_b64 s[26:27], 0
	v_cvt_pk_bf16_f32 v160, v160, v161
	v_cvt_pk_bf16_f32 v161, v152, v153
	global_store_dwordx2 v[150:151], v[160:161], off
	v_pk_add_f32 v[152:153], v[18:19], 0 op_sel_hi:[1,0]
	v_pk_add_f32 v[160:161], v[16:17], 0 op_sel_hi:[1,0]
	s_nop 0
	v_cvt_pk_bf16_f32 v160, v160, v161
	v_cvt_pk_bf16_f32 v161, v152, v153
	global_store_dwordx2 v[150:151], v[160:161], off offset:32
	v_pk_add_f32 v[152:153], v[6:7], 0 op_sel_hi:[1,0]
	v_pk_add_f32 v[160:161], v[4:5], 0 op_sel_hi:[1,0]
	s_nop 0
	v_cvt_pk_bf16_f32 v160, v160, v161
	v_cvt_pk_bf16_f32 v161, v152, v153
	global_store_dwordx2 v[150:151], v[160:161], off offset:256
	v_pk_add_f32 v[152:153], v[2:3], 0 op_sel_hi:[1,0]
	v_pk_add_f32 v[160:161], v[0:1], 0 op_sel_hi:[1,0]
	s_nop 0
	v_cvt_pk_bf16_f32 v160, v160, v161
	v_cvt_pk_bf16_f32 v161, v152, v153
	global_store_dwordx2 v[150:151], v[160:161], off offset:288

.LBB0_2676:
	ds_read_b128 v[128:131], v151
	ds_read_b128 v[144:147], v151 offset:1024
	ds_read_b128 v[154:157], v151 offset:2048
	ds_read_b128 v[158:161], v151 offset:3072
	s_add_u32 s28, s26, 0x100
	s_addc_u32 s29, s27, 0
	s_cmp_eq_u32 s62, 60
	s_cselect_b32 s35, s17, s29
	s_cselect_b32 s34, s52, s28
	s_cselect_b32 s31, s15, s57
	s_cselect_b32 s30, s53, s56
	s_add_i32 m0, s4, 0xc000
	ds_read_b128 v[162:165], v152
	ds_read_b128 v[166:169], v152 offset:1024
	ds_read_b128 v[170:173], v152 offset:2048
	ds_read_b128 v[174:177], v152 offset:3072
	ds_read_b128 v[178:181], v152 offset:4096
	ds_read_b128 v[182:185], v152 offset:5120
	ds_read_b128 v[186:189], v152 offset:6144
	ds_read_b128 v[190:193], v152 offset:7168
	global_load_lds_dwordx4 v136, s[26:27]
	v_lshl_add_u64 v[194:195], s[26:27], 0, v[138:139]
	s_add_i32 m0, s4, 0xe000
	s_nop 0
	global_load_lds_dwordx4 v[194:195], off
	s_waitcnt lgkmcnt(8)
	s_barrier
	s_waitcnt lgkmcnt(0)
	s_waitcnt lgkmcnt(0)
	v_mfma_f32_16x16x32_bf16 v[124:127], v[128:131], v[162:165], v[124:127]
	v_mfma_f32_16x16x32_bf16 v[92:95], v[154:157], v[162:165], v[92:95]
	v_mfma_f32_16x16x32_bf16 v[120:123], v[128:131], v[170:173], v[120:123]
	v_mfma_f32_16x16x32_bf16 v[88:91], v[154:157], v[170:173], v[88:91]
	v_mfma_f32_16x16x32_bf16 v[116:119], v[128:131], v[178:181], v[116:119]
	v_mfma_f32_16x16x32_bf16 v[84:87], v[154:157], v[178:181], v[84:87]
	v_mfma_f32_16x16x32_bf16 v[112:115], v[128:131], v[186:189], v[112:115]
	v_mfma_f32_16x16x32_bf16 v[80:83], v[154:157], v[186:189], v[80:83]
	v_mfma_f32_16x16x32_bf16 v[124:127], v[144:147], v[166:169], v[124:127]
	v_mfma_f32_16x16x32_bf16 v[92:95], v[158:161], v[166:169], v[92:95]
	v_mfma_f32_16x16x32_bf16 v[120:123], v[144:147], v[174:177], v[120:123]
	v_mfma_f32_16x16x32_bf16 v[88:91], v[158:161], v[174:177], v[88:91]
	v_mfma_f32_16x16x32_bf16 v[116:119], v[144:147], v[182:185], v[116:119]
	v_mfma_f32_16x16x32_bf16 v[84:87], v[158:161], v[182:185], v[84:87]
	v_mfma_f32_16x16x32_bf16 v[112:115], v[144:147], v[190:193], v[112:115]
	v_mfma_f32_16x16x32_bf16 v[80:83], v[158:161], v[190:193], v[80:83]
	s_barrier
	s_add_i32 s26, s43, s3
	v_lshl_add_u64 v[210:211], s[30:31], 0, v[132:133]
	s_mov_b32 m0, s26
	ds_read_b128 v[194:197], v153
	ds_read_b128 v[198:201], v153 offset:1024
	ds_read_b128 v[202:205], v153 offset:2048
	ds_read_b128 v[206:209], v153 offset:3072
	global_load_lds_dwordx4 v[210:211], off
	s_add_i32 m0, s26, 0x2000
	s_nop 0
	global_load_lds_dwordx4 v134, s[30:31]
	s_barrier
	s_waitcnt lgkmcnt(0)
	s_waitcnt lgkmcnt(0)
	v_mfma_f32_16x16x32_bf16 v[76:79], v[194:197], v[162:165], v[76:79]
	v_mfma_f32_16x16x32_bf16 v[48:51], v[202:205], v[162:165], v[48:51]
	v_mfma_f32_16x16x32_bf16 v[68:71], v[194:197], v[170:173], v[68:71]
	v_mfma_f32_16x16x32_bf16 v[40:43], v[202:205], v[170:173], v[40:43]
	v_mfma_f32_16x16x32_bf16 v[60:63], v[194:197], v[178:181], v[60:63]
	v_mfma_f32_16x16x32_bf16 v[36:39], v[202:205], v[178:181], v[36:39]
	v_mfma_f32_16x16x32_bf16 v[52:55], v[194:197], v[186:189], v[52:55]
	v_mfma_f32_16x16x32_bf16 v[28:31], v[202:205], v[186:189], v[28:31]
	v_mfma_f32_16x16x32_bf16 v[76:79], v[198:201], v[166:169], v[76:79]
	v_mfma_f32_16x16x32_bf16 v[48:51], v[206:209], v[166:169], v[48:51]
	v_mfma_f32_16x16x32_bf16 v[68:71], v[198:201], v[174:177], v[68:71]
	v_mfma_f32_16x16x32_bf16 v[40:43], v[206:209], v[174:177], v[40:43]
	v_mfma_f32_16x16x32_bf16 v[60:63], v[198:201], v[182:185], v[60:63]
	v_mfma_f32_16x16x32_bf16 v[36:39], v[206:209], v[182:185], v[36:39]
	v_mfma_f32_16x16x32_bf16 v[52:55], v[198:201], v[190:193], v[52:55]
	v_mfma_f32_16x16x32_bf16 v[28:31], v[206:209], v[190:193], v[28:31]
	s_mov_b32 m0, s4
	v_lshl_add_u64 v[214:215], s[34:35], 0, v[132:133]
	s_barrier
	ds_read_b128 v[162:165], v152 offset:16384
	ds_read_b128 v[166:169], v152 offset:17408
	ds_read_b128 v[170:173], v152 offset:18432
	ds_read_b128 v[174:177], v152 offset:19456
	ds_read_b128 v[178:181], v152 offset:20480
	ds_read_b128 v[182:185], v152 offset:21504
	ds_read_b128 v[186:189], v152 offset:22528
	ds_read_b128 v[190:193], v152 offset:23552
	global_load_lds_dwordx4 v[214:215], off
	v_lshl_add_u64 v[216:217], s[34:35], 0, v[134:135]
	s_mov_b32 m0, s5
	s_nop 0
	global_load_lds_dwordx4 v134, s[34:35]
	s_barrier
	s_waitcnt lgkmcnt(0)
	s_waitcnt lgkmcnt(0)
	v_mfma_f32_16x16x32_bf16 v[108:111], v[128:131], v[162:165], v[108:111]
	v_mfma_f32_16x16x32_bf16 v[72:75], v[154:157], v[162:165], v[72:75]
	v_mfma_f32_16x16x32_bf16 v[104:107], v[128:131], v[170:173], v[104:107]
	v_mfma_f32_16x16x32_bf16 v[64:67], v[154:157], v[170:173], v[64:67]
	v_mfma_f32_16x16x32_bf16 v[100:103], v[128:131], v[178:181], v[100:103]
	v_mfma_f32_16x16x32_bf16 v[56:59], v[154:157], v[178:181], v[56:59]
	v_mfma_f32_16x16x32_bf16 v[96:99], v[128:131], v[186:189], v[96:99]
	v_mfma_f32_16x16x32_bf16 v[44:47], v[154:157], v[186:189], v[44:47]
	v_mfma_f32_16x16x32_bf16 v[108:111], v[144:147], v[166:169], v[108:111]
	v_mfma_f32_16x16x32_bf16 v[72:75], v[158:161], v[166:169], v[72:75]
	v_mfma_f32_16x16x32_bf16 v[104:107], v[144:147], v[174:177], v[104:107]
	v_mfma_f32_16x16x32_bf16 v[64:67], v[158:161], v[174:177], v[64:67]
	v_mfma_f32_16x16x32_bf16 v[100:103], v[144:147], v[182:185], v[100:103]
	v_mfma_f32_16x16x32_bf16 v[56:59], v[158:161], v[182:185], v[56:59]
	v_mfma_f32_16x16x32_bf16 v[96:99], v[144:147], v[190:193], v[96:99]
	v_mfma_f32_16x16x32_bf16 v[44:47], v[158:161], v[190:193], v[44:47]
	s_barrier
	s_add_u32 s26, s30, 0x100000
	s_addc_u32 s27, s31, 0
	s_add_i32 s63, s46, s3
	v_lshl_add_u64 v[128:129], s[26:27], 0, v[132:133]
	s_mov_b32 m0, s63
	s_nop 0
	global_load_lds_dwordx4 v[128:129], off
	s_add_i32 m0, s63, 0x2000
	s_nop 0
	global_load_lds_dwordx4 v134, s[26:27]
	s_waitcnt vmcnt(6)
	s_barrier
	v_mfma_f32_16x16x32_bf16 v[32:35], v[194:197], v[162:165], v[32:35]
	v_mfma_f32_16x16x32_bf16 v[12:15], v[202:205], v[162:165], v[12:15]
	v_mfma_f32_16x16x32_bf16 v[24:27], v[194:197], v[170:173], v[24:27]
	v_mfma_f32_16x16x32_bf16 v[8:11], v[202:205], v[170:173], v[8:11]
	v_mfma_f32_16x16x32_bf16 v[20:23], v[194:197], v[178:181], v[20:23]
	v_mfma_f32_16x16x32_bf16 v[4:7], v[202:205], v[178:181], v[4:7]
	v_mfma_f32_16x16x32_bf16 v[16:19], v[194:197], v[186:189], v[16:19]
	v_mfma_f32_16x16x32_bf16 v[0:3], v[202:205], v[186:189], v[0:3]
	v_mfma_f32_16x16x32_bf16 v[32:35], v[198:201], v[166:169], v[32:35]
	v_mfma_f32_16x16x32_bf16 v[12:15], v[206:209], v[166:169], v[12:15]
	v_mfma_f32_16x16x32_bf16 v[24:27], v[198:201], v[174:177], v[24:27]
	v_mfma_f32_16x16x32_bf16 v[8:11], v[206:209], v[174:177], v[8:11]
	v_mfma_f32_16x16x32_bf16 v[20:23], v[198:201], v[182:185], v[20:23]
	v_mfma_f32_16x16x32_bf16 v[4:7], v[206:209], v[182:185], v[4:7]
	v_mfma_f32_16x16x32_bf16 v[16:19], v[198:201], v[190:193], v[16:19]
	v_mfma_f32_16x16x32_bf16 v[0:3], v[206:209], v[190:193], v[0:3]
	s_add_i32 s63, 0, 0x18000
	v_add_u32_e32 v158, s63, v149
	s_barrier
	ds_read_b128 v[128:131], v158
	ds_read_b128 v[144:147], v158 offset:1024
	ds_read_b128 v[154:157], v158 offset:2048
	ds_read_b128 v[158:161], v158 offset:3072
	s_add_u32 s26, s34, 0x100000
	s_addc_u32 s27, s35, 0
	s_mov_b32 m0, s23
	v_lshl_add_u64 v[194:195], s[26:27], 0, v[132:133]
	ds_read_b128 v[162:165], v152 offset:32768
	ds_read_b128 v[166:169], v152 offset:33792
	ds_read_b128 v[170:173], v152 offset:34816
	ds_read_b128 v[174:177], v152 offset:35840
	ds_read_b128 v[178:181], v152 offset:36864
	ds_read_b128 v[182:185], v152 offset:37888
	ds_read_b128 v[186:189], v152 offset:38912
	ds_read_b128 v[190:193], v152 offset:39936
	global_load_lds_dwordx4 v[194:195], off
	s_mov_b32 m0, s36
	s_nop 0
	global_load_lds_dwordx4 v134, s[26:27]
	s_waitcnt lgkmcnt(8)
	s_barrier
	s_waitcnt lgkmcnt(0)
	s_waitcnt lgkmcnt(0)
	v_mfma_f32_16x16x32_bf16 v[124:127], v[128:131], v[162:165], v[124:127]
	v_mfma_f32_16x16x32_bf16 v[92:95], v[154:157], v[162:165], v[92:95]
	v_mfma_f32_16x16x32_bf16 v[120:123], v[128:131], v[170:173], v[120:123]
	v_mfma_f32_16x16x32_bf16 v[88:91], v[154:157], v[170:173], v[88:91]
	v_mfma_f32_16x16x32_bf16 v[116:119], v[128:131], v[178:181], v[116:119]
	v_mfma_f32_16x16x32_bf16 v[84:87], v[154:157], v[178:181], v[84:87]
	v_mfma_f32_16x16x32_bf16 v[112:115], v[128:131], v[186:189], v[112:115]
	v_mfma_f32_16x16x32_bf16 v[80:83], v[154:157], v[186:189], v[80:83]
	v_mfma_f32_16x16x32_bf16 v[124:127], v[144:147], v[166:169], v[124:127]
	v_mfma_f32_16x16x32_bf16 v[92:95], v[158:161], v[166:169], v[92:95]
	v_mfma_f32_16x16x32_bf16 v[120:123], v[144:147], v[174:177], v[120:123]
	v_mfma_f32_16x16x32_bf16 v[88:91], v[158:161], v[174:177], v[88:91]
	v_mfma_f32_16x16x32_bf16 v[116:119], v[144:147], v[182:185], v[116:119]
	v_mfma_f32_16x16x32_bf16 v[84:87], v[158:161], v[182:185], v[84:87]
	v_mfma_f32_16x16x32_bf16 v[112:115], v[144:147], v[190:193], v[112:115]
	v_mfma_f32_16x16x32_bf16 v[80:83], v[158:161], v[190:193], v[80:83]
	s_barrier
	s_add_i32 s34, 0, 0x1c000
	s_add_i32 s26, s63, s3
	v_add_u32_e32 v206, s34, v149
	v_lshl_add_u64 v[210:211], v[210:211], 0, s[12:13]
	s_mov_b32 m0, s26
	ds_read_b128 v[194:197], v206
	ds_read_b128 v[198:201], v206 offset:1024
	ds_read_b128 v[202:205], v206 offset:2048
	ds_read_b128 v[206:209], v206 offset:3072
	global_load_lds_dwordx4 v[210:211], off
	s_add_u32 s98, s30, s12
	s_addc_u32 s99, s31, s13
	s_add_i32 m0, s26, 0x2000
	s_nop 0
	global_load_lds_dwordx4 v134, s[98:99]
	s_barrier
	s_waitcnt lgkmcnt(0)
	s_waitcnt lgkmcnt(0)
	v_mfma_f32_16x16x32_bf16 v[76:79], v[194:197], v[162:165], v[76:79]
	v_mfma_f32_16x16x32_bf16 v[48:51], v[202:205], v[162:165], v[48:51]
	v_mfma_f32_16x16x32_bf16 v[68:71], v[194:197], v[170:173], v[68:71]
	v_mfma_f32_16x16x32_bf16 v[40:43], v[202:205], v[170:173], v[40:43]
	v_mfma_f32_16x16x32_bf16 v[60:63], v[194:197], v[178:181], v[60:63]
	v_mfma_f32_16x16x32_bf16 v[36:39], v[202:205], v[178:181], v[36:39]
	v_mfma_f32_16x16x32_bf16 v[52:55], v[194:197], v[186:189], v[52:55]
	v_mfma_f32_16x16x32_bf16 v[28:31], v[202:205], v[186:189], v[28:31]
	v_mfma_f32_16x16x32_bf16 v[76:79], v[198:201], v[166:169], v[76:79]
	v_mfma_f32_16x16x32_bf16 v[48:51], v[206:209], v[166:169], v[48:51]
	v_mfma_f32_16x16x32_bf16 v[68:71], v[198:201], v[174:177], v[68:71]
	v_mfma_f32_16x16x32_bf16 v[40:43], v[206:209], v[174:177], v[40:43]
	v_mfma_f32_16x16x32_bf16 v[60:63], v[198:201], v[182:185], v[60:63]
	v_mfma_f32_16x16x32_bf16 v[36:39], v[206:209], v[182:185], v[36:39]
	v_mfma_f32_16x16x32_bf16 v[52:55], v[198:201], v[190:193], v[52:55]
	v_mfma_f32_16x16x32_bf16 v[28:31], v[206:209], v[190:193], v[28:31]
	s_mov_b32 m0, s38
	v_lshl_add_u64 v[210:211], v[214:215], 0, s[12:13]
	s_barrier
	ds_read_b128 v[162:165], v152 offset:49152
	ds_read_b128 v[166:169], v152 offset:50176
	ds_read_b128 v[170:173], v152 offset:51200
	ds_read_b128 v[174:177], v152 offset:52224
	ds_read_b128 v[178:181], v152 offset:53248
	ds_read_b128 v[182:185], v152 offset:54272
	ds_read_b128 v[186:189], v152 offset:55296
	ds_read_b128 v[190:193], v152 offset:56320
	global_load_lds_dwordx4 v[210:211], off
	v_lshl_add_u64 v[210:211], v[216:217], 0, s[12:13]
	s_mov_b32 m0, s39
	s_nop 0
	global_load_lds_dwordx4 v[210:211], off
	s_barrier
	s_waitcnt lgkmcnt(0)
	s_waitcnt lgkmcnt(0)
	v_mfma_f32_16x16x32_bf16 v[108:111], v[128:131], v[162:165], v[108:111]
	v_mfma_f32_16x16x32_bf16 v[72:75], v[154:157], v[162:165], v[72:75]
	v_mfma_f32_16x16x32_bf16 v[104:107], v[128:131], v[170:173], v[104:107]
	v_mfma_f32_16x16x32_bf16 v[64:67], v[154:157], v[170:173], v[64:67]
	v_mfma_f32_16x16x32_bf16 v[100:103], v[128:131], v[178:181], v[100:103]
	v_mfma_f32_16x16x32_bf16 v[56:59], v[154:157], v[178:181], v[56:59]
	v_mfma_f32_16x16x32_bf16 v[96:99], v[128:131], v[186:189], v[96:99]
	v_mfma_f32_16x16x32_bf16 v[44:47], v[154:157], v[186:189], v[44:47]
	v_mfma_f32_16x16x32_bf16 v[108:111], v[144:147], v[166:169], v[108:111]
	v_mfma_f32_16x16x32_bf16 v[72:75], v[158:161], v[166:169], v[72:75]
	v_mfma_f32_16x16x32_bf16 v[104:107], v[144:147], v[174:177], v[104:107]
	v_mfma_f32_16x16x32_bf16 v[64:67], v[158:161], v[174:177], v[64:67]
	v_mfma_f32_16x16x32_bf16 v[100:103], v[144:147], v[182:185], v[100:103]
	v_mfma_f32_16x16x32_bf16 v[56:59], v[158:161], v[182:185], v[56:59]
	v_mfma_f32_16x16x32_bf16 v[96:99], v[144:147], v[190:193], v[96:99]
	v_mfma_f32_16x16x32_bf16 v[44:47], v[158:161], v[190:193], v[44:47]
	s_barrier
	s_add_u32 s26, s30, 0x100080
	s_addc_u32 s27, s31, 0
	s_add_i32 s30, s34, s3
	v_lshl_add_u64 v[128:129], s[26:27], 0, v[132:133]
	s_mov_b32 m0, s30
	s_nop 0
	global_load_lds_dwordx4 v[128:129], off
	s_add_i32 m0, s30, 0x2000
	s_nop 0
	global_load_lds_dwordx4 v134, s[26:27]
	s_waitcnt vmcnt(6)
	s_barrier
	v_mfma_f32_16x16x32_bf16 v[32:35], v[194:197], v[162:165], v[32:35]
	v_mfma_f32_16x16x32_bf16 v[12:15], v[202:205], v[162:165], v[12:15]
	v_mfma_f32_16x16x32_bf16 v[24:27], v[194:197], v[170:173], v[24:27]
	v_mfma_f32_16x16x32_bf16 v[8:11], v[202:205], v[170:173], v[8:11]
	v_mfma_f32_16x16x32_bf16 v[20:23], v[194:197], v[178:181], v[20:23]
	v_mfma_f32_16x16x32_bf16 v[4:7], v[202:205], v[178:181], v[4:7]
	v_mfma_f32_16x16x32_bf16 v[16:19], v[194:197], v[186:189], v[16:19]
	v_mfma_f32_16x16x32_bf16 v[0:3], v[202:205], v[186:189], v[0:3]
	v_mfma_f32_16x16x32_bf16 v[32:35], v[198:201], v[166:169], v[32:35]
	v_mfma_f32_16x16x32_bf16 v[12:15], v[206:209], v[166:169], v[12:15]
	v_mfma_f32_16x16x32_bf16 v[24:27], v[198:201], v[174:177], v[24:27]
	v_mfma_f32_16x16x32_bf16 v[8:11], v[206:209], v[174:177], v[8:11]
	v_mfma_f32_16x16x32_bf16 v[20:23], v[198:201], v[182:185], v[20:23]
	v_mfma_f32_16x16x32_bf16 v[4:7], v[206:209], v[182:185], v[4:7]
	v_mfma_f32_16x16x32_bf16 v[16:19], v[198:201], v[190:193], v[16:19]
	v_mfma_f32_16x16x32_bf16 v[0:3], v[206:209], v[190:193], v[0:3]
	s_add_i32 s62, s62, 2
	s_add_u32 s56, s56, 0x100
	s_addc_u32 s57, s57, 0
	s_cmp_gt_u32 s62, 61
	s_mov_b64 s[26:27], s[28:29]
	s_barrier
	s_cbranch_scc0 .LBB0_2676
	s_cmp_lt_u32 s22, 32
	s_movk_i32 s15, 0x3000
	s_cselect_b32 s15, s15, 0x6000
	s_cmp_gt_i32 s22, 15
	v_lshl_add_u32 v158, s22, 8, v148
	s_cselect_b32 s15, s15, 0
	v_readlane_b32 s48, v240, 22
	v_lshl_or_b32 v128, s47, 8, v150
	s_lshl_b32 s15, s15, 2
	v_ashrrev_i32_e32 v159, 31, v158
	v_readlane_b32 s49, v240, 23
	v_readlane_b32 s50, v240, 24
	v_readlane_b32 s51, v240, 25
	v_readlane_b32 s52, v240, 26
	v_readlane_b32 s53, v240, 27
	s_add_u32 s26, s41, s15
	v_ashrrev_i32_e32 v129, 31, v128
	v_lshlrev_b64 v[146:147], 13, v[158:159]
	v_readlane_b32 s54, v240, 28
	v_readlane_b32 s55, v240, 29
	s_mov_b64 s[44:45], s[48:49]
	s_mov_b64 s[48:49], s[52:53]
	s_addc_u32 s27, s42, 0
	v_lshlrev_b64 v[160:161], 2, v[128:129]
	v_lshl_add_u64 v[146:147], s[48:49], 0, v[146:147]
	v_lshl_add_u64 v[144:145], s[26:27], 0, v[160:161]
	v_lshl_add_u64 v[146:147], v[146:147], 0, v[160:161]
	s_mov_b32 s15, 0x100000
	s_mov_b64 s[26:27], 0x100000
	v_readlane_b32 s58, v240, 32
	v_readlane_b32 s59, v240, 33
	v_readlane_b32 s62, v240, 36
	v_readlane_b32 s63, v240, 37
	s_mov_b32 s47, s14
	s_mov_b32 s22, s16
	s_mov_b64 s[28:29], s[20:21]
	v_readlane_b32 s56, v240, 30
	v_readlane_b32 s57, v240, 31
	v_readlane_b32 s60, v240, 34
	v_readlane_b32 s61, v240, 35
	s_mov_b64 s[50:51], s[54:55]
	v_or_b32_e32 v162, 16, v158
	v_ashrrev_i32_e32 v163, 31, v162
	v_lshlrev_b64 v[164:165], 13, v[162:163]
	v_lshl_add_u64 v[162:163], s[48:49], 0, v[164:165]
	v_lshl_add_u64 v[164:165], v[162:163], 0, v[160:161]
	v_or_b32_e32 v162, 32, v158
	v_ashrrev_i32_e32 v163, 31, v162
	v_lshlrev_b64 v[166:167], 13, v[162:163]
	v_lshl_add_u64 v[162:163], s[48:49], 0, v[166:167]
	v_lshl_add_u64 v[166:167], v[162:163], 0, v[160:161]
	v_or_b32_e32 v162, 48, v158
	v_ashrrev_i32_e32 v163, 31, v162
	v_lshlrev_b64 v[168:169], 13, v[162:163]
	v_lshl_add_u64 v[162:163], s[48:49], 0, v[168:169]
	v_lshl_add_u64 v[168:169], v[162:163], 0, v[160:161]
	v_add_co_u32_e32 v162, vcc, s15, v146
	s_mov_b32 s15, 0x120000
	s_nop 0
	v_addc_co_u32_e32 v163, vcc, 0, v147, vcc
	v_lshl_add_u64 v[170:171], v[146:147], 0, s[26:27]
	s_mov_b64 s[26:27], 0x120000
	v_add_co_u32_e32 v172, vcc, s15, v146
	s_mov_b32 s15, 0x140000
	s_nop 0
	v_addc_co_u32_e32 v173, vcc, 0, v147, vcc
	v_lshl_add_u64 v[174:175], v[146:147], 0, s[26:27]
	s_mov_b64 s[26:27], 0x140000
	v_add_co_u32_e32 v176, vcc, s15, v146
	s_mov_b32 s15, 0x160000
	s_nop 0
	v_addc_co_u32_e32 v177, vcc, 0, v147, vcc
	v_lshl_add_u64 v[178:179], v[146:147], 0, s[26:27]
	s_mov_b64 s[26:27], 0x160000
	v_add_co_u32_e32 v180, vcc, s15, v146
	v_lshl_add_u64 v[182:183], v[146:147], 0, s[26:27]
	s_nop 0
	v_addc_co_u32_e32 v181, vcc, 0, v147, vcc
	s_and_b64 vcc, exec, s[10:11]
	s_mov_b64 s[26:27], s[18:19]
	global_load_dwordx4 v[184:187], v[144:145], off
	global_load_dwordx4 v[188:191], v[146:147], off
	v_pk_add_f32 v[126:127], v[126:127], 0 op_sel_hi:[1,0]
	v_pk_add_f32 v[124:125], v[124:125], 0 op_sel_hi:[1,0]
	v_pk_add_f32 v[122:123], v[122:123], 0 op_sel_hi:[1,0]
	v_pk_add_f32 v[120:121], v[120:121], 0 op_sel_hi:[1,0]
	v_pk_add_f32 v[118:119], v[118:119], 0 op_sel_hi:[1,0]
	v_pk_add_f32 v[116:117], v[116:117], 0 op_sel_hi:[1,0]
	v_pk_add_f32 v[114:115], v[114:115], 0 op_sel_hi:[1,0]
	v_pk_add_f32 v[112:113], v[112:113], 0 op_sel_hi:[1,0]
	v_pk_add_f32 v[110:111], v[110:111], 0 op_sel_hi:[1,0]
	v_pk_add_f32 v[108:109], v[108:109], 0 op_sel_hi:[1,0]
	v_pk_add_f32 v[106:107], v[106:107], 0 op_sel_hi:[1,0]
	v_pk_add_f32 v[104:105], v[104:105], 0 op_sel_hi:[1,0]
	v_pk_add_f32 v[102:103], v[102:103], 0 op_sel_hi:[1,0]
	v_pk_add_f32 v[100:101], v[100:101], 0 op_sel_hi:[1,0]
	v_pk_add_f32 v[98:99], v[98:99], 0 op_sel_hi:[1,0]
	v_pk_add_f32 v[96:97], v[96:97], 0 op_sel_hi:[1,0]
	v_pk_add_f32 v[94:95], v[94:95], 0 op_sel_hi:[1,0]
	v_pk_add_f32 v[92:93], v[92:93], 0 op_sel_hi:[1,0]
	v_pk_add_f32 v[90:91], v[90:91], 0 op_sel_hi:[1,0]
	v_pk_add_f32 v[88:89], v[88:89], 0 op_sel_hi:[1,0]
	v_pk_add_f32 v[86:87], v[86:87], 0 op_sel_hi:[1,0]
	v_pk_add_f32 v[84:85], v[84:85], 0 op_sel_hi:[1,0]
	v_pk_add_f32 v[82:83], v[82:83], 0 op_sel_hi:[1,0]
	v_pk_add_f32 v[80:81], v[80:81], 0 op_sel_hi:[1,0]
	v_pk_add_f32 v[74:75], v[74:75], 0 op_sel_hi:[1,0]
	v_pk_add_f32 v[72:73], v[72:73], 0 op_sel_hi:[1,0]
	v_pk_add_f32 v[66:67], v[66:67], 0 op_sel_hi:[1,0]
	v_pk_add_f32 v[64:65], v[64:65], 0 op_sel_hi:[1,0]
	v_pk_add_f32 v[58:59], v[58:59], 0 op_sel_hi:[1,0]
	v_pk_add_f32 v[56:57], v[56:57], 0 op_sel_hi:[1,0]
	v_pk_add_f32 v[46:47], v[46:47], 0 op_sel_hi:[1,0]
	v_pk_add_f32 v[44:45], v[44:45], 0 op_sel_hi:[1,0]
	v_pk_add_f32 v[62:63], v[62:63], 0 op_sel_hi:[1,0]
	v_pk_add_f32 v[60:61], v[60:61], 0 op_sel_hi:[1,0]
	v_pk_add_f32 v[54:55], v[54:55], 0 op_sel_hi:[1,0]
	v_pk_add_f32 v[52:53], v[52:53], 0 op_sel_hi:[1,0]
	v_pk_add_f32 v[34:35], v[34:35], 0 op_sel_hi:[1,0]
	v_pk_add_f32 v[32:33], v[32:33], 0 op_sel_hi:[1,0]
	v_pk_add_f32 v[26:27], v[26:27], 0 op_sel_hi:[1,0]
	v_pk_add_f32 v[24:25], v[24:25], 0 op_sel_hi:[1,0]
	v_pk_add_f32 v[22:23], v[22:23], 0 op_sel_hi:[1,0]
	v_pk_add_f32 v[20:21], v[20:21], 0 op_sel_hi:[1,0]
	v_pk_add_f32 v[18:19], v[18:19], 0 op_sel_hi:[1,0]
	v_pk_add_f32 v[16:17], v[16:17], 0 op_sel_hi:[1,0]
	v_pk_add_f32 v[14:15], v[14:15], 0 op_sel_hi:[1,0]
	v_pk_add_f32 v[12:13], v[12:13], 0 op_sel_hi:[1,0]
	v_pk_add_f32 v[10:11], v[10:11], 0 op_sel_hi:[1,0]
	v_pk_add_f32 v[8:9], v[8:9], 0 op_sel_hi:[1,0]
	v_pk_add_f32 v[6:7], v[6:7], 0 op_sel_hi:[1,0]
	v_pk_add_f32 v[4:5], v[4:5], 0 op_sel_hi:[1,0]
	v_pk_add_f32 v[2:3], v[2:3], 0 op_sel_hi:[1,0]
	v_pk_add_f32 v[0:1], v[0:1], 0 op_sel_hi:[1,0]
	s_waitcnt vmcnt(0)
	v_pk_fma_f32 v[126:127], v[126:127], v[186:187], v[190:191]
	v_pk_fma_f32 v[124:125], v[124:125], v[184:185], v[188:189]
	global_store_dwordx4 v[146:147], v[124:127], off
	global_load_dwordx4 v[188:191], v[164:165], off
	global_load_dwordx4 v[192:195], v[166:167], off
	global_load_dwordx4 v[196:199], v[168:169], off
	global_load_dwordx4 v[200:203], v[162:163], off
	global_load_dwordx4 v[204:207], v[172:173], off
	global_load_dwordx4 v[208:211], v[176:177], off
	global_load_dwordx4 v[212:215], v[180:181], off
	global_load_dwordx4 v[216:219], v[144:145], off offset:64
	global_load_dwordx4 v[220:223], v[146:147], off offset:64
	global_load_dwordx4 v[224:227], v[164:165], off offset:64
	global_load_dwordx4 v[228:231], v[166:167], off offset:64
	global_load_dwordx4 v[232:235], v[168:169], off offset:64
	s_waitcnt vmcnt(11)
	v_pk_fma_f32 v[122:123], v[122:123], v[186:187], v[190:191]
	v_pk_fma_f32 v[120:121], v[120:121], v[184:185], v[188:189]
	global_store_dwordx4 v[164:165], v[120:123], off
	global_load_dwordx4 v[188:191], v[170:171], off offset:64
	s_waitcnt vmcnt(12)
	v_pk_fma_f32 v[118:119], v[118:119], v[186:187], v[194:195]
	v_pk_fma_f32 v[116:117], v[116:117], v[184:185], v[192:193]
	global_store_dwordx4 v[166:167], v[116:119], off
	global_load_dwordx4 v[192:195], v[174:175], off offset:64
	s_waitcnt vmcnt(13)
	v_pk_fma_f32 v[114:115], v[114:115], v[186:187], v[198:199]
	v_pk_fma_f32 v[112:113], v[112:113], v[184:185], v[196:197]
	global_store_dwordx4 v[168:169], v[112:115], off
	global_load_dwordx4 v[196:199], v[178:179], off offset:64
	s_waitcnt vmcnt(14)
	v_pk_fma_f32 v[110:111], v[110:111], v[186:187], v[202:203]
	v_pk_fma_f32 v[108:109], v[108:109], v[184:185], v[200:201]
	global_store_dwordx4 v[162:163], v[108:111], off
	global_load_dwordx4 v[200:203], v[182:183], off offset:64
	s_waitcnt vmcnt(15)
	v_pk_fma_f32 v[106:107], v[106:107], v[186:187], v[206:207]
	v_pk_fma_f32 v[104:105], v[104:105], v[184:185], v[204:205]
	global_store_dwordx4 v[172:173], v[104:107], off
	global_load_dwordx4 v[204:207], v[144:145], off offset:512
	s_waitcnt vmcnt(16)
	v_pk_fma_f32 v[102:103], v[102:103], v[186:187], v[210:211]
	v_pk_fma_f32 v[100:101], v[100:101], v[184:185], v[208:209]
	global_store_dwordx4 v[176:177], v[100:103], off
	global_load_dwordx4 v[208:211], v[146:147], off offset:512
	s_waitcnt vmcnt(17)
	v_pk_fma_f32 v[98:99], v[98:99], v[186:187], v[214:215]
	v_pk_fma_f32 v[96:97], v[96:97], v[184:185], v[212:213]
	global_store_dwordx4 v[180:181], v[96:99], off
	global_load_dwordx4 v[184:187], v[164:165], off offset:512
	s_waitcnt vmcnt(17)
	v_pk_fma_f32 v[94:95], v[94:95], v[218:219], v[222:223]
	v_pk_fma_f32 v[92:93], v[92:93], v[216:217], v[220:221]
	global_store_dwordx4 v[146:147], v[92:95], off offset:64
	global_load_dwordx4 v[212:215], v[166:167], off offset:512
	global_load_dwordx4 v[220:223], v[168:169], off offset:512
	s_waitcnt vmcnt(19)
	v_pk_fma_f32 v[90:91], v[90:91], v[218:219], v[226:227]
	v_pk_fma_f32 v[88:89], v[88:89], v[216:217], v[224:225]
	global_store_dwordx4 v[164:165], v[88:91], off offset:64
	global_load_dwordx4 v[224:227], v[170:171], off offset:512
	s_waitcnt vmcnt(20)
	v_pk_fma_f32 v[86:87], v[86:87], v[218:219], v[230:231]
	v_pk_fma_f32 v[84:85], v[84:85], v[216:217], v[228:229]
	global_store_dwordx4 v[166:167], v[84:87], off offset:64
	global_load_dwordx4 v[228:231], v[174:175], off offset:512
	s_waitcnt vmcnt(21)
	v_pk_fma_f32 v[82:83], v[82:83], v[218:219], v[234:235]
	v_pk_fma_f32 v[80:81], v[80:81], v[216:217], v[232:233]
	global_store_dwordx4 v[168:169], v[80:83], off offset:64
	global_load_dwordx4 v[232:235], v[178:179], off offset:512
	s_waitcnt vmcnt(21)
	v_pk_fma_f32 v[74:75], v[74:75], v[218:219], v[190:191]
	v_pk_fma_f32 v[72:73], v[72:73], v[216:217], v[188:189]
	global_store_dwordx4 v[170:171], v[72:75], off offset:64
	global_load_dwordx4 v[188:191], v[182:183], off offset:512
	s_waitcnt vmcnt(21)
	v_pk_fma_f32 v[66:67], v[66:67], v[218:219], v[194:195]
	v_pk_fma_f32 v[64:65], v[64:65], v[216:217], v[192:193]
	global_store_dwordx4 v[174:175], v[64:67], off offset:64
	global_load_dwordx4 v[192:195], v[144:145], off offset:576
	s_waitcnt vmcnt(21)
	v_pk_fma_f32 v[58:59], v[58:59], v[218:219], v[198:199]
	v_pk_fma_f32 v[56:57], v[56:57], v[216:217], v[196:197]
	global_store_dwordx4 v[178:179], v[56:59], off offset:64
	global_load_dwordx4 v[196:199], v[146:147], off offset:576
	v_pk_add_f32 v[64:65], v[78:79], 0 op_sel_hi:[1,0]
	v_pk_add_f32 v[66:67], v[76:77], 0 op_sel_hi:[1,0]
	s_waitcnt vmcnt(21)
	v_pk_fma_f32 v[46:47], v[46:47], v[218:219], v[202:203]
	v_pk_fma_f32 v[44:45], v[44:45], v[216:217], v[200:201]
	global_store_dwordx4 v[182:183], v[44:47], off offset:64
	global_load_dwordx4 v[200:203], v[164:165], off offset:576
	s_waitcnt vmcnt(19)
	v_pk_fma_f32 v[58:59], v[64:65], v[206:207], v[210:211]
	v_pk_fma_f32 v[56:57], v[66:67], v[204:205], v[208:209]
	global_store_dwordx4 v[146:147], v[56:59], off offset:512
	global_load_dwordx4 v[208:211], v[166:167], off offset:576
	global_load_dwordx4 v[216:219], v[168:169], off offset:576
	v_pk_add_f32 v[64:65], v[70:71], 0 op_sel_hi:[1,0]
	v_pk_add_f32 v[66:67], v[68:69], 0 op_sel_hi:[1,0]
	s_waitcnt vmcnt(20)
	v_pk_fma_f32 v[58:59], v[64:65], v[206:207], v[186:187]
	v_pk_fma_f32 v[56:57], v[66:67], v[204:205], v[184:185]
	global_store_dwordx4 v[164:165], v[56:59], off offset:512
	global_load_dwordx4 v[184:187], v[170:171], off offset:576
	s_waitcnt vmcnt(20)
	v_pk_fma_f32 v[58:59], v[62:63], v[206:207], v[214:215]
	v_pk_fma_f32 v[56:57], v[60:61], v[204:205], v[212:213]
	global_store_dwordx4 v[166:167], v[56:59], off offset:512
	global_load_dwordx4 v[212:215], v[174:175], off offset:576
	s_waitcnt vmcnt(21)
	v_pk_fma_f32 v[54:55], v[54:55], v[206:207], v[222:223]
	v_pk_fma_f32 v[52:53], v[52:53], v[204:205], v[220:221]
	global_store_dwordx4 v[168:169], v[52:55], off offset:512
	global_load_dwordx4 v[220:223], v[178:179], off offset:576
	s_waitcnt vmcnt(21)
	v_pk_fma_f32 v[34:35], v[34:35], v[206:207], v[226:227]
	v_pk_fma_f32 v[32:33], v[32:33], v[204:205], v[224:225]
	global_store_dwordx4 v[170:171], v[32:35], off offset:512
	global_load_dwordx4 v[224:227], v[182:183], off offset:576
	s_waitcnt vmcnt(21)
	v_pk_fma_f32 v[26:27], v[26:27], v[206:207], v[230:231]
	v_pk_fma_f32 v[24:25], v[24:25], v[204:205], v[228:229]
	global_store_dwordx4 v[174:175], v[24:27], off offset:512
	s_waitcnt vmcnt(20)
	v_pk_fma_f32 v[22:23], v[22:23], v[206:207], v[234:235]
	v_pk_fma_f32 v[20:21], v[20:21], v[204:205], v[232:233]
	global_store_dwordx4 v[178:179], v[20:23], off offset:512
	v_pk_add_f32 v[24:25], v[50:51], 0 op_sel_hi:[1,0]
	v_pk_add_f32 v[26:27], v[48:49], 0 op_sel_hi:[1,0]
	s_waitcnt vmcnt(19)
	v_pk_fma_f32 v[18:19], v[18:19], v[206:207], v[190:191]
	v_pk_fma_f32 v[16:17], v[16:17], v[204:205], v[188:189]
	global_store_dwordx4 v[182:183], v[16:19], off offset:512
	s_waitcnt vmcnt(16)
	v_pk_fma_f32 v[22:23], v[24:25], v[194:195], v[198:199]
	v_pk_fma_f32 v[20:21], v[26:27], v[192:193], v[196:197]
	global_store_dwordx4 v[146:147], v[20:23], off offset:576
	v_pk_add_f32 v[24:25], v[42:43], 0 op_sel_hi:[1,0]
	v_pk_add_f32 v[26:27], v[40:41], 0 op_sel_hi:[1,0]
	s_waitcnt vmcnt(15)
	v_pk_fma_f32 v[22:23], v[24:25], v[194:195], v[202:203]
	v_pk_fma_f32 v[20:21], v[26:27], v[192:193], v[200:201]
	global_store_dwordx4 v[164:165], v[20:23], off offset:576
	v_pk_add_f32 v[24:25], v[38:39], 0 op_sel_hi:[1,0]
	v_pk_add_f32 v[26:27], v[36:37], 0 op_sel_hi:[1,0]
	s_waitcnt vmcnt(14)
	v_pk_fma_f32 v[22:23], v[24:25], v[194:195], v[210:211]
	v_pk_fma_f32 v[20:21], v[26:27], v[192:193], v[208:209]
	global_store_dwordx4 v[166:167], v[20:23], off offset:576
	v_pk_add_f32 v[24:25], v[30:31], 0 op_sel_hi:[1,0]
	v_pk_add_f32 v[26:27], v[28:29], 0 op_sel_hi:[1,0]
	s_waitcnt vmcnt(14)
	v_pk_fma_f32 v[22:23], v[24:25], v[194:195], v[218:219]
	v_pk_fma_f32 v[20:21], v[26:27], v[192:193], v[216:217]
	global_store_dwordx4 v[168:169], v[20:23], off offset:576
	s_waitcnt vmcnt(13)
	v_pk_fma_f32 v[14:15], v[14:15], v[194:195], v[186:187]
	v_pk_fma_f32 v[12:13], v[12:13], v[192:193], v[184:185]
	global_store_dwordx4 v[170:171], v[12:15], off offset:576
	s_waitcnt vmcnt(12)
	v_pk_fma_f32 v[10:11], v[10:11], v[194:195], v[214:215]
	v_pk_fma_f32 v[8:9], v[8:9], v[192:193], v[212:213]
	global_store_dwordx4 v[174:175], v[8:11], off offset:576
	s_waitcnt vmcnt(11)
	v_pk_fma_f32 v[6:7], v[6:7], v[194:195], v[222:223]
	v_pk_fma_f32 v[4:5], v[4:5], v[192:193], v[220:221]
	global_store_dwordx4 v[178:179], v[4:7], off offset:576
	s_waitcnt vmcnt(10)
	v_pk_fma_f32 v[2:3], v[2:3], v[194:195], v[226:227]
	v_pk_fma_f32 v[0:1], v[0:1], v[192:193], v[224:225]
	global_store_dwordx4 v[182:183], v[0:3], off offset:576
	s_cbranch_vccz .LBB0_2669
	s_waitcnt vmcnt(0)
	s_mov_b64 s[54:55], s[58:59]
	s_mov_b64 s[58:59], s[62:63]
	s_cmpk_gt_u32 s1, 0xff
	s_cbranch_scc1 .LBB0_2680
	s_barrier

.LBB0_2688:
	ds_read_b128 v[142:145], v139
	ds_read_b128 v[146:149], v139 offset:1024
	ds_read_b128 v[150:153], v139 offset:2048
	ds_read_b128 v[154:157], v139 offset:3072
	s_add_u32 s30, s28, 0x100
	s_addc_u32 s31, s29, 0
	s_cmp_eq_u32 s62, 4
	s_cselect_b32 s37, s19, s31
	s_cselect_b32 s36, s52, s30
	s_cselect_b32 s35, s17, s57
	s_cselect_b32 s34, s53, s56
	v_lshl_add_u64 v[190:191], s[28:29], 0, v[132:133]
	s_add_i32 m0, s5, 0xc000
	ds_read_b128 v[158:161], v140
	ds_read_b128 v[162:165], v140 offset:1024
	ds_read_b128 v[166:169], v140 offset:2048
	ds_read_b128 v[170:173], v140 offset:3072
	ds_read_b128 v[174:177], v140 offset:4096
	ds_read_b128 v[178:181], v140 offset:5120
	ds_read_b128 v[182:185], v140 offset:6144
	ds_read_b128 v[186:189], v140 offset:7168
	global_load_lds_dwordx4 v[190:191], off
	s_add_i32 m0, s5, 0xe000
	s_nop 0
	global_load_lds_dwordx4 v134, s[28:29]
	s_waitcnt lgkmcnt(8)
	s_barrier
	s_waitcnt lgkmcnt(0)
	s_waitcnt lgkmcnt(0)
	v_mfma_f32_16x16x32_bf16 v[124:127], v[142:145], v[158:161], v[124:127]
	v_mfma_f32_16x16x32_bf16 v[120:123], v[150:153], v[158:161], v[120:123]
	v_mfma_f32_16x16x32_bf16 v[116:119], v[142:145], v[166:169], v[116:119]
	v_mfma_f32_16x16x32_bf16 v[112:115], v[150:153], v[166:169], v[112:115]
	v_mfma_f32_16x16x32_bf16 v[100:103], v[142:145], v[174:177], v[100:103]
	v_mfma_f32_16x16x32_bf16 v[96:99], v[150:153], v[174:177], v[96:99]
	v_mfma_f32_16x16x32_bf16 v[84:87], v[142:145], v[182:185], v[84:87]
	v_mfma_f32_16x16x32_bf16 v[80:83], v[150:153], v[182:185], v[80:83]
	v_mfma_f32_16x16x32_bf16 v[124:127], v[146:149], v[162:165], v[124:127]
	v_mfma_f32_16x16x32_bf16 v[120:123], v[154:157], v[162:165], v[120:123]
	v_mfma_f32_16x16x32_bf16 v[116:119], v[146:149], v[170:173], v[116:119]
	v_mfma_f32_16x16x32_bf16 v[112:115], v[154:157], v[170:173], v[112:115]
	v_mfma_f32_16x16x32_bf16 v[100:103], v[146:149], v[178:181], v[100:103]
	v_mfma_f32_16x16x32_bf16 v[96:99], v[154:157], v[178:181], v[96:99]
	v_mfma_f32_16x16x32_bf16 v[84:87], v[146:149], v[186:189], v[84:87]
	v_mfma_f32_16x16x32_bf16 v[80:83], v[154:157], v[186:189], v[80:83]
	s_barrier
	s_add_i32 s28, s43, s4
	s_mov_b32 m0, s28
	ds_read_b128 v[190:193], v141
	ds_read_b128 v[194:197], v141 offset:1024
	ds_read_b128 v[198:201], v141 offset:2048
	ds_read_b128 v[202:205], v141 offset:3072
	global_load_lds_dwordx4 v130, s[34:35]
	s_add_i32 m0, s28, 0x2000
	s_nop 0
	global_load_lds_dwordx4 v128, s[34:35]
	s_barrier
	s_waitcnt lgkmcnt(0)
	s_waitcnt lgkmcnt(0)
	v_mfma_f32_16x16x32_bf16 v[108:111], v[190:193], v[158:161], v[108:111]
	v_mfma_f32_16x16x32_bf16 v[104:107], v[198:201], v[158:161], v[104:107]
	v_mfma_f32_16x16x32_bf16 v[92:95], v[190:193], v[166:169], v[92:95]
	v_mfma_f32_16x16x32_bf16 v[88:91], v[198:201], v[166:169], v[88:91]
	v_mfma_f32_16x16x32_bf16 v[76:79], v[190:193], v[174:177], v[76:79]
	v_mfma_f32_16x16x32_bf16 v[72:75], v[198:201], v[174:177], v[72:75]
	v_mfma_f32_16x16x32_bf16 v[68:71], v[190:193], v[182:185], v[68:71]
	v_mfma_f32_16x16x32_bf16 v[64:67], v[198:201], v[182:185], v[64:67]
	v_mfma_f32_16x16x32_bf16 v[108:111], v[194:197], v[162:165], v[108:111]
	v_mfma_f32_16x16x32_bf16 v[104:107], v[202:205], v[162:165], v[104:107]
	v_mfma_f32_16x16x32_bf16 v[92:95], v[194:197], v[170:173], v[92:95]
	v_mfma_f32_16x16x32_bf16 v[88:91], v[202:205], v[170:173], v[88:91]
	v_mfma_f32_16x16x32_bf16 v[76:79], v[194:197], v[178:181], v[76:79]
	v_mfma_f32_16x16x32_bf16 v[72:75], v[202:205], v[178:181], v[72:75]
	v_mfma_f32_16x16x32_bf16 v[68:71], v[194:197], v[186:189], v[68:71]
	v_mfma_f32_16x16x32_bf16 v[64:67], v[202:205], v[186:189], v[64:67]
	s_mov_b32 m0, s5
	v_lshl_add_u64 v[210:211], s[36:37], 0, v[130:131]
	s_barrier
	ds_read_b128 v[158:161], v140 offset:16384
	ds_read_b128 v[162:165], v140 offset:17408
	ds_read_b128 v[166:169], v140 offset:18432
	ds_read_b128 v[170:173], v140 offset:19456
	ds_read_b128 v[174:177], v140 offset:20480
	ds_read_b128 v[178:181], v140 offset:21504
	ds_read_b128 v[182:185], v140 offset:22528
	ds_read_b128 v[186:189], v140 offset:23552
	global_load_lds_dwordx4 v130, s[36:37]
	v_lshl_add_u64 v[212:213], s[36:37], 0, v[128:129]
	s_mov_b32 m0, s11
	s_nop 0
	global_load_lds_dwordx4 v128, s[36:37]
	s_barrier
	s_waitcnt lgkmcnt(0)
	s_waitcnt lgkmcnt(0)
	v_mfma_f32_16x16x32_bf16 v[60:63], v[142:145], v[158:161], v[60:63]
	v_mfma_f32_16x16x32_bf16 v[56:59], v[150:153], v[158:161], v[56:59]
	v_mfma_f32_16x16x32_bf16 v[52:55], v[142:145], v[166:169], v[52:55]
	v_mfma_f32_16x16x32_bf16 v[48:51], v[150:153], v[166:169], v[48:51]
	v_mfma_f32_16x16x32_bf16 v[36:39], v[142:145], v[174:177], v[36:39]
	v_mfma_f32_16x16x32_bf16 v[32:35], v[150:153], v[174:177], v[32:35]
	v_mfma_f32_16x16x32_bf16 v[20:23], v[142:145], v[182:185], v[20:23]
	v_mfma_f32_16x16x32_bf16 v[16:19], v[150:153], v[182:185], v[16:19]
	v_mfma_f32_16x16x32_bf16 v[60:63], v[146:149], v[162:165], v[60:63]
	v_mfma_f32_16x16x32_bf16 v[56:59], v[154:157], v[162:165], v[56:59]
	v_mfma_f32_16x16x32_bf16 v[52:55], v[146:149], v[170:173], v[52:55]
	v_mfma_f32_16x16x32_bf16 v[48:51], v[154:157], v[170:173], v[48:51]
	v_mfma_f32_16x16x32_bf16 v[36:39], v[146:149], v[178:181], v[36:39]
	v_mfma_f32_16x16x32_bf16 v[32:35], v[154:157], v[178:181], v[32:35]
	v_mfma_f32_16x16x32_bf16 v[20:23], v[146:149], v[186:189], v[20:23]
	v_mfma_f32_16x16x32_bf16 v[16:19], v[154:157], v[186:189], v[16:19]
	s_barrier
	s_add_u32 s28, s34, 0x100000
	s_addc_u32 s29, s35, 0
	s_add_i32 s63, s46, s4
	s_mov_b32 m0, s63
	s_nop 0
	global_load_lds_dwordx4 v130, s[28:29]
	s_add_i32 m0, s63, 0x2000
	s_nop 0
	global_load_lds_dwordx4 v128, s[28:29]
	s_waitcnt vmcnt(6)
	s_barrier
	v_mfma_f32_16x16x32_bf16 v[44:47], v[190:193], v[158:161], v[44:47]
	v_mfma_f32_16x16x32_bf16 v[40:43], v[198:201], v[158:161], v[40:43]
	v_mfma_f32_16x16x32_bf16 v[28:31], v[190:193], v[166:169], v[28:31]
	v_mfma_f32_16x16x32_bf16 v[24:27], v[198:201], v[166:169], v[24:27]
	v_mfma_f32_16x16x32_bf16 v[12:15], v[190:193], v[174:177], v[12:15]
	v_mfma_f32_16x16x32_bf16 v[8:11], v[198:201], v[174:177], v[8:11]
	v_mfma_f32_16x16x32_bf16 v[4:7], v[190:193], v[182:185], v[4:7]
	v_mfma_f32_16x16x32_bf16 v[0:3], v[198:201], v[182:185], v[0:3]
	v_mfma_f32_16x16x32_bf16 v[44:47], v[194:197], v[162:165], v[44:47]
	v_mfma_f32_16x16x32_bf16 v[40:43], v[202:205], v[162:165], v[40:43]
	v_mfma_f32_16x16x32_bf16 v[28:31], v[194:197], v[170:173], v[28:31]
	v_mfma_f32_16x16x32_bf16 v[24:27], v[202:205], v[170:173], v[24:27]
	v_mfma_f32_16x16x32_bf16 v[12:15], v[194:197], v[178:181], v[12:15]
	v_mfma_f32_16x16x32_bf16 v[8:11], v[202:205], v[178:181], v[8:11]
	v_mfma_f32_16x16x32_bf16 v[4:7], v[194:197], v[186:189], v[4:7]
	v_mfma_f32_16x16x32_bf16 v[0:3], v[202:205], v[186:189], v[0:3]
	s_add_i32 s63, 0, 0x18000
	v_add_u32_e32 v154, s63, v137
	s_barrier
	ds_read_b128 v[142:145], v154
	ds_read_b128 v[146:149], v154 offset:1024
	ds_read_b128 v[150:153], v154 offset:2048
	ds_read_b128 v[154:157], v154 offset:3072
	s_add_u32 s28, s36, 0x100000
	s_addc_u32 s29, s37, 0
	s_mov_b32 m0, s13
	ds_read_b128 v[158:161], v140 offset:32768
	ds_read_b128 v[162:165], v140 offset:33792
	ds_read_b128 v[166:169], v140 offset:34816
	ds_read_b128 v[170:173], v140 offset:35840
	ds_read_b128 v[174:177], v140 offset:36864
	ds_read_b128 v[178:181], v140 offset:37888
	ds_read_b128 v[182:185], v140 offset:38912
	ds_read_b128 v[186:189], v140 offset:39936
	global_load_lds_dwordx4 v130, s[28:29]
	s_mov_b32 m0, s38
	s_nop 0
	global_load_lds_dwordx4 v128, s[28:29]
	s_waitcnt lgkmcnt(8)
	s_barrier
	s_waitcnt lgkmcnt(0)
	s_waitcnt lgkmcnt(0)
	v_mfma_f32_16x16x32_bf16 v[124:127], v[142:145], v[158:161], v[124:127]
	v_mfma_f32_16x16x32_bf16 v[120:123], v[150:153], v[158:161], v[120:123]
	v_mfma_f32_16x16x32_bf16 v[116:119], v[142:145], v[166:169], v[116:119]
	v_mfma_f32_16x16x32_bf16 v[112:115], v[150:153], v[166:169], v[112:115]
	v_mfma_f32_16x16x32_bf16 v[100:103], v[142:145], v[174:177], v[100:103]
	v_mfma_f32_16x16x32_bf16 v[96:99], v[150:153], v[174:177], v[96:99]
	v_mfma_f32_16x16x32_bf16 v[84:87], v[142:145], v[182:185], v[84:87]
	v_mfma_f32_16x16x32_bf16 v[80:83], v[150:153], v[182:185], v[80:83]
	v_mfma_f32_16x16x32_bf16 v[124:127], v[146:149], v[162:165], v[124:127]
	v_mfma_f32_16x16x32_bf16 v[120:123], v[154:157], v[162:165], v[120:123]
	v_mfma_f32_16x16x32_bf16 v[116:119], v[146:149], v[170:173], v[116:119]
	v_mfma_f32_16x16x32_bf16 v[112:115], v[154:157], v[170:173], v[112:115]
	v_mfma_f32_16x16x32_bf16 v[100:103], v[146:149], v[178:181], v[100:103]
	v_mfma_f32_16x16x32_bf16 v[96:99], v[154:157], v[178:181], v[96:99]
	v_mfma_f32_16x16x32_bf16 v[84:87], v[146:149], v[186:189], v[84:87]
	v_mfma_f32_16x16x32_bf16 v[80:83], v[154:157], v[186:189], v[80:83]
	s_barrier
	s_add_i32 s36, 0, 0x1c000
	s_add_i32 s28, s63, s4
	v_add_u32_e32 v202, s36, v137
	s_add_u32 s98, s34, s14
	s_addc_u32 s99, s35, s15
	s_mov_b32 m0, s28
	ds_read_b128 v[190:193], v202
	ds_read_b128 v[194:197], v202 offset:1024
	ds_read_b128 v[198:201], v202 offset:2048
	ds_read_b128 v[202:205], v202 offset:3072
	global_load_lds_dwordx4 v130, s[98:99]
	s_add_i32 m0, s28, 0x2000
	s_nop 0
	global_load_lds_dwordx4 v128, s[98:99]
	s_barrier
	s_waitcnt lgkmcnt(0)
	s_waitcnt lgkmcnt(0)
	v_mfma_f32_16x16x32_bf16 v[108:111], v[190:193], v[158:161], v[108:111]
	v_mfma_f32_16x16x32_bf16 v[104:107], v[198:201], v[158:161], v[104:107]
	v_mfma_f32_16x16x32_bf16 v[92:95], v[190:193], v[166:169], v[92:95]
	v_mfma_f32_16x16x32_bf16 v[88:91], v[198:201], v[166:169], v[88:91]
	v_mfma_f32_16x16x32_bf16 v[76:79], v[190:193], v[174:177], v[76:79]
	v_mfma_f32_16x16x32_bf16 v[72:75], v[198:201], v[174:177], v[72:75]
	v_mfma_f32_16x16x32_bf16 v[68:71], v[190:193], v[182:185], v[68:71]
	v_mfma_f32_16x16x32_bf16 v[64:67], v[198:201], v[182:185], v[64:67]
	v_mfma_f32_16x16x32_bf16 v[108:111], v[194:197], v[162:165], v[108:111]
	v_mfma_f32_16x16x32_bf16 v[104:107], v[202:205], v[162:165], v[104:107]
	v_mfma_f32_16x16x32_bf16 v[92:95], v[194:197], v[170:173], v[92:95]
	v_mfma_f32_16x16x32_bf16 v[88:91], v[202:205], v[170:173], v[88:91]
	v_mfma_f32_16x16x32_bf16 v[76:79], v[194:197], v[178:181], v[76:79]
	v_mfma_f32_16x16x32_bf16 v[72:75], v[202:205], v[178:181], v[72:75]
	v_mfma_f32_16x16x32_bf16 v[68:71], v[194:197], v[186:189], v[68:71]
	v_mfma_f32_16x16x32_bf16 v[64:67], v[202:205], v[186:189], v[64:67]
	s_mov_b32 m0, s41
	v_lshl_add_u64 v[206:207], v[210:211], 0, s[14:15]
	s_barrier
	ds_read_b128 v[158:161], v140 offset:49152
	ds_read_b128 v[162:165], v140 offset:50176
	ds_read_b128 v[166:169], v140 offset:51200
	ds_read_b128 v[170:173], v140 offset:52224
	ds_read_b128 v[174:177], v140 offset:53248
	ds_read_b128 v[178:181], v140 offset:54272
	ds_read_b128 v[182:185], v140 offset:55296
	ds_read_b128 v[186:189], v140 offset:56320
	global_load_lds_dwordx4 v[206:207], off
	v_lshl_add_u64 v[206:207], v[212:213], 0, s[14:15]
	s_mov_b32 m0, s42
	s_nop 0
	global_load_lds_dwordx4 v[206:207], off
	s_barrier
	s_waitcnt lgkmcnt(0)
	s_waitcnt lgkmcnt(0)
	v_mfma_f32_16x16x32_bf16 v[60:63], v[142:145], v[158:161], v[60:63]
	v_mfma_f32_16x16x32_bf16 v[56:59], v[150:153], v[158:161], v[56:59]
	v_mfma_f32_16x16x32_bf16 v[52:55], v[142:145], v[166:169], v[52:55]
	v_mfma_f32_16x16x32_bf16 v[48:51], v[150:153], v[166:169], v[48:51]
	v_mfma_f32_16x16x32_bf16 v[36:39], v[142:145], v[174:177], v[36:39]
	v_mfma_f32_16x16x32_bf16 v[32:35], v[150:153], v[174:177], v[32:35]
	v_mfma_f32_16x16x32_bf16 v[20:23], v[142:145], v[182:185], v[20:23]
	v_mfma_f32_16x16x32_bf16 v[16:19], v[150:153], v[182:185], v[16:19]
	v_mfma_f32_16x16x32_bf16 v[60:63], v[146:149], v[162:165], v[60:63]
	v_mfma_f32_16x16x32_bf16 v[56:59], v[154:157], v[162:165], v[56:59]
	v_mfma_f32_16x16x32_bf16 v[52:55], v[146:149], v[170:173], v[52:55]
	v_mfma_f32_16x16x32_bf16 v[48:51], v[154:157], v[170:173], v[48:51]
	v_mfma_f32_16x16x32_bf16 v[36:39], v[146:149], v[178:181], v[36:39]
	v_mfma_f32_16x16x32_bf16 v[32:35], v[154:157], v[178:181], v[32:35]
	v_mfma_f32_16x16x32_bf16 v[20:23], v[146:149], v[186:189], v[20:23]
	v_mfma_f32_16x16x32_bf16 v[16:19], v[154:157], v[186:189], v[16:19]
	s_barrier
	s_add_u32 s28, s34, 0x100080
	s_addc_u32 s29, s35, 0
	s_add_i32 s34, s36, s4
	s_mov_b32 m0, s34
	s_nop 0
	global_load_lds_dwordx4 v130, s[28:29]
	s_add_i32 m0, s34, 0x2000
	s_nop 0
	global_load_lds_dwordx4 v128, s[28:29]
	s_waitcnt vmcnt(6)
	s_barrier
	v_mfma_f32_16x16x32_bf16 v[44:47], v[190:193], v[158:161], v[44:47]
	v_mfma_f32_16x16x32_bf16 v[40:43], v[198:201], v[158:161], v[40:43]
	v_mfma_f32_16x16x32_bf16 v[28:31], v[190:193], v[166:169], v[28:31]
	v_mfma_f32_16x16x32_bf16 v[24:27], v[198:201], v[166:169], v[24:27]
	v_mfma_f32_16x16x32_bf16 v[12:15], v[190:193], v[174:177], v[12:15]
	v_mfma_f32_16x16x32_bf16 v[8:11], v[198:201], v[174:177], v[8:11]
	v_mfma_f32_16x16x32_bf16 v[4:7], v[190:193], v[182:185], v[4:7]
	v_mfma_f32_16x16x32_bf16 v[0:3], v[198:201], v[182:185], v[0:3]
	v_mfma_f32_16x16x32_bf16 v[44:47], v[194:197], v[162:165], v[44:47]
	v_mfma_f32_16x16x32_bf16 v[40:43], v[202:205], v[162:165], v[40:43]
	v_mfma_f32_16x16x32_bf16 v[28:31], v[194:197], v[170:173], v[28:31]
	v_mfma_f32_16x16x32_bf16 v[24:27], v[202:205], v[170:173], v[24:27]
	v_mfma_f32_16x16x32_bf16 v[12:15], v[194:197], v[178:181], v[12:15]
	v_mfma_f32_16x16x32_bf16 v[8:11], v[202:205], v[178:181], v[8:11]
	v_mfma_f32_16x16x32_bf16 v[4:7], v[194:197], v[186:189], v[4:7]
	v_mfma_f32_16x16x32_bf16 v[0:3], v[202:205], v[186:189], v[0:3]
	s_add_i32 s62, s62, 2
	s_add_u32 s56, s56, 0x100
	s_addc_u32 s57, s57, 0
	s_cmp_gt_u32 s62, 5
	s_mov_b64 s[28:29], s[30:31]
	s_barrier
	s_cbranch_scc0 .LBB0_2688
	s_ashr_i32 s17, s40, 1
	s_and_b32 s17, s17, 0xfffffe00
	s_lshl_b32 s12, s12, 8
	s_add_i32 s12, s12, s17
	v_readlane_b32 s48, v240, 22
	v_add_u32_e32 v144, s12, v136
	v_readlane_b32 s49, v240, 23
	v_readlane_b32 s50, v240, 24
	v_readlane_b32 s51, v240, 25
	v_readlane_b32 s52, v240, 26
	v_readlane_b32 s53, v240, 27
	v_lshl_or_b32 v142, s10, 8, v138
	v_ashrrev_i32_e32 v145, 31, v144
	v_readlane_b32 s54, v240, 28
	v_readlane_b32 s55, v240, 29
	v_readlane_b32 s58, v240, 32
	v_readlane_b32 s59, v240, 33
	v_readlane_b32 s62, v240, 36
	v_readlane_b32 s63, v240, 37
	s_mov_b64 s[44:45], s[48:49]
	s_mov_b64 s[48:49], s[52:53]
	v_ashrrev_i32_e32 v143, 31, v142
	v_lshlrev_b64 v[146:147], 13, v[144:145]
	s_mov_b64 s[50:51], s[54:55]
	s_mov_b64 s[54:55], s[58:59]
	s_mov_b64 s[58:59], s[62:63]
	v_lshl_add_u64 v[146:147], s[58:59], 0, v[146:147]
	v_lshlrev_b64 v[142:143], 2, v[142:143]
	v_lshl_add_u64 v[146:147], v[146:147], 0, v[142:143]
	global_store_dwordx4 v[146:147], v[124:127], off
	global_store_dwordx4 v[146:147], v[120:123], off offset:64
	global_store_dwordx4 v[146:147], v[108:111], off offset:512
	global_store_dwordx4 v[146:147], v[104:107], off offset:576
	s_mov_b32 s10, 0x100000
	s_mov_b64 s[28:29], 0x100000
	v_or_b32_e32 v104, 16, v144
	v_ashrrev_i32_e32 v105, 31, v104
	v_lshlrev_b64 v[104:105], 13, v[104:105]
	v_lshl_add_u64 v[104:105], s[58:59], 0, v[104:105]
	v_lshl_add_u64 v[104:105], v[104:105], 0, v[142:143]
	global_store_dwordx4 v[104:105], v[116:119], off
	global_store_dwordx4 v[104:105], v[112:115], off offset:64
	global_store_dwordx4 v[104:105], v[92:95], off offset:512
	global_store_dwordx4 v[104:105], v[88:91], off offset:576
	s_mov_b32 s40, s47
	s_mov_b32 s12, s18
	v_or_b32_e32 v88, 32, v144
	v_ashrrev_i32_e32 v89, 31, v88
	v_lshlrev_b64 v[88:89], 13, v[88:89]
	v_lshl_add_u64 v[88:89], s[58:59], 0, v[88:89]
	v_lshl_add_u64 v[88:89], v[88:89], 0, v[142:143]
	global_store_dwordx4 v[88:89], v[100:103], off
	global_store_dwordx4 v[88:89], v[96:99], off offset:64
	global_store_dwordx4 v[88:89], v[76:79], off offset:512
	global_store_dwordx4 v[88:89], v[72:75], off offset:576
	s_mov_b64 s[30:31], s[26:27]
	v_readlane_b32 s56, v240, 30
	v_or_b32_e32 v72, 48, v144
	v_ashrrev_i32_e32 v73, 31, v72
	v_lshlrev_b64 v[72:73], 13, v[72:73]
	v_lshl_add_u64 v[72:73], s[58:59], 0, v[72:73]
	v_lshl_add_u64 v[72:73], v[72:73], 0, v[142:143]
	global_store_dwordx4 v[72:73], v[84:87], off
	global_store_dwordx4 v[72:73], v[80:83], off offset:64
	global_store_dwordx4 v[72:73], v[68:71], off offset:512
	global_store_dwordx4 v[72:73], v[64:67], off offset:576
	v_readlane_b32 s57, v240, 31
	v_readlane_b32 s60, v240, 34
	v_add_co_u32_e32 v66, vcc, s10, v146
	s_mov_b32 s10, 0x120000
	s_nop 0
	v_addc_co_u32_e32 v67, vcc, 0, v147, vcc
	v_lshl_add_u64 v[64:65], v[146:147], 0, s[28:29]
	global_store_dwordx4 v[66:67], v[60:63], off
	global_store_dwordx4 v[64:65], v[56:59], off offset:64
	global_store_dwordx4 v[64:65], v[44:47], off offset:512
	global_store_dwordx4 v[64:65], v[40:43], off offset:576
	s_mov_b64 s[28:29], 0x120000
	v_readlane_b32 s61, v240, 35
	v_add_co_u32_e32 v42, vcc, s10, v146
	s_mov_b32 s10, 0x140000
	s_nop 0
	v_addc_co_u32_e32 v43, vcc, 0, v147, vcc
	v_lshl_add_u64 v[40:41], v[146:147], 0, s[28:29]
	global_store_dwordx4 v[42:43], v[52:55], off
	global_store_dwordx4 v[40:41], v[48:51], off offset:64
	global_store_dwordx4 v[40:41], v[28:31], off offset:512
	global_store_dwordx4 v[40:41], v[24:27], off offset:576
	s_mov_b64 s[28:29], 0x140000
	s_nop 0
	v_add_co_u32_e32 v26, vcc, s10, v146
	v_lshl_add_u64 v[24:25], v[146:147], 0, s[28:29]
	s_nop 0
	v_addc_co_u32_e32 v27, vcc, 0, v147, vcc
	global_store_dwordx4 v[26:27], v[36:39], off
	global_store_dwordx4 v[24:25], v[32:35], off offset:64
	global_store_dwordx4 v[24:25], v[12:15], off offset:512
	global_store_dwordx4 v[24:25], v[8:11], off offset:576
	s_mov_b64 s[28:29], 0x160000
	s_mov_b32 s10, s16
	v_add_co_u32_e32 v10, vcc, 0x160000, v146
	v_lshl_add_u64 v[8:9], v[146:147], 0, s[28:29]
	s_nop 0
	v_addc_co_u32_e32 v11, vcc, 0, v147, vcc
	s_and_b64 vcc, exec, s[20:21]
	s_mov_b64 s[28:29], s[22:23]
	global_store_dwordx4 v[10:11], v[20:23], off
	global_store_dwordx4 v[8:9], v[16:19], off offset:64
	global_store_dwordx4 v[8:9], v[4:7], off offset:512
	global_store_dwordx4 v[8:9], v[0:3], off offset:576
	s_cbranch_vccz .LBB0_2685
	s_waitcnt vmcnt(0)
	s_cmpk_gt_u32 s1, 0xff
	s_cbranch_scc1 .LBB0_2692
	s_barrier

.LBB0_2812:
	ds_read_b128 v[148:151], v144
	ds_read_b128 v[152:155], v144 offset:1024
	ds_read_b128 v[156:159], v144 offset:2048
	ds_read_b128 v[160:163], v144 offset:3072
	s_add_u32 s26, s22, 0x100
	s_addc_u32 s27, s23, 0
	s_cmp_eq_u32 s57, 28
	s_cselect_b32 s31, s15, s27
	s_cselect_b32 s30, s47, s26
	s_cselect_b32 s29, s13, s56
	s_cselect_b32 s28, s52, s53
	s_add_i32 m0, s5, 0xc000
	ds_read_b128 v[164:167], v145
	ds_read_b128 v[168:171], v145 offset:1024
	ds_read_b128 v[172:175], v145 offset:2048
	ds_read_b128 v[176:179], v145 offset:3072
	ds_read_b128 v[180:183], v145 offset:4096
	ds_read_b128 v[184:187], v145 offset:5120
	ds_read_b128 v[188:191], v145 offset:6144
	ds_read_b128 v[192:195], v145 offset:7168
	global_load_lds_dwordx4 v134, s[22:23]
	s_add_i32 m0, s5, 0xe000
	s_nop 0
	global_load_lds_dwordx4 v136, s[22:23]
	s_waitcnt lgkmcnt(8)
	s_barrier
	s_waitcnt lgkmcnt(0)
	s_waitcnt lgkmcnt(0)
	v_mfma_f32_16x16x32_bf16 v[124:127], v[148:151], v[164:167], v[124:127]
	v_mfma_f32_16x16x32_bf16 v[120:123], v[156:159], v[164:167], v[120:123]
	v_mfma_f32_16x16x32_bf16 v[108:111], v[148:151], v[172:175], v[108:111]
	v_mfma_f32_16x16x32_bf16 v[104:107], v[156:159], v[172:175], v[104:107]
	v_mfma_f32_16x16x32_bf16 v[92:95], v[148:151], v[180:183], v[92:95]
	v_mfma_f32_16x16x32_bf16 v[88:91], v[156:159], v[180:183], v[88:91]
	v_mfma_f32_16x16x32_bf16 v[76:79], v[148:151], v[188:191], v[76:79]
	v_mfma_f32_16x16x32_bf16 v[72:75], v[156:159], v[188:191], v[72:75]
	v_mfma_f32_16x16x32_bf16 v[124:127], v[152:155], v[168:171], v[124:127]
	v_mfma_f32_16x16x32_bf16 v[120:123], v[160:163], v[168:171], v[120:123]
	v_mfma_f32_16x16x32_bf16 v[108:111], v[152:155], v[176:179], v[108:111]
	v_mfma_f32_16x16x32_bf16 v[104:107], v[160:163], v[176:179], v[104:107]
	v_mfma_f32_16x16x32_bf16 v[92:95], v[152:155], v[184:187], v[92:95]
	v_mfma_f32_16x16x32_bf16 v[88:91], v[160:163], v[184:187], v[88:91]
	v_mfma_f32_16x16x32_bf16 v[76:79], v[152:155], v[192:195], v[76:79]
	v_mfma_f32_16x16x32_bf16 v[72:75], v[160:163], v[192:195], v[72:75]
	s_barrier
	s_add_i32 s22, s42, s2
	s_mov_b32 m0, s22
	ds_read_b128 v[196:199], v146
	ds_read_b128 v[200:203], v146 offset:1024
	ds_read_b128 v[204:207], v146 offset:2048
	ds_read_b128 v[208:211], v146 offset:3072
	global_load_lds_dwordx4 v130, s[28:29]
	s_add_i32 m0, s22, 0x2000
	s_nop 0
	global_load_lds_dwordx4 v128, s[28:29]
	s_barrier
	s_waitcnt lgkmcnt(0)
	s_waitcnt lgkmcnt(0)
	v_mfma_f32_16x16x32_bf16 v[116:119], v[196:199], v[164:167], v[116:119]
	v_mfma_f32_16x16x32_bf16 v[112:115], v[204:207], v[164:167], v[112:115]
	v_mfma_f32_16x16x32_bf16 v[100:103], v[196:199], v[172:175], v[100:103]
	v_mfma_f32_16x16x32_bf16 v[96:99], v[204:207], v[172:175], v[96:99]
	v_mfma_f32_16x16x32_bf16 v[84:87], v[196:199], v[180:183], v[84:87]
	v_mfma_f32_16x16x32_bf16 v[80:83], v[204:207], v[180:183], v[80:83]
	v_mfma_f32_16x16x32_bf16 v[68:71], v[196:199], v[188:191], v[68:71]
	v_mfma_f32_16x16x32_bf16 v[64:67], v[204:207], v[188:191], v[64:67]
	v_mfma_f32_16x16x32_bf16 v[116:119], v[200:203], v[168:171], v[116:119]
	v_mfma_f32_16x16x32_bf16 v[112:115], v[208:211], v[168:171], v[112:115]
	v_mfma_f32_16x16x32_bf16 v[100:103], v[200:203], v[176:179], v[100:103]
	v_mfma_f32_16x16x32_bf16 v[96:99], v[208:211], v[176:179], v[96:99]
	v_mfma_f32_16x16x32_bf16 v[84:87], v[200:203], v[184:187], v[84:87]
	v_mfma_f32_16x16x32_bf16 v[80:83], v[208:211], v[184:187], v[80:83]
	v_mfma_f32_16x16x32_bf16 v[68:71], v[200:203], v[192:195], v[68:71]
	v_mfma_f32_16x16x32_bf16 v[64:67], v[208:211], v[192:195], v[64:67]
	s_mov_b32 m0, s5
	v_lshl_add_u64 v[216:217], s[30:31], 0, v[130:131]
	s_barrier
	ds_read_b128 v[164:167], v145 offset:16384
	ds_read_b128 v[168:171], v145 offset:17408
	ds_read_b128 v[172:175], v145 offset:18432
	ds_read_b128 v[176:179], v145 offset:19456
	ds_read_b128 v[180:183], v145 offset:20480
	ds_read_b128 v[184:187], v145 offset:21504
	ds_read_b128 v[188:191], v145 offset:22528
	ds_read_b128 v[192:195], v145 offset:23552
	global_load_lds_dwordx4 v130, s[30:31]
	v_lshl_add_u64 v[218:219], s[30:31], 0, v[128:129]
	s_mov_b32 m0, s34
	s_nop 0
	global_load_lds_dwordx4 v128, s[30:31]
	s_barrier
	s_waitcnt lgkmcnt(0)
	s_waitcnt lgkmcnt(0)
	v_mfma_f32_16x16x32_bf16 v[60:63], v[148:151], v[164:167], v[60:63]
	v_mfma_f32_16x16x32_bf16 v[56:59], v[156:159], v[164:167], v[56:59]
	v_mfma_f32_16x16x32_bf16 v[44:47], v[148:151], v[172:175], v[44:47]
	v_mfma_f32_16x16x32_bf16 v[40:43], v[156:159], v[172:175], v[40:43]
	v_mfma_f32_16x16x32_bf16 v[28:31], v[148:151], v[180:183], v[28:31]
	v_mfma_f32_16x16x32_bf16 v[24:27], v[156:159], v[180:183], v[24:27]
	v_mfma_f32_16x16x32_bf16 v[12:15], v[148:151], v[188:191], v[12:15]
	v_mfma_f32_16x16x32_bf16 v[8:11], v[156:159], v[188:191], v[8:11]
	v_mfma_f32_16x16x32_bf16 v[60:63], v[152:155], v[168:171], v[60:63]
	v_mfma_f32_16x16x32_bf16 v[56:59], v[160:163], v[168:171], v[56:59]
	v_mfma_f32_16x16x32_bf16 v[44:47], v[152:155], v[176:179], v[44:47]
	v_mfma_f32_16x16x32_bf16 v[40:43], v[160:163], v[176:179], v[40:43]
	v_mfma_f32_16x16x32_bf16 v[28:31], v[152:155], v[184:187], v[28:31]
	v_mfma_f32_16x16x32_bf16 v[24:27], v[160:163], v[184:187], v[24:27]
	v_mfma_f32_16x16x32_bf16 v[12:15], v[152:155], v[192:195], v[12:15]
	v_mfma_f32_16x16x32_bf16 v[8:11], v[160:163], v[192:195], v[8:11]
	s_barrier
	s_add_u32 s22, s28, 0x80000
	s_addc_u32 s23, s29, 0
	s_add_i32 s60, s43, s2
	s_mov_b32 m0, s60
	s_nop 0
	global_load_lds_dwordx4 v130, s[22:23]
	s_add_i32 m0, s60, 0x2000
	s_nop 0
	global_load_lds_dwordx4 v128, s[22:23]
	s_waitcnt vmcnt(6)
	s_barrier
	v_mfma_f32_16x16x32_bf16 v[52:55], v[196:199], v[164:167], v[52:55]
	v_mfma_f32_16x16x32_bf16 v[48:51], v[204:207], v[164:167], v[48:51]
	v_mfma_f32_16x16x32_bf16 v[36:39], v[196:199], v[172:175], v[36:39]
	v_mfma_f32_16x16x32_bf16 v[32:35], v[204:207], v[172:175], v[32:35]
	v_mfma_f32_16x16x32_bf16 v[20:23], v[196:199], v[180:183], v[20:23]
	v_mfma_f32_16x16x32_bf16 v[16:19], v[204:207], v[180:183], v[16:19]
	v_mfma_f32_16x16x32_bf16 v[4:7], v[196:199], v[188:191], v[4:7]
	v_mfma_f32_16x16x32_bf16 v[0:3], v[204:207], v[188:191], v[0:3]
	v_mfma_f32_16x16x32_bf16 v[52:55], v[200:203], v[168:171], v[52:55]
	v_mfma_f32_16x16x32_bf16 v[48:51], v[208:211], v[168:171], v[48:51]
	v_mfma_f32_16x16x32_bf16 v[36:39], v[200:203], v[176:179], v[36:39]
	v_mfma_f32_16x16x32_bf16 v[32:35], v[208:211], v[176:179], v[32:35]
	v_mfma_f32_16x16x32_bf16 v[20:23], v[200:203], v[184:187], v[20:23]
	v_mfma_f32_16x16x32_bf16 v[16:19], v[208:211], v[184:187], v[16:19]
	v_mfma_f32_16x16x32_bf16 v[4:7], v[200:203], v[192:195], v[4:7]
	v_mfma_f32_16x16x32_bf16 v[0:3], v[208:211], v[192:195], v[0:3]
	s_add_i32 s60, 0, 0x18000
	v_add_u32_e32 v147, s60, v143
	s_barrier
	ds_read_b128 v[148:151], v147
	ds_read_b128 v[152:155], v147 offset:1024
	ds_read_b128 v[156:159], v147 offset:2048
	ds_read_b128 v[160:163], v147 offset:3072
	s_add_u32 s22, s30, 0x80000
	s_addc_u32 s23, s31, 0
	s_mov_b32 m0, s35
	ds_read_b128 v[164:167], v145 offset:32768
	ds_read_b128 v[168:171], v145 offset:33792
	ds_read_b128 v[172:175], v145 offset:34816
	ds_read_b128 v[176:179], v145 offset:35840
	ds_read_b128 v[180:183], v145 offset:36864
	ds_read_b128 v[184:187], v145 offset:37888
	ds_read_b128 v[188:191], v145 offset:38912
	ds_read_b128 v[192:195], v145 offset:39936
	global_load_lds_dwordx4 v130, s[22:23]
	s_mov_b32 m0, s36
	s_nop 0
	global_load_lds_dwordx4 v128, s[22:23]
	s_waitcnt lgkmcnt(8)
	s_barrier
	s_waitcnt lgkmcnt(0)
	s_waitcnt lgkmcnt(0)
	v_mfma_f32_16x16x32_bf16 v[124:127], v[148:151], v[164:167], v[124:127]
	v_mfma_f32_16x16x32_bf16 v[120:123], v[156:159], v[164:167], v[120:123]
	v_mfma_f32_16x16x32_bf16 v[108:111], v[148:151], v[172:175], v[108:111]
	v_mfma_f32_16x16x32_bf16 v[104:107], v[156:159], v[172:175], v[104:107]
	v_mfma_f32_16x16x32_bf16 v[92:95], v[148:151], v[180:183], v[92:95]
	v_mfma_f32_16x16x32_bf16 v[88:91], v[156:159], v[180:183], v[88:91]
	v_mfma_f32_16x16x32_bf16 v[76:79], v[148:151], v[188:191], v[76:79]
	v_mfma_f32_16x16x32_bf16 v[72:75], v[156:159], v[188:191], v[72:75]
	v_mfma_f32_16x16x32_bf16 v[124:127], v[152:155], v[168:171], v[124:127]
	v_mfma_f32_16x16x32_bf16 v[120:123], v[160:163], v[168:171], v[120:123]
	v_mfma_f32_16x16x32_bf16 v[108:111], v[152:155], v[176:179], v[108:111]
	v_mfma_f32_16x16x32_bf16 v[104:107], v[160:163], v[176:179], v[104:107]
	v_mfma_f32_16x16x32_bf16 v[92:95], v[152:155], v[184:187], v[92:95]
	v_mfma_f32_16x16x32_bf16 v[88:91], v[160:163], v[184:187], v[88:91]
	v_mfma_f32_16x16x32_bf16 v[76:79], v[152:155], v[192:195], v[76:79]
	v_mfma_f32_16x16x32_bf16 v[72:75], v[160:163], v[192:195], v[72:75]
	s_barrier
	s_add_i32 s30, 0, 0x1c000
	s_add_i32 s22, s60, s2
	v_add_u32_e32 v147, s30, v143
	s_add_u32 s98, s28, s10
	s_addc_u32 s99, s29, s11
	s_mov_b32 m0, s22
	ds_read_b128 v[196:199], v147
	ds_read_b128 v[200:203], v147 offset:1024
	ds_read_b128 v[204:207], v147 offset:2048
	ds_read_b128 v[208:211], v147 offset:3072
	global_load_lds_dwordx4 v130, s[98:99]
	s_add_i32 m0, s22, 0x2000
	s_nop 0
	global_load_lds_dwordx4 v128, s[98:99]
	s_barrier
	s_waitcnt lgkmcnt(0)
	s_waitcnt lgkmcnt(0)
	v_mfma_f32_16x16x32_bf16 v[116:119], v[196:199], v[164:167], v[116:119]
	v_mfma_f32_16x16x32_bf16 v[112:115], v[204:207], v[164:167], v[112:115]
	v_mfma_f32_16x16x32_bf16 v[100:103], v[196:199], v[172:175], v[100:103]
	v_mfma_f32_16x16x32_bf16 v[96:99], v[204:207], v[172:175], v[96:99]
	v_mfma_f32_16x16x32_bf16 v[84:87], v[196:199], v[180:183], v[84:87]
	v_mfma_f32_16x16x32_bf16 v[80:83], v[204:207], v[180:183], v[80:83]
	v_mfma_f32_16x16x32_bf16 v[68:71], v[196:199], v[188:191], v[68:71]
	v_mfma_f32_16x16x32_bf16 v[64:67], v[204:207], v[188:191], v[64:67]
	v_mfma_f32_16x16x32_bf16 v[116:119], v[200:203], v[168:171], v[116:119]
	v_mfma_f32_16x16x32_bf16 v[112:115], v[208:211], v[168:171], v[112:115]
	v_mfma_f32_16x16x32_bf16 v[100:103], v[200:203], v[176:179], v[100:103]
	v_mfma_f32_16x16x32_bf16 v[96:99], v[208:211], v[176:179], v[96:99]
	v_mfma_f32_16x16x32_bf16 v[84:87], v[200:203], v[184:187], v[84:87]
	v_mfma_f32_16x16x32_bf16 v[80:83], v[208:211], v[184:187], v[80:83]
	v_mfma_f32_16x16x32_bf16 v[68:71], v[200:203], v[192:195], v[68:71]
	v_mfma_f32_16x16x32_bf16 v[64:67], v[208:211], v[192:195], v[64:67]
	s_mov_b32 m0, s38
	v_lshl_add_u64 v[212:213], v[216:217], 0, s[10:11]
	s_barrier
	ds_read_b128 v[164:167], v145 offset:49152
	ds_read_b128 v[168:171], v145 offset:50176
	ds_read_b128 v[172:175], v145 offset:51200
	ds_read_b128 v[176:179], v145 offset:52224
	ds_read_b128 v[180:183], v145 offset:53248
	ds_read_b128 v[184:187], v145 offset:54272
	ds_read_b128 v[188:191], v145 offset:55296
	ds_read_b128 v[192:195], v145 offset:56320
	global_load_lds_dwordx4 v[212:213], off
	v_lshl_add_u64 v[212:213], v[218:219], 0, s[10:11]
	s_mov_b32 m0, s39
	s_nop 0
	global_load_lds_dwordx4 v[212:213], off
	s_barrier
	s_waitcnt lgkmcnt(0)
	s_waitcnt lgkmcnt(0)
	v_mfma_f32_16x16x32_bf16 v[60:63], v[148:151], v[164:167], v[60:63]
	v_mfma_f32_16x16x32_bf16 v[56:59], v[156:159], v[164:167], v[56:59]
	v_mfma_f32_16x16x32_bf16 v[44:47], v[148:151], v[172:175], v[44:47]
	v_mfma_f32_16x16x32_bf16 v[40:43], v[156:159], v[172:175], v[40:43]
	v_mfma_f32_16x16x32_bf16 v[28:31], v[148:151], v[180:183], v[28:31]
	v_mfma_f32_16x16x32_bf16 v[24:27], v[156:159], v[180:183], v[24:27]
	v_mfma_f32_16x16x32_bf16 v[12:15], v[148:151], v[188:191], v[12:15]
	v_mfma_f32_16x16x32_bf16 v[8:11], v[156:159], v[188:191], v[8:11]
	v_mfma_f32_16x16x32_bf16 v[60:63], v[152:155], v[168:171], v[60:63]
	v_mfma_f32_16x16x32_bf16 v[56:59], v[160:163], v[168:171], v[56:59]
	v_mfma_f32_16x16x32_bf16 v[44:47], v[152:155], v[176:179], v[44:47]
	v_mfma_f32_16x16x32_bf16 v[40:43], v[160:163], v[176:179], v[40:43]
	v_mfma_f32_16x16x32_bf16 v[28:31], v[152:155], v[184:187], v[28:31]
	v_mfma_f32_16x16x32_bf16 v[24:27], v[160:163], v[184:187], v[24:27]
	v_mfma_f32_16x16x32_bf16 v[12:15], v[152:155], v[192:195], v[12:15]
	v_mfma_f32_16x16x32_bf16 v[8:11], v[160:163], v[192:195], v[8:11]
	s_barrier
	s_add_u32 s22, s28, 0x80080
	s_addc_u32 s23, s29, 0
	s_add_i32 s28, s30, s2
	s_mov_b32 m0, s28
	s_nop 0
	global_load_lds_dwordx4 v130, s[22:23]
	s_add_i32 m0, s28, 0x2000
	s_nop 0
	global_load_lds_dwordx4 v128, s[22:23]
	s_waitcnt vmcnt(6)
	s_barrier
	v_mfma_f32_16x16x32_bf16 v[52:55], v[196:199], v[164:167], v[52:55]
	v_mfma_f32_16x16x32_bf16 v[48:51], v[204:207], v[164:167], v[48:51]
	v_mfma_f32_16x16x32_bf16 v[36:39], v[196:199], v[172:175], v[36:39]
	v_mfma_f32_16x16x32_bf16 v[32:35], v[204:207], v[172:175], v[32:35]
	v_mfma_f32_16x16x32_bf16 v[20:23], v[196:199], v[180:183], v[20:23]
	v_mfma_f32_16x16x32_bf16 v[16:19], v[204:207], v[180:183], v[16:19]
	v_mfma_f32_16x16x32_bf16 v[4:7], v[196:199], v[188:191], v[4:7]
	v_mfma_f32_16x16x32_bf16 v[0:3], v[204:207], v[188:191], v[0:3]
	v_mfma_f32_16x16x32_bf16 v[52:55], v[200:203], v[168:171], v[52:55]
	v_mfma_f32_16x16x32_bf16 v[48:51], v[208:211], v[168:171], v[48:51]
	v_mfma_f32_16x16x32_bf16 v[36:39], v[200:203], v[176:179], v[36:39]
	v_mfma_f32_16x16x32_bf16 v[32:35], v[208:211], v[176:179], v[32:35]
	v_mfma_f32_16x16x32_bf16 v[20:23], v[200:203], v[184:187], v[20:23]
	v_mfma_f32_16x16x32_bf16 v[16:19], v[208:211], v[184:187], v[16:19]
	v_mfma_f32_16x16x32_bf16 v[4:7], v[200:203], v[192:195], v[4:7]
	v_mfma_f32_16x16x32_bf16 v[0:3], v[208:211], v[192:195], v[0:3]
	s_add_i32 s57, s57, 2
	s_add_u32 s53, s53, 0x100
	s_addc_u32 s56, s56, 0
	s_cmp_gt_u32 s57, 29
	s_mov_b64 s[22:23], s[26:27]
	s_barrier
	s_cbranch_scc0 .LBB0_2812
	v_mul_f32_e32 v150, 0xbfb8aa3b, v124
	v_mul_f32_e32 v151, 0xbfb8aa3b, v125
	v_exp_f32_e32 v150, v150
	v_exp_f32_e32 v151, v151
	s_lshl_b32 s13, s21, 7
	v_lshl_add_u32 v147, s20, 8, v142
	v_add_f32_e32 v150, 1.0, v150
	v_add_f32_e32 v151, 1.0, v151
	v_rcp_f32_e32 v150, v150
	v_rcp_f32_e32 v151, v151
	s_or_b32 s20, s13, s40
	s_ashr_i32 s21, s20, 31
	v_mad_i64_i32 v[148:149], s[22:23], v147, s46, v[132:133]
	v_pk_mul_f32 v[124:125], v[124:125], v[150:151]
	s_lshl_b64 s[20:21], s[20:21], 1
	v_pk_mul_f32 v[120:121], v[120:121], v[124:125]
	s_and_b64 vcc, exec, s[8:9]
	v_cvt_pk_bf16_f32 v120, v120, v121
	v_mul_f32_e32 v121, 0xbfb8aa3b, v126
	v_exp_f32_e32 v121, v121
	s_mov_b64 s[26:27], s[18:19]
	v_add_f32_e32 v121, 1.0, v121
	v_rcp_f32_e32 v124, v121
	v_mul_f32_e32 v121, 0xbfb8aa3b, v127
	v_exp_f32_e32 v121, v121
	s_nop 0
	v_add_f32_e32 v121, 1.0, v121
	v_rcp_f32_e32 v125, v121
	s_nop 0
	v_pk_mul_f32 v[124:125], v[126:127], v[124:125]
	s_nop 0
	v_pk_mul_f32 v[122:123], v[122:123], v[124:125]
	s_nop 0
	v_cvt_pk_bf16_f32 v121, v122, v123
	v_lshl_add_u64 v[122:123], v[148:149], 0, s[20:21]
	global_store_dwordx2 v[122:123], v[120:121], off
	v_mul_f32_e32 v120, 0xbfb8aa3b, v116
	v_mul_f32_e32 v121, 0xbfb8aa3b, v117
	v_exp_f32_e32 v120, v120
	v_exp_f32_e32 v121, v121
	v_add_f32_e32 v120, 1.0, v120
	v_add_f32_e32 v121, 1.0, v121
	v_rcp_f32_e32 v120, v120
	v_rcp_f32_e32 v121, v121
	s_nop 0
	v_pk_mul_f32 v[116:117], v[116:117], v[120:121]
	s_nop 0
	v_pk_mul_f32 v[112:113], v[112:113], v[116:117]
	s_nop 0
	v_cvt_pk_bf16_f32 v112, v112, v113
	v_mul_f32_e32 v113, 0xbfb8aa3b, v118
	v_exp_f32_e32 v113, v113
	s_nop 0
	v_add_f32_e32 v113, 1.0, v113
	v_rcp_f32_e32 v116, v113
	v_mul_f32_e32 v113, 0xbfb8aa3b, v119
	v_exp_f32_e32 v113, v113
	s_nop 0
	v_add_f32_e32 v113, 1.0, v113
	v_rcp_f32_e32 v117, v113
	s_nop 0
	v_pk_mul_f32 v[116:117], v[118:119], v[116:117]
	s_nop 0
	v_pk_mul_f32 v[114:115], v[114:115], v[116:117]
	s_nop 0
	v_cvt_pk_bf16_f32 v113, v114, v115
	v_mul_f32_e32 v114, 0xbfb8aa3b, v108
	v_mul_f32_e32 v115, 0xbfb8aa3b, v109
	v_exp_f32_e32 v114, v114
	v_exp_f32_e32 v115, v115
	global_store_dwordx2 v[122:123], v[112:113], off offset:128
	v_or_b32_e32 v112, 16, v147
	v_add_f32_e32 v114, 1.0, v114
	v_add_f32_e32 v115, 1.0, v115
	v_rcp_f32_e32 v114, v114
	v_rcp_f32_e32 v115, v115
	v_mad_i64_i32 v[112:113], s[22:23], v112, s46, v[132:133]
	v_pk_mul_f32 v[108:109], v[108:109], v[114:115]
	s_nop 0
	v_pk_mul_f32 v[104:105], v[104:105], v[108:109]
	s_nop 0
	v_cvt_pk_bf16_f32 v104, v104, v105
	v_mul_f32_e32 v105, 0xbfb8aa3b, v110
	v_exp_f32_e32 v105, v105
	s_nop 0
	v_add_f32_e32 v105, 1.0, v105
	v_rcp_f32_e32 v108, v105
	v_mul_f32_e32 v105, 0xbfb8aa3b, v111
	v_exp_f32_e32 v105, v105
	s_nop 0
	v_add_f32_e32 v105, 1.0, v105
	v_rcp_f32_e32 v109, v105
	s_nop 0
	v_pk_mul_f32 v[108:109], v[110:111], v[108:109]
	s_nop 0
	v_pk_mul_f32 v[106:107], v[106:107], v[108:109]
	s_nop 0
	v_cvt_pk_bf16_f32 v105, v106, v107
	v_lshl_add_u64 v[106:107], v[112:113], 0, s[20:21]
	global_store_dwordx2 v[106:107], v[104:105], off
	v_mul_f32_e32 v104, 0xbfb8aa3b, v100
	v_mul_f32_e32 v105, 0xbfb8aa3b, v101
	v_exp_f32_e32 v104, v104
	v_exp_f32_e32 v105, v105
	v_add_f32_e32 v104, 1.0, v104
	v_add_f32_e32 v105, 1.0, v105
	v_rcp_f32_e32 v104, v104
	v_rcp_f32_e32 v105, v105
	s_nop 0
	v_pk_mul_f32 v[100:101], v[100:101], v[104:105]
	s_nop 0
	v_pk_mul_f32 v[96:97], v[96:97], v[100:101]
	s_nop 0
	v_cvt_pk_bf16_f32 v96, v96, v97
	v_mul_f32_e32 v97, 0xbfb8aa3b, v102
	v_exp_f32_e32 v97, v97
	s_nop 0
	v_add_f32_e32 v97, 1.0, v97
	v_rcp_f32_e32 v100, v97
	v_mul_f32_e32 v97, 0xbfb8aa3b, v103
	v_exp_f32_e32 v97, v97
	s_nop 0
	v_add_f32_e32 v97, 1.0, v97
	v_rcp_f32_e32 v101, v97
	s_nop 0
	v_pk_mul_f32 v[100:101], v[102:103], v[100:101]
	s_nop 0
	v_pk_mul_f32 v[98:99], v[98:99], v[100:101]
	s_nop 0
	v_cvt_pk_bf16_f32 v97, v98, v99
	v_mul_f32_e32 v98, 0xbfb8aa3b, v92
	v_mul_f32_e32 v99, 0xbfb8aa3b, v93
	v_exp_f32_e32 v98, v98
	v_exp_f32_e32 v99, v99
	global_store_dwordx2 v[106:107], v[96:97], off offset:128
	v_or_b32_e32 v96, 32, v147
	v_add_f32_e32 v98, 1.0, v98
	v_add_f32_e32 v99, 1.0, v99
	v_rcp_f32_e32 v98, v98
	v_rcp_f32_e32 v99, v99
	v_mad_i64_i32 v[96:97], s[22:23], v96, s46, v[132:133]
	v_pk_mul_f32 v[92:93], v[92:93], v[98:99]
	s_nop 0
	v_pk_mul_f32 v[88:89], v[88:89], v[92:93]
	s_nop 0
	v_cvt_pk_bf16_f32 v88, v88, v89
	v_mul_f32_e32 v89, 0xbfb8aa3b, v94
	v_exp_f32_e32 v89, v89
	s_nop 0
	v_add_f32_e32 v89, 1.0, v89
	v_rcp_f32_e32 v92, v89
	v_mul_f32_e32 v89, 0xbfb8aa3b, v95
	v_exp_f32_e32 v89, v89
	s_nop 0
	v_add_f32_e32 v89, 1.0, v89
	v_rcp_f32_e32 v93, v89
	s_nop 0
	v_pk_mul_f32 v[92:93], v[94:95], v[92:93]
	s_nop 0
	v_pk_mul_f32 v[90:91], v[90:91], v[92:93]
	s_nop 0
	v_cvt_pk_bf16_f32 v89, v90, v91
	v_lshl_add_u64 v[90:91], v[96:97], 0, s[20:21]
	global_store_dwordx2 v[90:91], v[88:89], off
	v_mul_f32_e32 v88, 0xbfb8aa3b, v84
	v_mul_f32_e32 v89, 0xbfb8aa3b, v85
	v_exp_f32_e32 v88, v88
	v_exp_f32_e32 v89, v89
	v_add_f32_e32 v88, 1.0, v88
	v_add_f32_e32 v89, 1.0, v89
	v_rcp_f32_e32 v88, v88
	v_rcp_f32_e32 v89, v89
	s_nop 0
	v_pk_mul_f32 v[84:85], v[84:85], v[88:89]
	s_nop 0
	v_pk_mul_f32 v[80:81], v[80:81], v[84:85]
	s_nop 0
	v_cvt_pk_bf16_f32 v80, v80, v81
	v_mul_f32_e32 v81, 0xbfb8aa3b, v86
	v_exp_f32_e32 v81, v81
	s_nop 0
	v_add_f32_e32 v81, 1.0, v81
	v_rcp_f32_e32 v84, v81
	v_mul_f32_e32 v81, 0xbfb8aa3b, v87
	v_exp_f32_e32 v81, v81
	s_nop 0
	v_add_f32_e32 v81, 1.0, v81
	v_rcp_f32_e32 v85, v81
	s_nop 0
	v_pk_mul_f32 v[84:85], v[86:87], v[84:85]
	s_nop 0
	v_pk_mul_f32 v[82:83], v[82:83], v[84:85]
	s_nop 0
	v_cvt_pk_bf16_f32 v81, v82, v83
	v_mul_f32_e32 v82, 0xbfb8aa3b, v76
	v_mul_f32_e32 v83, 0xbfb8aa3b, v77
	v_exp_f32_e32 v82, v82
	v_exp_f32_e32 v83, v83
	global_store_dwordx2 v[90:91], v[80:81], off offset:128
	v_or_b32_e32 v80, 48, v147
	v_add_f32_e32 v82, 1.0, v82
	v_add_f32_e32 v83, 1.0, v83
	v_rcp_f32_e32 v82, v82
	v_rcp_f32_e32 v83, v83
	v_mad_i64_i32 v[80:81], s[22:23], v80, s46, v[132:133]
	v_pk_mul_f32 v[76:77], v[76:77], v[82:83]
	s_nop 0
	v_pk_mul_f32 v[72:73], v[72:73], v[76:77]
	s_nop 0
	v_cvt_pk_bf16_f32 v72, v72, v73
	v_mul_f32_e32 v73, 0xbfb8aa3b, v78
	v_exp_f32_e32 v73, v73
	s_nop 0
	v_add_f32_e32 v73, 1.0, v73
	v_rcp_f32_e32 v76, v73
	v_mul_f32_e32 v73, 0xbfb8aa3b, v79
	v_exp_f32_e32 v73, v73
	s_nop 0
	v_add_f32_e32 v73, 1.0, v73
	v_rcp_f32_e32 v77, v73
	s_nop 0
	v_pk_mul_f32 v[76:77], v[78:79], v[76:77]
	s_nop 0
	v_pk_mul_f32 v[74:75], v[74:75], v[76:77]
	s_nop 0
	v_cvt_pk_bf16_f32 v73, v74, v75
	v_lshl_add_u64 v[74:75], v[80:81], 0, s[20:21]
	global_store_dwordx2 v[74:75], v[72:73], off
	v_mul_f32_e32 v72, 0xbfb8aa3b, v68
	v_mul_f32_e32 v73, 0xbfb8aa3b, v69
	v_exp_f32_e32 v72, v72
	v_exp_f32_e32 v73, v73
	v_add_f32_e32 v72, 1.0, v72
	v_add_f32_e32 v73, 1.0, v73
	v_rcp_f32_e32 v72, v72
	v_rcp_f32_e32 v73, v73
	s_nop 0
	v_pk_mul_f32 v[68:69], v[68:69], v[72:73]
	s_nop 0
	v_pk_mul_f32 v[64:65], v[64:65], v[68:69]
	s_nop 0
	v_cvt_pk_bf16_f32 v64, v64, v65
	v_mul_f32_e32 v65, 0xbfb8aa3b, v70
	v_exp_f32_e32 v65, v65
	s_nop 0
	v_add_f32_e32 v65, 1.0, v65
	v_rcp_f32_e32 v68, v65
	v_mul_f32_e32 v65, 0xbfb8aa3b, v71
	v_exp_f32_e32 v65, v65
	s_nop 0
	v_add_f32_e32 v65, 1.0, v65
	v_rcp_f32_e32 v69, v65
	s_nop 0
	v_pk_mul_f32 v[68:69], v[70:71], v[68:69]
	s_nop 0
	v_pk_mul_f32 v[66:67], v[66:67], v[68:69]
	s_nop 0
	v_cvt_pk_bf16_f32 v65, v66, v67
	v_mul_f32_e32 v66, 0xbfb8aa3b, v60
	v_mul_f32_e32 v67, 0xbfb8aa3b, v61
	v_exp_f32_e32 v66, v66
	v_exp_f32_e32 v67, v67
	global_store_dwordx2 v[74:75], v[64:65], off offset:128
	v_add_u32_e32 v64, 0x80, v147
	v_add_f32_e32 v66, 1.0, v66
	v_add_f32_e32 v67, 1.0, v67
	v_rcp_f32_e32 v66, v66
	v_rcp_f32_e32 v67, v67
	v_mad_i64_i32 v[64:65], s[22:23], v64, s46, v[132:133]
	v_pk_mul_f32 v[60:61], v[60:61], v[66:67]
	s_nop 0
	v_pk_mul_f32 v[56:57], v[56:57], v[60:61]
	s_nop 0
	v_cvt_pk_bf16_f32 v56, v56, v57
	v_mul_f32_e32 v57, 0xbfb8aa3b, v62
	v_exp_f32_e32 v57, v57
	s_nop 0
	v_add_f32_e32 v57, 1.0, v57
	v_rcp_f32_e32 v60, v57
	v_mul_f32_e32 v57, 0xbfb8aa3b, v63
	v_exp_f32_e32 v57, v57
	s_nop 0
	v_add_f32_e32 v57, 1.0, v57
	v_rcp_f32_e32 v61, v57
	s_nop 0
	v_pk_mul_f32 v[60:61], v[62:63], v[60:61]
	s_nop 0
	v_pk_mul_f32 v[58:59], v[58:59], v[60:61]
	s_nop 0
	v_cvt_pk_bf16_f32 v57, v58, v59
	v_lshl_add_u64 v[58:59], v[64:65], 0, s[20:21]
	global_store_dwordx2 v[58:59], v[56:57], off
	v_mul_f32_e32 v56, 0xbfb8aa3b, v52
	v_mul_f32_e32 v57, 0xbfb8aa3b, v53
	v_exp_f32_e32 v56, v56
	v_exp_f32_e32 v57, v57
	v_add_f32_e32 v56, 1.0, v56
	v_add_f32_e32 v57, 1.0, v57
	v_rcp_f32_e32 v56, v56
	v_rcp_f32_e32 v57, v57
	s_nop 0
	v_pk_mul_f32 v[52:53], v[52:53], v[56:57]
	s_nop 0
	v_pk_mul_f32 v[48:49], v[48:49], v[52:53]
	s_nop 0
	v_cvt_pk_bf16_f32 v48, v48, v49
	v_mul_f32_e32 v49, 0xbfb8aa3b, v54
	v_exp_f32_e32 v49, v49
	s_nop 0
	v_add_f32_e32 v49, 1.0, v49
	v_rcp_f32_e32 v52, v49
	v_mul_f32_e32 v49, 0xbfb8aa3b, v55
	v_exp_f32_e32 v49, v49
	s_nop 0
	v_add_f32_e32 v49, 1.0, v49
	v_rcp_f32_e32 v53, v49
	s_nop 0
	v_pk_mul_f32 v[52:53], v[54:55], v[52:53]
	s_nop 0
	v_pk_mul_f32 v[50:51], v[50:51], v[52:53]
	s_nop 0
	v_cvt_pk_bf16_f32 v49, v50, v51
	v_mul_f32_e32 v50, 0xbfb8aa3b, v44
	v_mul_f32_e32 v51, 0xbfb8aa3b, v45
	v_exp_f32_e32 v50, v50
	v_exp_f32_e32 v51, v51
	global_store_dwordx2 v[58:59], v[48:49], off offset:128
	v_add_u32_e32 v48, 0x90, v147
	v_add_f32_e32 v50, 1.0, v50
	v_add_f32_e32 v51, 1.0, v51
	v_rcp_f32_e32 v50, v50
	v_rcp_f32_e32 v51, v51
	v_mad_i64_i32 v[48:49], s[22:23], v48, s46, v[132:133]
	v_pk_mul_f32 v[44:45], v[44:45], v[50:51]
	s_nop 0
	v_pk_mul_f32 v[40:41], v[40:41], v[44:45]
	s_nop 0
	v_cvt_pk_bf16_f32 v40, v40, v41
	v_mul_f32_e32 v41, 0xbfb8aa3b, v46
	v_exp_f32_e32 v41, v41
	s_nop 0
	v_add_f32_e32 v41, 1.0, v41
	v_rcp_f32_e32 v44, v41
	v_mul_f32_e32 v41, 0xbfb8aa3b, v47
	v_exp_f32_e32 v41, v41
	s_nop 0
	v_add_f32_e32 v41, 1.0, v41
	v_rcp_f32_e32 v45, v41
	s_nop 0
	v_pk_mul_f32 v[44:45], v[46:47], v[44:45]
	s_nop 0
	v_pk_mul_f32 v[42:43], v[42:43], v[44:45]
	s_nop 0
	v_cvt_pk_bf16_f32 v41, v42, v43
	v_lshl_add_u64 v[42:43], v[48:49], 0, s[20:21]
	global_store_dwordx2 v[42:43], v[40:41], off
	v_mul_f32_e32 v40, 0xbfb8aa3b, v36
	v_mul_f32_e32 v41, 0xbfb8aa3b, v37
	v_exp_f32_e32 v40, v40
	v_exp_f32_e32 v41, v41
	v_add_f32_e32 v40, 1.0, v40
	v_add_f32_e32 v41, 1.0, v41
	v_rcp_f32_e32 v40, v40
	v_rcp_f32_e32 v41, v41
	s_nop 0
	v_pk_mul_f32 v[36:37], v[36:37], v[40:41]
	s_nop 0
	v_pk_mul_f32 v[32:33], v[32:33], v[36:37]
	s_nop 0
	v_cvt_pk_bf16_f32 v32, v32, v33
	v_mul_f32_e32 v33, 0xbfb8aa3b, v38
	v_exp_f32_e32 v33, v33
	s_nop 0
	v_add_f32_e32 v33, 1.0, v33
	v_rcp_f32_e32 v36, v33
	v_mul_f32_e32 v33, 0xbfb8aa3b, v39
	v_exp_f32_e32 v33, v33
	s_nop 0
	v_add_f32_e32 v33, 1.0, v33
	v_rcp_f32_e32 v37, v33
	s_nop 0
	v_pk_mul_f32 v[36:37], v[38:39], v[36:37]
	s_nop 0
	v_pk_mul_f32 v[34:35], v[34:35], v[36:37]
	s_nop 0
	v_cvt_pk_bf16_f32 v33, v34, v35
	v_mul_f32_e32 v34, 0xbfb8aa3b, v28
	v_mul_f32_e32 v35, 0xbfb8aa3b, v29
	v_exp_f32_e32 v34, v34
	v_exp_f32_e32 v35, v35
	global_store_dwordx2 v[42:43], v[32:33], off offset:128
	v_add_u32_e32 v32, 0xa0, v147
	v_add_f32_e32 v34, 1.0, v34
	v_add_f32_e32 v35, 1.0, v35
	v_rcp_f32_e32 v34, v34
	v_rcp_f32_e32 v35, v35
	v_mad_i64_i32 v[32:33], s[22:23], v32, s46, v[132:133]
	v_pk_mul_f32 v[28:29], v[28:29], v[34:35]
	s_nop 0
	v_pk_mul_f32 v[24:25], v[24:25], v[28:29]
	s_nop 0
	v_cvt_pk_bf16_f32 v24, v24, v25
	v_mul_f32_e32 v25, 0xbfb8aa3b, v30
	v_exp_f32_e32 v25, v25
	s_nop 0
	v_add_f32_e32 v25, 1.0, v25
	v_rcp_f32_e32 v28, v25
	v_mul_f32_e32 v25, 0xbfb8aa3b, v31
	v_exp_f32_e32 v25, v25
	s_nop 0
	v_add_f32_e32 v25, 1.0, v25
	v_rcp_f32_e32 v29, v25
	s_nop 0
	v_pk_mul_f32 v[28:29], v[30:31], v[28:29]
	s_nop 0
	v_pk_mul_f32 v[26:27], v[26:27], v[28:29]
	s_nop 0
	v_cvt_pk_bf16_f32 v25, v26, v27
	v_lshl_add_u64 v[26:27], v[32:33], 0, s[20:21]
	global_store_dwordx2 v[26:27], v[24:25], off
	v_mul_f32_e32 v24, 0xbfb8aa3b, v20
	v_mul_f32_e32 v25, 0xbfb8aa3b, v21
	v_exp_f32_e32 v24, v24
	v_exp_f32_e32 v25, v25
	v_add_f32_e32 v24, 1.0, v24
	v_add_f32_e32 v25, 1.0, v25
	v_rcp_f32_e32 v24, v24
	v_rcp_f32_e32 v25, v25
	s_nop 0
	v_pk_mul_f32 v[20:21], v[20:21], v[24:25]
	s_nop 0
	v_pk_mul_f32 v[16:17], v[16:17], v[20:21]
	s_nop 0
	v_cvt_pk_bf16_f32 v16, v16, v17
	v_mul_f32_e32 v17, 0xbfb8aa3b, v22
	v_exp_f32_e32 v17, v17
	s_nop 0
	v_add_f32_e32 v17, 1.0, v17
	v_rcp_f32_e32 v20, v17
	v_mul_f32_e32 v17, 0xbfb8aa3b, v23
	v_exp_f32_e32 v17, v17
	s_nop 0
	v_add_f32_e32 v17, 1.0, v17
	v_rcp_f32_e32 v21, v17
	s_nop 0
	v_pk_mul_f32 v[20:21], v[22:23], v[20:21]
	s_nop 0
	v_pk_mul_f32 v[18:19], v[18:19], v[20:21]
	s_nop 0
	v_cvt_pk_bf16_f32 v17, v18, v19
	v_mul_f32_e32 v18, 0xbfb8aa3b, v12
	v_mul_f32_e32 v19, 0xbfb8aa3b, v13
	v_exp_f32_e32 v18, v18
	v_exp_f32_e32 v19, v19
	global_store_dwordx2 v[26:27], v[16:17], off offset:128
	v_add_u32_e32 v16, 0xb0, v147
	v_add_f32_e32 v18, 1.0, v18
	v_add_f32_e32 v19, 1.0, v19
	v_rcp_f32_e32 v18, v18
	v_rcp_f32_e32 v19, v19
	v_mad_i64_i32 v[16:17], s[22:23], v16, s46, v[132:133]
	s_mov_b64 s[22:23], s[16:17]
	v_pk_mul_f32 v[12:13], v[12:13], v[18:19]
	s_nop 0
	v_pk_mul_f32 v[8:9], v[8:9], v[12:13]
	s_nop 0
	v_cvt_pk_bf16_f32 v8, v8, v9
	v_mul_f32_e32 v9, 0xbfb8aa3b, v14
	v_exp_f32_e32 v9, v9
	s_nop 0
	v_add_f32_e32 v9, 1.0, v9
	v_rcp_f32_e32 v12, v9
	v_mul_f32_e32 v9, 0xbfb8aa3b, v15
	v_exp_f32_e32 v9, v9
	s_nop 0
	v_add_f32_e32 v9, 1.0, v9
	v_rcp_f32_e32 v13, v9
	s_nop 0
	v_pk_mul_f32 v[12:13], v[14:15], v[12:13]
	s_nop 0
	v_pk_mul_f32 v[10:11], v[10:11], v[12:13]
	s_nop 0
	v_cvt_pk_bf16_f32 v9, v10, v11
	v_lshl_add_u64 v[10:11], v[16:17], 0, s[20:21]
	global_store_dwordx2 v[10:11], v[8:9], off
	v_mul_f32_e32 v8, 0xbfb8aa3b, v4
	v_mul_f32_e32 v9, 0xbfb8aa3b, v5
	v_exp_f32_e32 v8, v8
	v_exp_f32_e32 v9, v9
	s_mov_b32 s21, s12
	s_mov_b32 s20, s14
	v_add_f32_e32 v8, 1.0, v8
	v_add_f32_e32 v9, 1.0, v9
	v_rcp_f32_e32 v8, v8
	v_rcp_f32_e32 v9, v9
	s_nop 0
	v_pk_mul_f32 v[4:5], v[4:5], v[8:9]
	s_nop 0
	v_pk_mul_f32 v[0:1], v[0:1], v[4:5]
	s_nop 0
	v_cvt_pk_bf16_f32 v0, v0, v1
	v_mul_f32_e32 v1, 0xbfb8aa3b, v6
	v_exp_f32_e32 v1, v1
	s_nop 0
	v_add_f32_e32 v1, 1.0, v1
	v_rcp_f32_e32 v4, v1
	v_mul_f32_e32 v1, 0xbfb8aa3b, v7
	v_exp_f32_e32 v1, v1
	s_nop 0
	v_add_f32_e32 v1, 1.0, v1
	v_rcp_f32_e32 v5, v1
	s_nop 0
	v_pk_mul_f32 v[4:5], v[6:7], v[4:5]
	s_nop 0
	v_pk_mul_f32 v[2:3], v[2:3], v[4:5]
	s_nop 0
	v_cvt_pk_bf16_f32 v1, v2, v3
	global_store_dwordx2 v[10:11], v[0:1], off offset:128
	s_cbranch_vccz .LBB0_2809
	s_waitcnt vmcnt(0)
	s_cmpk_gt_u32 s1, 0xff
	s_cbranch_scc1 .LBB0_2816
	s_barrier

.LBB0_2911:
	ds_read_b128 v[128:131], v151
	ds_read_b128 v[144:147], v151 offset:1024
	ds_read_b128 v[154:157], v151 offset:2048
	ds_read_b128 v[158:161], v151 offset:3072
	s_add_u32 s18, s16, 0x100
	s_addc_u32 s19, s17, 0
	s_cmpk_eq_i32 s46, 0x54
	s_cselect_b32 s23, s11, s19
	s_cselect_b32 s22, s10, s18
	s_cselect_b32 s21, s13, s43
	s_cselect_b32 s20, s12, s42
	s_add_i32 m0, s4, 0xc000
	ds_read_b128 v[162:165], v152
	ds_read_b128 v[166:169], v152 offset:1024
	ds_read_b128 v[170:173], v152 offset:2048
	ds_read_b128 v[174:177], v152 offset:3072
	ds_read_b128 v[178:181], v152 offset:4096
	ds_read_b128 v[182:185], v152 offset:5120
	ds_read_b128 v[186:189], v152 offset:6144
	ds_read_b128 v[190:193], v152 offset:7168
	global_load_lds_dwordx4 v136, s[16:17]
	v_lshl_add_u64 v[194:195], s[16:17], 0, v[138:139]
	s_add_i32 m0, s4, 0xe000
	s_nop 0
	global_load_lds_dwordx4 v[194:195], off
	s_waitcnt lgkmcnt(8)
	s_barrier
	s_waitcnt lgkmcnt(0)
	s_waitcnt lgkmcnt(0)
	v_mfma_f32_16x16x32_bf16 v[124:127], v[128:131], v[162:165], v[124:127]
	v_mfma_f32_16x16x32_bf16 v[92:95], v[154:157], v[162:165], v[92:95]
	v_mfma_f32_16x16x32_bf16 v[120:123], v[128:131], v[170:173], v[120:123]
	v_mfma_f32_16x16x32_bf16 v[88:91], v[154:157], v[170:173], v[88:91]
	v_mfma_f32_16x16x32_bf16 v[116:119], v[128:131], v[178:181], v[116:119]
	v_mfma_f32_16x16x32_bf16 v[84:87], v[154:157], v[178:181], v[84:87]
	v_mfma_f32_16x16x32_bf16 v[112:115], v[128:131], v[186:189], v[112:115]
	v_mfma_f32_16x16x32_bf16 v[80:83], v[154:157], v[186:189], v[80:83]
	v_mfma_f32_16x16x32_bf16 v[124:127], v[144:147], v[166:169], v[124:127]
	v_mfma_f32_16x16x32_bf16 v[92:95], v[158:161], v[166:169], v[92:95]
	v_mfma_f32_16x16x32_bf16 v[120:123], v[144:147], v[174:177], v[120:123]
	v_mfma_f32_16x16x32_bf16 v[88:91], v[158:161], v[174:177], v[88:91]
	v_mfma_f32_16x16x32_bf16 v[116:119], v[144:147], v[182:185], v[116:119]
	v_mfma_f32_16x16x32_bf16 v[84:87], v[158:161], v[182:185], v[84:87]
	v_mfma_f32_16x16x32_bf16 v[112:115], v[144:147], v[190:193], v[112:115]
	v_mfma_f32_16x16x32_bf16 v[80:83], v[158:161], v[190:193], v[80:83]
	s_barrier
	s_add_i32 s16, s36, s3
	v_lshl_add_u64 v[210:211], s[20:21], 0, v[132:133]
	s_mov_b32 m0, s16
	ds_read_b128 v[194:197], v153
	ds_read_b128 v[198:201], v153 offset:1024
	ds_read_b128 v[202:205], v153 offset:2048
	ds_read_b128 v[206:209], v153 offset:3072
	global_load_lds_dwordx4 v[210:211], off
	s_add_i32 m0, s16, 0x2000
	s_nop 0
	global_load_lds_dwordx4 v134, s[20:21]
	s_barrier
	s_waitcnt lgkmcnt(0)
	s_waitcnt lgkmcnt(0)
	v_mfma_f32_16x16x32_bf16 v[76:79], v[194:197], v[162:165], v[76:79]
	v_mfma_f32_16x16x32_bf16 v[48:51], v[202:205], v[162:165], v[48:51]
	v_mfma_f32_16x16x32_bf16 v[68:71], v[194:197], v[170:173], v[68:71]
	v_mfma_f32_16x16x32_bf16 v[40:43], v[202:205], v[170:173], v[40:43]
	v_mfma_f32_16x16x32_bf16 v[60:63], v[194:197], v[178:181], v[60:63]
	v_mfma_f32_16x16x32_bf16 v[36:39], v[202:205], v[178:181], v[36:39]
	v_mfma_f32_16x16x32_bf16 v[52:55], v[194:197], v[186:189], v[52:55]
	v_mfma_f32_16x16x32_bf16 v[28:31], v[202:205], v[186:189], v[28:31]
	v_mfma_f32_16x16x32_bf16 v[76:79], v[198:201], v[166:169], v[76:79]
	v_mfma_f32_16x16x32_bf16 v[48:51], v[206:209], v[166:169], v[48:51]
	v_mfma_f32_16x16x32_bf16 v[68:71], v[198:201], v[174:177], v[68:71]
	v_mfma_f32_16x16x32_bf16 v[40:43], v[206:209], v[174:177], v[40:43]
	v_mfma_f32_16x16x32_bf16 v[60:63], v[198:201], v[182:185], v[60:63]
	v_mfma_f32_16x16x32_bf16 v[36:39], v[206:209], v[182:185], v[36:39]
	v_mfma_f32_16x16x32_bf16 v[52:55], v[198:201], v[190:193], v[52:55]
	v_mfma_f32_16x16x32_bf16 v[28:31], v[206:209], v[190:193], v[28:31]
	s_mov_b32 m0, s4
	v_lshl_add_u64 v[214:215], s[22:23], 0, v[132:133]
	s_barrier
	ds_read_b128 v[162:165], v152 offset:16384
	ds_read_b128 v[166:169], v152 offset:17408
	ds_read_b128 v[170:173], v152 offset:18432
	ds_read_b128 v[174:177], v152 offset:19456
	ds_read_b128 v[178:181], v152 offset:20480
	ds_read_b128 v[182:185], v152 offset:21504
	ds_read_b128 v[186:189], v152 offset:22528
	ds_read_b128 v[190:193], v152 offset:23552
	global_load_lds_dwordx4 v[214:215], off
	v_lshl_add_u64 v[216:217], s[22:23], 0, v[134:135]
	s_mov_b32 m0, s5
	s_nop 0
	global_load_lds_dwordx4 v134, s[22:23]
	s_barrier
	s_waitcnt lgkmcnt(0)
	s_waitcnt lgkmcnt(0)
	v_mfma_f32_16x16x32_bf16 v[108:111], v[128:131], v[162:165], v[108:111]
	v_mfma_f32_16x16x32_bf16 v[72:75], v[154:157], v[162:165], v[72:75]
	v_mfma_f32_16x16x32_bf16 v[104:107], v[128:131], v[170:173], v[104:107]
	v_mfma_f32_16x16x32_bf16 v[64:67], v[154:157], v[170:173], v[64:67]
	v_mfma_f32_16x16x32_bf16 v[100:103], v[128:131], v[178:181], v[100:103]
	v_mfma_f32_16x16x32_bf16 v[56:59], v[154:157], v[178:181], v[56:59]
	v_mfma_f32_16x16x32_bf16 v[96:99], v[128:131], v[186:189], v[96:99]
	v_mfma_f32_16x16x32_bf16 v[44:47], v[154:157], v[186:189], v[44:47]
	v_mfma_f32_16x16x32_bf16 v[108:111], v[144:147], v[166:169], v[108:111]
	v_mfma_f32_16x16x32_bf16 v[72:75], v[158:161], v[166:169], v[72:75]
	v_mfma_f32_16x16x32_bf16 v[104:107], v[144:147], v[174:177], v[104:107]
	v_mfma_f32_16x16x32_bf16 v[64:67], v[158:161], v[174:177], v[64:67]
	v_mfma_f32_16x16x32_bf16 v[100:103], v[144:147], v[182:185], v[100:103]
	v_mfma_f32_16x16x32_bf16 v[56:59], v[158:161], v[182:185], v[56:59]
	v_mfma_f32_16x16x32_bf16 v[96:99], v[144:147], v[190:193], v[96:99]
	v_mfma_f32_16x16x32_bf16 v[44:47], v[158:161], v[190:193], v[44:47]
	s_barrier
	s_add_u32 s16, s20, 0x160000
	s_addc_u32 s17, s21, 0
	s_add_i32 s47, s37, s3
	v_lshl_add_u64 v[128:129], s[16:17], 0, v[132:133]
	s_mov_b32 m0, s47
	s_nop 0
	global_load_lds_dwordx4 v[128:129], off
	s_add_i32 m0, s47, 0x2000
	s_nop 0
	global_load_lds_dwordx4 v134, s[16:17]
	s_waitcnt vmcnt(6)
	s_barrier
	v_mfma_f32_16x16x32_bf16 v[32:35], v[194:197], v[162:165], v[32:35]
	v_mfma_f32_16x16x32_bf16 v[12:15], v[202:205], v[162:165], v[12:15]
	v_mfma_f32_16x16x32_bf16 v[24:27], v[194:197], v[170:173], v[24:27]
	v_mfma_f32_16x16x32_bf16 v[8:11], v[202:205], v[170:173], v[8:11]
	v_mfma_f32_16x16x32_bf16 v[20:23], v[194:197], v[178:181], v[20:23]
	v_mfma_f32_16x16x32_bf16 v[4:7], v[202:205], v[178:181], v[4:7]
	v_mfma_f32_16x16x32_bf16 v[16:19], v[194:197], v[186:189], v[16:19]
	v_mfma_f32_16x16x32_bf16 v[0:3], v[202:205], v[186:189], v[0:3]
	v_mfma_f32_16x16x32_bf16 v[32:35], v[198:201], v[166:169], v[32:35]
	v_mfma_f32_16x16x32_bf16 v[12:15], v[206:209], v[166:169], v[12:15]
	v_mfma_f32_16x16x32_bf16 v[24:27], v[198:201], v[174:177], v[24:27]
	v_mfma_f32_16x16x32_bf16 v[8:11], v[206:209], v[174:177], v[8:11]
	v_mfma_f32_16x16x32_bf16 v[20:23], v[198:201], v[182:185], v[20:23]
	v_mfma_f32_16x16x32_bf16 v[4:7], v[206:209], v[182:185], v[4:7]
	v_mfma_f32_16x16x32_bf16 v[16:19], v[198:201], v[190:193], v[16:19]
	v_mfma_f32_16x16x32_bf16 v[0:3], v[206:209], v[190:193], v[0:3]
	s_add_i32 s47, 0, 0x18000
	v_add_u32_e32 v158, s47, v149
	s_barrier
	ds_read_b128 v[128:131], v158
	ds_read_b128 v[144:147], v158 offset:1024
	ds_read_b128 v[154:157], v158 offset:2048
	ds_read_b128 v[158:161], v158 offset:3072
	s_add_u32 s16, s22, 0x160000
	s_addc_u32 s17, s23, 0
	s_mov_b32 m0, s26
	v_lshl_add_u64 v[194:195], s[16:17], 0, v[132:133]
	ds_read_b128 v[162:165], v152 offset:32768
	ds_read_b128 v[166:169], v152 offset:33792
	ds_read_b128 v[170:173], v152 offset:34816
	ds_read_b128 v[174:177], v152 offset:35840
	ds_read_b128 v[178:181], v152 offset:36864
	ds_read_b128 v[182:185], v152 offset:37888
	ds_read_b128 v[186:189], v152 offset:38912
	ds_read_b128 v[190:193], v152 offset:39936
	global_load_lds_dwordx4 v[194:195], off
	s_mov_b32 m0, s27
	s_nop 0
	global_load_lds_dwordx4 v134, s[16:17]
	s_waitcnt lgkmcnt(8)
	s_barrier
	s_waitcnt lgkmcnt(0)
	s_waitcnt lgkmcnt(0)
	v_mfma_f32_16x16x32_bf16 v[124:127], v[128:131], v[162:165], v[124:127]
	v_mfma_f32_16x16x32_bf16 v[92:95], v[154:157], v[162:165], v[92:95]
	v_mfma_f32_16x16x32_bf16 v[120:123], v[128:131], v[170:173], v[120:123]
	v_mfma_f32_16x16x32_bf16 v[88:91], v[154:157], v[170:173], v[88:91]
	v_mfma_f32_16x16x32_bf16 v[116:119], v[128:131], v[178:181], v[116:119]
	v_mfma_f32_16x16x32_bf16 v[84:87], v[154:157], v[178:181], v[84:87]
	v_mfma_f32_16x16x32_bf16 v[112:115], v[128:131], v[186:189], v[112:115]
	v_mfma_f32_16x16x32_bf16 v[80:83], v[154:157], v[186:189], v[80:83]
	v_mfma_f32_16x16x32_bf16 v[124:127], v[144:147], v[166:169], v[124:127]
	v_mfma_f32_16x16x32_bf16 v[92:95], v[158:161], v[166:169], v[92:95]
	v_mfma_f32_16x16x32_bf16 v[120:123], v[144:147], v[174:177], v[120:123]
	v_mfma_f32_16x16x32_bf16 v[88:91], v[158:161], v[174:177], v[88:91]
	v_mfma_f32_16x16x32_bf16 v[116:119], v[144:147], v[182:185], v[116:119]
	v_mfma_f32_16x16x32_bf16 v[84:87], v[158:161], v[182:185], v[84:87]
	v_mfma_f32_16x16x32_bf16 v[112:115], v[144:147], v[190:193], v[112:115]
	v_mfma_f32_16x16x32_bf16 v[80:83], v[158:161], v[190:193], v[80:83]
	s_barrier
	s_add_i32 s22, 0, 0x1c000
	s_add_i32 s16, s47, s3
	v_add_u32_e32 v206, s22, v149
	v_lshl_add_u64 v[210:211], v[210:211], 0, s[14:15]
	s_mov_b32 m0, s16
	ds_read_b128 v[194:197], v206
	ds_read_b128 v[198:201], v206 offset:1024
	ds_read_b128 v[202:205], v206 offset:2048
	ds_read_b128 v[206:209], v206 offset:3072
	global_load_lds_dwordx4 v[210:211], off
	s_add_u32 s98, s20, s14
	s_addc_u32 s99, s21, s15
	s_add_i32 m0, s16, 0x2000
	s_nop 0
	global_load_lds_dwordx4 v134, s[98:99]
	s_barrier
	s_waitcnt lgkmcnt(0)
	s_waitcnt lgkmcnt(0)
	v_mfma_f32_16x16x32_bf16 v[76:79], v[194:197], v[162:165], v[76:79]
	v_mfma_f32_16x16x32_bf16 v[48:51], v[202:205], v[162:165], v[48:51]
	v_mfma_f32_16x16x32_bf16 v[68:71], v[194:197], v[170:173], v[68:71]
	v_mfma_f32_16x16x32_bf16 v[40:43], v[202:205], v[170:173], v[40:43]
	v_mfma_f32_16x16x32_bf16 v[60:63], v[194:197], v[178:181], v[60:63]
	v_mfma_f32_16x16x32_bf16 v[36:39], v[202:205], v[178:181], v[36:39]
	v_mfma_f32_16x16x32_bf16 v[52:55], v[194:197], v[186:189], v[52:55]
	v_mfma_f32_16x16x32_bf16 v[28:31], v[202:205], v[186:189], v[28:31]
	v_mfma_f32_16x16x32_bf16 v[76:79], v[198:201], v[166:169], v[76:79]
	v_mfma_f32_16x16x32_bf16 v[48:51], v[206:209], v[166:169], v[48:51]
	v_mfma_f32_16x16x32_bf16 v[68:71], v[198:201], v[174:177], v[68:71]
	v_mfma_f32_16x16x32_bf16 v[40:43], v[206:209], v[174:177], v[40:43]
	v_mfma_f32_16x16x32_bf16 v[60:63], v[198:201], v[182:185], v[60:63]
	v_mfma_f32_16x16x32_bf16 v[36:39], v[206:209], v[182:185], v[36:39]
	v_mfma_f32_16x16x32_bf16 v[52:55], v[198:201], v[190:193], v[52:55]
	v_mfma_f32_16x16x32_bf16 v[28:31], v[206:209], v[190:193], v[28:31]
	s_mov_b32 m0, s29
	v_lshl_add_u64 v[210:211], v[214:215], 0, s[14:15]
	s_barrier
	ds_read_b128 v[162:165], v152 offset:49152
	ds_read_b128 v[166:169], v152 offset:50176
	ds_read_b128 v[170:173], v152 offset:51200
	ds_read_b128 v[174:177], v152 offset:52224
	ds_read_b128 v[178:181], v152 offset:53248
	ds_read_b128 v[182:185], v152 offset:54272
	ds_read_b128 v[186:189], v152 offset:55296
	ds_read_b128 v[190:193], v152 offset:56320
	global_load_lds_dwordx4 v[210:211], off
	v_lshl_add_u64 v[210:211], v[216:217], 0, s[14:15]
	s_mov_b32 m0, s30
	s_nop 0
	global_load_lds_dwordx4 v[210:211], off
	s_barrier
	s_waitcnt lgkmcnt(0)
	s_waitcnt lgkmcnt(0)
	v_mfma_f32_16x16x32_bf16 v[108:111], v[128:131], v[162:165], v[108:111]
	v_mfma_f32_16x16x32_bf16 v[72:75], v[154:157], v[162:165], v[72:75]
	v_mfma_f32_16x16x32_bf16 v[104:107], v[128:131], v[170:173], v[104:107]
	v_mfma_f32_16x16x32_bf16 v[64:67], v[154:157], v[170:173], v[64:67]
	v_mfma_f32_16x16x32_bf16 v[100:103], v[128:131], v[178:181], v[100:103]
	v_mfma_f32_16x16x32_bf16 v[56:59], v[154:157], v[178:181], v[56:59]
	v_mfma_f32_16x16x32_bf16 v[96:99], v[128:131], v[186:189], v[96:99]
	v_mfma_f32_16x16x32_bf16 v[44:47], v[154:157], v[186:189], v[44:47]
	v_mfma_f32_16x16x32_bf16 v[108:111], v[144:147], v[166:169], v[108:111]
	v_mfma_f32_16x16x32_bf16 v[72:75], v[158:161], v[166:169], v[72:75]
	v_mfma_f32_16x16x32_bf16 v[104:107], v[144:147], v[174:177], v[104:107]
	v_mfma_f32_16x16x32_bf16 v[64:67], v[158:161], v[174:177], v[64:67]
	v_mfma_f32_16x16x32_bf16 v[100:103], v[144:147], v[182:185], v[100:103]
	v_mfma_f32_16x16x32_bf16 v[56:59], v[158:161], v[182:185], v[56:59]
	v_mfma_f32_16x16x32_bf16 v[96:99], v[144:147], v[190:193], v[96:99]
	v_mfma_f32_16x16x32_bf16 v[44:47], v[158:161], v[190:193], v[44:47]
	s_barrier
	s_add_u32 s16, s20, 0x160080
	s_addc_u32 s17, s21, 0
	s_add_i32 s20, s22, s3
	v_lshl_add_u64 v[128:129], s[16:17], 0, v[132:133]
	s_mov_b32 m0, s20
	s_nop 0
	global_load_lds_dwordx4 v[128:129], off
	s_add_i32 m0, s20, 0x2000
	s_nop 0
	global_load_lds_dwordx4 v134, s[16:17]
	s_waitcnt vmcnt(6)
	s_barrier
	v_mfma_f32_16x16x32_bf16 v[32:35], v[194:197], v[162:165], v[32:35]
	v_mfma_f32_16x16x32_bf16 v[12:15], v[202:205], v[162:165], v[12:15]
	v_mfma_f32_16x16x32_bf16 v[24:27], v[194:197], v[170:173], v[24:27]
	v_mfma_f32_16x16x32_bf16 v[8:11], v[202:205], v[170:173], v[8:11]
	v_mfma_f32_16x16x32_bf16 v[20:23], v[194:197], v[178:181], v[20:23]
	v_mfma_f32_16x16x32_bf16 v[4:7], v[202:205], v[178:181], v[4:7]
	v_mfma_f32_16x16x32_bf16 v[16:19], v[194:197], v[186:189], v[16:19]
	v_mfma_f32_16x16x32_bf16 v[0:3], v[202:205], v[186:189], v[0:3]
	v_mfma_f32_16x16x32_bf16 v[32:35], v[198:201], v[166:169], v[32:35]
	v_mfma_f32_16x16x32_bf16 v[12:15], v[206:209], v[166:169], v[12:15]
	v_mfma_f32_16x16x32_bf16 v[24:27], v[198:201], v[174:177], v[24:27]
	v_mfma_f32_16x16x32_bf16 v[8:11], v[206:209], v[174:177], v[8:11]
	v_mfma_f32_16x16x32_bf16 v[20:23], v[198:201], v[182:185], v[20:23]
	v_mfma_f32_16x16x32_bf16 v[4:7], v[206:209], v[182:185], v[4:7]
	v_mfma_f32_16x16x32_bf16 v[16:19], v[198:201], v[190:193], v[16:19]
	v_mfma_f32_16x16x32_bf16 v[0:3], v[206:209], v[190:193], v[0:3]
	s_add_i32 s46, s46, 2
	s_add_u32 s42, s42, 0x100
	s_addc_u32 s43, s43, 0
	s_cmpk_gt_u32 s46, 0x55
	s_mov_b64 s[16:17], s[18:19]
	s_barrier
	s_cbranch_scc0 .LBB0_2911
	s_cmp_lt_u32 s40, 32
	s_movk_i32 s16, 0x3000
	s_cselect_b32 s16, s16, 0x6000
	s_cmp_gt_i32 s40, 15
	v_lshl_add_u32 v158, s40, 8, v148
	s_cselect_b32 s16, s16, 0
	v_lshl_or_b32 v128, s41, 8, v150
	s_lshl_b32 s16, s16, 2
	v_ashrrev_i32_e32 v159, 31, v158
	s_add_u32 s16, s34, s16
	v_ashrrev_i32_e32 v129, 31, v128
	v_lshlrev_b64 v[146:147], 13, v[158:159]
	s_addc_u32 s17, s35, 0
	v_lshlrev_b64 v[160:161], 2, v[128:129]
	v_lshl_add_u64 v[146:147], s[48:49], 0, v[146:147]
	v_lshl_add_u64 v[144:145], s[16:17], 0, v[160:161]
	v_lshl_add_u64 v[146:147], v[146:147], 0, v[160:161]
	s_mov_b64 s[16:17], 0x100000
	s_mov_b32 s41, s38
	s_mov_b32 s40, s39
	s_mov_b64 s[18:19], s[12:13]
	v_or_b32_e32 v162, 16, v158
	v_ashrrev_i32_e32 v163, 31, v162
	v_lshlrev_b64 v[164:165], 13, v[162:163]
	v_lshl_add_u64 v[162:163], s[48:49], 0, v[164:165]
	v_lshl_add_u64 v[164:165], v[162:163], 0, v[160:161]
	v_or_b32_e32 v162, 32, v158
	v_ashrrev_i32_e32 v163, 31, v162
	v_lshlrev_b64 v[166:167], 13, v[162:163]
	v_lshl_add_u64 v[162:163], s[48:49], 0, v[166:167]
	v_lshl_add_u64 v[166:167], v[162:163], 0, v[160:161]
	v_or_b32_e32 v162, 48, v158
	v_ashrrev_i32_e32 v163, 31, v162
	v_lshlrev_b64 v[168:169], 13, v[162:163]
	v_lshl_add_u64 v[162:163], s[48:49], 0, v[168:169]
	v_lshl_add_u64 v[168:169], v[162:163], 0, v[160:161]
	v_lshl_add_u64 v[162:163], v[146:147], 0, s[16:17]
	s_mov_b32 s16, 0x100000
	v_add_co_u32_e32 v170, vcc, s16, v146
	s_mov_b64 s[16:17], 0x120000
	s_nop 0
	v_addc_co_u32_e32 v171, vcc, 0, v147, vcc
	v_lshl_add_u64 v[172:173], v[146:147], 0, s[16:17]
	s_mov_b32 s16, 0x120000
	v_add_co_u32_e32 v174, vcc, s16, v146
	s_mov_b64 s[16:17], 0x140000
	s_nop 0
	v_addc_co_u32_e32 v175, vcc, 0, v147, vcc
	v_lshl_add_u64 v[176:177], v[146:147], 0, s[16:17]
	s_mov_b32 s16, 0x140000
	v_add_co_u32_e32 v178, vcc, s16, v146
	s_mov_b64 s[16:17], 0x160000
	s_nop 0
	v_addc_co_u32_e32 v179, vcc, 0, v147, vcc
	v_lshl_add_u64 v[180:181], v[146:147], 0, s[16:17]
	s_mov_b32 s16, 0x160000
	v_add_co_u32_e32 v182, vcc, s16, v146
	s_mov_b64 s[16:17], s[10:11]
	s_nop 0
	v_addc_co_u32_e32 v183, vcc, 0, v147, vcc
	s_and_b64 vcc, exec, s[8:9]
	global_load_dwordx4 v[184:187], v[144:145], off
	global_load_dwordx4 v[188:191], v[146:147], off
	v_pk_add_f32 v[126:127], v[126:127], 0 op_sel_hi:[1,0]
	v_pk_add_f32 v[124:125], v[124:125], 0 op_sel_hi:[1,0]
	v_pk_add_f32 v[122:123], v[122:123], 0 op_sel_hi:[1,0]
	v_pk_add_f32 v[120:121], v[120:121], 0 op_sel_hi:[1,0]
	v_pk_add_f32 v[118:119], v[118:119], 0 op_sel_hi:[1,0]
	v_pk_add_f32 v[116:117], v[116:117], 0 op_sel_hi:[1,0]
	v_pk_add_f32 v[114:115], v[114:115], 0 op_sel_hi:[1,0]
	v_pk_add_f32 v[112:113], v[112:113], 0 op_sel_hi:[1,0]
	v_pk_add_f32 v[110:111], v[110:111], 0 op_sel_hi:[1,0]
	v_pk_add_f32 v[108:109], v[108:109], 0 op_sel_hi:[1,0]
	v_pk_add_f32 v[106:107], v[106:107], 0 op_sel_hi:[1,0]
	v_pk_add_f32 v[104:105], v[104:105], 0 op_sel_hi:[1,0]
	v_pk_add_f32 v[102:103], v[102:103], 0 op_sel_hi:[1,0]
	v_pk_add_f32 v[100:101], v[100:101], 0 op_sel_hi:[1,0]
	v_pk_add_f32 v[98:99], v[98:99], 0 op_sel_hi:[1,0]
	v_pk_add_f32 v[96:97], v[96:97], 0 op_sel_hi:[1,0]
	v_pk_add_f32 v[94:95], v[94:95], 0 op_sel_hi:[1,0]
	v_pk_add_f32 v[92:93], v[92:93], 0 op_sel_hi:[1,0]
	v_pk_add_f32 v[90:91], v[90:91], 0 op_sel_hi:[1,0]
	v_pk_add_f32 v[88:89], v[88:89], 0 op_sel_hi:[1,0]
	v_pk_add_f32 v[86:87], v[86:87], 0 op_sel_hi:[1,0]
	v_pk_add_f32 v[84:85], v[84:85], 0 op_sel_hi:[1,0]
	v_pk_add_f32 v[82:83], v[82:83], 0 op_sel_hi:[1,0]
	v_pk_add_f32 v[80:81], v[80:81], 0 op_sel_hi:[1,0]
	v_pk_add_f32 v[74:75], v[74:75], 0 op_sel_hi:[1,0]
	v_pk_add_f32 v[72:73], v[72:73], 0 op_sel_hi:[1,0]
	v_pk_add_f32 v[66:67], v[66:67], 0 op_sel_hi:[1,0]
	v_pk_add_f32 v[64:65], v[64:65], 0 op_sel_hi:[1,0]
	v_pk_add_f32 v[58:59], v[58:59], 0 op_sel_hi:[1,0]
	v_pk_add_f32 v[56:57], v[56:57], 0 op_sel_hi:[1,0]
	v_pk_add_f32 v[46:47], v[46:47], 0 op_sel_hi:[1,0]
	v_pk_add_f32 v[44:45], v[44:45], 0 op_sel_hi:[1,0]
	v_pk_add_f32 v[62:63], v[62:63], 0 op_sel_hi:[1,0]
	v_pk_add_f32 v[60:61], v[60:61], 0 op_sel_hi:[1,0]
	v_pk_add_f32 v[54:55], v[54:55], 0 op_sel_hi:[1,0]
	v_pk_add_f32 v[52:53], v[52:53], 0 op_sel_hi:[1,0]
	v_pk_add_f32 v[34:35], v[34:35], 0 op_sel_hi:[1,0]
	v_pk_add_f32 v[32:33], v[32:33], 0 op_sel_hi:[1,0]
	v_pk_add_f32 v[26:27], v[26:27], 0 op_sel_hi:[1,0]
	v_pk_add_f32 v[24:25], v[24:25], 0 op_sel_hi:[1,0]
	v_pk_add_f32 v[22:23], v[22:23], 0 op_sel_hi:[1,0]
	v_pk_add_f32 v[20:21], v[20:21], 0 op_sel_hi:[1,0]
	v_pk_add_f32 v[18:19], v[18:19], 0 op_sel_hi:[1,0]
	v_pk_add_f32 v[16:17], v[16:17], 0 op_sel_hi:[1,0]
	v_pk_add_f32 v[14:15], v[14:15], 0 op_sel_hi:[1,0]
	v_pk_add_f32 v[12:13], v[12:13], 0 op_sel_hi:[1,0]
	v_pk_add_f32 v[10:11], v[10:11], 0 op_sel_hi:[1,0]
	v_pk_add_f32 v[8:9], v[8:9], 0 op_sel_hi:[1,0]
	v_pk_add_f32 v[6:7], v[6:7], 0 op_sel_hi:[1,0]
	v_pk_add_f32 v[4:5], v[4:5], 0 op_sel_hi:[1,0]
	v_pk_add_f32 v[2:3], v[2:3], 0 op_sel_hi:[1,0]
	v_pk_add_f32 v[0:1], v[0:1], 0 op_sel_hi:[1,0]
	s_waitcnt vmcnt(0)
	v_pk_fma_f32 v[126:127], v[126:127], v[186:187], v[190:191]
	v_pk_fma_f32 v[124:125], v[124:125], v[184:185], v[188:189]
	global_store_dwordx4 v[146:147], v[124:127], off
	global_load_dwordx4 v[188:191], v[164:165], off
	global_load_dwordx4 v[192:195], v[166:167], off
	global_load_dwordx4 v[196:199], v[168:169], off
	global_load_dwordx4 v[200:203], v[170:171], off
	global_load_dwordx4 v[204:207], v[174:175], off
	global_load_dwordx4 v[208:211], v[178:179], off
	global_load_dwordx4 v[212:215], v[182:183], off
	global_load_dwordx4 v[216:219], v[144:145], off offset:64
	global_load_dwordx4 v[220:223], v[146:147], off offset:64
	global_load_dwordx4 v[224:227], v[164:165], off offset:64
	global_load_dwordx4 v[228:231], v[166:167], off offset:64
	global_load_dwordx4 v[232:235], v[168:169], off offset:64
	s_waitcnt vmcnt(11)
	v_pk_fma_f32 v[122:123], v[122:123], v[186:187], v[190:191]
	v_pk_fma_f32 v[120:121], v[120:121], v[184:185], v[188:189]
	global_store_dwordx4 v[164:165], v[120:123], off
	global_load_dwordx4 v[188:191], v[162:163], off offset:64
	s_waitcnt vmcnt(12)
	v_pk_fma_f32 v[118:119], v[118:119], v[186:187], v[194:195]
	v_pk_fma_f32 v[116:117], v[116:117], v[184:185], v[192:193]
	global_store_dwordx4 v[166:167], v[116:119], off
	global_load_dwordx4 v[192:195], v[172:173], off offset:64
	s_waitcnt vmcnt(13)
	v_pk_fma_f32 v[114:115], v[114:115], v[186:187], v[198:199]
	v_pk_fma_f32 v[112:113], v[112:113], v[184:185], v[196:197]
	global_store_dwordx4 v[168:169], v[112:115], off
	global_load_dwordx4 v[196:199], v[176:177], off offset:64
	s_waitcnt vmcnt(14)
	v_pk_fma_f32 v[110:111], v[110:111], v[186:187], v[202:203]
	v_pk_fma_f32 v[108:109], v[108:109], v[184:185], v[200:201]
	global_store_dwordx4 v[170:171], v[108:111], off
	global_load_dwordx4 v[200:203], v[180:181], off offset:64
	s_waitcnt vmcnt(15)
	v_pk_fma_f32 v[106:107], v[106:107], v[186:187], v[206:207]
	v_pk_fma_f32 v[104:105], v[104:105], v[184:185], v[204:205]
	global_store_dwordx4 v[174:175], v[104:107], off
	global_load_dwordx4 v[204:207], v[144:145], off offset:512
	s_waitcnt vmcnt(16)
	v_pk_fma_f32 v[102:103], v[102:103], v[186:187], v[210:211]
	v_pk_fma_f32 v[100:101], v[100:101], v[184:185], v[208:209]
	global_store_dwordx4 v[178:179], v[100:103], off
	global_load_dwordx4 v[208:211], v[146:147], off offset:512
	s_waitcnt vmcnt(17)
	v_pk_fma_f32 v[98:99], v[98:99], v[186:187], v[214:215]
	v_pk_fma_f32 v[96:97], v[96:97], v[184:185], v[212:213]
	global_store_dwordx4 v[182:183], v[96:99], off
	global_load_dwordx4 v[184:187], v[164:165], off offset:512
	s_waitcnt vmcnt(17)
	v_pk_fma_f32 v[94:95], v[94:95], v[218:219], v[222:223]
	v_pk_fma_f32 v[92:93], v[92:93], v[216:217], v[220:221]
	global_store_dwordx4 v[146:147], v[92:95], off offset:64
	global_load_dwordx4 v[212:215], v[166:167], off offset:512
	global_load_dwordx4 v[220:223], v[168:169], off offset:512
	s_waitcnt vmcnt(19)
	v_pk_fma_f32 v[90:91], v[90:91], v[218:219], v[226:227]
	v_pk_fma_f32 v[88:89], v[88:89], v[216:217], v[224:225]
	global_store_dwordx4 v[164:165], v[88:91], off offset:64
	global_load_dwordx4 v[224:227], v[162:163], off offset:512
	s_waitcnt vmcnt(20)
	v_pk_fma_f32 v[86:87], v[86:87], v[218:219], v[230:231]
	v_pk_fma_f32 v[84:85], v[84:85], v[216:217], v[228:229]
	global_store_dwordx4 v[166:167], v[84:87], off offset:64
	global_load_dwordx4 v[228:231], v[172:173], off offset:512
	s_waitcnt vmcnt(21)
	v_pk_fma_f32 v[82:83], v[82:83], v[218:219], v[234:235]
	v_pk_fma_f32 v[80:81], v[80:81], v[216:217], v[232:233]
	global_store_dwordx4 v[168:169], v[80:83], off offset:64
	global_load_dwordx4 v[232:235], v[176:177], off offset:512
	s_waitcnt vmcnt(21)
	v_pk_fma_f32 v[74:75], v[74:75], v[218:219], v[190:191]
	v_pk_fma_f32 v[72:73], v[72:73], v[216:217], v[188:189]
	global_store_dwordx4 v[162:163], v[72:75], off offset:64
	global_load_dwordx4 v[188:191], v[180:181], off offset:512
	s_waitcnt vmcnt(21)
	v_pk_fma_f32 v[66:67], v[66:67], v[218:219], v[194:195]
	v_pk_fma_f32 v[64:65], v[64:65], v[216:217], v[192:193]
	global_store_dwordx4 v[172:173], v[64:67], off offset:64
	global_load_dwordx4 v[192:195], v[144:145], off offset:576
	s_waitcnt vmcnt(21)
	v_pk_fma_f32 v[58:59], v[58:59], v[218:219], v[198:199]
	v_pk_fma_f32 v[56:57], v[56:57], v[216:217], v[196:197]
	global_store_dwordx4 v[176:177], v[56:59], off offset:64
	global_load_dwordx4 v[196:199], v[146:147], off offset:576
	v_pk_add_f32 v[64:65], v[78:79], 0 op_sel_hi:[1,0]
	v_pk_add_f32 v[66:67], v[76:77], 0 op_sel_hi:[1,0]
	s_waitcnt vmcnt(21)
	v_pk_fma_f32 v[46:47], v[46:47], v[218:219], v[202:203]
	v_pk_fma_f32 v[44:45], v[44:45], v[216:217], v[200:201]
	global_store_dwordx4 v[180:181], v[44:47], off offset:64
	global_load_dwordx4 v[200:203], v[164:165], off offset:576
	s_waitcnt vmcnt(19)
	v_pk_fma_f32 v[58:59], v[64:65], v[206:207], v[210:211]
	v_pk_fma_f32 v[56:57], v[66:67], v[204:205], v[208:209]
	global_store_dwordx4 v[146:147], v[56:59], off offset:512
	global_load_dwordx4 v[208:211], v[166:167], off offset:576
	global_load_dwordx4 v[216:219], v[168:169], off offset:576
	v_pk_add_f32 v[64:65], v[70:71], 0 op_sel_hi:[1,0]
	v_pk_add_f32 v[66:67], v[68:69], 0 op_sel_hi:[1,0]
	s_waitcnt vmcnt(20)
	v_pk_fma_f32 v[58:59], v[64:65], v[206:207], v[186:187]
	v_pk_fma_f32 v[56:57], v[66:67], v[204:205], v[184:185]
	global_store_dwordx4 v[164:165], v[56:59], off offset:512
	global_load_dwordx4 v[184:187], v[162:163], off offset:576
	s_waitcnt vmcnt(20)
	v_pk_fma_f32 v[58:59], v[62:63], v[206:207], v[214:215]
	v_pk_fma_f32 v[56:57], v[60:61], v[204:205], v[212:213]
	global_store_dwordx4 v[166:167], v[56:59], off offset:512
	global_load_dwordx4 v[212:215], v[172:173], off offset:576
	s_waitcnt vmcnt(21)
	v_pk_fma_f32 v[54:55], v[54:55], v[206:207], v[222:223]
	v_pk_fma_f32 v[52:53], v[52:53], v[204:205], v[220:221]
	global_store_dwordx4 v[168:169], v[52:55], off offset:512
	global_load_dwordx4 v[220:223], v[176:177], off offset:576
	s_waitcnt vmcnt(21)
	v_pk_fma_f32 v[34:35], v[34:35], v[206:207], v[226:227]
	v_pk_fma_f32 v[32:33], v[32:33], v[204:205], v[224:225]
	global_store_dwordx4 v[162:163], v[32:35], off offset:512
	global_load_dwordx4 v[224:227], v[180:181], off offset:576
	s_waitcnt vmcnt(21)
	v_pk_fma_f32 v[26:27], v[26:27], v[206:207], v[230:231]
	v_pk_fma_f32 v[24:25], v[24:25], v[204:205], v[228:229]
	global_store_dwordx4 v[172:173], v[24:27], off offset:512
	s_waitcnt vmcnt(20)
	v_pk_fma_f32 v[22:23], v[22:23], v[206:207], v[234:235]
	v_pk_fma_f32 v[20:21], v[20:21], v[204:205], v[232:233]
	global_store_dwordx4 v[176:177], v[20:23], off offset:512
	v_pk_add_f32 v[24:25], v[50:51], 0 op_sel_hi:[1,0]
	v_pk_add_f32 v[26:27], v[48:49], 0 op_sel_hi:[1,0]
	s_waitcnt vmcnt(19)
	v_pk_fma_f32 v[18:19], v[18:19], v[206:207], v[190:191]
	v_pk_fma_f32 v[16:17], v[16:17], v[204:205], v[188:189]
	global_store_dwordx4 v[180:181], v[16:19], off offset:512
	s_waitcnt vmcnt(16)
	v_pk_fma_f32 v[22:23], v[24:25], v[194:195], v[198:199]
	v_pk_fma_f32 v[20:21], v[26:27], v[192:193], v[196:197]
	global_store_dwordx4 v[146:147], v[20:23], off offset:576
	v_pk_add_f32 v[24:25], v[42:43], 0 op_sel_hi:[1,0]
	v_pk_add_f32 v[26:27], v[40:41], 0 op_sel_hi:[1,0]
	s_waitcnt vmcnt(15)
	v_pk_fma_f32 v[22:23], v[24:25], v[194:195], v[202:203]
	v_pk_fma_f32 v[20:21], v[26:27], v[192:193], v[200:201]
	global_store_dwordx4 v[164:165], v[20:23], off offset:576
	v_pk_add_f32 v[24:25], v[38:39], 0 op_sel_hi:[1,0]
	v_pk_add_f32 v[26:27], v[36:37], 0 op_sel_hi:[1,0]
	s_waitcnt vmcnt(14)
	v_pk_fma_f32 v[22:23], v[24:25], v[194:195], v[210:211]
	v_pk_fma_f32 v[20:21], v[26:27], v[192:193], v[208:209]
	global_store_dwordx4 v[166:167], v[20:23], off offset:576
	v_pk_add_f32 v[24:25], v[30:31], 0 op_sel_hi:[1,0]
	v_pk_add_f32 v[26:27], v[28:29], 0 op_sel_hi:[1,0]
	s_waitcnt vmcnt(14)
	v_pk_fma_f32 v[22:23], v[24:25], v[194:195], v[218:219]
	v_pk_fma_f32 v[20:21], v[26:27], v[192:193], v[216:217]
	global_store_dwordx4 v[168:169], v[20:23], off offset:576
	s_waitcnt vmcnt(13)
	v_pk_fma_f32 v[14:15], v[14:15], v[194:195], v[186:187]
	v_pk_fma_f32 v[12:13], v[12:13], v[192:193], v[184:185]
	global_store_dwordx4 v[162:163], v[12:15], off offset:576
	s_waitcnt vmcnt(12)
	v_pk_fma_f32 v[10:11], v[10:11], v[194:195], v[214:215]
	v_pk_fma_f32 v[8:9], v[8:9], v[192:193], v[212:213]
	global_store_dwordx4 v[172:173], v[8:11], off offset:576
	s_waitcnt vmcnt(11)
	v_pk_fma_f32 v[6:7], v[6:7], v[194:195], v[222:223]
	v_pk_fma_f32 v[4:5], v[4:5], v[192:193], v[220:221]
	global_store_dwordx4 v[176:177], v[4:7], off offset:576
	s_waitcnt vmcnt(10)
	v_pk_fma_f32 v[2:3], v[2:3], v[194:195], v[226:227]
	v_pk_fma_f32 v[0:1], v[0:1], v[192:193], v[224:225]
	global_store_dwordx4 v[180:181], v[0:3], off offset:576
	s_cbranch_vccz .LBB0_2900
	s_waitcnt vmcnt(0)
	s_cmpk_gt_u32 s1, 0xff
	s_cbranch_scc1 .LBB0_2915
	s_barrier

.LBB0_2927:
	ds_read_b128 v[144:147], v139
	ds_read_b128 v[148:151], v139 offset:1024
	ds_read_b128 v[152:155], v139 offset:2048
	ds_read_b128 v[156:159], v139 offset:3072
	s_add_u32 s16, s14, 0x100
	s_addc_u32 s17, s15, 0
	s_cmp_eq_u32 s47, 4
	s_cselect_b32 s21, s13, s17
	s_cselect_b32 s20, s12, s16
	s_cselect_b32 s19, s7, s46
	s_cselect_b32 s18, s6, s43
	s_mov_b32 m0, s31
	v_lshl_add_u64 v[192:193], s[14:15], 0, v[132:133]
	ds_read_b128 v[160:163], v140
	ds_read_b128 v[164:167], v140 offset:1024
	ds_read_b128 v[168:171], v140 offset:2048
	ds_read_b128 v[172:175], v140 offset:3072
	ds_read_b128 v[176:179], v140 offset:4096
	ds_read_b128 v[180:183], v140 offset:5120
	ds_read_b128 v[184:187], v140 offset:6144
	ds_read_b128 v[188:191], v140 offset:7168
	global_load_lds_dwordx4 v[192:193], off
	s_mov_b32 m0, s34
	s_nop 0
	global_load_lds_dwordx4 v134, s[14:15]
	s_waitcnt lgkmcnt(8)
	s_barrier
	s_waitcnt lgkmcnt(0)
	s_waitcnt lgkmcnt(0)
	v_mfma_f32_16x16x32_bf16 v[124:127], v[144:147], v[160:163], v[124:127]
	v_mfma_f32_16x16x32_bf16 v[120:123], v[152:155], v[160:163], v[120:123]
	v_mfma_f32_16x16x32_bf16 v[116:119], v[144:147], v[168:171], v[116:119]
	v_mfma_f32_16x16x32_bf16 v[112:115], v[152:155], v[168:171], v[112:115]
	v_mfma_f32_16x16x32_bf16 v[100:103], v[144:147], v[176:179], v[100:103]
	v_mfma_f32_16x16x32_bf16 v[96:99], v[152:155], v[176:179], v[96:99]
	v_mfma_f32_16x16x32_bf16 v[84:87], v[144:147], v[184:187], v[84:87]
	v_mfma_f32_16x16x32_bf16 v[80:83], v[152:155], v[184:187], v[80:83]
	v_mfma_f32_16x16x32_bf16 v[124:127], v[148:151], v[164:167], v[124:127]
	v_mfma_f32_16x16x32_bf16 v[120:123], v[156:159], v[164:167], v[120:123]
	v_mfma_f32_16x16x32_bf16 v[116:119], v[148:151], v[172:175], v[116:119]
	v_mfma_f32_16x16x32_bf16 v[112:115], v[156:159], v[172:175], v[112:115]
	v_mfma_f32_16x16x32_bf16 v[100:103], v[148:151], v[180:183], v[100:103]
	v_mfma_f32_16x16x32_bf16 v[96:99], v[156:159], v[180:183], v[96:99]
	v_mfma_f32_16x16x32_bf16 v[84:87], v[148:151], v[188:191], v[84:87]
	v_mfma_f32_16x16x32_bf16 v[80:83], v[156:159], v[188:191], v[80:83]
	s_barrier
	s_mov_b32 m0, s35
	ds_read_b128 v[192:195], v141
	ds_read_b128 v[196:199], v141 offset:1024
	ds_read_b128 v[200:203], v141 offset:2048
	ds_read_b128 v[204:207], v141 offset:3072
	global_load_lds_dwordx4 v130, s[18:19]
	s_mov_b32 m0, s36
	s_nop 0
	global_load_lds_dwordx4 v128, s[18:19]
	s_barrier
	s_waitcnt lgkmcnt(0)
	s_waitcnt lgkmcnt(0)
	v_mfma_f32_16x16x32_bf16 v[108:111], v[192:195], v[160:163], v[108:111]
	v_mfma_f32_16x16x32_bf16 v[104:107], v[200:203], v[160:163], v[104:107]
	v_mfma_f32_16x16x32_bf16 v[92:95], v[192:195], v[168:171], v[92:95]
	v_mfma_f32_16x16x32_bf16 v[88:91], v[200:203], v[168:171], v[88:91]
	v_mfma_f32_16x16x32_bf16 v[76:79], v[192:195], v[176:179], v[76:79]
	v_mfma_f32_16x16x32_bf16 v[72:75], v[200:203], v[176:179], v[72:75]
	v_mfma_f32_16x16x32_bf16 v[68:71], v[192:195], v[184:187], v[68:71]
	v_mfma_f32_16x16x32_bf16 v[64:67], v[200:203], v[184:187], v[64:67]
	v_mfma_f32_16x16x32_bf16 v[108:111], v[196:199], v[164:167], v[108:111]
	v_mfma_f32_16x16x32_bf16 v[104:107], v[204:207], v[164:167], v[104:107]
	v_mfma_f32_16x16x32_bf16 v[92:95], v[196:199], v[172:175], v[92:95]
	v_mfma_f32_16x16x32_bf16 v[88:91], v[204:207], v[172:175], v[88:91]
	v_mfma_f32_16x16x32_bf16 v[76:79], v[196:199], v[180:183], v[76:79]
	v_mfma_f32_16x16x32_bf16 v[72:75], v[204:207], v[180:183], v[72:75]
	v_mfma_f32_16x16x32_bf16 v[68:71], v[196:199], v[188:191], v[68:71]
	v_mfma_f32_16x16x32_bf16 v[64:67], v[204:207], v[188:191], v[64:67]
	s_mov_b32 m0, s3
	v_lshl_add_u64 v[212:213], s[20:21], 0, v[130:131]
	s_barrier
	ds_read_b128 v[160:163], v140 offset:16384
	ds_read_b128 v[164:167], v140 offset:17408
	ds_read_b128 v[168:171], v140 offset:18432
	ds_read_b128 v[172:175], v140 offset:19456
	ds_read_b128 v[176:179], v140 offset:20480
	ds_read_b128 v[180:183], v140 offset:21504
	ds_read_b128 v[184:187], v140 offset:22528
	ds_read_b128 v[188:191], v140 offset:23552
	global_load_lds_dwordx4 v130, s[20:21]
	v_lshl_add_u64 v[214:215], s[20:21], 0, v[128:129]
	s_mov_b32 m0, s4
	s_nop 0
	global_load_lds_dwordx4 v128, s[20:21]
	s_barrier
	s_waitcnt lgkmcnt(0)
	s_waitcnt lgkmcnt(0)
	v_mfma_f32_16x16x32_bf16 v[60:63], v[144:147], v[160:163], v[60:63]
	v_mfma_f32_16x16x32_bf16 v[56:59], v[152:155], v[160:163], v[56:59]
	v_mfma_f32_16x16x32_bf16 v[52:55], v[144:147], v[168:171], v[52:55]
	v_mfma_f32_16x16x32_bf16 v[48:51], v[152:155], v[168:171], v[48:51]
	v_mfma_f32_16x16x32_bf16 v[36:39], v[144:147], v[176:179], v[36:39]
	v_mfma_f32_16x16x32_bf16 v[32:35], v[152:155], v[176:179], v[32:35]
	v_mfma_f32_16x16x32_bf16 v[20:23], v[144:147], v[184:187], v[20:23]
	v_mfma_f32_16x16x32_bf16 v[16:19], v[152:155], v[184:187], v[16:19]
	v_mfma_f32_16x16x32_bf16 v[60:63], v[148:151], v[164:167], v[60:63]
	v_mfma_f32_16x16x32_bf16 v[56:59], v[156:159], v[164:167], v[56:59]
	v_mfma_f32_16x16x32_bf16 v[52:55], v[148:151], v[172:175], v[52:55]
	v_mfma_f32_16x16x32_bf16 v[48:51], v[156:159], v[172:175], v[48:51]
	v_mfma_f32_16x16x32_bf16 v[36:39], v[148:151], v[180:183], v[36:39]
	v_mfma_f32_16x16x32_bf16 v[32:35], v[156:159], v[180:183], v[32:35]
	v_mfma_f32_16x16x32_bf16 v[20:23], v[148:151], v[188:191], v[20:23]
	v_mfma_f32_16x16x32_bf16 v[16:19], v[156:159], v[188:191], v[16:19]
	s_barrier
	s_add_u32 s14, s18, 0x160000
	s_addc_u32 s15, s19, 0
	s_mov_b32 m0, s37
	global_load_lds_dwordx4 v130, s[14:15]
	s_mov_b32 m0, s38
	s_nop 0
	global_load_lds_dwordx4 v128, s[14:15]
	s_waitcnt vmcnt(6)
	s_barrier
	v_mfma_f32_16x16x32_bf16 v[44:47], v[192:195], v[160:163], v[44:47]
	v_mfma_f32_16x16x32_bf16 v[40:43], v[200:203], v[160:163], v[40:43]
	v_mfma_f32_16x16x32_bf16 v[28:31], v[192:195], v[168:171], v[28:31]
	v_mfma_f32_16x16x32_bf16 v[24:27], v[200:203], v[168:171], v[24:27]
	v_mfma_f32_16x16x32_bf16 v[12:15], v[192:195], v[176:179], v[12:15]
	v_mfma_f32_16x16x32_bf16 v[8:11], v[200:203], v[176:179], v[8:11]
	v_mfma_f32_16x16x32_bf16 v[4:7], v[192:195], v[184:187], v[4:7]
	v_mfma_f32_16x16x32_bf16 v[0:3], v[200:203], v[184:187], v[0:3]
	v_mfma_f32_16x16x32_bf16 v[44:47], v[196:199], v[164:167], v[44:47]
	v_mfma_f32_16x16x32_bf16 v[40:43], v[204:207], v[164:167], v[40:43]
	v_mfma_f32_16x16x32_bf16 v[28:31], v[196:199], v[172:175], v[28:31]
	v_mfma_f32_16x16x32_bf16 v[24:27], v[204:207], v[172:175], v[24:27]
	v_mfma_f32_16x16x32_bf16 v[12:15], v[196:199], v[180:183], v[12:15]
	v_mfma_f32_16x16x32_bf16 v[8:11], v[204:207], v[180:183], v[8:11]
	v_mfma_f32_16x16x32_bf16 v[4:7], v[196:199], v[188:191], v[4:7]
	v_mfma_f32_16x16x32_bf16 v[0:3], v[204:207], v[188:191], v[0:3]
	s_barrier
	ds_read_b128 v[144:147], v142
	ds_read_b128 v[148:151], v142 offset:1024
	ds_read_b128 v[152:155], v142 offset:2048
	ds_read_b128 v[156:159], v142 offset:3072
	s_add_u32 s14, s20, 0x160000
	s_addc_u32 s15, s21, 0
	s_mov_b32 m0, s5
	ds_read_b128 v[160:163], v140 offset:32768
	ds_read_b128 v[164:167], v140 offset:33792
	ds_read_b128 v[168:171], v140 offset:34816
	ds_read_b128 v[172:175], v140 offset:35840
	ds_read_b128 v[176:179], v140 offset:36864
	ds_read_b128 v[180:183], v140 offset:37888
	ds_read_b128 v[184:187], v140 offset:38912
	ds_read_b128 v[188:191], v140 offset:39936
	global_load_lds_dwordx4 v130, s[14:15]
	s_mov_b32 m0, s22
	s_nop 0
	global_load_lds_dwordx4 v128, s[14:15]
	s_waitcnt lgkmcnt(8)
	s_barrier
	s_waitcnt lgkmcnt(0)
	s_waitcnt lgkmcnt(0)
	v_mfma_f32_16x16x32_bf16 v[124:127], v[144:147], v[160:163], v[124:127]
	v_mfma_f32_16x16x32_bf16 v[120:123], v[152:155], v[160:163], v[120:123]
	v_mfma_f32_16x16x32_bf16 v[116:119], v[144:147], v[168:171], v[116:119]
	v_mfma_f32_16x16x32_bf16 v[112:115], v[152:155], v[168:171], v[112:115]
	v_mfma_f32_16x16x32_bf16 v[100:103], v[144:147], v[176:179], v[100:103]
	v_mfma_f32_16x16x32_bf16 v[96:99], v[152:155], v[176:179], v[96:99]
	v_mfma_f32_16x16x32_bf16 v[84:87], v[144:147], v[184:187], v[84:87]
	v_mfma_f32_16x16x32_bf16 v[80:83], v[152:155], v[184:187], v[80:83]
	v_mfma_f32_16x16x32_bf16 v[124:127], v[148:151], v[164:167], v[124:127]
	v_mfma_f32_16x16x32_bf16 v[120:123], v[156:159], v[164:167], v[120:123]
	v_mfma_f32_16x16x32_bf16 v[116:119], v[148:151], v[172:175], v[116:119]
	v_mfma_f32_16x16x32_bf16 v[112:115], v[156:159], v[172:175], v[112:115]
	v_mfma_f32_16x16x32_bf16 v[100:103], v[148:151], v[180:183], v[100:103]
	v_mfma_f32_16x16x32_bf16 v[96:99], v[156:159], v[180:183], v[96:99]
	v_mfma_f32_16x16x32_bf16 v[84:87], v[148:151], v[188:191], v[84:87]
	v_mfma_f32_16x16x32_bf16 v[80:83], v[156:159], v[188:191], v[80:83]
	s_barrier
	s_add_i32 s20, 0, 0x1c000
	s_add_i32 s14, s39, s2
	v_add_u32_e32 v143, s20, v137
	s_add_u32 s98, s18, s8
	s_addc_u32 s99, s19, s9
	s_mov_b32 m0, s14
	ds_read_b128 v[192:195], v143
	ds_read_b128 v[196:199], v143 offset:1024
	ds_read_b128 v[200:203], v143 offset:2048
	ds_read_b128 v[204:207], v143 offset:3072
	global_load_lds_dwordx4 v130, s[98:99]
	s_add_i32 m0, s14, 0x2000
	s_nop 0
	global_load_lds_dwordx4 v128, s[98:99]
	s_barrier
	s_waitcnt lgkmcnt(0)
	s_waitcnt lgkmcnt(0)
	v_mfma_f32_16x16x32_bf16 v[108:111], v[192:195], v[160:163], v[108:111]
	v_mfma_f32_16x16x32_bf16 v[104:107], v[200:203], v[160:163], v[104:107]
	v_mfma_f32_16x16x32_bf16 v[92:95], v[192:195], v[168:171], v[92:95]
	v_mfma_f32_16x16x32_bf16 v[88:91], v[200:203], v[168:171], v[88:91]
	v_mfma_f32_16x16x32_bf16 v[76:79], v[192:195], v[176:179], v[76:79]
	v_mfma_f32_16x16x32_bf16 v[72:75], v[200:203], v[176:179], v[72:75]
	v_mfma_f32_16x16x32_bf16 v[68:71], v[192:195], v[184:187], v[68:71]
	v_mfma_f32_16x16x32_bf16 v[64:67], v[200:203], v[184:187], v[64:67]
	v_mfma_f32_16x16x32_bf16 v[108:111], v[196:199], v[164:167], v[108:111]
	v_mfma_f32_16x16x32_bf16 v[104:107], v[204:207], v[164:167], v[104:107]
	v_mfma_f32_16x16x32_bf16 v[92:95], v[196:199], v[172:175], v[92:95]
	v_mfma_f32_16x16x32_bf16 v[88:91], v[204:207], v[172:175], v[88:91]
	v_mfma_f32_16x16x32_bf16 v[76:79], v[196:199], v[180:183], v[76:79]
	v_mfma_f32_16x16x32_bf16 v[72:75], v[204:207], v[180:183], v[72:75]
	v_mfma_f32_16x16x32_bf16 v[68:71], v[196:199], v[188:191], v[68:71]
	v_mfma_f32_16x16x32_bf16 v[64:67], v[204:207], v[188:191], v[64:67]
	s_mov_b32 m0, s29
	v_lshl_add_u64 v[208:209], v[212:213], 0, s[8:9]
	s_barrier
	ds_read_b128 v[160:163], v140 offset:49152
	ds_read_b128 v[164:167], v140 offset:50176
	ds_read_b128 v[168:171], v140 offset:51200
	ds_read_b128 v[172:175], v140 offset:52224
	ds_read_b128 v[176:179], v140 offset:53248
	ds_read_b128 v[180:183], v140 offset:54272
	ds_read_b128 v[184:187], v140 offset:55296
	ds_read_b128 v[188:191], v140 offset:56320
	global_load_lds_dwordx4 v[208:209], off
	v_lshl_add_u64 v[208:209], v[214:215], 0, s[8:9]
	s_mov_b32 m0, s30
	s_nop 0
	global_load_lds_dwordx4 v[208:209], off
	s_barrier
	s_waitcnt lgkmcnt(0)
	s_waitcnt lgkmcnt(0)
	v_mfma_f32_16x16x32_bf16 v[60:63], v[144:147], v[160:163], v[60:63]
	v_mfma_f32_16x16x32_bf16 v[56:59], v[152:155], v[160:163], v[56:59]
	v_mfma_f32_16x16x32_bf16 v[52:55], v[144:147], v[168:171], v[52:55]
	v_mfma_f32_16x16x32_bf16 v[48:51], v[152:155], v[168:171], v[48:51]
	v_mfma_f32_16x16x32_bf16 v[36:39], v[144:147], v[176:179], v[36:39]
	v_mfma_f32_16x16x32_bf16 v[32:35], v[152:155], v[176:179], v[32:35]
	v_mfma_f32_16x16x32_bf16 v[20:23], v[144:147], v[184:187], v[20:23]
	v_mfma_f32_16x16x32_bf16 v[16:19], v[152:155], v[184:187], v[16:19]
	v_mfma_f32_16x16x32_bf16 v[60:63], v[148:151], v[164:167], v[60:63]
	v_mfma_f32_16x16x32_bf16 v[56:59], v[156:159], v[164:167], v[56:59]
	v_mfma_f32_16x16x32_bf16 v[52:55], v[148:151], v[172:175], v[52:55]
	v_mfma_f32_16x16x32_bf16 v[48:51], v[156:159], v[172:175], v[48:51]
	v_mfma_f32_16x16x32_bf16 v[36:39], v[148:151], v[180:183], v[36:39]
	v_mfma_f32_16x16x32_bf16 v[32:35], v[156:159], v[180:183], v[32:35]
	v_mfma_f32_16x16x32_bf16 v[20:23], v[148:151], v[188:191], v[20:23]
	v_mfma_f32_16x16x32_bf16 v[16:19], v[156:159], v[188:191], v[16:19]
	s_barrier
	s_add_u32 s14, s18, 0x160080
	s_addc_u32 s15, s19, 0
	s_add_i32 s18, s20, s2
	s_mov_b32 m0, s18
	s_nop 0
	global_load_lds_dwordx4 v130, s[14:15]
	s_add_i32 m0, s18, 0x2000
	s_nop 0
	global_load_lds_dwordx4 v128, s[14:15]
	s_waitcnt vmcnt(6)
	s_barrier
	v_mfma_f32_16x16x32_bf16 v[44:47], v[192:195], v[160:163], v[44:47]
	v_mfma_f32_16x16x32_bf16 v[40:43], v[200:203], v[160:163], v[40:43]
	v_mfma_f32_16x16x32_bf16 v[28:31], v[192:195], v[168:171], v[28:31]
	v_mfma_f32_16x16x32_bf16 v[24:27], v[200:203], v[168:171], v[24:27]
	v_mfma_f32_16x16x32_bf16 v[12:15], v[192:195], v[176:179], v[12:15]
	v_mfma_f32_16x16x32_bf16 v[8:11], v[200:203], v[176:179], v[8:11]
	v_mfma_f32_16x16x32_bf16 v[4:7], v[192:195], v[184:187], v[4:7]
	v_mfma_f32_16x16x32_bf16 v[0:3], v[200:203], v[184:187], v[0:3]
	v_mfma_f32_16x16x32_bf16 v[44:47], v[196:199], v[164:167], v[44:47]
	v_mfma_f32_16x16x32_bf16 v[40:43], v[204:207], v[164:167], v[40:43]
	v_mfma_f32_16x16x32_bf16 v[28:31], v[196:199], v[172:175], v[28:31]
	v_mfma_f32_16x16x32_bf16 v[24:27], v[204:207], v[172:175], v[24:27]
	v_mfma_f32_16x16x32_bf16 v[12:15], v[196:199], v[180:183], v[12:15]
	v_mfma_f32_16x16x32_bf16 v[8:11], v[204:207], v[180:183], v[8:11]
	v_mfma_f32_16x16x32_bf16 v[4:7], v[196:199], v[188:191], v[4:7]
	v_mfma_f32_16x16x32_bf16 v[0:3], v[204:207], v[188:191], v[0:3]
	s_add_i32 s47, s47, 2
	s_add_u32 s43, s43, 0x100
	s_addc_u32 s46, s46, 0
	s_cmp_gt_u32 s47, 5
	s_mov_b64 s[14:15], s[16:17]
	s_barrier
	s_cbranch_scc0 .LBB0_2927
	s_ashr_i32 s14, s28, 1
	s_and_b32 s14, s14, 0xfffffe00
	s_lshl_b32 s15, s27, 8
	s_add_i32 s15, s15, s14
	v_add_u32_e32 v146, s15, v136
	v_lshl_or_b32 v144, s26, 8, v138
	v_ashrrev_i32_e32 v147, 31, v146
	v_ashrrev_i32_e32 v145, 31, v144
	v_lshlrev_b64 v[148:149], 13, v[146:147]
	v_lshl_add_u64 v[148:149], s[58:59], 0, v[148:149]
	v_lshlrev_b64 v[144:145], 2, v[144:145]
	v_lshl_add_u64 v[148:149], v[148:149], 0, v[144:145]
	global_store_dwordx4 v[148:149], v[124:127], off
	global_store_dwordx4 v[148:149], v[120:123], off offset:64
	global_store_dwordx4 v[148:149], v[108:111], off offset:512
	global_store_dwordx4 v[148:149], v[104:107], off offset:576
	s_mov_b64 s[14:15], 0x100000
	s_mov_b32 s28, s41
	v_or_b32_e32 v104, 16, v146
	v_ashrrev_i32_e32 v105, 31, v104
	v_lshlrev_b64 v[104:105], 13, v[104:105]
	v_lshl_add_u64 v[104:105], s[58:59], 0, v[104:105]
	v_lshl_add_u64 v[104:105], v[104:105], 0, v[144:145]
	global_store_dwordx4 v[104:105], v[116:119], off
	global_store_dwordx4 v[104:105], v[112:115], off offset:64
	global_store_dwordx4 v[104:105], v[92:95], off offset:512
	global_store_dwordx4 v[104:105], v[88:91], off offset:576
	s_mov_b32 s26, s40
	s_mov_b32 s27, s42
	v_or_b32_e32 v88, 32, v146
	v_ashrrev_i32_e32 v89, 31, v88
	v_lshlrev_b64 v[88:89], 13, v[88:89]
	v_lshl_add_u64 v[88:89], s[58:59], 0, v[88:89]
	v_lshl_add_u64 v[88:89], v[88:89], 0, v[144:145]
	global_store_dwordx4 v[88:89], v[100:103], off
	global_store_dwordx4 v[88:89], v[96:99], off offset:64
	global_store_dwordx4 v[88:89], v[76:79], off offset:512
	global_store_dwordx4 v[88:89], v[72:75], off offset:576
	s_mov_b64 s[16:17], s[6:7]
	s_nop 0
	v_or_b32_e32 v72, 48, v146
	v_ashrrev_i32_e32 v73, 31, v72
	v_lshlrev_b64 v[72:73], 13, v[72:73]
	v_lshl_add_u64 v[72:73], s[58:59], 0, v[72:73]
	v_lshl_add_u64 v[72:73], v[72:73], 0, v[144:145]
	global_store_dwordx4 v[72:73], v[84:87], off
	global_store_dwordx4 v[72:73], v[80:83], off offset:64
	global_store_dwordx4 v[72:73], v[68:71], off offset:512
	global_store_dwordx4 v[72:73], v[64:67], off offset:576
	s_nop 1
	v_lshl_add_u64 v[64:65], v[148:149], 0, s[14:15]
	s_mov_b32 s14, 0x100000
	v_add_co_u32_e32 v66, vcc, s14, v148
	s_mov_b64 s[14:15], 0x120000
	s_nop 0
	v_addc_co_u32_e32 v67, vcc, 0, v149, vcc
	global_store_dwordx4 v[66:67], v[60:63], off
	global_store_dwordx4 v[64:65], v[56:59], off offset:64
	global_store_dwordx4 v[64:65], v[44:47], off offset:512
	global_store_dwordx4 v[64:65], v[40:43], off offset:576
	s_nop 1
	v_lshl_add_u64 v[40:41], v[148:149], 0, s[14:15]
	s_mov_b32 s14, 0x120000
	v_add_co_u32_e32 v42, vcc, s14, v148
	s_mov_b64 s[14:15], 0x140000
	s_nop 0
	v_addc_co_u32_e32 v43, vcc, 0, v149, vcc
	global_store_dwordx4 v[42:43], v[52:55], off
	global_store_dwordx4 v[40:41], v[48:51], off offset:64
	global_store_dwordx4 v[40:41], v[28:31], off offset:512
	global_store_dwordx4 v[40:41], v[24:27], off offset:576
	s_nop 1
	v_lshl_add_u64 v[24:25], v[148:149], 0, s[14:15]
	s_mov_b32 s14, 0x140000
	v_add_co_u32_e32 v26, vcc, s14, v148
	s_mov_b64 s[14:15], 0x160000
	s_nop 0
	v_addc_co_u32_e32 v27, vcc, 0, v149, vcc
	global_store_dwordx4 v[26:27], v[36:39], off
	global_store_dwordx4 v[24:25], v[32:35], off offset:64
	global_store_dwordx4 v[24:25], v[12:15], off offset:512
	global_store_dwordx4 v[24:25], v[8:11], off offset:576
	s_nop 1
	v_add_co_u32_e32 v10, vcc, 0x160000, v148
	v_lshl_add_u64 v[8:9], v[148:149], 0, s[14:15]
	s_nop 0
	v_addc_co_u32_e32 v11, vcc, 0, v149, vcc
	s_and_b64 vcc, exec, s[10:11]
	s_mov_b64 s[14:15], s[12:13]
	global_store_dwordx4 v[10:11], v[20:23], off
	global_store_dwordx4 v[8:9], v[16:19], off offset:64
	global_store_dwordx4 v[8:9], v[4:7], off offset:512
	global_store_dwordx4 v[8:9], v[0:3], off offset:576
	s_cbranch_vccz .LBB0_2920
	s_waitcnt vmcnt(0)
	s_cmpk_gt_u32 s1, 0xff
	s_cbranch_scc1 .LBB0_2931
	s_barrier

.LBB0_3443:
	ds_read_b128 v[148:151], v144
	ds_read_b128 v[152:155], v144 offset:1024
	ds_read_b128 v[156:159], v144 offset:2048
	ds_read_b128 v[160:163], v144 offset:3072
	s_add_u32 s20, s18, 0x100
	s_addc_u32 s21, s19, 0
	s_cmp_eq_u32 s46, 28
	s_cselect_b32 s25, s11, s21
	s_cselect_b32 s24, s40, s20
	s_cselect_b32 s23, s9, s43
	s_cselect_b32 s22, s41, s42
	s_add_i32 m0, s26, 0xc000
	ds_read_b128 v[164:167], v145
	ds_read_b128 v[168:171], v145 offset:1024
	ds_read_b128 v[172:175], v145 offset:2048
	ds_read_b128 v[176:179], v145 offset:3072
	ds_read_b128 v[180:183], v145 offset:4096
	ds_read_b128 v[184:187], v145 offset:5120
	ds_read_b128 v[188:191], v145 offset:6144
	ds_read_b128 v[192:195], v145 offset:7168
	global_load_lds_dwordx4 v134, s[18:19]
	s_add_i32 m0, s26, 0xe000
	s_nop 0
	global_load_lds_dwordx4 v136, s[18:19]
	s_waitcnt lgkmcnt(8)
	s_barrier
	s_waitcnt lgkmcnt(0)
	s_waitcnt lgkmcnt(0)
	v_mfma_f32_16x16x32_bf16 v[124:127], v[148:151], v[164:167], v[124:127]
	v_mfma_f32_16x16x32_bf16 v[120:123], v[156:159], v[164:167], v[120:123]
	v_mfma_f32_16x16x32_bf16 v[108:111], v[148:151], v[172:175], v[108:111]
	v_mfma_f32_16x16x32_bf16 v[104:107], v[156:159], v[172:175], v[104:107]
	v_mfma_f32_16x16x32_bf16 v[92:95], v[148:151], v[180:183], v[92:95]
	v_mfma_f32_16x16x32_bf16 v[88:91], v[156:159], v[180:183], v[88:91]
	v_mfma_f32_16x16x32_bf16 v[76:79], v[148:151], v[188:191], v[76:79]
	v_mfma_f32_16x16x32_bf16 v[72:75], v[156:159], v[188:191], v[72:75]
	v_mfma_f32_16x16x32_bf16 v[124:127], v[152:155], v[168:171], v[124:127]
	v_mfma_f32_16x16x32_bf16 v[120:123], v[160:163], v[168:171], v[120:123]
	v_mfma_f32_16x16x32_bf16 v[108:111], v[152:155], v[176:179], v[108:111]
	v_mfma_f32_16x16x32_bf16 v[104:107], v[160:163], v[176:179], v[104:107]
	v_mfma_f32_16x16x32_bf16 v[92:95], v[152:155], v[184:187], v[92:95]
	v_mfma_f32_16x16x32_bf16 v[88:91], v[160:163], v[184:187], v[88:91]
	v_mfma_f32_16x16x32_bf16 v[76:79], v[152:155], v[192:195], v[76:79]
	v_mfma_f32_16x16x32_bf16 v[72:75], v[160:163], v[192:195], v[72:75]
	s_barrier
	s_add_i32 s18, s37, s1
	s_mov_b32 m0, s18
	ds_read_b128 v[196:199], v146
	ds_read_b128 v[200:203], v146 offset:1024
	ds_read_b128 v[204:207], v146 offset:2048
	ds_read_b128 v[208:211], v146 offset:3072
	global_load_lds_dwordx4 v130, s[22:23]
	s_add_i32 m0, s18, 0x2000
	s_nop 0
	global_load_lds_dwordx4 v128, s[22:23]
	s_barrier
	s_waitcnt lgkmcnt(0)
	s_waitcnt lgkmcnt(0)
	v_mfma_f32_16x16x32_bf16 v[116:119], v[196:199], v[164:167], v[116:119]
	v_mfma_f32_16x16x32_bf16 v[112:115], v[204:207], v[164:167], v[112:115]
	v_mfma_f32_16x16x32_bf16 v[100:103], v[196:199], v[172:175], v[100:103]
	v_mfma_f32_16x16x32_bf16 v[96:99], v[204:207], v[172:175], v[96:99]
	v_mfma_f32_16x16x32_bf16 v[84:87], v[196:199], v[180:183], v[84:87]
	v_mfma_f32_16x16x32_bf16 v[80:83], v[204:207], v[180:183], v[80:83]
	v_mfma_f32_16x16x32_bf16 v[68:71], v[196:199], v[188:191], v[68:71]
	v_mfma_f32_16x16x32_bf16 v[64:67], v[204:207], v[188:191], v[64:67]
	v_mfma_f32_16x16x32_bf16 v[116:119], v[200:203], v[168:171], v[116:119]
	v_mfma_f32_16x16x32_bf16 v[112:115], v[208:211], v[168:171], v[112:115]
	v_mfma_f32_16x16x32_bf16 v[100:103], v[200:203], v[176:179], v[100:103]
	v_mfma_f32_16x16x32_bf16 v[96:99], v[208:211], v[176:179], v[96:99]
	v_mfma_f32_16x16x32_bf16 v[84:87], v[200:203], v[184:187], v[84:87]
	v_mfma_f32_16x16x32_bf16 v[80:83], v[208:211], v[184:187], v[80:83]
	v_mfma_f32_16x16x32_bf16 v[68:71], v[200:203], v[192:195], v[68:71]
	v_mfma_f32_16x16x32_bf16 v[64:67], v[208:211], v[192:195], v[64:67]
	s_mov_b32 m0, s26
	v_lshl_add_u64 v[216:217], s[24:25], 0, v[130:131]
	s_barrier
	ds_read_b128 v[164:167], v145 offset:16384
	ds_read_b128 v[168:171], v145 offset:17408
	ds_read_b128 v[172:175], v145 offset:18432
	ds_read_b128 v[176:179], v145 offset:19456
	ds_read_b128 v[180:183], v145 offset:20480
	ds_read_b128 v[184:187], v145 offset:21504
	ds_read_b128 v[188:191], v145 offset:22528
	ds_read_b128 v[192:195], v145 offset:23552
	global_load_lds_dwordx4 v130, s[24:25]
	v_lshl_add_u64 v[218:219], s[24:25], 0, v[128:129]
	s_mov_b32 m0, s27
	s_nop 0
	global_load_lds_dwordx4 v128, s[24:25]
	s_barrier
	s_waitcnt lgkmcnt(0)
	s_waitcnt lgkmcnt(0)
	v_mfma_f32_16x16x32_bf16 v[60:63], v[148:151], v[164:167], v[60:63]
	v_mfma_f32_16x16x32_bf16 v[56:59], v[156:159], v[164:167], v[56:59]
	v_mfma_f32_16x16x32_bf16 v[44:47], v[148:151], v[172:175], v[44:47]
	v_mfma_f32_16x16x32_bf16 v[40:43], v[156:159], v[172:175], v[40:43]
	v_mfma_f32_16x16x32_bf16 v[28:31], v[148:151], v[180:183], v[28:31]
	v_mfma_f32_16x16x32_bf16 v[24:27], v[156:159], v[180:183], v[24:27]
	v_mfma_f32_16x16x32_bf16 v[12:15], v[148:151], v[188:191], v[12:15]
	v_mfma_f32_16x16x32_bf16 v[8:11], v[156:159], v[188:191], v[8:11]
	v_mfma_f32_16x16x32_bf16 v[60:63], v[152:155], v[168:171], v[60:63]
	v_mfma_f32_16x16x32_bf16 v[56:59], v[160:163], v[168:171], v[56:59]
	v_mfma_f32_16x16x32_bf16 v[44:47], v[152:155], v[176:179], v[44:47]
	v_mfma_f32_16x16x32_bf16 v[40:43], v[160:163], v[176:179], v[40:43]
	v_mfma_f32_16x16x32_bf16 v[28:31], v[152:155], v[184:187], v[28:31]
	v_mfma_f32_16x16x32_bf16 v[24:27], v[160:163], v[184:187], v[24:27]
	v_mfma_f32_16x16x32_bf16 v[12:15], v[152:155], v[192:195], v[12:15]
	v_mfma_f32_16x16x32_bf16 v[8:11], v[160:163], v[192:195], v[8:11]
	s_barrier
	s_add_u32 s18, s22, 0x80000
	s_addc_u32 s19, s23, 0
	s_add_i32 s47, s38, s1
	s_mov_b32 m0, s47
	s_nop 0
	global_load_lds_dwordx4 v130, s[18:19]
	s_add_i32 m0, s47, 0x2000
	s_nop 0
	global_load_lds_dwordx4 v128, s[18:19]
	s_waitcnt vmcnt(6)
	s_barrier
	v_mfma_f32_16x16x32_bf16 v[52:55], v[196:199], v[164:167], v[52:55]
	v_mfma_f32_16x16x32_bf16 v[48:51], v[204:207], v[164:167], v[48:51]
	v_mfma_f32_16x16x32_bf16 v[36:39], v[196:199], v[172:175], v[36:39]
	v_mfma_f32_16x16x32_bf16 v[32:35], v[204:207], v[172:175], v[32:35]
	v_mfma_f32_16x16x32_bf16 v[20:23], v[196:199], v[180:183], v[20:23]
	v_mfma_f32_16x16x32_bf16 v[16:19], v[204:207], v[180:183], v[16:19]
	v_mfma_f32_16x16x32_bf16 v[4:7], v[196:199], v[188:191], v[4:7]
	v_mfma_f32_16x16x32_bf16 v[0:3], v[204:207], v[188:191], v[0:3]
	v_mfma_f32_16x16x32_bf16 v[52:55], v[200:203], v[168:171], v[52:55]
	v_mfma_f32_16x16x32_bf16 v[48:51], v[208:211], v[168:171], v[48:51]
	v_mfma_f32_16x16x32_bf16 v[36:39], v[200:203], v[176:179], v[36:39]
	v_mfma_f32_16x16x32_bf16 v[32:35], v[208:211], v[176:179], v[32:35]
	v_mfma_f32_16x16x32_bf16 v[20:23], v[200:203], v[184:187], v[20:23]
	v_mfma_f32_16x16x32_bf16 v[16:19], v[208:211], v[184:187], v[16:19]
	v_mfma_f32_16x16x32_bf16 v[4:7], v[200:203], v[192:195], v[4:7]
	v_mfma_f32_16x16x32_bf16 v[0:3], v[208:211], v[192:195], v[0:3]
	s_add_i32 s47, 0, 0x18000
	v_add_u32_e32 v147, s47, v143
	s_barrier
	ds_read_b128 v[148:151], v147
	ds_read_b128 v[152:155], v147 offset:1024
	ds_read_b128 v[156:159], v147 offset:2048
	ds_read_b128 v[160:163], v147 offset:3072
	s_add_u32 s18, s24, 0x80000
	s_addc_u32 s19, s25, 0
	s_mov_b32 m0, s28
	ds_read_b128 v[164:167], v145 offset:32768
	ds_read_b128 v[168:171], v145 offset:33792
	ds_read_b128 v[172:175], v145 offset:34816
	ds_read_b128 v[176:179], v145 offset:35840
	ds_read_b128 v[180:183], v145 offset:36864
	ds_read_b128 v[184:187], v145 offset:37888
	ds_read_b128 v[188:191], v145 offset:38912
	ds_read_b128 v[192:195], v145 offset:39936
	global_load_lds_dwordx4 v130, s[18:19]
	s_mov_b32 m0, s29
	s_nop 0
	global_load_lds_dwordx4 v128, s[18:19]
	s_waitcnt lgkmcnt(8)
	s_barrier
	s_waitcnt lgkmcnt(0)
	s_waitcnt lgkmcnt(0)
	v_mfma_f32_16x16x32_bf16 v[124:127], v[148:151], v[164:167], v[124:127]
	v_mfma_f32_16x16x32_bf16 v[120:123], v[156:159], v[164:167], v[120:123]
	v_mfma_f32_16x16x32_bf16 v[108:111], v[148:151], v[172:175], v[108:111]
	v_mfma_f32_16x16x32_bf16 v[104:107], v[156:159], v[172:175], v[104:107]
	v_mfma_f32_16x16x32_bf16 v[92:95], v[148:151], v[180:183], v[92:95]
	v_mfma_f32_16x16x32_bf16 v[88:91], v[156:159], v[180:183], v[88:91]
	v_mfma_f32_16x16x32_bf16 v[76:79], v[148:151], v[188:191], v[76:79]
	v_mfma_f32_16x16x32_bf16 v[72:75], v[156:159], v[188:191], v[72:75]
	v_mfma_f32_16x16x32_bf16 v[124:127], v[152:155], v[168:171], v[124:127]
	v_mfma_f32_16x16x32_bf16 v[120:123], v[160:163], v[168:171], v[120:123]
	v_mfma_f32_16x16x32_bf16 v[108:111], v[152:155], v[176:179], v[108:111]
	v_mfma_f32_16x16x32_bf16 v[104:107], v[160:163], v[176:179], v[104:107]
	v_mfma_f32_16x16x32_bf16 v[92:95], v[152:155], v[184:187], v[92:95]
	v_mfma_f32_16x16x32_bf16 v[88:91], v[160:163], v[184:187], v[88:91]
	v_mfma_f32_16x16x32_bf16 v[76:79], v[152:155], v[192:195], v[76:79]
	v_mfma_f32_16x16x32_bf16 v[72:75], v[160:163], v[192:195], v[72:75]
	s_barrier
	s_add_i32 s24, 0, 0x1c000
	s_add_i32 s18, s47, s1
	v_add_u32_e32 v147, s24, v143
	s_add_u32 s98, s22, s6
	s_addc_u32 s99, s23, s7
	s_mov_b32 m0, s18
	ds_read_b128 v[196:199], v147
	ds_read_b128 v[200:203], v147 offset:1024
	ds_read_b128 v[204:207], v147 offset:2048
	ds_read_b128 v[208:211], v147 offset:3072
	global_load_lds_dwordx4 v130, s[98:99]
	s_add_i32 m0, s18, 0x2000
	s_nop 0
	global_load_lds_dwordx4 v128, s[98:99]
	s_barrier
	s_waitcnt lgkmcnt(0)
	s_waitcnt lgkmcnt(0)
	v_mfma_f32_16x16x32_bf16 v[116:119], v[196:199], v[164:167], v[116:119]
	v_mfma_f32_16x16x32_bf16 v[112:115], v[204:207], v[164:167], v[112:115]
	v_mfma_f32_16x16x32_bf16 v[100:103], v[196:199], v[172:175], v[100:103]
	v_mfma_f32_16x16x32_bf16 v[96:99], v[204:207], v[172:175], v[96:99]
	v_mfma_f32_16x16x32_bf16 v[84:87], v[196:199], v[180:183], v[84:87]
	v_mfma_f32_16x16x32_bf16 v[80:83], v[204:207], v[180:183], v[80:83]
	v_mfma_f32_16x16x32_bf16 v[68:71], v[196:199], v[188:191], v[68:71]
	v_mfma_f32_16x16x32_bf16 v[64:67], v[204:207], v[188:191], v[64:67]
	v_mfma_f32_16x16x32_bf16 v[116:119], v[200:203], v[168:171], v[116:119]
	v_mfma_f32_16x16x32_bf16 v[112:115], v[208:211], v[168:171], v[112:115]
	v_mfma_f32_16x16x32_bf16 v[100:103], v[200:203], v[176:179], v[100:103]
	v_mfma_f32_16x16x32_bf16 v[96:99], v[208:211], v[176:179], v[96:99]
	v_mfma_f32_16x16x32_bf16 v[84:87], v[200:203], v[184:187], v[84:87]
	v_mfma_f32_16x16x32_bf16 v[80:83], v[208:211], v[184:187], v[80:83]
	v_mfma_f32_16x16x32_bf16 v[68:71], v[200:203], v[192:195], v[68:71]
	v_mfma_f32_16x16x32_bf16 v[64:67], v[208:211], v[192:195], v[64:67]
	s_mov_b32 m0, s31
	v_lshl_add_u64 v[212:213], v[216:217], 0, s[6:7]
	s_barrier
	ds_read_b128 v[164:167], v145 offset:49152
	ds_read_b128 v[168:171], v145 offset:50176
	ds_read_b128 v[172:175], v145 offset:51200
	ds_read_b128 v[176:179], v145 offset:52224
	ds_read_b128 v[180:183], v145 offset:53248
	ds_read_b128 v[184:187], v145 offset:54272
	ds_read_b128 v[188:191], v145 offset:55296
	ds_read_b128 v[192:195], v145 offset:56320
	global_load_lds_dwordx4 v[212:213], off
	v_lshl_add_u64 v[212:213], v[218:219], 0, s[6:7]
	s_mov_b32 m0, s34
	s_nop 0
	global_load_lds_dwordx4 v[212:213], off
	s_barrier
	s_waitcnt lgkmcnt(0)
	s_waitcnt lgkmcnt(0)
	v_mfma_f32_16x16x32_bf16 v[60:63], v[148:151], v[164:167], v[60:63]
	v_mfma_f32_16x16x32_bf16 v[56:59], v[156:159], v[164:167], v[56:59]
	v_mfma_f32_16x16x32_bf16 v[44:47], v[148:151], v[172:175], v[44:47]
	v_mfma_f32_16x16x32_bf16 v[40:43], v[156:159], v[172:175], v[40:43]
	v_mfma_f32_16x16x32_bf16 v[28:31], v[148:151], v[180:183], v[28:31]
	v_mfma_f32_16x16x32_bf16 v[24:27], v[156:159], v[180:183], v[24:27]
	v_mfma_f32_16x16x32_bf16 v[12:15], v[148:151], v[188:191], v[12:15]
	v_mfma_f32_16x16x32_bf16 v[8:11], v[156:159], v[188:191], v[8:11]
	v_mfma_f32_16x16x32_bf16 v[60:63], v[152:155], v[168:171], v[60:63]
	v_mfma_f32_16x16x32_bf16 v[56:59], v[160:163], v[168:171], v[56:59]
	v_mfma_f32_16x16x32_bf16 v[44:47], v[152:155], v[176:179], v[44:47]
	v_mfma_f32_16x16x32_bf16 v[40:43], v[160:163], v[176:179], v[40:43]
	v_mfma_f32_16x16x32_bf16 v[28:31], v[152:155], v[184:187], v[28:31]
	v_mfma_f32_16x16x32_bf16 v[24:27], v[160:163], v[184:187], v[24:27]
	v_mfma_f32_16x16x32_bf16 v[12:15], v[152:155], v[192:195], v[12:15]
	v_mfma_f32_16x16x32_bf16 v[8:11], v[160:163], v[192:195], v[8:11]
	s_barrier
	s_add_u32 s18, s22, 0x80080
	s_addc_u32 s19, s23, 0
	s_add_i32 s22, s24, s1
	s_mov_b32 m0, s22
	s_nop 0
	global_load_lds_dwordx4 v130, s[18:19]
	s_add_i32 m0, s22, 0x2000
	s_nop 0
	global_load_lds_dwordx4 v128, s[18:19]
	s_waitcnt vmcnt(6)
	s_barrier
	v_mfma_f32_16x16x32_bf16 v[52:55], v[196:199], v[164:167], v[52:55]
	v_mfma_f32_16x16x32_bf16 v[48:51], v[204:207], v[164:167], v[48:51]
	v_mfma_f32_16x16x32_bf16 v[36:39], v[196:199], v[172:175], v[36:39]
	v_mfma_f32_16x16x32_bf16 v[32:35], v[204:207], v[172:175], v[32:35]
	v_mfma_f32_16x16x32_bf16 v[20:23], v[196:199], v[180:183], v[20:23]
	v_mfma_f32_16x16x32_bf16 v[16:19], v[204:207], v[180:183], v[16:19]
	v_mfma_f32_16x16x32_bf16 v[4:7], v[196:199], v[188:191], v[4:7]
	v_mfma_f32_16x16x32_bf16 v[0:3], v[204:207], v[188:191], v[0:3]
	v_mfma_f32_16x16x32_bf16 v[52:55], v[200:203], v[168:171], v[52:55]
	v_mfma_f32_16x16x32_bf16 v[48:51], v[208:211], v[168:171], v[48:51]
	v_mfma_f32_16x16x32_bf16 v[36:39], v[200:203], v[176:179], v[36:39]
	v_mfma_f32_16x16x32_bf16 v[32:35], v[208:211], v[176:179], v[32:35]
	v_mfma_f32_16x16x32_bf16 v[20:23], v[200:203], v[184:187], v[20:23]
	v_mfma_f32_16x16x32_bf16 v[16:19], v[208:211], v[184:187], v[16:19]
	v_mfma_f32_16x16x32_bf16 v[4:7], v[200:203], v[192:195], v[4:7]
	v_mfma_f32_16x16x32_bf16 v[0:3], v[208:211], v[192:195], v[0:3]
	s_add_i32 s46, s46, 2
	s_add_u32 s42, s42, 0x100
	s_addc_u32 s43, s43, 0
	s_cmp_gt_u32 s46, 29
	s_mov_b64 s[18:19], s[20:21]
	s_barrier
	s_cbranch_scc0 .LBB0_3443
	v_mul_f32_e32 v148, 0xbfb8aa3b, v124
	v_exp_f32_e32 v150, v148
	v_mul_f32_e32 v148, 0xbfb8aa3b, v125
	v_exp_f32_e32 v151, v148
	v_mul_f32_e32 v152, 0xbfb8aa3b, v126
	v_mul_f32_e32 v153, 0xbfb8aa3b, v127
	v_exp_f32_e32 v152, v152
	v_exp_f32_e32 v153, v153
	v_add_f32_e32 v150, 1.0, v150
	v_add_f32_e32 v151, 1.0, v151
	v_rcp_f32_e32 v150, v150
	v_rcp_f32_e32 v151, v151
	v_add_f32_e32 v152, 1.0, v152
	v_add_f32_e32 v153, 1.0, v153
	v_rcp_f32_e32 v152, v152
	v_rcp_f32_e32 v153, v153
	v_pk_mul_f32 v[124:125], v[124:125], v[150:151]
	s_lshl_b32 s9, s17, 7
	v_pk_mul_f32 v[120:121], v[120:121], v[124:125]
	v_pk_mul_f32 v[124:125], v[126:127], v[152:153]
	v_lshl_add_u32 v147, s16, 8, v142
	v_pk_mul_f32 v[122:123], v[122:123], v[124:125]
	v_mul_f32_e32 v124, 0xbfb8aa3b, v116
	v_mul_f32_e32 v125, 0xbfb8aa3b, v117
	s_or_b32 s16, s9, s35
	v_exp_f32_e32 v124, v124
	v_exp_f32_e32 v125, v125
	s_ashr_i32 s17, s16, 31
	v_mad_i64_i32 v[148:149], s[18:19], v147, s39, v[132:133]
	s_lshl_b64 s[16:17], s[16:17], 1
	v_cvt_pk_bf16_f32 v120, v120, v121
	v_cvt_pk_bf16_f32 v121, v122, v123
	v_lshl_add_u64 v[122:123], v[148:149], 0, s[16:17]
	global_store_dwordx2 v[122:123], v[120:121], off
	v_add_f32_e32 v120, 1.0, v124
	v_add_f32_e32 v121, 1.0, v125
	v_mul_f32_e32 v124, 0xbfb8aa3b, v118
	v_mul_f32_e32 v125, 0xbfb8aa3b, v119
	v_exp_f32_e32 v124, v124
	v_exp_f32_e32 v125, v125
	v_rcp_f32_e32 v120, v120
	v_rcp_f32_e32 v121, v121
	v_add_f32_e32 v124, 1.0, v124
	v_add_f32_e32 v125, 1.0, v125
	v_rcp_f32_e32 v124, v124
	v_rcp_f32_e32 v125, v125
	v_pk_mul_f32 v[116:117], v[116:117], v[120:121]
	s_and_b64 vcc, exec, s[4:5]
	v_pk_mul_f32 v[112:113], v[112:113], v[116:117]
	v_pk_mul_f32 v[116:117], v[118:119], v[124:125]
	v_cvt_pk_bf16_f32 v112, v112, v113
	v_pk_mul_f32 v[114:115], v[114:115], v[116:117]
	v_mul_f32_e32 v116, 0xbfb8aa3b, v110
	v_cvt_pk_bf16_f32 v113, v114, v115
	global_store_dwordx2 v[122:123], v[112:113], off offset:128
	v_mul_f32_e32 v113, 0xbfb8aa3b, v108
	v_exp_f32_e32 v114, v113
	v_mul_f32_e32 v113, 0xbfb8aa3b, v109
	v_exp_f32_e32 v115, v113
	v_mul_f32_e32 v117, 0xbfb8aa3b, v111
	v_exp_f32_e32 v116, v116
	v_exp_f32_e32 v117, v117
	v_add_f32_e32 v114, 1.0, v114
	v_add_f32_e32 v115, 1.0, v115
	v_rcp_f32_e32 v114, v114
	v_rcp_f32_e32 v115, v115
	v_add_f32_e32 v116, 1.0, v116
	v_add_f32_e32 v117, 1.0, v117
	v_rcp_f32_e32 v116, v116
	v_rcp_f32_e32 v117, v117
	v_pk_mul_f32 v[108:109], v[108:109], v[114:115]
	v_or_b32_e32 v112, 16, v147
	v_pk_mul_f32 v[104:105], v[104:105], v[108:109]
	v_pk_mul_f32 v[108:109], v[110:111], v[116:117]
	v_mad_i64_i32 v[112:113], s[18:19], v112, s39, v[132:133]
	v_pk_mul_f32 v[106:107], v[106:107], v[108:109]
	v_mul_f32_e32 v108, 0xbfb8aa3b, v100
	v_mul_f32_e32 v109, 0xbfb8aa3b, v101
	v_exp_f32_e32 v108, v108
	v_exp_f32_e32 v109, v109
	v_cvt_pk_bf16_f32 v104, v104, v105
	v_cvt_pk_bf16_f32 v105, v106, v107
	v_lshl_add_u64 v[106:107], v[112:113], 0, s[16:17]
	global_store_dwordx2 v[106:107], v[104:105], off
	v_add_f32_e32 v104, 1.0, v108
	v_add_f32_e32 v105, 1.0, v109
	v_mul_f32_e32 v108, 0xbfb8aa3b, v102
	v_mul_f32_e32 v109, 0xbfb8aa3b, v103
	v_exp_f32_e32 v108, v108
	v_exp_f32_e32 v109, v109
	v_rcp_f32_e32 v104, v104
	v_rcp_f32_e32 v105, v105
	v_add_f32_e32 v108, 1.0, v108
	v_add_f32_e32 v109, 1.0, v109
	v_rcp_f32_e32 v108, v108
	v_rcp_f32_e32 v109, v109
	v_pk_mul_f32 v[100:101], v[100:101], v[104:105]
	s_mov_b64 s[20:21], s[14:15]
	v_pk_mul_f32 v[96:97], v[96:97], v[100:101]
	v_pk_mul_f32 v[100:101], v[102:103], v[108:109]
	v_cvt_pk_bf16_f32 v96, v96, v97
	v_pk_mul_f32 v[98:99], v[98:99], v[100:101]
	v_mul_f32_e32 v100, 0xbfb8aa3b, v94
	v_cvt_pk_bf16_f32 v97, v98, v99
	global_store_dwordx2 v[106:107], v[96:97], off offset:128
	v_mul_f32_e32 v97, 0xbfb8aa3b, v92
	v_exp_f32_e32 v98, v97
	v_mul_f32_e32 v97, 0xbfb8aa3b, v93
	v_exp_f32_e32 v99, v97
	v_mul_f32_e32 v101, 0xbfb8aa3b, v95
	v_exp_f32_e32 v100, v100
	v_exp_f32_e32 v101, v101
	v_add_f32_e32 v98, 1.0, v98
	v_add_f32_e32 v99, 1.0, v99
	v_rcp_f32_e32 v98, v98
	v_rcp_f32_e32 v99, v99
	v_add_f32_e32 v100, 1.0, v100
	v_add_f32_e32 v101, 1.0, v101
	v_rcp_f32_e32 v100, v100
	v_rcp_f32_e32 v101, v101
	v_pk_mul_f32 v[92:93], v[92:93], v[98:99]
	v_or_b32_e32 v96, 32, v147
	v_pk_mul_f32 v[88:89], v[88:89], v[92:93]
	v_pk_mul_f32 v[92:93], v[94:95], v[100:101]
	v_mad_i64_i32 v[96:97], s[18:19], v96, s39, v[132:133]
	v_pk_mul_f32 v[90:91], v[90:91], v[92:93]
	v_mul_f32_e32 v92, 0xbfb8aa3b, v84
	v_mul_f32_e32 v93, 0xbfb8aa3b, v85
	v_exp_f32_e32 v92, v92
	v_exp_f32_e32 v93, v93
	v_cvt_pk_bf16_f32 v88, v88, v89
	v_cvt_pk_bf16_f32 v89, v90, v91
	v_lshl_add_u64 v[90:91], v[96:97], 0, s[16:17]
	global_store_dwordx2 v[90:91], v[88:89], off
	v_add_f32_e32 v88, 1.0, v92
	v_add_f32_e32 v89, 1.0, v93
	v_mul_f32_e32 v92, 0xbfb8aa3b, v86
	v_mul_f32_e32 v93, 0xbfb8aa3b, v87
	v_exp_f32_e32 v92, v92
	v_exp_f32_e32 v93, v93
	v_rcp_f32_e32 v88, v88
	v_rcp_f32_e32 v89, v89
	v_add_f32_e32 v92, 1.0, v92
	v_add_f32_e32 v93, 1.0, v93
	v_rcp_f32_e32 v92, v92
	v_rcp_f32_e32 v93, v93
	v_pk_mul_f32 v[84:85], v[84:85], v[88:89]
	s_nop 0
	v_pk_mul_f32 v[80:81], v[80:81], v[84:85]
	v_pk_mul_f32 v[84:85], v[86:87], v[92:93]
	v_cvt_pk_bf16_f32 v80, v80, v81
	v_pk_mul_f32 v[82:83], v[82:83], v[84:85]
	v_mul_f32_e32 v84, 0xbfb8aa3b, v78
	v_cvt_pk_bf16_f32 v81, v82, v83
	global_store_dwordx2 v[90:91], v[80:81], off offset:128
	v_mul_f32_e32 v81, 0xbfb8aa3b, v76
	v_exp_f32_e32 v82, v81
	v_mul_f32_e32 v81, 0xbfb8aa3b, v77
	v_exp_f32_e32 v83, v81
	v_mul_f32_e32 v85, 0xbfb8aa3b, v79
	v_exp_f32_e32 v84, v84
	v_exp_f32_e32 v85, v85
	v_add_f32_e32 v82, 1.0, v82
	v_add_f32_e32 v83, 1.0, v83
	v_rcp_f32_e32 v82, v82
	v_rcp_f32_e32 v83, v83
	v_add_f32_e32 v84, 1.0, v84
	v_add_f32_e32 v85, 1.0, v85
	v_rcp_f32_e32 v84, v84
	v_rcp_f32_e32 v85, v85
	v_pk_mul_f32 v[76:77], v[76:77], v[82:83]
	v_or_b32_e32 v80, 48, v147
	v_pk_mul_f32 v[72:73], v[72:73], v[76:77]
	v_pk_mul_f32 v[76:77], v[78:79], v[84:85]
	v_mad_i64_i32 v[80:81], s[18:19], v80, s39, v[132:133]
	v_pk_mul_f32 v[74:75], v[74:75], v[76:77]
	v_mul_f32_e32 v76, 0xbfb8aa3b, v68
	v_mul_f32_e32 v77, 0xbfb8aa3b, v69
	v_exp_f32_e32 v76, v76
	v_exp_f32_e32 v77, v77
	v_cvt_pk_bf16_f32 v72, v72, v73
	v_cvt_pk_bf16_f32 v73, v74, v75
	v_lshl_add_u64 v[74:75], v[80:81], 0, s[16:17]
	global_store_dwordx2 v[74:75], v[72:73], off
	v_add_f32_e32 v72, 1.0, v76
	v_add_f32_e32 v73, 1.0, v77
	v_mul_f32_e32 v76, 0xbfb8aa3b, v70
	v_mul_f32_e32 v77, 0xbfb8aa3b, v71
	v_exp_f32_e32 v76, v76
	v_exp_f32_e32 v77, v77
	v_rcp_f32_e32 v72, v72
	v_rcp_f32_e32 v73, v73
	v_add_f32_e32 v76, 1.0, v76
	v_add_f32_e32 v77, 1.0, v77
	v_rcp_f32_e32 v76, v76
	v_rcp_f32_e32 v77, v77
	v_pk_mul_f32 v[68:69], v[68:69], v[72:73]
	s_nop 0
	v_pk_mul_f32 v[64:65], v[64:65], v[68:69]
	v_pk_mul_f32 v[68:69], v[70:71], v[76:77]
	v_cvt_pk_bf16_f32 v64, v64, v65
	v_pk_mul_f32 v[66:67], v[66:67], v[68:69]
	v_mul_f32_e32 v68, 0xbfb8aa3b, v62
	v_cvt_pk_bf16_f32 v65, v66, v67
	global_store_dwordx2 v[74:75], v[64:65], off offset:128
	v_mul_f32_e32 v65, 0xbfb8aa3b, v60
	v_exp_f32_e32 v66, v65
	v_mul_f32_e32 v65, 0xbfb8aa3b, v61
	v_exp_f32_e32 v67, v65
	v_mul_f32_e32 v69, 0xbfb8aa3b, v63
	v_exp_f32_e32 v68, v68
	v_exp_f32_e32 v69, v69
	v_add_f32_e32 v66, 1.0, v66
	v_add_f32_e32 v67, 1.0, v67
	v_rcp_f32_e32 v66, v66
	v_rcp_f32_e32 v67, v67
	v_add_f32_e32 v68, 1.0, v68
	v_add_f32_e32 v69, 1.0, v69
	v_rcp_f32_e32 v68, v68
	v_rcp_f32_e32 v69, v69
	v_pk_mul_f32 v[60:61], v[60:61], v[66:67]
	v_add_u32_e32 v64, 0x80, v147
	v_pk_mul_f32 v[56:57], v[56:57], v[60:61]
	v_pk_mul_f32 v[60:61], v[62:63], v[68:69]
	v_mad_i64_i32 v[64:65], s[18:19], v64, s39, v[132:133]
	v_pk_mul_f32 v[58:59], v[58:59], v[60:61]
	v_mul_f32_e32 v60, 0xbfb8aa3b, v52
	v_mul_f32_e32 v61, 0xbfb8aa3b, v53
	v_exp_f32_e32 v60, v60
	v_exp_f32_e32 v61, v61
	v_cvt_pk_bf16_f32 v56, v56, v57
	v_cvt_pk_bf16_f32 v57, v58, v59
	v_lshl_add_u64 v[58:59], v[64:65], 0, s[16:17]
	global_store_dwordx2 v[58:59], v[56:57], off
	v_add_f32_e32 v56, 1.0, v60
	v_add_f32_e32 v57, 1.0, v61
	v_mul_f32_e32 v60, 0xbfb8aa3b, v54
	v_mul_f32_e32 v61, 0xbfb8aa3b, v55
	v_exp_f32_e32 v60, v60
	v_exp_f32_e32 v61, v61
	v_rcp_f32_e32 v56, v56
	v_rcp_f32_e32 v57, v57
	v_add_f32_e32 v60, 1.0, v60
	v_add_f32_e32 v61, 1.0, v61
	v_rcp_f32_e32 v60, v60
	v_rcp_f32_e32 v61, v61
	v_pk_mul_f32 v[52:53], v[52:53], v[56:57]
	s_nop 0
	v_pk_mul_f32 v[48:49], v[48:49], v[52:53]
	v_pk_mul_f32 v[52:53], v[54:55], v[60:61]
	v_cvt_pk_bf16_f32 v48, v48, v49
	v_pk_mul_f32 v[50:51], v[50:51], v[52:53]
	v_mul_f32_e32 v52, 0xbfb8aa3b, v46
	v_cvt_pk_bf16_f32 v49, v50, v51
	global_store_dwordx2 v[58:59], v[48:49], off offset:128
	v_mul_f32_e32 v49, 0xbfb8aa3b, v44
	v_exp_f32_e32 v50, v49
	v_mul_f32_e32 v49, 0xbfb8aa3b, v45
	v_exp_f32_e32 v51, v49
	v_mul_f32_e32 v53, 0xbfb8aa3b, v47
	v_exp_f32_e32 v52, v52
	v_exp_f32_e32 v53, v53
	v_add_f32_e32 v50, 1.0, v50
	v_add_f32_e32 v51, 1.0, v51
	v_rcp_f32_e32 v50, v50
	v_rcp_f32_e32 v51, v51
	v_add_f32_e32 v52, 1.0, v52
	v_add_f32_e32 v53, 1.0, v53
	v_rcp_f32_e32 v52, v52
	v_rcp_f32_e32 v53, v53
	v_pk_mul_f32 v[44:45], v[44:45], v[50:51]
	v_add_u32_e32 v48, 0x90, v147
	v_pk_mul_f32 v[40:41], v[40:41], v[44:45]
	v_pk_mul_f32 v[44:45], v[46:47], v[52:53]
	v_mad_i64_i32 v[48:49], s[18:19], v48, s39, v[132:133]
	v_pk_mul_f32 v[42:43], v[42:43], v[44:45]
	v_mul_f32_e32 v44, 0xbfb8aa3b, v36
	v_mul_f32_e32 v45, 0xbfb8aa3b, v37
	v_exp_f32_e32 v44, v44
	v_exp_f32_e32 v45, v45
	v_cvt_pk_bf16_f32 v40, v40, v41
	v_cvt_pk_bf16_f32 v41, v42, v43
	v_lshl_add_u64 v[42:43], v[48:49], 0, s[16:17]
	global_store_dwordx2 v[42:43], v[40:41], off
	v_add_f32_e32 v40, 1.0, v44
	v_add_f32_e32 v41, 1.0, v45
	v_mul_f32_e32 v44, 0xbfb8aa3b, v38
	v_mul_f32_e32 v45, 0xbfb8aa3b, v39
	v_exp_f32_e32 v44, v44
	v_exp_f32_e32 v45, v45
	v_rcp_f32_e32 v40, v40
	v_rcp_f32_e32 v41, v41
	v_add_f32_e32 v44, 1.0, v44
	v_add_f32_e32 v45, 1.0, v45
	v_rcp_f32_e32 v44, v44
	v_rcp_f32_e32 v45, v45
	v_pk_mul_f32 v[36:37], v[36:37], v[40:41]
	s_nop 0
	v_pk_mul_f32 v[32:33], v[32:33], v[36:37]
	v_pk_mul_f32 v[36:37], v[38:39], v[44:45]
	v_cvt_pk_bf16_f32 v32, v32, v33
	v_pk_mul_f32 v[34:35], v[34:35], v[36:37]
	v_mul_f32_e32 v36, 0xbfb8aa3b, v30
	v_cvt_pk_bf16_f32 v33, v34, v35
	global_store_dwordx2 v[42:43], v[32:33], off offset:128
	v_mul_f32_e32 v33, 0xbfb8aa3b, v28
	v_exp_f32_e32 v34, v33
	v_mul_f32_e32 v33, 0xbfb8aa3b, v29
	v_exp_f32_e32 v35, v33
	v_mul_f32_e32 v37, 0xbfb8aa3b, v31
	v_exp_f32_e32 v36, v36
	v_exp_f32_e32 v37, v37
	v_add_f32_e32 v34, 1.0, v34
	v_add_f32_e32 v35, 1.0, v35
	v_rcp_f32_e32 v34, v34
	v_rcp_f32_e32 v35, v35
	v_add_f32_e32 v36, 1.0, v36
	v_add_f32_e32 v37, 1.0, v37
	v_rcp_f32_e32 v36, v36
	v_rcp_f32_e32 v37, v37
	v_pk_mul_f32 v[28:29], v[28:29], v[34:35]
	v_add_u32_e32 v32, 0xa0, v147
	v_pk_mul_f32 v[24:25], v[24:25], v[28:29]
	v_pk_mul_f32 v[28:29], v[30:31], v[36:37]
	v_mad_i64_i32 v[32:33], s[18:19], v32, s39, v[132:133]
	v_pk_mul_f32 v[26:27], v[26:27], v[28:29]
	v_mul_f32_e32 v28, 0xbfb8aa3b, v20
	v_mul_f32_e32 v29, 0xbfb8aa3b, v21
	v_exp_f32_e32 v28, v28
	v_exp_f32_e32 v29, v29
	v_cvt_pk_bf16_f32 v24, v24, v25
	v_cvt_pk_bf16_f32 v25, v26, v27
	v_lshl_add_u64 v[26:27], v[32:33], 0, s[16:17]
	global_store_dwordx2 v[26:27], v[24:25], off
	v_add_f32_e32 v24, 1.0, v28
	v_add_f32_e32 v25, 1.0, v29
	v_mul_f32_e32 v28, 0xbfb8aa3b, v22
	v_mul_f32_e32 v29, 0xbfb8aa3b, v23
	v_exp_f32_e32 v28, v28
	v_exp_f32_e32 v29, v29
	v_rcp_f32_e32 v24, v24
	v_rcp_f32_e32 v25, v25
	v_add_f32_e32 v28, 1.0, v28
	v_add_f32_e32 v29, 1.0, v29
	v_rcp_f32_e32 v28, v28
	v_rcp_f32_e32 v29, v29
	v_pk_mul_f32 v[20:21], v[20:21], v[24:25]
	s_nop 0
	v_pk_mul_f32 v[16:17], v[16:17], v[20:21]
	v_pk_mul_f32 v[20:21], v[22:23], v[28:29]
	v_cvt_pk_bf16_f32 v16, v16, v17
	v_pk_mul_f32 v[18:19], v[18:19], v[20:21]
	v_mul_f32_e32 v20, 0xbfb8aa3b, v14
	v_cvt_pk_bf16_f32 v17, v18, v19
	global_store_dwordx2 v[26:27], v[16:17], off offset:128
	v_mul_f32_e32 v17, 0xbfb8aa3b, v12
	v_exp_f32_e32 v18, v17
	v_mul_f32_e32 v17, 0xbfb8aa3b, v13
	v_exp_f32_e32 v19, v17
	v_mul_f32_e32 v21, 0xbfb8aa3b, v15
	v_exp_f32_e32 v20, v20
	v_exp_f32_e32 v21, v21
	v_add_f32_e32 v18, 1.0, v18
	v_add_f32_e32 v19, 1.0, v19
	v_rcp_f32_e32 v18, v18
	v_rcp_f32_e32 v19, v19
	v_add_f32_e32 v20, 1.0, v20
	v_add_f32_e32 v21, 1.0, v21
	v_rcp_f32_e32 v20, v20
	v_rcp_f32_e32 v21, v21
	v_pk_mul_f32 v[12:13], v[12:13], v[18:19]
	v_add_u32_e32 v16, 0xb0, v147
	v_pk_mul_f32 v[8:9], v[8:9], v[12:13]
	v_pk_mul_f32 v[12:13], v[14:15], v[20:21]
	v_mad_i64_i32 v[16:17], s[18:19], v16, s39, v[132:133]
	v_pk_mul_f32 v[10:11], v[10:11], v[12:13]
	v_mul_f32_e32 v12, 0xbfb8aa3b, v4
	v_mul_f32_e32 v13, 0xbfb8aa3b, v5
	v_exp_f32_e32 v12, v12
	v_exp_f32_e32 v13, v13
	v_cvt_pk_bf16_f32 v8, v8, v9
	v_cvt_pk_bf16_f32 v9, v10, v11
	v_lshl_add_u64 v[10:11], v[16:17], 0, s[16:17]
	global_store_dwordx2 v[10:11], v[8:9], off
	v_add_f32_e32 v8, 1.0, v12
	v_add_f32_e32 v9, 1.0, v13
	v_mul_f32_e32 v12, 0xbfb8aa3b, v6
	v_mul_f32_e32 v13, 0xbfb8aa3b, v7
	v_exp_f32_e32 v12, v12
	v_exp_f32_e32 v13, v13
	v_rcp_f32_e32 v8, v8
	v_rcp_f32_e32 v9, v9
	v_add_f32_e32 v12, 1.0, v12
	v_add_f32_e32 v13, 1.0, v13
	v_rcp_f32_e32 v12, v12
	v_rcp_f32_e32 v13, v13
	v_pk_mul_f32 v[4:5], v[4:5], v[8:9]
	s_mov_b32 s17, s8
	v_pk_mul_f32 v[0:1], v[0:1], v[4:5]
	v_pk_mul_f32 v[4:5], v[6:7], v[12:13]
	v_cvt_pk_bf16_f32 v0, v0, v1
	v_pk_mul_f32 v[2:3], v[2:3], v[4:5]
	s_mov_b32 s16, s10
	v_cvt_pk_bf16_f32 v1, v2, v3
	s_mov_b64 s[18:19], s[12:13]
	global_store_dwordx2 v[10:11], v[0:1], off offset:128
	s_cbranch_vccz .LBB0_3440
	s_waitcnt vmcnt(0)
	s_cmpk_gt_u32 s0, 0xff
	s_cbranch_scc1 .LBB0_3447
	s_barrier
